# c18 without the mid-block s_setprio 0/1 pair inside each 32-MFMA block (MFMA half's stream is MFMA-only between its two barriers)
# baseline (speedup 1.0000x reference)
;     __host__ __device__ bool next(int i, Unit& u) const { if (!StaticOrder::next(i >> 1, u)) return false; u.seg = i & 1; return true; }
;     ...
;         const bool has_next = S.next(ui + 1, nxt);
;         const char* nA = has_next ? PG8_APTR(nxt) : cA; const char* nB = has_next ? PG8_BPTR(nxt) : cB;
;         const char* pfc = PG8_PFPTR(cA, cB); const char* pfn = PG8_PFPTR(nA, nB);
;         PG8_KITER(0);
.LBB0_248:
	s_ashr_i32 s47, s46, 31
	ds_read_b128 v[2:5], v146
	ds_read_b128 v[6:9], v146 offset:1024
	ds_read_b128 v[10:13], v146 offset:2048
	ds_read_b128 v[14:17], v146 offset:3072
	ds_read_b128 v[18:21], v147
	ds_read_b128 v[22:25], v147 offset:1024
	ds_read_b128 v[26:29], v147 offset:2048
	ds_read_b128 v[30:33], v147 offset:3072
	s_lshl_b64 s[14:15], s[46:47], 21
	s_add_u32 s60, s36, s14
	s_addc_u32 s61, s37, s15
	s_and_b64 s[14:15], s[0:1], exec
	s_cselect_b32 s47, s61, s71
	s_cselect_b32 s93, s60, s70
	s_and_b32 s4, s91, 0x7fffffff
	s_lshl_b64 s[14:15], s[4:5], 21
	s_add_u32 s62, s96, s14
	s_addc_u32 s63, s97, s15
	s_and_b64 s[14:15], s[0:1], exec
	s_cselect_b32 s4, s63, s67
	s_cselect_b32 s94, s62, s66
	s_add_u32 s14, s70, 0x100080
	s_addc_u32 s15, s71, 0
	s_mov_b32 m0, s78
	v_lshl_add_u64 v[66:67], s[14:15], 0, v[136:137]
	ds_read_b128 v[34:37], v148
	ds_read_b128 v[38:41], v148 offset:1024
	ds_read_b128 v[42:45], v148 offset:2048
	ds_read_b128 v[46:49], v148 offset:3072
	ds_read_b128 v[50:53], v148 offset:4096
	ds_read_b128 v[54:57], v148 offset:5120
	ds_read_b128 v[58:61], v148 offset:6144
	ds_read_b128 v[62:65], v148 offset:7168
	global_load_lds_dwordx4 v[66:67], off
	v_lshl_add_u64 v[66:67], s[14:15], 0, v[132:133]
	s_mov_b32 m0, s79
	s_nop 0
	global_load_lds_dwordx4 v[66:67], off
	s_waitcnt vmcnt(8)
	s_waitcnt lgkmcnt(0)
	s_setprio 1
	s_barrier
	v_mfma_f32_16x16x32_bf16 v[90:93], v[2:5], v[58:61], 0
	v_mfma_f32_16x16x32_bf16 v[66:69], v[2:5], v[34:37], 0
	v_mfma_f32_16x16x32_bf16 v[70:73], v[10:13], v[34:37], 0
	v_mfma_f32_16x16x32_bf16 v[74:77], v[2:5], v[42:45], 0
	v_mfma_f32_16x16x32_bf16 v[78:81], v[10:13], v[42:45], 0
	v_mfma_f32_16x16x32_bf16 v[82:85], v[2:5], v[50:53], 0
	v_mfma_f32_16x16x32_bf16 v[86:89], v[10:13], v[50:53], 0
	v_mfma_f32_16x16x32_bf16 v[94:97], v[6:9], v[62:65], v[90:93]
	v_mfma_f32_16x16x32_bf16 v[90:93], v[10:13], v[58:61], 0
	v_mfma_f32_16x16x32_bf16 v[66:69], v[6:9], v[38:41], v[66:69]
	v_mfma_f32_16x16x32_bf16 v[70:73], v[14:17], v[38:41], v[70:73]
	v_mfma_f32_16x16x32_bf16 v[74:77], v[6:9], v[46:49], v[74:77]
	v_mfma_f32_16x16x32_bf16 v[78:81], v[14:17], v[46:49], v[78:81]
	v_mfma_f32_16x16x32_bf16 v[82:85], v[6:9], v[54:57], v[82:85]
	v_mfma_f32_16x16x32_bf16 v[86:89], v[14:17], v[54:57], v[86:89]
	v_mfma_f32_16x16x32_bf16 v[102:105], v[14:17], v[62:65], v[90:93]
	v_mfma_f32_16x16x32_bf16 v[90:93], v[18:21], v[34:37], 0
	v_mfma_f32_16x16x32_bf16 v[34:37], v[26:29], v[34:37], 0
	v_mfma_f32_16x16x32_bf16 v[110:113], v[22:25], v[38:41], v[90:93]
	v_mfma_f32_16x16x32_bf16 v[34:37], v[30:33], v[38:41], v[34:37]
	v_mfma_f32_16x16x32_bf16 v[38:41], v[18:21], v[42:45], 0
	v_mfma_f32_16x16x32_bf16 v[42:45], v[26:29], v[42:45], 0
	v_mfma_f32_16x16x32_bf16 v[38:41], v[22:25], v[46:49], v[38:41]
	v_mfma_f32_16x16x32_bf16 v[42:45], v[30:33], v[46:49], v[42:45]
	v_mfma_f32_16x16x32_bf16 v[46:49], v[18:21], v[50:53], 0
	v_mfma_f32_16x16x32_bf16 v[50:53], v[26:29], v[50:53], 0
	v_mfma_f32_16x16x32_bf16 v[46:49], v[22:25], v[54:57], v[46:49]
	v_mfma_f32_16x16x32_bf16 v[50:53], v[30:33], v[54:57], v[50:53]
	v_mfma_f32_16x16x32_bf16 v[54:57], v[18:21], v[58:61], 0
	v_mfma_f32_16x16x32_bf16 v[58:61], v[26:29], v[58:61], 0
	v_mfma_f32_16x16x32_bf16 v[54:57], v[22:25], v[62:65], v[54:57]
	v_mfma_f32_16x16x32_bf16 v[62:65], v[30:33], v[62:65], v[58:61]
	s_barrier
	s_setprio 0
	v_lshl_add_u64 v[248:249], s[66:67], 0, v[134:135]
	s_mov_b32 m0, s81
	v_lshl_add_u64 v[152:153], v[248:249], 0, s[18:19]
	v_lshl_add_u64 v[250:251], s[66:67], 0, v[130:131]
	s_add_u32 s14, s66, 0x100100
	ds_read_b128 v[58:61], v148 offset:16384
	ds_read_b128 v[90:93], v148 offset:17408
	ds_read_b128 v[98:101], v148 offset:18432
	ds_read_b128 v[106:109], v148 offset:19456
	ds_read_b128 v[114:117], v148 offset:20480
	ds_read_b128 v[118:121], v148 offset:21504
	ds_read_b128 v[122:125], v148 offset:22528
	ds_read_b128 v[126:129], v148 offset:23552
	global_load_lds_dwordx4 v[152:153], off
	v_lshl_add_u64 v[152:153], v[250:251], 0, s[18:19]
	s_mov_b32 m0, s82
	s_addc_u32 s15, s67, 0
	global_load_lds_dwordx4 v[152:153], off
	v_lshl_add_u64 v[152:153], s[14:15], 0, v[134:135]
	s_mov_b32 m0, s83
	v_lshl_add_u64 v[252:253], s[70:71], 0, v[136:137]
	global_load_lds_dwordx4 v[152:153], off
	v_lshl_add_u64 v[152:153], s[14:15], 0, v[130:131]
	s_mov_b32 m0, s86
	v_lshl_add_u64 v[142:143], s[70:71], 0, v[132:133]
	global_load_lds_dwordx4 v[152:153], off
	v_lshl_add_u64 v[152:153], v[252:253], 0, s[18:19]
	s_mov_b32 m0, s29
	s_nop 0
	global_load_lds_dwordx4 v[152:153], off
	v_lshl_add_u64 v[152:153], v[142:143], 0, s[18:19]
	s_mov_b32 m0, s33
	s_nop 0
	global_load_lds_dwordx4 v[152:153], off
	s_waitcnt vmcnt(8)
	s_waitcnt lgkmcnt(0)
	s_setprio 1
	s_barrier
	v_mfma_f32_16x16x32_bf16 v[152:155], v[2:5], v[58:61], 0
	v_mfma_f32_16x16x32_bf16 v[160:163], v[2:5], v[98:101], 0
	v_mfma_f32_16x16x32_bf16 v[168:171], v[2:5], v[114:117], 0
	v_mfma_f32_16x16x32_bf16 v[2:5], v[2:5], v[122:125], 0
	v_mfma_f32_16x16x32_bf16 v[152:155], v[6:9], v[90:93], v[152:155]
	v_mfma_f32_16x16x32_bf16 v[160:163], v[6:9], v[106:109], v[160:163]
	v_mfma_f32_16x16x32_bf16 v[168:171], v[6:9], v[118:121], v[168:171]
	v_mfma_f32_16x16x32_bf16 v[2:5], v[6:9], v[126:129], v[2:5]
	v_mfma_f32_16x16x32_bf16 v[6:9], v[10:13], v[122:125], 0
	v_mfma_f32_16x16x32_bf16 v[156:159], v[10:13], v[58:61], 0
	v_mfma_f32_16x16x32_bf16 v[164:167], v[10:13], v[98:101], 0
	v_mfma_f32_16x16x32_bf16 v[172:175], v[10:13], v[114:117], 0
	v_mfma_f32_16x16x32_bf16 v[6:9], v[14:17], v[126:129], v[6:9]
	v_mfma_f32_16x16x32_bf16 v[156:159], v[14:17], v[90:93], v[156:159]
	v_mfma_f32_16x16x32_bf16 v[164:167], v[14:17], v[106:109], v[164:167]
	v_mfma_f32_16x16x32_bf16 v[172:175], v[14:17], v[118:121], v[172:175]
	v_mfma_f32_16x16x32_bf16 v[10:13], v[18:21], v[58:61], 0
	v_mfma_f32_16x16x32_bf16 v[14:17], v[22:25], v[90:93], v[10:13]
	v_mfma_f32_16x16x32_bf16 v[10:13], v[26:29], v[58:61], 0
	v_mfma_f32_16x16x32_bf16 v[176:179], v[30:33], v[90:93], v[10:13]
	v_mfma_f32_16x16x32_bf16 v[10:13], v[18:21], v[98:101], 0
	v_mfma_f32_16x16x32_bf16 v[180:183], v[22:25], v[106:109], v[10:13]
	v_mfma_f32_16x16x32_bf16 v[10:13], v[26:29], v[98:101], 0
	v_mfma_f32_16x16x32_bf16 v[184:187], v[30:33], v[106:109], v[10:13]
	v_mfma_f32_16x16x32_bf16 v[10:13], v[18:21], v[114:117], 0
	v_mfma_f32_16x16x32_bf16 v[188:191], v[22:25], v[118:121], v[10:13]
	v_mfma_f32_16x16x32_bf16 v[10:13], v[26:29], v[114:117], 0
	v_mfma_f32_16x16x32_bf16 v[192:195], v[30:33], v[118:121], v[10:13]
	v_mfma_f32_16x16x32_bf16 v[10:13], v[18:21], v[122:125], 0
	v_mfma_f32_16x16x32_bf16 v[196:199], v[22:25], v[126:129], v[10:13]
	v_mfma_f32_16x16x32_bf16 v[10:13], v[26:29], v[122:125], 0
	v_mfma_f32_16x16x32_bf16 v[200:203], v[30:33], v[126:129], v[10:13]
	s_barrier
	s_setprio 0
	s_nop 4
	ds_read_b128 v[10:13], v149
	ds_read_b128 v[22:25], v149 offset:1024
	ds_read_b128 v[30:33], v149 offset:2048
	ds_read_b128 v[204:207], v149 offset:3072
	ds_read_b128 v[208:211], v150
	ds_read_b128 v[212:215], v150 offset:1024
	ds_read_b128 v[216:219], v150 offset:2048
	ds_read_b128 v[220:223], v150 offset:3072
	s_add_u32 s14, s70, 0x100100
	s_addc_u32 s15, s71, 0
	s_mov_b32 m0, s58
	v_lshl_add_u64 v[58:59], s[14:15], 0, v[136:137]
	ds_read_b128 v[18:21], v148 offset:32768
	ds_read_b128 v[26:29], v148 offset:33792
	ds_read_b128 v[224:227], v148 offset:34816
	ds_read_b128 v[228:231], v148 offset:35840
	ds_read_b128 v[232:235], v148 offset:36864
	ds_read_b128 v[236:239], v148 offset:37888
	ds_read_b128 v[240:243], v148 offset:38912
	ds_read_b128 v[244:247], v148 offset:39936
	global_load_lds_dwordx4 v[58:59], off
	v_lshl_add_u64 v[58:59], s[14:15], 0, v[132:133]
	s_mov_b32 m0, s59
	s_nop 0
	global_load_lds_dwordx4 v[58:59], off
	s_waitcnt vmcnt(8)
	s_waitcnt lgkmcnt(0)
	s_setprio 1
	s_barrier
	v_mfma_f32_16x16x32_bf16 v[58:61], v[10:13], v[18:21], v[66:69]
	v_mfma_f32_16x16x32_bf16 v[122:125], v[22:25], v[26:29], v[58:61]
	v_mfma_f32_16x16x32_bf16 v[58:61], v[30:33], v[18:21], v[70:73]
	v_mfma_f32_16x16x32_bf16 v[114:117], v[204:207], v[26:29], v[58:61]
	v_mfma_f32_16x16x32_bf16 v[58:61], v[10:13], v[224:227], v[74:77]
	v_mfma_f32_16x16x32_bf16 v[106:109], v[22:25], v[228:231], v[58:61]
	v_mfma_f32_16x16x32_bf16 v[58:61], v[30:33], v[224:227], v[78:81]
	v_mfma_f32_16x16x32_bf16 v[98:101], v[204:207], v[228:231], v[58:61]
	v_mfma_f32_16x16x32_bf16 v[58:61], v[10:13], v[232:235], v[82:85]
	v_mfma_f32_16x16x32_bf16 v[90:93], v[22:25], v[236:239], v[58:61]
	v_mfma_f32_16x16x32_bf16 v[58:61], v[30:33], v[232:235], v[86:89]
	v_mfma_f32_16x16x32_bf16 v[82:85], v[204:207], v[236:239], v[58:61]
	v_mfma_f32_16x16x32_bf16 v[58:61], v[10:13], v[240:243], v[94:97]
	v_mfma_f32_16x16x32_bf16 v[74:77], v[22:25], v[244:247], v[58:61]
	v_mfma_f32_16x16x32_bf16 v[58:61], v[30:33], v[240:243], v[102:105]
	v_mfma_f32_16x16x32_bf16 v[58:61], v[204:207], v[244:247], v[58:61]
	v_mfma_f32_16x16x32_bf16 v[66:69], v[208:211], v[18:21], v[110:113]
	v_mfma_f32_16x16x32_bf16 v[18:21], v[216:219], v[18:21], v[34:37]
	v_mfma_f32_16x16x32_bf16 v[118:121], v[220:223], v[26:29], v[18:21]
	v_mfma_f32_16x16x32_bf16 v[18:21], v[208:211], v[224:227], v[38:41]
	v_mfma_f32_16x16x32_bf16 v[110:113], v[212:215], v[228:231], v[18:21]
	v_mfma_f32_16x16x32_bf16 v[18:21], v[216:219], v[224:227], v[42:45]
	v_mfma_f32_16x16x32_bf16 v[102:105], v[220:223], v[228:231], v[18:21]
	v_mfma_f32_16x16x32_bf16 v[18:21], v[208:211], v[232:235], v[46:49]
	v_mfma_f32_16x16x32_bf16 v[94:97], v[212:215], v[236:239], v[18:21]
	v_mfma_f32_16x16x32_bf16 v[18:21], v[216:219], v[232:235], v[50:53]
	v_mfma_f32_16x16x32_bf16 v[86:89], v[220:223], v[236:239], v[18:21]
	v_mfma_f32_16x16x32_bf16 v[18:21], v[208:211], v[240:243], v[54:57]
	v_mfma_f32_16x16x32_bf16 v[78:81], v[212:215], v[244:247], v[18:21]
	v_mfma_f32_16x16x32_bf16 v[18:21], v[216:219], v[240:243], v[62:65]
	v_mfma_f32_16x16x32_bf16 v[126:129], v[212:215], v[26:29], v[66:69]
	v_mfma_f32_16x16x32_bf16 v[66:69], v[220:223], v[244:247], v[18:21]
	s_barrier
	s_setprio 0
	s_mov_b32 m0, s87
	s_nop 2
	v_lshl_add_u64 v[18:19], v[248:249], 0, s[30:31]
	s_add_u32 s14, s66, 0x100180
	ds_read_b128 v[38:41], v148 offset:49152
	ds_read_b128 v[46:49], v148 offset:50176
	ds_read_b128 v[224:227], v148 offset:51200
	ds_read_b128 v[228:231], v148 offset:52224
	ds_read_b128 v[232:235], v148 offset:53248
	ds_read_b128 v[236:239], v148 offset:54272
	ds_read_b128 v[240:243], v148 offset:55296
	ds_read_b128 v[244:247], v148 offset:56320
	global_load_lds_dwordx4 v[18:19], off
	v_lshl_add_u64 v[18:19], v[250:251], 0, s[30:31]
	s_mov_b32 m0, s88
	s_addc_u32 s15, s67, 0
	global_load_lds_dwordx4 v[18:19], off
	v_lshl_add_u64 v[18:19], s[14:15], 0, v[134:135]
	s_mov_b32 m0, s89
	s_add_i32 s56, s89, 0x2000
	global_load_lds_dwordx4 v[18:19], off
	v_lshl_add_u64 v[18:19], s[14:15], 0, v[130:131]
	s_mov_b32 m0, s56
	s_nop 0
	global_load_lds_dwordx4 v[18:19], off
	v_lshl_add_u64 v[18:19], v[252:253], 0, s[30:31]
	s_mov_b32 m0, s65
	s_nop 0
	global_load_lds_dwordx4 v[18:19], off
	v_lshl_add_u64 v[18:19], v[142:143], 0, s[30:31]
	s_mov_b32 m0, s76
	s_nop 0
	global_load_lds_dwordx4 v[18:19], off
	s_waitcnt vmcnt(8)
	s_waitcnt lgkmcnt(0)
	s_setprio 1
	s_barrier
	v_mfma_f32_16x16x32_bf16 v[18:21], v[10:13], v[38:41], v[152:155]
	v_mfma_f32_16x16x32_bf16 v[62:65], v[22:25], v[46:49], v[18:21]
	v_mfma_f32_16x16x32_bf16 v[18:21], v[30:33], v[38:41], v[156:159]
	v_mfma_f32_16x16x32_bf16 v[50:53], v[204:207], v[46:49], v[18:21]
	v_mfma_f32_16x16x32_bf16 v[18:21], v[10:13], v[224:227], v[160:163]
	v_mfma_f32_16x16x32_bf16 v[42:45], v[22:25], v[228:231], v[18:21]
	v_mfma_f32_16x16x32_bf16 v[18:21], v[30:33], v[224:227], v[164:167]
	v_mfma_f32_16x16x32_bf16 v[34:37], v[204:207], v[228:231], v[18:21]
	v_mfma_f32_16x16x32_bf16 v[18:21], v[10:13], v[232:235], v[168:171]
	v_mfma_f32_16x16x32_bf16 v[2:5], v[10:13], v[240:243], v[2:5]
	v_mfma_f32_16x16x32_bf16 v[26:29], v[22:25], v[236:239], v[18:21]
	v_mfma_f32_16x16x32_bf16 v[18:21], v[30:33], v[232:235], v[172:175]
	v_mfma_f32_16x16x32_bf16 v[10:13], v[22:25], v[244:247], v[2:5]
	v_mfma_f32_16x16x32_bf16 v[2:5], v[30:33], v[240:243], v[6:9]
	v_mfma_f32_16x16x32_bf16 v[18:21], v[204:207], v[236:239], v[18:21]
	v_mfma_f32_16x16x32_bf16 v[2:5], v[204:207], v[244:247], v[2:5]
	v_mfma_f32_16x16x32_bf16 v[6:9], v[208:211], v[38:41], v[14:17]
	v_mfma_f32_16x16x32_bf16 v[70:73], v[212:215], v[46:49], v[6:9]
	v_mfma_f32_16x16x32_bf16 v[6:9], v[216:219], v[38:41], v[176:179]
	v_mfma_f32_16x16x32_bf16 v[54:57], v[220:223], v[46:49], v[6:9]
	v_mfma_f32_16x16x32_bf16 v[6:9], v[208:211], v[224:227], v[180:183]
	v_mfma_f32_16x16x32_bf16 v[46:49], v[212:215], v[228:231], v[6:9]
	v_mfma_f32_16x16x32_bf16 v[6:9], v[216:219], v[224:227], v[184:187]
	v_mfma_f32_16x16x32_bf16 v[38:41], v[220:223], v[228:231], v[6:9]
	v_mfma_f32_16x16x32_bf16 v[6:9], v[208:211], v[232:235], v[188:191]
	v_mfma_f32_16x16x32_bf16 v[30:33], v[212:215], v[236:239], v[6:9]
	v_mfma_f32_16x16x32_bf16 v[6:9], v[216:219], v[232:235], v[192:195]
	v_mfma_f32_16x16x32_bf16 v[22:25], v[220:223], v[236:239], v[6:9]
	v_mfma_f32_16x16x32_bf16 v[6:9], v[208:211], v[240:243], v[196:199]
	v_mfma_f32_16x16x32_bf16 v[14:17], v[212:215], v[244:247], v[6:9]
	v_mfma_f32_16x16x32_bf16 v[6:9], v[216:219], v[240:243], v[200:203]
	v_mfma_f32_16x16x32_bf16 v[6:9], v[220:223], v[244:247], v[6:9]
	s_barrier
	s_setprio 0
	s_add_u32 s70, s70, 0x100180
	s_addc_u32 s71, s71, 0
	s_add_u32 s57, s66, 0x200
	s_addc_u32 s14, s67, 0
	s_mov_b32 s15, 0

.Lrb2_skip_7701:
	s_mov_b32 m0, s78
	ds_read_b128 v[184:187], v148
	ds_read_b128 v[188:191], v148 offset:1024
	ds_read_b128 v[192:195], v148 offset:2048
	ds_read_b128 v[196:199], v148 offset:3072
	ds_read_b128 v[200:203], v148 offset:4096
	ds_read_b128 v[204:207], v148 offset:5120
	ds_read_b128 v[208:211], v148 offset:6144
	ds_read_b128 v[212:215], v148 offset:7168
	global_load_lds_dwordx4 v138, s[70:71]
	s_mov_b32 m0, s79
	s_nop 0
	global_load_lds_dwordx4 v140, s[70:71]
	s_waitcnt vmcnt(8)
	s_waitcnt lgkmcnt(0)
	s_setprio 1
	s_barrier
	v_mfma_f32_16x16x32_bf16 v[122:125], v[152:155], v[184:187], v[122:125]
	v_mfma_f32_16x16x32_bf16 v[114:117], v[160:163], v[184:187], v[114:117]
	v_mfma_f32_16x16x32_bf16 v[106:109], v[152:155], v[192:195], v[106:109]
	v_mfma_f32_16x16x32_bf16 v[98:101], v[160:163], v[192:195], v[98:101]
	v_mfma_f32_16x16x32_bf16 v[90:93], v[152:155], v[200:203], v[90:93]
	v_mfma_f32_16x16x32_bf16 v[82:85], v[160:163], v[200:203], v[82:85]
	v_mfma_f32_16x16x32_bf16 v[74:77], v[152:155], v[208:211], v[74:77]
	v_mfma_f32_16x16x32_bf16 v[58:61], v[160:163], v[208:211], v[58:61]
	v_mfma_f32_16x16x32_bf16 v[122:125], v[156:159], v[188:191], v[122:125]
	v_mfma_f32_16x16x32_bf16 v[114:117], v[164:167], v[188:191], v[114:117]
	v_mfma_f32_16x16x32_bf16 v[106:109], v[156:159], v[196:199], v[106:109]
	v_mfma_f32_16x16x32_bf16 v[98:101], v[164:167], v[196:199], v[98:101]
	v_mfma_f32_16x16x32_bf16 v[90:93], v[156:159], v[204:207], v[90:93]
	v_mfma_f32_16x16x32_bf16 v[82:85], v[164:167], v[204:207], v[82:85]
	v_mfma_f32_16x16x32_bf16 v[74:77], v[156:159], v[212:215], v[74:77]
	v_mfma_f32_16x16x32_bf16 v[58:61], v[164:167], v[212:215], v[58:61]
	v_mfma_f32_16x16x32_bf16 v[126:129], v[168:171], v[184:187], v[126:129]
	v_mfma_f32_16x16x32_bf16 v[118:121], v[176:179], v[184:187], v[118:121]
	v_mfma_f32_16x16x32_bf16 v[110:113], v[168:171], v[192:195], v[110:113]
	v_mfma_f32_16x16x32_bf16 v[102:105], v[176:179], v[192:195], v[102:105]
	v_mfma_f32_16x16x32_bf16 v[94:97], v[168:171], v[200:203], v[94:97]
	v_mfma_f32_16x16x32_bf16 v[86:89], v[176:179], v[200:203], v[86:89]
	v_mfma_f32_16x16x32_bf16 v[78:81], v[168:171], v[208:211], v[78:81]
	v_mfma_f32_16x16x32_bf16 v[66:69], v[176:179], v[208:211], v[66:69]
	v_mfma_f32_16x16x32_bf16 v[126:129], v[172:175], v[188:191], v[126:129]
	v_mfma_f32_16x16x32_bf16 v[118:121], v[180:183], v[188:191], v[118:121]
	v_mfma_f32_16x16x32_bf16 v[110:113], v[172:175], v[196:199], v[110:113]
	v_mfma_f32_16x16x32_bf16 v[102:105], v[180:183], v[196:199], v[102:105]
	v_mfma_f32_16x16x32_bf16 v[94:97], v[172:175], v[204:207], v[94:97]
	v_mfma_f32_16x16x32_bf16 v[86:89], v[180:183], v[204:207], v[86:89]
	v_mfma_f32_16x16x32_bf16 v[78:81], v[172:175], v[212:215], v[78:81]
	v_mfma_f32_16x16x32_bf16 v[66:69], v[180:183], v[212:215], v[66:69]
	s_barrier
	s_setprio 0
	s_mov_b32 m0, s81
	s_mov_b64 s[98:99], s[66:67]
	s_add_u32 s16, s66, 0x100000
	ds_read_b128 v[184:187], v148 offset:16384
	ds_read_b128 v[188:191], v148 offset:17408
	ds_read_b128 v[192:195], v148 offset:18432
	ds_read_b128 v[196:199], v148 offset:19456
	ds_read_b128 v[200:203], v148 offset:20480
	ds_read_b128 v[204:207], v148 offset:21504
	ds_read_b128 v[208:211], v148 offset:22528
	ds_read_b128 v[212:215], v148 offset:23552
	global_load_lds_dwordx4 v134, s[66:67]
	s_mov_b32 m0, s82
	s_addc_u32 s17, s67, 0
	global_load_lds_dwordx4 v130, s[66:67]
	s_mov_b32 m0, s83
	s_mov_b64 s[100:101], s[74:75]
	global_load_lds_dwordx4 v134, s[16:17]
	s_mov_b32 m0, s86
	s_nop 0
	global_load_lds_dwordx4 v130, s[16:17]
	s_waitcnt vmcnt(6)
	s_waitcnt lgkmcnt(0)
	s_setprio 1
	s_barrier
	v_mfma_f32_16x16x32_bf16 v[62:65], v[152:155], v[184:187], v[62:65]
	v_mfma_f32_16x16x32_bf16 v[50:53], v[160:163], v[184:187], v[50:53]
	v_mfma_f32_16x16x32_bf16 v[42:45], v[152:155], v[192:195], v[42:45]
	v_mfma_f32_16x16x32_bf16 v[34:37], v[160:163], v[192:195], v[34:37]
	v_mfma_f32_16x16x32_bf16 v[26:29], v[152:155], v[200:203], v[26:29]
	v_mfma_f32_16x16x32_bf16 v[18:21], v[160:163], v[200:203], v[18:21]
	v_mfma_f32_16x16x32_bf16 v[10:13], v[152:155], v[208:211], v[10:13]
	v_mfma_f32_16x16x32_bf16 v[2:5], v[160:163], v[208:211], v[2:5]
	v_mfma_f32_16x16x32_bf16 v[62:65], v[156:159], v[188:191], v[62:65]
	v_mfma_f32_16x16x32_bf16 v[50:53], v[164:167], v[188:191], v[50:53]
	v_mfma_f32_16x16x32_bf16 v[42:45], v[156:159], v[196:199], v[42:45]
	v_mfma_f32_16x16x32_bf16 v[34:37], v[164:167], v[196:199], v[34:37]
	v_mfma_f32_16x16x32_bf16 v[26:29], v[156:159], v[204:207], v[26:29]
	v_mfma_f32_16x16x32_bf16 v[18:21], v[164:167], v[204:207], v[18:21]
	v_mfma_f32_16x16x32_bf16 v[10:13], v[156:159], v[212:215], v[10:13]
	v_mfma_f32_16x16x32_bf16 v[2:5], v[164:167], v[212:215], v[2:5]
	v_mfma_f32_16x16x32_bf16 v[70:73], v[168:171], v[184:187], v[70:73]
	v_mfma_f32_16x16x32_bf16 v[54:57], v[176:179], v[184:187], v[54:57]
	v_mfma_f32_16x16x32_bf16 v[46:49], v[168:171], v[192:195], v[46:49]
	v_mfma_f32_16x16x32_bf16 v[38:41], v[176:179], v[192:195], v[38:41]
	v_mfma_f32_16x16x32_bf16 v[30:33], v[168:171], v[200:203], v[30:33]
	v_mfma_f32_16x16x32_bf16 v[22:25], v[176:179], v[200:203], v[22:25]
	v_mfma_f32_16x16x32_bf16 v[14:17], v[168:171], v[208:211], v[14:17]
	v_mfma_f32_16x16x32_bf16 v[6:9], v[176:179], v[208:211], v[6:9]
	v_mfma_f32_16x16x32_bf16 v[70:73], v[172:175], v[188:191], v[70:73]
	v_mfma_f32_16x16x32_bf16 v[54:57], v[180:183], v[188:191], v[54:57]
	v_mfma_f32_16x16x32_bf16 v[46:49], v[172:175], v[196:199], v[46:49]
	v_mfma_f32_16x16x32_bf16 v[38:41], v[180:183], v[196:199], v[38:41]
	v_mfma_f32_16x16x32_bf16 v[30:33], v[172:175], v[204:207], v[30:33]
	v_mfma_f32_16x16x32_bf16 v[22:25], v[180:183], v[204:207], v[22:25]
	v_mfma_f32_16x16x32_bf16 v[14:17], v[172:175], v[212:215], v[14:17]
	v_mfma_f32_16x16x32_bf16 v[6:9], v[180:183], v[212:215], v[6:9]
	s_barrier
; #define PG8_BAR __builtin_amdgcn_s_barrier()
;     ...
;         for (int t = 2; t < nt; t += 2) PG8_KITER(t);
;         if constexpr (ALIGN_EPI) { if (wr == 0) PG8_BAR; }
	s_setprio 0
	ds_read_b128 v[152:155], v149
	ds_read_b128 v[156:159], v149 offset:1024
	ds_read_b128 v[160:163], v149 offset:2048
	ds_read_b128 v[164:167], v149 offset:3072
	ds_read_b128 v[168:171], v150
	ds_read_b128 v[172:175], v150 offset:1024
	ds_read_b128 v[176:179], v150 offset:2048
	ds_read_b128 v[180:183], v150 offset:3072
	s_add_u32 s16, s74, 0x100000
	s_addc_u32 s17, s75, 0
	s_mov_b32 m0, s29
	s_nop 0
	global_load_lds_dwordx4 v136, s[100:101]
	s_mov_b32 m0, s33
	s_nop 0
	global_load_lds_dwordx4 v132, s[100:101]
	s_mov_b32 m0, s58
	ds_read_b128 v[184:187], v148 offset:32768
	ds_read_b128 v[188:191], v148 offset:33792
	ds_read_b128 v[192:195], v148 offset:34816
	ds_read_b128 v[196:199], v148 offset:35840
	ds_read_b128 v[200:203], v148 offset:36864
	ds_read_b128 v[204:207], v148 offset:37888
	ds_read_b128 v[208:211], v148 offset:38912
	ds_read_b128 v[212:215], v148 offset:39936
	global_load_lds_dwordx4 v136, s[16:17]
	s_mov_b32 m0, s59
	s_nop 0
	global_load_lds_dwordx4 v132, s[16:17]
	s_waitcnt vmcnt(8)
	s_waitcnt lgkmcnt(0)
	s_setprio 1
	s_barrier
	v_mfma_f32_16x16x32_bf16 v[122:125], v[152:155], v[184:187], v[122:125]
	v_mfma_f32_16x16x32_bf16 v[114:117], v[160:163], v[184:187], v[114:117]
	v_mfma_f32_16x16x32_bf16 v[106:109], v[152:155], v[192:195], v[106:109]
	v_mfma_f32_16x16x32_bf16 v[98:101], v[160:163], v[192:195], v[98:101]
	v_mfma_f32_16x16x32_bf16 v[90:93], v[152:155], v[200:203], v[90:93]
	v_mfma_f32_16x16x32_bf16 v[82:85], v[160:163], v[200:203], v[82:85]
	v_mfma_f32_16x16x32_bf16 v[74:77], v[152:155], v[208:211], v[74:77]
	v_mfma_f32_16x16x32_bf16 v[58:61], v[160:163], v[208:211], v[58:61]
	v_mfma_f32_16x16x32_bf16 v[122:125], v[156:159], v[188:191], v[122:125]
	v_mfma_f32_16x16x32_bf16 v[114:117], v[164:167], v[188:191], v[114:117]
	v_mfma_f32_16x16x32_bf16 v[106:109], v[156:159], v[196:199], v[106:109]
	v_mfma_f32_16x16x32_bf16 v[98:101], v[164:167], v[196:199], v[98:101]
	v_mfma_f32_16x16x32_bf16 v[90:93], v[156:159], v[204:207], v[90:93]
	v_mfma_f32_16x16x32_bf16 v[82:85], v[164:167], v[204:207], v[82:85]
	v_mfma_f32_16x16x32_bf16 v[74:77], v[156:159], v[212:215], v[74:77]
	v_mfma_f32_16x16x32_bf16 v[58:61], v[164:167], v[212:215], v[58:61]
	v_mfma_f32_16x16x32_bf16 v[126:129], v[168:171], v[184:187], v[126:129]
	v_mfma_f32_16x16x32_bf16 v[118:121], v[176:179], v[184:187], v[118:121]
	v_mfma_f32_16x16x32_bf16 v[110:113], v[168:171], v[192:195], v[110:113]
	v_mfma_f32_16x16x32_bf16 v[102:105], v[176:179], v[192:195], v[102:105]
	v_mfma_f32_16x16x32_bf16 v[94:97], v[168:171], v[200:203], v[94:97]
	v_mfma_f32_16x16x32_bf16 v[86:89], v[176:179], v[200:203], v[86:89]
	v_mfma_f32_16x16x32_bf16 v[78:81], v[168:171], v[208:211], v[78:81]
	v_mfma_f32_16x16x32_bf16 v[66:69], v[176:179], v[208:211], v[66:69]
	v_mfma_f32_16x16x32_bf16 v[126:129], v[172:175], v[188:191], v[126:129]
	v_mfma_f32_16x16x32_bf16 v[118:121], v[180:183], v[188:191], v[118:121]
	v_mfma_f32_16x16x32_bf16 v[110:113], v[172:175], v[196:199], v[110:113]
	v_mfma_f32_16x16x32_bf16 v[102:105], v[180:183], v[196:199], v[102:105]
	v_mfma_f32_16x16x32_bf16 v[94:97], v[172:175], v[204:207], v[94:97]
	v_mfma_f32_16x16x32_bf16 v[86:89], v[180:183], v[204:207], v[86:89]
	v_mfma_f32_16x16x32_bf16 v[78:81], v[172:175], v[212:215], v[78:81]
	v_mfma_f32_16x16x32_bf16 v[66:69], v[180:183], v[212:215], v[66:69]
	s_barrier
	s_setprio 0
	s_mov_b32 m0, s87
	s_add_u32 s98, s98, 0x80
	s_addc_u32 s99, s99, 0
	s_add_u32 s100, s100, 0x80
	s_addc_u32 s101, s101, 0
	s_add_u32 s16, s66, 0x100080
	ds_read_b128 v[184:187], v148 offset:49152
	ds_read_b128 v[188:191], v148 offset:50176
	ds_read_b128 v[192:195], v148 offset:51200
	ds_read_b128 v[196:199], v148 offset:52224
	ds_read_b128 v[200:203], v148 offset:53248
	ds_read_b128 v[204:207], v148 offset:54272
	ds_read_b128 v[208:211], v148 offset:55296
	ds_read_b128 v[212:215], v148 offset:56320
	global_load_lds_dwordx4 v134, s[98:99]
	s_mov_b32 m0, s88
	s_addc_u32 s17, s67, 0
	global_load_lds_dwordx4 v130, s[98:99]
	s_mov_b32 m0, s89
	s_nop 0
	global_load_lds_dwordx4 v134, s[16:17]
	s_mov_b32 m0, s56
	s_nop 0
	global_load_lds_dwordx4 v130, s[16:17]
	s_waitcnt vmcnt(6)
	s_waitcnt lgkmcnt(0)
	s_setprio 1
	s_barrier
	v_mfma_f32_16x16x32_bf16 v[62:65], v[152:155], v[184:187], v[62:65]
	v_mfma_f32_16x16x32_bf16 v[50:53], v[160:163], v[184:187], v[50:53]
	v_mfma_f32_16x16x32_bf16 v[42:45], v[152:155], v[192:195], v[42:45]
	v_mfma_f32_16x16x32_bf16 v[34:37], v[160:163], v[192:195], v[34:37]
	v_mfma_f32_16x16x32_bf16 v[26:29], v[152:155], v[200:203], v[26:29]
	v_mfma_f32_16x16x32_bf16 v[18:21], v[160:163], v[200:203], v[18:21]
	v_mfma_f32_16x16x32_bf16 v[10:13], v[152:155], v[208:211], v[10:13]
	v_mfma_f32_16x16x32_bf16 v[2:5], v[160:163], v[208:211], v[2:5]
	v_mfma_f32_16x16x32_bf16 v[62:65], v[156:159], v[188:191], v[62:65]
	v_mfma_f32_16x16x32_bf16 v[50:53], v[164:167], v[188:191], v[50:53]
	v_mfma_f32_16x16x32_bf16 v[42:45], v[156:159], v[196:199], v[42:45]
	v_mfma_f32_16x16x32_bf16 v[34:37], v[164:167], v[196:199], v[34:37]
	v_mfma_f32_16x16x32_bf16 v[26:29], v[156:159], v[204:207], v[26:29]
	v_mfma_f32_16x16x32_bf16 v[18:21], v[164:167], v[204:207], v[18:21]
	v_mfma_f32_16x16x32_bf16 v[10:13], v[156:159], v[212:215], v[10:13]
	v_mfma_f32_16x16x32_bf16 v[2:5], v[164:167], v[212:215], v[2:5]
	v_mfma_f32_16x16x32_bf16 v[70:73], v[168:171], v[184:187], v[70:73]
	v_mfma_f32_16x16x32_bf16 v[54:57], v[176:179], v[184:187], v[54:57]
	v_mfma_f32_16x16x32_bf16 v[46:49], v[168:171], v[192:195], v[46:49]
	v_mfma_f32_16x16x32_bf16 v[38:41], v[176:179], v[192:195], v[38:41]
	v_mfma_f32_16x16x32_bf16 v[30:33], v[168:171], v[200:203], v[30:33]
	v_mfma_f32_16x16x32_bf16 v[22:25], v[176:179], v[200:203], v[22:25]
	v_mfma_f32_16x16x32_bf16 v[14:17], v[168:171], v[208:211], v[14:17]
	v_mfma_f32_16x16x32_bf16 v[6:9], v[176:179], v[208:211], v[6:9]
	v_mfma_f32_16x16x32_bf16 v[70:73], v[172:175], v[188:191], v[70:73]
	v_mfma_f32_16x16x32_bf16 v[54:57], v[180:183], v[188:191], v[54:57]
	v_mfma_f32_16x16x32_bf16 v[46:49], v[172:175], v[196:199], v[46:49]
	v_mfma_f32_16x16x32_bf16 v[38:41], v[180:183], v[196:199], v[38:41]
	v_mfma_f32_16x16x32_bf16 v[30:33], v[172:175], v[204:207], v[30:33]
	v_mfma_f32_16x16x32_bf16 v[22:25], v[180:183], v[204:207], v[22:25]
	v_mfma_f32_16x16x32_bf16 v[14:17], v[172:175], v[212:215], v[14:17]
	v_mfma_f32_16x16x32_bf16 v[6:9], v[180:183], v[212:215], v[6:9]
	s_barrier
	s_setprio 0
	s_add_i32 s15, s15, 2
	s_add_u32 s70, s70, 0x100
	s_addc_u32 s71, s71, 0
	s_add_u32 s57, s57, 0x100
	s_addc_u32 s14, s14, 0
	s_cmp_gt_u32 s15, 61
	s_cbranch_scc0 .LBB0_249
	s_mov_b32 m0, s65
	s_nop 0
	global_load_lds_dwordx4 v136, s[100:101]
	s_mov_b32 m0, s76
	s_nop 0
	global_load_lds_dwordx4 v132, s[100:101]
	s_and_b64 vcc, exec, s[12:13]
	s_cbranch_vccz .LBB0_252
	s_barrier

.LBB0_330:
	ds_read_b128 v[2:5], v207
	ds_read_b128 v[6:9], v207 offset:1024
	ds_read_b128 v[10:13], v207 offset:2048
	ds_read_b128 v[14:17], v207 offset:3072
	ds_read_b128 v[18:21], v208
	ds_read_b128 v[22:25], v208 offset:1024
	ds_read_b128 v[26:29], v208 offset:2048
	ds_read_b128 v[30:33], v208 offset:3072
	s_add_u32 s14, s66, 0x2b0080
	s_addc_u32 s15, s67, 0
	s_add_i32 s86, s11, 0xc000
	v_lshl_add_u64 v[66:67], s[14:15], 0, v[178:179]
	s_mov_b32 m0, s86
	s_add_i32 s87, s11, 0xe000
	ds_read_b128 v[34:37], v209
	ds_read_b128 v[38:41], v209 offset:1024
	ds_read_b128 v[42:45], v209 offset:2048
	ds_read_b128 v[46:49], v209 offset:3072
	ds_read_b128 v[50:53], v209 offset:4096
	ds_read_b128 v[54:57], v209 offset:5120
	ds_read_b128 v[58:61], v209 offset:6144
	ds_read_b128 v[62:65], v209 offset:7168
	global_load_lds_dwordx4 v[66:67], off
	v_lshl_add_u64 v[66:67], s[14:15], 0, v[182:183]
	s_mov_b32 m0, s87
	s_nop 0
	global_load_lds_dwordx4 v[66:67], off
	s_waitcnt vmcnt(8)
	s_waitcnt lgkmcnt(0)
	s_setprio 1
	s_barrier
	v_mfma_f32_16x16x32_bf16 v[90:93], v[2:5], v[58:61], 0
	v_mfma_f32_16x16x32_bf16 v[66:69], v[2:5], v[34:37], 0
	v_mfma_f32_16x16x32_bf16 v[70:73], v[10:13], v[34:37], 0
	v_mfma_f32_16x16x32_bf16 v[74:77], v[2:5], v[42:45], 0
	v_mfma_f32_16x16x32_bf16 v[78:81], v[10:13], v[42:45], 0
	v_mfma_f32_16x16x32_bf16 v[82:85], v[2:5], v[50:53], 0
	v_mfma_f32_16x16x32_bf16 v[86:89], v[10:13], v[50:53], 0
	v_mfma_f32_16x16x32_bf16 v[98:101], v[6:9], v[62:65], v[90:93]
	v_mfma_f32_16x16x32_bf16 v[90:93], v[10:13], v[58:61], 0
	v_mfma_f32_16x16x32_bf16 v[66:69], v[6:9], v[38:41], v[66:69]
	v_mfma_f32_16x16x32_bf16 v[70:73], v[14:17], v[38:41], v[70:73]
	v_mfma_f32_16x16x32_bf16 v[74:77], v[6:9], v[46:49], v[74:77]
	v_mfma_f32_16x16x32_bf16 v[78:81], v[14:17], v[46:49], v[78:81]
	v_mfma_f32_16x16x32_bf16 v[82:85], v[6:9], v[54:57], v[82:85]
	v_mfma_f32_16x16x32_bf16 v[86:89], v[14:17], v[54:57], v[86:89]
	v_mfma_f32_16x16x32_bf16 v[102:105], v[14:17], v[62:65], v[90:93]
	v_mfma_f32_16x16x32_bf16 v[90:93], v[18:21], v[34:37], 0
	v_mfma_f32_16x16x32_bf16 v[34:37], v[26:29], v[34:37], 0
	v_mfma_f32_16x16x32_bf16 v[114:117], v[22:25], v[38:41], v[90:93]
	v_mfma_f32_16x16x32_bf16 v[34:37], v[30:33], v[38:41], v[34:37]
	v_mfma_f32_16x16x32_bf16 v[38:41], v[18:21], v[42:45], 0
	v_mfma_f32_16x16x32_bf16 v[42:45], v[26:29], v[42:45], 0
	v_mfma_f32_16x16x32_bf16 v[38:41], v[22:25], v[46:49], v[38:41]
	v_mfma_f32_16x16x32_bf16 v[42:45], v[30:33], v[46:49], v[42:45]
	v_mfma_f32_16x16x32_bf16 v[46:49], v[18:21], v[50:53], 0
	v_mfma_f32_16x16x32_bf16 v[50:53], v[26:29], v[50:53], 0
	v_mfma_f32_16x16x32_bf16 v[46:49], v[22:25], v[54:57], v[46:49]
	v_mfma_f32_16x16x32_bf16 v[50:53], v[30:33], v[54:57], v[50:53]
	v_mfma_f32_16x16x32_bf16 v[54:57], v[18:21], v[58:61], 0
	v_mfma_f32_16x16x32_bf16 v[58:61], v[26:29], v[58:61], 0
	v_mfma_f32_16x16x32_bf16 v[54:57], v[22:25], v[62:65], v[54:57]
	v_mfma_f32_16x16x32_bf16 v[58:61], v[30:33], v[62:65], v[58:61]
	s_barrier
	s_setprio 0
	s_add_i32 s88, s78, s10
	v_lshl_add_u64 v[176:177], s[70:71], 0, v[180:181]
	s_add_i32 s84, s88, 0x2000
	v_lshl_add_u64 v[130:131], v[176:177], 0, s[60:61]
	s_mov_b32 m0, s88
	v_lshl_add_u64 v[250:251], s[70:71], 0, v[184:185]
	s_add_u32 s14, s70, 0x2b0100
	ds_read_b128 v[62:65], v209 offset:16384
	ds_read_b128 v[90:93], v209 offset:17408
	ds_read_b128 v[94:97], v209 offset:18432
	ds_read_b128 v[106:109], v209 offset:19456
	ds_read_b128 v[110:113], v209 offset:20480
	ds_read_b128 v[118:121], v209 offset:21504
	ds_read_b128 v[122:125], v209 offset:22528
	ds_read_b128 v[126:129], v209 offset:23552
	global_load_lds_dwordx4 v[130:131], off
	v_lshl_add_u64 v[130:131], v[250:251], 0, s[60:61]
	s_mov_b32 m0, s84
	s_addc_u32 s15, s71, 0
	s_add_i32 s85, s79, s10
	global_load_lds_dwordx4 v[130:131], off
	v_lshl_add_u64 v[130:131], s[14:15], 0, v[180:181]
	s_mov_b32 m0, s85
	s_add_i32 s46, s85, 0x2000
	global_load_lds_dwordx4 v[130:131], off
	v_lshl_add_u64 v[130:131], s[14:15], 0, v[184:185]
	s_mov_b32 m0, s46
	v_lshl_add_u64 v[252:253], s[66:67], 0, v[178:179]
	global_load_lds_dwordx4 v[130:131], off
	v_lshl_add_u64 v[130:131], v[252:253], 0, s[60:61]
	s_mov_b32 m0, s11
	v_lshl_add_u64 v[190:191], s[66:67], 0, v[182:183]
	global_load_lds_dwordx4 v[130:131], off
	v_lshl_add_u64 v[130:131], v[190:191], 0, s[60:61]
	s_mov_b32 m0, s12
	s_nop 0
	global_load_lds_dwordx4 v[130:131], off
	s_waitcnt vmcnt(8)
	s_waitcnt lgkmcnt(0)
	s_setprio 1
	s_barrier
	v_mfma_f32_16x16x32_bf16 v[130:133], v[2:5], v[62:65], 0
	v_mfma_f32_16x16x32_bf16 v[140:143], v[2:5], v[94:97], 0
	v_mfma_f32_16x16x32_bf16 v[148:151], v[2:5], v[110:113], 0
	v_mfma_f32_16x16x32_bf16 v[2:5], v[2:5], v[122:125], 0
	v_mfma_f32_16x16x32_bf16 v[132:135], v[6:9], v[90:93], v[130:133]
	v_mfma_f32_16x16x32_bf16 v[140:143], v[6:9], v[106:109], v[140:143]
	v_mfma_f32_16x16x32_bf16 v[148:151], v[6:9], v[118:121], v[148:151]
	v_mfma_f32_16x16x32_bf16 v[2:5], v[6:9], v[126:129], v[2:5]
	v_mfma_f32_16x16x32_bf16 v[6:9], v[10:13], v[122:125], 0
	v_mfma_f32_16x16x32_bf16 v[136:139], v[10:13], v[62:65], 0
	v_mfma_f32_16x16x32_bf16 v[144:147], v[10:13], v[94:97], 0
	v_mfma_f32_16x16x32_bf16 v[152:155], v[10:13], v[110:113], 0
	v_mfma_f32_16x16x32_bf16 v[6:9], v[14:17], v[126:129], v[6:9]
	v_mfma_f32_16x16x32_bf16 v[136:139], v[14:17], v[90:93], v[136:139]
	v_mfma_f32_16x16x32_bf16 v[144:147], v[14:17], v[106:109], v[144:147]
	v_mfma_f32_16x16x32_bf16 v[152:155], v[14:17], v[118:121], v[152:155]
	v_mfma_f32_16x16x32_bf16 v[10:13], v[18:21], v[62:65], 0
	v_mfma_f32_16x16x32_bf16 v[156:159], v[22:25], v[90:93], v[10:13]
	v_mfma_f32_16x16x32_bf16 v[10:13], v[26:29], v[62:65], 0
	v_mfma_f32_16x16x32_bf16 v[160:163], v[30:33], v[90:93], v[10:13]
	v_mfma_f32_16x16x32_bf16 v[10:13], v[18:21], v[94:97], 0
	v_mfma_f32_16x16x32_bf16 v[164:167], v[22:25], v[106:109], v[10:13]
	v_mfma_f32_16x16x32_bf16 v[10:13], v[26:29], v[94:97], 0
	v_mfma_f32_16x16x32_bf16 v[168:171], v[30:33], v[106:109], v[10:13]
	v_mfma_f32_16x16x32_bf16 v[10:13], v[18:21], v[110:113], 0
	v_mfma_f32_16x16x32_bf16 v[172:175], v[22:25], v[118:121], v[10:13]
	v_mfma_f32_16x16x32_bf16 v[10:13], v[26:29], v[110:113], 0
	v_mfma_f32_16x16x32_bf16 v[194:197], v[30:33], v[118:121], v[10:13]
	v_mfma_f32_16x16x32_bf16 v[10:13], v[18:21], v[122:125], 0
	v_mfma_f32_16x16x32_bf16 v[198:201], v[22:25], v[126:129], v[10:13]
	v_mfma_f32_16x16x32_bf16 v[10:13], v[26:29], v[122:125], 0
	v_mfma_f32_16x16x32_bf16 v[202:205], v[30:33], v[126:129], v[10:13]
	s_barrier
	s_setprio 0
	s_add_i32 s47, 0, 0x18000
	s_add_i32 s56, 0, 0x1c000
	v_add_u32_e32 v130, s47, v206
	v_add_u32_e32 v131, s56, v206
	s_nop 0
	ds_read_b128 v[10:13], v130
	ds_read_b128 v[14:17], v130 offset:1024
	ds_read_b128 v[18:21], v130 offset:2048
	ds_read_b128 v[22:25], v130 offset:3072
	ds_read_b128 v[210:213], v131
	ds_read_b128 v[214:217], v131 offset:1024
	ds_read_b128 v[218:221], v131 offset:2048
	ds_read_b128 v[222:225], v131 offset:3072
	s_add_u32 s14, s66, 0x2b0100
	s_addc_u32 s15, s67, 0
	s_mov_b32 m0, s13
	v_lshl_add_u64 v[90:91], s[14:15], 0, v[178:179]
	ds_read_b128 v[26:29], v209 offset:32768
	ds_read_b128 v[30:33], v209 offset:33792
	ds_read_b128 v[62:65], v209 offset:34816
	ds_read_b128 v[226:229], v209 offset:35840
	ds_read_b128 v[230:233], v209 offset:36864
	ds_read_b128 v[234:237], v209 offset:37888
	ds_read_b128 v[238:241], v209 offset:38912
	ds_read_b128 v[242:245], v209 offset:39936
	global_load_lds_dwordx4 v[90:91], off
	v_lshl_add_u64 v[90:91], s[14:15], 0, v[182:183]
	s_mov_b32 m0, s29
	s_nop 0
	global_load_lds_dwordx4 v[90:91], off
	s_waitcnt vmcnt(8)
	s_waitcnt lgkmcnt(0)
	s_setprio 1
	s_barrier
	v_mfma_f32_16x16x32_bf16 v[66:69], v[10:13], v[26:29], v[66:69]
	v_mfma_f32_16x16x32_bf16 v[122:125], v[14:17], v[30:33], v[66:69]
	v_mfma_f32_16x16x32_bf16 v[66:69], v[18:21], v[26:29], v[70:73]
	v_mfma_f32_16x16x32_bf16 v[118:121], v[22:25], v[30:33], v[66:69]
	v_mfma_f32_16x16x32_bf16 v[66:69], v[10:13], v[62:65], v[74:77]
	v_mfma_f32_16x16x32_bf16 v[110:113], v[14:17], v[226:229], v[66:69]
	v_mfma_f32_16x16x32_bf16 v[66:69], v[18:21], v[62:65], v[78:81]
	v_mfma_f32_16x16x32_bf16 v[106:109], v[22:25], v[226:229], v[66:69]
	v_mfma_f32_16x16x32_bf16 v[66:69], v[10:13], v[230:233], v[82:85]
	v_mfma_f32_16x16x32_bf16 v[94:97], v[14:17], v[234:237], v[66:69]
	v_mfma_f32_16x16x32_bf16 v[66:69], v[18:21], v[230:233], v[86:89]
	v_mfma_f32_16x16x32_bf16 v[90:93], v[22:25], v[234:237], v[66:69]
	v_mfma_f32_16x16x32_bf16 v[66:69], v[10:13], v[238:241], v[98:101]
	v_mfma_f32_16x16x32_bf16 v[78:81], v[14:17], v[242:245], v[66:69]
	v_mfma_f32_16x16x32_bf16 v[66:69], v[18:21], v[238:241], v[102:105]
	v_mfma_f32_16x16x32_bf16 v[74:77], v[22:25], v[242:245], v[66:69]
	v_mfma_f32_16x16x32_bf16 v[66:69], v[210:213], v[26:29], v[114:117]
	v_mfma_f32_16x16x32_bf16 v[26:29], v[218:221], v[26:29], v[34:37]
	v_mfma_f32_16x16x32_bf16 v[114:117], v[222:225], v[30:33], v[26:29]
	v_mfma_f32_16x16x32_bf16 v[26:29], v[210:213], v[62:65], v[38:41]
	v_mfma_f32_16x16x32_bf16 v[102:105], v[214:217], v[226:229], v[26:29]
	v_mfma_f32_16x16x32_bf16 v[26:29], v[218:221], v[62:65], v[42:45]
	v_mfma_f32_16x16x32_bf16 v[98:101], v[222:225], v[226:229], v[26:29]
	v_mfma_f32_16x16x32_bf16 v[26:29], v[210:213], v[230:233], v[46:49]
	v_mfma_f32_16x16x32_bf16 v[86:89], v[214:217], v[234:237], v[26:29]
	v_mfma_f32_16x16x32_bf16 v[26:29], v[218:221], v[230:233], v[50:53]
	v_mfma_f32_16x16x32_bf16 v[82:85], v[222:225], v[234:237], v[26:29]
	v_mfma_f32_16x16x32_bf16 v[26:29], v[210:213], v[238:241], v[54:57]
	v_mfma_f32_16x16x32_bf16 v[70:73], v[214:217], v[242:245], v[26:29]
	v_mfma_f32_16x16x32_bf16 v[26:29], v[218:221], v[238:241], v[58:61]
	v_mfma_f32_16x16x32_bf16 v[126:129], v[214:217], v[30:33], v[66:69]
	v_mfma_f32_16x16x32_bf16 v[66:69], v[222:225], v[242:245], v[26:29]
	s_barrier
	s_setprio 0
	s_add_i32 s47, s47, s10
	s_add_i32 s89, s47, 0x2000
	s_nop 1
	v_lshl_add_u64 v[26:27], v[176:177], 0, s[62:63]
	s_mov_b32 m0, s47
	s_add_u32 s14, s70, 0x2b0180
	ds_read_b128 v[34:37], v209 offset:49152
	ds_read_b128 v[38:41], v209 offset:50176
	ds_read_b128 v[226:229], v209 offset:51200
	ds_read_b128 v[230:233], v209 offset:52224
	ds_read_b128 v[234:237], v209 offset:53248
	ds_read_b128 v[238:241], v209 offset:54272
	ds_read_b128 v[242:245], v209 offset:55296
	ds_read_b128 v[246:249], v209 offset:56320
	global_load_lds_dwordx4 v[26:27], off
	v_lshl_add_u64 v[26:27], v[250:251], 0, s[62:63]
	s_mov_b32 m0, s89
	s_addc_u32 s15, s71, 0
	s_add_i32 s56, s56, s10
	global_load_lds_dwordx4 v[26:27], off
	v_lshl_add_u64 v[26:27], s[14:15], 0, v[180:181]
	s_mov_b32 m0, s56
	s_add_i32 s57, s56, 0x2000
	global_load_lds_dwordx4 v[26:27], off
	v_lshl_add_u64 v[26:27], s[14:15], 0, v[184:185]
	s_mov_b32 m0, s57
	s_nop 0
	global_load_lds_dwordx4 v[26:27], off
	v_lshl_add_u64 v[26:27], v[252:253], 0, s[62:63]
	s_mov_b32 m0, s58
	s_nop 0
	global_load_lds_dwordx4 v[26:27], off
	v_lshl_add_u64 v[26:27], v[190:191], 0, s[62:63]
	s_mov_b32 m0, s59
	s_nop 0
	global_load_lds_dwordx4 v[26:27], off
	s_waitcnt vmcnt(8)
	s_waitcnt lgkmcnt(0)
	s_setprio 1
	s_barrier
	v_mfma_f32_16x16x32_bf16 v[26:29], v[10:13], v[34:37], v[132:135]
	v_mfma_f32_16x16x32_bf16 v[58:61], v[14:17], v[38:41], v[26:29]
	v_mfma_f32_16x16x32_bf16 v[26:29], v[18:21], v[34:37], v[136:139]
	v_mfma_f32_16x16x32_bf16 v[54:57], v[22:25], v[38:41], v[26:29]
	v_mfma_f32_16x16x32_bf16 v[26:29], v[10:13], v[226:229], v[140:143]
	v_mfma_f32_16x16x32_bf16 v[46:49], v[14:17], v[230:233], v[26:29]
	v_mfma_f32_16x16x32_bf16 v[26:29], v[18:21], v[226:229], v[144:147]
	v_mfma_f32_16x16x32_bf16 v[42:45], v[22:25], v[230:233], v[26:29]
	v_mfma_f32_16x16x32_bf16 v[26:29], v[10:13], v[234:237], v[148:151]
	v_mfma_f32_16x16x32_bf16 v[2:5], v[10:13], v[242:245], v[2:5]
	v_mfma_f32_16x16x32_bf16 v[30:33], v[14:17], v[238:241], v[26:29]
	v_mfma_f32_16x16x32_bf16 v[26:29], v[18:21], v[234:237], v[152:155]
	v_mfma_f32_16x16x32_bf16 v[14:17], v[14:17], v[246:249], v[2:5]
	v_mfma_f32_16x16x32_bf16 v[2:5], v[18:21], v[242:245], v[6:9]
	v_mfma_f32_16x16x32_bf16 v[26:29], v[22:25], v[238:241], v[26:29]
	v_mfma_f32_16x16x32_bf16 v[10:13], v[22:25], v[246:249], v[2:5]
	v_mfma_f32_16x16x32_bf16 v[2:5], v[210:213], v[34:37], v[156:159]
	v_mfma_f32_16x16x32_bf16 v[62:65], v[214:217], v[38:41], v[2:5]
	v_mfma_f32_16x16x32_bf16 v[2:5], v[218:221], v[34:37], v[160:163]
	v_mfma_f32_16x16x32_bf16 v[50:53], v[222:225], v[38:41], v[2:5]
	v_mfma_f32_16x16x32_bf16 v[2:5], v[210:213], v[226:229], v[164:167]
	v_mfma_f32_16x16x32_bf16 v[38:41], v[214:217], v[230:233], v[2:5]
	v_mfma_f32_16x16x32_bf16 v[2:5], v[218:221], v[226:229], v[168:171]
	v_mfma_f32_16x16x32_bf16 v[34:37], v[222:225], v[230:233], v[2:5]
	v_mfma_f32_16x16x32_bf16 v[2:5], v[210:213], v[234:237], v[172:175]
	v_mfma_f32_16x16x32_bf16 v[22:25], v[214:217], v[238:241], v[2:5]
	v_mfma_f32_16x16x32_bf16 v[2:5], v[218:221], v[234:237], v[194:197]
	v_mfma_f32_16x16x32_bf16 v[18:21], v[222:225], v[238:241], v[2:5]
	v_mfma_f32_16x16x32_bf16 v[2:5], v[210:213], v[242:245], v[198:201]
	v_mfma_f32_16x16x32_bf16 v[6:9], v[214:217], v[246:249], v[2:5]
	v_mfma_f32_16x16x32_bf16 v[2:5], v[218:221], v[242:245], v[202:205]
	v_mfma_f32_16x16x32_bf16 v[2:5], v[222:225], v[246:249], v[2:5]
	s_barrier
	s_setprio 0
	s_add_u32 s90, s70, 0x200
	s_addc_u32 s14, s71, 0
	s_mov_b32 s15, 0

.Lrb2_skip_9715:
	s_mov_b32 m0, s86
	ds_read_b128 v[164:167], v209
	ds_read_b128 v[168:171], v209 offset:1024
	ds_read_b128 v[172:175], v209 offset:2048
	ds_read_b128 v[194:197], v209 offset:3072
	ds_read_b128 v[198:201], v209 offset:4096
	ds_read_b128 v[202:205], v209 offset:5120
	ds_read_b128 v[210:213], v209 offset:6144
	ds_read_b128 v[214:217], v209 offset:7168
	global_load_lds_dwordx4 v186, s[66:67]
	s_mov_b32 m0, s87
	s_nop 0
	global_load_lds_dwordx4 v188, s[66:67]
	s_waitcnt vmcnt(8)
	s_waitcnt lgkmcnt(0)
	s_setprio 1
	s_barrier
	v_mfma_f32_16x16x32_bf16 v[122:125], v[132:135], v[164:167], v[122:125]
	v_mfma_f32_16x16x32_bf16 v[118:121], v[140:143], v[164:167], v[118:121]
	v_mfma_f32_16x16x32_bf16 v[110:113], v[132:135], v[172:175], v[110:113]
	v_mfma_f32_16x16x32_bf16 v[106:109], v[140:143], v[172:175], v[106:109]
	v_mfma_f32_16x16x32_bf16 v[94:97], v[132:135], v[198:201], v[94:97]
	v_mfma_f32_16x16x32_bf16 v[90:93], v[140:143], v[198:201], v[90:93]
	v_mfma_f32_16x16x32_bf16 v[78:81], v[132:135], v[210:213], v[78:81]
	v_mfma_f32_16x16x32_bf16 v[74:77], v[140:143], v[210:213], v[74:77]
	v_mfma_f32_16x16x32_bf16 v[122:125], v[136:139], v[168:171], v[122:125]
	v_mfma_f32_16x16x32_bf16 v[118:121], v[144:147], v[168:171], v[118:121]
	v_mfma_f32_16x16x32_bf16 v[110:113], v[136:139], v[194:197], v[110:113]
	v_mfma_f32_16x16x32_bf16 v[106:109], v[144:147], v[194:197], v[106:109]
	v_mfma_f32_16x16x32_bf16 v[94:97], v[136:139], v[202:205], v[94:97]
	v_mfma_f32_16x16x32_bf16 v[90:93], v[144:147], v[202:205], v[90:93]
	v_mfma_f32_16x16x32_bf16 v[78:81], v[136:139], v[214:217], v[78:81]
	v_mfma_f32_16x16x32_bf16 v[74:77], v[144:147], v[214:217], v[74:77]
	v_mfma_f32_16x16x32_bf16 v[126:129], v[148:151], v[164:167], v[126:129]
	v_mfma_f32_16x16x32_bf16 v[114:117], v[156:159], v[164:167], v[114:117]
	v_mfma_f32_16x16x32_bf16 v[102:105], v[148:151], v[172:175], v[102:105]
	v_mfma_f32_16x16x32_bf16 v[98:101], v[156:159], v[172:175], v[98:101]
	v_mfma_f32_16x16x32_bf16 v[86:89], v[148:151], v[198:201], v[86:89]
	v_mfma_f32_16x16x32_bf16 v[82:85], v[156:159], v[198:201], v[82:85]
	v_mfma_f32_16x16x32_bf16 v[70:73], v[148:151], v[210:213], v[70:73]
	v_mfma_f32_16x16x32_bf16 v[66:69], v[156:159], v[210:213], v[66:69]
	v_mfma_f32_16x16x32_bf16 v[126:129], v[152:155], v[168:171], v[126:129]
	v_mfma_f32_16x16x32_bf16 v[114:117], v[160:163], v[168:171], v[114:117]
	v_mfma_f32_16x16x32_bf16 v[102:105], v[152:155], v[194:197], v[102:105]
	v_mfma_f32_16x16x32_bf16 v[98:101], v[160:163], v[194:197], v[98:101]
	v_mfma_f32_16x16x32_bf16 v[86:89], v[152:155], v[202:205], v[86:89]
	v_mfma_f32_16x16x32_bf16 v[82:85], v[160:163], v[202:205], v[82:85]
	v_mfma_f32_16x16x32_bf16 v[70:73], v[152:155], v[214:217], v[70:73]
	v_mfma_f32_16x16x32_bf16 v[66:69], v[160:163], v[214:217], v[66:69]
	s_barrier
	s_setprio 0
	s_mov_b32 m0, s88
	s_mov_b64 s[98:99], s[70:71]
	s_add_u32 s16, s70, 0x2b0000
	ds_read_b128 v[164:167], v209 offset:16384
	ds_read_b128 v[168:171], v209 offset:17408
	ds_read_b128 v[172:175], v209 offset:18432
	ds_read_b128 v[194:197], v209 offset:19456
	ds_read_b128 v[198:201], v209 offset:20480
	ds_read_b128 v[202:205], v209 offset:21504
	ds_read_b128 v[210:213], v209 offset:22528
	ds_read_b128 v[214:217], v209 offset:23552
	global_load_lds_dwordx4 v180, s[70:71]
	s_mov_b32 m0, s84
	s_addc_u32 s17, s71, 0
	global_load_lds_dwordx4 v184, s[70:71]
	s_mov_b32 m0, s85
	s_mov_b64 s[100:101], s[74:75]
	global_load_lds_dwordx4 v180, s[16:17]
	s_mov_b32 m0, s46
	s_nop 0
	global_load_lds_dwordx4 v184, s[16:17]
	s_waitcnt vmcnt(6)
	s_waitcnt lgkmcnt(0)
	s_setprio 1
	s_barrier
	v_mfma_f32_16x16x32_bf16 v[58:61], v[132:135], v[164:167], v[58:61]
	v_mfma_f32_16x16x32_bf16 v[54:57], v[140:143], v[164:167], v[54:57]
	v_mfma_f32_16x16x32_bf16 v[46:49], v[132:135], v[172:175], v[46:49]
	v_mfma_f32_16x16x32_bf16 v[42:45], v[140:143], v[172:175], v[42:45]
	v_mfma_f32_16x16x32_bf16 v[30:33], v[132:135], v[198:201], v[30:33]
	v_mfma_f32_16x16x32_bf16 v[26:29], v[140:143], v[198:201], v[26:29]
	v_mfma_f32_16x16x32_bf16 v[14:17], v[132:135], v[210:213], v[14:17]
	v_mfma_f32_16x16x32_bf16 v[10:13], v[140:143], v[210:213], v[10:13]
	v_mfma_f32_16x16x32_bf16 v[58:61], v[136:139], v[168:171], v[58:61]
	v_mfma_f32_16x16x32_bf16 v[54:57], v[144:147], v[168:171], v[54:57]
	v_mfma_f32_16x16x32_bf16 v[46:49], v[136:139], v[194:197], v[46:49]
	v_mfma_f32_16x16x32_bf16 v[42:45], v[144:147], v[194:197], v[42:45]
	v_mfma_f32_16x16x32_bf16 v[30:33], v[136:139], v[202:205], v[30:33]
	v_mfma_f32_16x16x32_bf16 v[26:29], v[144:147], v[202:205], v[26:29]
	v_mfma_f32_16x16x32_bf16 v[14:17], v[136:139], v[214:217], v[14:17]
	v_mfma_f32_16x16x32_bf16 v[10:13], v[144:147], v[214:217], v[10:13]
	v_mfma_f32_16x16x32_bf16 v[62:65], v[148:151], v[164:167], v[62:65]
	v_mfma_f32_16x16x32_bf16 v[50:53], v[156:159], v[164:167], v[50:53]
	v_mfma_f32_16x16x32_bf16 v[38:41], v[148:151], v[172:175], v[38:41]
	v_mfma_f32_16x16x32_bf16 v[34:37], v[156:159], v[172:175], v[34:37]
	v_mfma_f32_16x16x32_bf16 v[22:25], v[148:151], v[198:201], v[22:25]
	v_mfma_f32_16x16x32_bf16 v[18:21], v[156:159], v[198:201], v[18:21]
	v_mfma_f32_16x16x32_bf16 v[6:9], v[148:151], v[210:213], v[6:9]
	v_mfma_f32_16x16x32_bf16 v[2:5], v[156:159], v[210:213], v[2:5]
	v_mfma_f32_16x16x32_bf16 v[62:65], v[152:155], v[168:171], v[62:65]
	v_mfma_f32_16x16x32_bf16 v[50:53], v[160:163], v[168:171], v[50:53]
	v_mfma_f32_16x16x32_bf16 v[38:41], v[152:155], v[194:197], v[38:41]
	v_mfma_f32_16x16x32_bf16 v[34:37], v[160:163], v[194:197], v[34:37]
	v_mfma_f32_16x16x32_bf16 v[22:25], v[152:155], v[202:205], v[22:25]
	v_mfma_f32_16x16x32_bf16 v[18:21], v[160:163], v[202:205], v[18:21]
	v_mfma_f32_16x16x32_bf16 v[6:9], v[152:155], v[214:217], v[6:9]
	v_mfma_f32_16x16x32_bf16 v[2:5], v[160:163], v[214:217], v[2:5]
	s_barrier
; #define PG8_BAR __builtin_amdgcn_s_barrier()
;     ...
;         for (int t = 2; t < nt; t += 2) PG8_KITER(t);
;         if constexpr (ALIGN_EPI) { if (wr == 0) PG8_BAR; }
	s_setprio 0
	ds_read_b128 v[132:135], v130
	ds_read_b128 v[136:139], v130 offset:1024
	ds_read_b128 v[140:143], v130 offset:2048
	ds_read_b128 v[144:147], v130 offset:3072
	ds_read_b128 v[148:151], v131
	ds_read_b128 v[152:155], v131 offset:1024
	ds_read_b128 v[156:159], v131 offset:2048
	ds_read_b128 v[160:163], v131 offset:3072
	s_add_u32 s16, s74, 0x2b0000
	s_addc_u32 s17, s75, 0
	s_mov_b32 m0, s11
	s_nop 0
	global_load_lds_dwordx4 v178, s[100:101]
	s_mov_b32 m0, s12
	s_nop 0
	global_load_lds_dwordx4 v182, s[100:101]
	s_mov_b32 m0, s13
	ds_read_b128 v[164:167], v209 offset:32768
	ds_read_b128 v[168:171], v209 offset:33792
	ds_read_b128 v[172:175], v209 offset:34816
	ds_read_b128 v[194:197], v209 offset:35840
	ds_read_b128 v[198:201], v209 offset:36864
	ds_read_b128 v[202:205], v209 offset:37888
	ds_read_b128 v[210:213], v209 offset:38912
	ds_read_b128 v[214:217], v209 offset:39936
	global_load_lds_dwordx4 v178, s[16:17]
	s_mov_b32 m0, s29
	s_nop 0
	global_load_lds_dwordx4 v182, s[16:17]
	s_waitcnt vmcnt(8)
	s_waitcnt lgkmcnt(0)
	s_setprio 1
	s_barrier
	v_mfma_f32_16x16x32_bf16 v[122:125], v[132:135], v[164:167], v[122:125]
	v_mfma_f32_16x16x32_bf16 v[118:121], v[140:143], v[164:167], v[118:121]
	v_mfma_f32_16x16x32_bf16 v[110:113], v[132:135], v[172:175], v[110:113]
	v_mfma_f32_16x16x32_bf16 v[106:109], v[140:143], v[172:175], v[106:109]
	v_mfma_f32_16x16x32_bf16 v[94:97], v[132:135], v[198:201], v[94:97]
	v_mfma_f32_16x16x32_bf16 v[90:93], v[140:143], v[198:201], v[90:93]
	v_mfma_f32_16x16x32_bf16 v[78:81], v[132:135], v[210:213], v[78:81]
	v_mfma_f32_16x16x32_bf16 v[74:77], v[140:143], v[210:213], v[74:77]
	v_mfma_f32_16x16x32_bf16 v[122:125], v[136:139], v[168:171], v[122:125]
	v_mfma_f32_16x16x32_bf16 v[118:121], v[144:147], v[168:171], v[118:121]
	v_mfma_f32_16x16x32_bf16 v[110:113], v[136:139], v[194:197], v[110:113]
	v_mfma_f32_16x16x32_bf16 v[106:109], v[144:147], v[194:197], v[106:109]
	v_mfma_f32_16x16x32_bf16 v[94:97], v[136:139], v[202:205], v[94:97]
	v_mfma_f32_16x16x32_bf16 v[90:93], v[144:147], v[202:205], v[90:93]
	v_mfma_f32_16x16x32_bf16 v[78:81], v[136:139], v[214:217], v[78:81]
	v_mfma_f32_16x16x32_bf16 v[74:77], v[144:147], v[214:217], v[74:77]
	v_mfma_f32_16x16x32_bf16 v[126:129], v[148:151], v[164:167], v[126:129]
	v_mfma_f32_16x16x32_bf16 v[114:117], v[156:159], v[164:167], v[114:117]
	v_mfma_f32_16x16x32_bf16 v[102:105], v[148:151], v[172:175], v[102:105]
	v_mfma_f32_16x16x32_bf16 v[98:101], v[156:159], v[172:175], v[98:101]
	v_mfma_f32_16x16x32_bf16 v[86:89], v[148:151], v[198:201], v[86:89]
	v_mfma_f32_16x16x32_bf16 v[82:85], v[156:159], v[198:201], v[82:85]
	v_mfma_f32_16x16x32_bf16 v[70:73], v[148:151], v[210:213], v[70:73]
	v_mfma_f32_16x16x32_bf16 v[66:69], v[156:159], v[210:213], v[66:69]
	v_mfma_f32_16x16x32_bf16 v[126:129], v[152:155], v[168:171], v[126:129]
	v_mfma_f32_16x16x32_bf16 v[114:117], v[160:163], v[168:171], v[114:117]
	v_mfma_f32_16x16x32_bf16 v[102:105], v[152:155], v[194:197], v[102:105]
	v_mfma_f32_16x16x32_bf16 v[98:101], v[160:163], v[194:197], v[98:101]
	v_mfma_f32_16x16x32_bf16 v[86:89], v[152:155], v[202:205], v[86:89]
	v_mfma_f32_16x16x32_bf16 v[82:85], v[160:163], v[202:205], v[82:85]
	v_mfma_f32_16x16x32_bf16 v[70:73], v[152:155], v[214:217], v[70:73]
	v_mfma_f32_16x16x32_bf16 v[66:69], v[160:163], v[214:217], v[66:69]
	s_barrier
	s_setprio 0
	s_mov_b32 m0, s47
	s_add_u32 s98, s98, 0x80
	s_addc_u32 s99, s99, 0
	s_add_u32 s100, s100, 0x80
	s_addc_u32 s101, s101, 0
	s_add_u32 s16, s70, 0x2b0080
	ds_read_b128 v[164:167], v209 offset:49152
	ds_read_b128 v[168:171], v209 offset:50176
	ds_read_b128 v[172:175], v209 offset:51200
	ds_read_b128 v[194:197], v209 offset:52224
	ds_read_b128 v[198:201], v209 offset:53248
	ds_read_b128 v[202:205], v209 offset:54272
	ds_read_b128 v[210:213], v209 offset:55296
	ds_read_b128 v[214:217], v209 offset:56320
	global_load_lds_dwordx4 v180, s[98:99]
	s_mov_b32 m0, s89
	s_addc_u32 s17, s71, 0
	global_load_lds_dwordx4 v184, s[98:99]
	s_mov_b32 m0, s56
	s_nop 0
	global_load_lds_dwordx4 v180, s[16:17]
	s_mov_b32 m0, s57
	s_nop 0
	global_load_lds_dwordx4 v184, s[16:17]
	s_waitcnt vmcnt(6)
	s_waitcnt lgkmcnt(0)
	s_setprio 1
	s_barrier
	v_mfma_f32_16x16x32_bf16 v[58:61], v[132:135], v[164:167], v[58:61]
	v_mfma_f32_16x16x32_bf16 v[54:57], v[140:143], v[164:167], v[54:57]
	v_mfma_f32_16x16x32_bf16 v[46:49], v[132:135], v[172:175], v[46:49]
	v_mfma_f32_16x16x32_bf16 v[42:45], v[140:143], v[172:175], v[42:45]
	v_mfma_f32_16x16x32_bf16 v[30:33], v[132:135], v[198:201], v[30:33]
	v_mfma_f32_16x16x32_bf16 v[26:29], v[140:143], v[198:201], v[26:29]
	v_mfma_f32_16x16x32_bf16 v[14:17], v[132:135], v[210:213], v[14:17]
	v_mfma_f32_16x16x32_bf16 v[10:13], v[140:143], v[210:213], v[10:13]
	v_mfma_f32_16x16x32_bf16 v[58:61], v[136:139], v[168:171], v[58:61]
	v_mfma_f32_16x16x32_bf16 v[54:57], v[144:147], v[168:171], v[54:57]
	v_mfma_f32_16x16x32_bf16 v[46:49], v[136:139], v[194:197], v[46:49]
	v_mfma_f32_16x16x32_bf16 v[42:45], v[144:147], v[194:197], v[42:45]
	v_mfma_f32_16x16x32_bf16 v[30:33], v[136:139], v[202:205], v[30:33]
	v_mfma_f32_16x16x32_bf16 v[26:29], v[144:147], v[202:205], v[26:29]
	v_mfma_f32_16x16x32_bf16 v[14:17], v[136:139], v[214:217], v[14:17]
	v_mfma_f32_16x16x32_bf16 v[10:13], v[144:147], v[214:217], v[10:13]
	v_mfma_f32_16x16x32_bf16 v[62:65], v[148:151], v[164:167], v[62:65]
	v_mfma_f32_16x16x32_bf16 v[50:53], v[156:159], v[164:167], v[50:53]
	v_mfma_f32_16x16x32_bf16 v[38:41], v[148:151], v[172:175], v[38:41]
	v_mfma_f32_16x16x32_bf16 v[34:37], v[156:159], v[172:175], v[34:37]
	v_mfma_f32_16x16x32_bf16 v[22:25], v[148:151], v[198:201], v[22:25]
	v_mfma_f32_16x16x32_bf16 v[18:21], v[156:159], v[198:201], v[18:21]
	v_mfma_f32_16x16x32_bf16 v[6:9], v[148:151], v[210:213], v[6:9]
	v_mfma_f32_16x16x32_bf16 v[2:5], v[156:159], v[210:213], v[2:5]
	v_mfma_f32_16x16x32_bf16 v[62:65], v[152:155], v[168:171], v[62:65]
	v_mfma_f32_16x16x32_bf16 v[50:53], v[160:163], v[168:171], v[50:53]
	v_mfma_f32_16x16x32_bf16 v[38:41], v[152:155], v[194:197], v[38:41]
	v_mfma_f32_16x16x32_bf16 v[34:37], v[160:163], v[194:197], v[34:37]
	v_mfma_f32_16x16x32_bf16 v[22:25], v[152:155], v[202:205], v[22:25]
	v_mfma_f32_16x16x32_bf16 v[18:21], v[160:163], v[202:205], v[18:21]
	v_mfma_f32_16x16x32_bf16 v[6:9], v[152:155], v[214:217], v[6:9]
	v_mfma_f32_16x16x32_bf16 v[2:5], v[160:163], v[214:217], v[2:5]
	s_barrier
	s_setprio 0
	s_add_i32 s15, s15, 2
	s_add_u32 s66, s66, 0x100
	s_addc_u32 s67, s67, 0
	s_add_u32 s90, s90, 0x100
	s_addc_u32 s14, s14, 0
	s_cmpk_gt_u32 s15, 0xa9
	s_cbranch_scc0 .LBB0_331
	s_mov_b32 m0, s58
	s_nop 0
	global_load_lds_dwordx4 v178, s[100:101]
	s_mov_b32 m0, s59
	s_nop 0
	global_load_lds_dwordx4 v182, s[100:101]
	s_and_b64 vcc, exec, s[30:31]
	s_cbranch_vccz .LBB0_334
	s_barrier

;     __host__ __device__ bool next(int i, Unit& u) const { if (!StaticOrder::next(i >> 1, u)) return false; u.seg = i & 1; return true; }
;     ...
;         const bool has_next = S.next(ui + 1, nxt);
;         const char* nA = has_next ? PG8_APTR(nxt) : cA; const char* nB = has_next ? PG8_BPTR(nxt) : cB;
;         const char* pfc = PG8_PFPTR(cA, cB); const char* pfn = PG8_PFPTR(nA, nB);
;         PG8_KITER(0);
.LBB0_414:
	s_ashr_i32 s75, s74, 31
	ds_read_b128 v[2:5], v163
	ds_read_b128 v[6:9], v163 offset:1024
	ds_read_b128 v[10:13], v163 offset:2048
	ds_read_b128 v[14:17], v163 offset:3072
	ds_read_b128 v[18:21], v164
	ds_read_b128 v[22:25], v164 offset:1024
	ds_read_b128 v[26:29], v164 offset:2048
	ds_read_b128 v[30:33], v164 offset:3072
	s_lshl_b64 s[14:15], s[74:75], 21
	s_add_u32 s76, s36, s14
	s_addc_u32 s77, s37, s15
	s_and_b64 s[14:15], s[4:5], exec
	s_cselect_b32 s1, s77, s81
	s_cselect_b32 s75, s76, s80
	s_and_b32 s18, s10, 0x7fffffff
	s_lshl_b64 s[14:15], s[18:19], 21
	s_add_u32 s78, s33, s14
	s_addc_u32 s79, s71, s15
	s_and_b64 s[14:15], s[4:5], exec
	s_cselect_b32 s18, s79, s7
	s_cselect_b32 vcc_lo, s78, s6
	s_add_u32 s14, s80, 0x100080
	s_addc_u32 s15, s81, 0
	s_mov_b32 m0, s89
	v_lshl_add_u64 v[66:67], s[14:15], 0, v[136:137]
	ds_read_b128 v[34:37], v165
	ds_read_b128 v[38:41], v165 offset:1024
	ds_read_b128 v[42:45], v165 offset:2048
	ds_read_b128 v[46:49], v165 offset:3072
	ds_read_b128 v[50:53], v165 offset:4096
	ds_read_b128 v[54:57], v165 offset:5120
	ds_read_b128 v[58:61], v165 offset:6144
	ds_read_b128 v[62:65], v165 offset:7168
	global_load_lds_dwordx4 v[66:67], off
	v_lshl_add_u64 v[66:67], s[14:15], 0, v[132:133]
	s_mov_b32 m0, s92
	s_nop 0
	global_load_lds_dwordx4 v[66:67], off
	s_waitcnt vmcnt(8)
	s_waitcnt lgkmcnt(0)
	s_setprio 1
	s_barrier
	v_mfma_f32_16x16x32_bf16 v[86:89], v[10:13], v[50:53], 0
	v_mfma_f32_16x16x32_bf16 v[90:93], v[14:17], v[54:57], v[86:89]
	v_mfma_f32_16x16x32_bf16 v[86:89], v[2:5], v[58:61], 0
	v_mfma_f32_16x16x32_bf16 v[66:69], v[2:5], v[34:37], 0
	v_mfma_f32_16x16x32_bf16 v[70:73], v[10:13], v[34:37], 0
	v_mfma_f32_16x16x32_bf16 v[74:77], v[2:5], v[42:45], 0
	v_mfma_f32_16x16x32_bf16 v[78:81], v[10:13], v[42:45], 0
	v_mfma_f32_16x16x32_bf16 v[82:85], v[2:5], v[50:53], 0
	v_mfma_f32_16x16x32_bf16 v[94:97], v[6:9], v[62:65], v[86:89]
	v_mfma_f32_16x16x32_bf16 v[86:89], v[10:13], v[58:61], 0
	v_mfma_f32_16x16x32_bf16 v[66:69], v[6:9], v[38:41], v[66:69]
	v_mfma_f32_16x16x32_bf16 v[70:73], v[14:17], v[38:41], v[70:73]
	v_mfma_f32_16x16x32_bf16 v[74:77], v[6:9], v[46:49], v[74:77]
	v_mfma_f32_16x16x32_bf16 v[78:81], v[14:17], v[46:49], v[78:81]
	v_mfma_f32_16x16x32_bf16 v[82:85], v[6:9], v[54:57], v[82:85]
	v_mfma_f32_16x16x32_bf16 v[106:109], v[14:17], v[62:65], v[86:89]
	v_mfma_f32_16x16x32_bf16 v[86:89], v[18:21], v[34:37], 0
	v_mfma_f32_16x16x32_bf16 v[34:37], v[26:29], v[34:37], 0
	v_mfma_f32_16x16x32_bf16 v[110:113], v[22:25], v[38:41], v[86:89]
	v_mfma_f32_16x16x32_bf16 v[34:37], v[30:33], v[38:41], v[34:37]
	v_mfma_f32_16x16x32_bf16 v[38:41], v[18:21], v[42:45], 0
	v_mfma_f32_16x16x32_bf16 v[42:45], v[26:29], v[42:45], 0
	v_mfma_f32_16x16x32_bf16 v[38:41], v[22:25], v[46:49], v[38:41]
	v_mfma_f32_16x16x32_bf16 v[42:45], v[30:33], v[46:49], v[42:45]
	v_mfma_f32_16x16x32_bf16 v[46:49], v[18:21], v[50:53], 0
	v_mfma_f32_16x16x32_bf16 v[50:53], v[26:29], v[50:53], 0
	v_mfma_f32_16x16x32_bf16 v[46:49], v[22:25], v[54:57], v[46:49]
	v_mfma_f32_16x16x32_bf16 v[50:53], v[30:33], v[54:57], v[50:53]
	v_mfma_f32_16x16x32_bf16 v[54:57], v[18:21], v[58:61], 0
	v_mfma_f32_16x16x32_bf16 v[58:61], v[26:29], v[58:61], 0
	v_mfma_f32_16x16x32_bf16 v[54:57], v[22:25], v[62:65], v[54:57]
	v_mfma_f32_16x16x32_bf16 v[58:61], v[30:33], v[62:65], v[58:61]
	s_barrier
	s_setprio 0
	s_add_i32 vcc_hi, s59, s29
	v_lshl_add_u64 v[248:249], s[6:7], 0, v[134:135]
	s_add_i32 s84, vcc_hi, 0x2000
	v_lshl_add_u64 v[148:149], v[248:249], 0, s[66:67]
	s_mov_b32 m0, vcc_hi
	v_lshl_add_u64 v[250:251], s[6:7], 0, v[130:131]
	s_add_u32 s14, s6, 0x100100
	ds_read_b128 v[62:65], v165 offset:16384
	ds_read_b128 v[86:89], v165 offset:17408
	ds_read_b128 v[98:101], v165 offset:18432
	ds_read_b128 v[102:105], v165 offset:19456
	ds_read_b128 v[114:117], v165 offset:20480
	ds_read_b128 v[118:121], v165 offset:21504
	ds_read_b128 v[122:125], v165 offset:22528
	ds_read_b128 v[126:129], v165 offset:23552
	global_load_lds_dwordx4 v[148:149], off
	v_lshl_add_u64 v[148:149], v[250:251], 0, s[66:67]
	s_mov_b32 m0, s84
	s_addc_u32 s15, s7, 0
	s_add_i32 s85, s88, s29
	global_load_lds_dwordx4 v[148:149], off
	v_lshl_add_u64 v[148:149], s[14:15], 0, v[134:135]
	s_mov_b32 m0, s85
	s_add_i32 s46, s85, 0x2000
	global_load_lds_dwordx4 v[148:149], off
	v_lshl_add_u64 v[148:149], s[14:15], 0, v[130:131]
	s_mov_b32 m0, s46
	v_lshl_add_u64 v[252:253], s[80:81], 0, v[136:137]
	global_load_lds_dwordx4 v[148:149], off
	v_lshl_add_u64 v[148:149], v[252:253], 0, s[66:67]
	s_mov_b32 m0, s86
	v_lshl_add_u64 v[144:145], s[80:81], 0, v[132:133]
	global_load_lds_dwordx4 v[148:149], off
	v_lshl_add_u64 v[148:149], v[144:145], 0, s[66:67]
	s_mov_b32 m0, s93
	s_nop 0
	global_load_lds_dwordx4 v[148:149], off
	s_waitcnt vmcnt(8)
	s_waitcnt lgkmcnt(0)
	s_setprio 1
	s_barrier
	v_mfma_f32_16x16x32_bf16 v[148:151], v[2:5], v[62:65], 0
	v_mfma_f32_16x16x32_bf16 v[158:161], v[2:5], v[98:101], 0
	v_mfma_f32_16x16x32_bf16 v[172:175], v[2:5], v[114:117], 0
	v_mfma_f32_16x16x32_bf16 v[2:5], v[2:5], v[122:125], 0
	v_mfma_f32_16x16x32_bf16 v[150:153], v[6:9], v[86:89], v[148:151]
	v_mfma_f32_16x16x32_bf16 v[158:161], v[6:9], v[102:105], v[158:161]
	v_mfma_f32_16x16x32_bf16 v[172:175], v[6:9], v[118:121], v[172:175]
	v_mfma_f32_16x16x32_bf16 v[2:5], v[6:9], v[126:129], v[2:5]
	v_mfma_f32_16x16x32_bf16 v[6:9], v[10:13], v[122:125], 0
	v_mfma_f32_16x16x32_bf16 v[154:157], v[10:13], v[62:65], 0
	v_mfma_f32_16x16x32_bf16 v[168:171], v[10:13], v[98:101], 0
	v_mfma_f32_16x16x32_bf16 v[176:179], v[10:13], v[114:117], 0
	v_mfma_f32_16x16x32_bf16 v[10:13], v[14:17], v[126:129], v[6:9]
	v_mfma_f32_16x16x32_bf16 v[154:157], v[14:17], v[86:89], v[154:157]
	v_mfma_f32_16x16x32_bf16 v[168:171], v[14:17], v[102:105], v[168:171]
	v_mfma_f32_16x16x32_bf16 v[176:179], v[14:17], v[118:121], v[176:179]
	v_mfma_f32_16x16x32_bf16 v[6:9], v[18:21], v[62:65], 0
	v_mfma_f32_16x16x32_bf16 v[14:17], v[22:25], v[86:89], v[6:9]
	v_mfma_f32_16x16x32_bf16 v[6:9], v[26:29], v[62:65], 0
	v_mfma_f32_16x16x32_bf16 v[180:183], v[30:33], v[86:89], v[6:9]
	v_mfma_f32_16x16x32_bf16 v[6:9], v[18:21], v[98:101], 0
	v_mfma_f32_16x16x32_bf16 v[184:187], v[22:25], v[102:105], v[6:9]
	v_mfma_f32_16x16x32_bf16 v[6:9], v[26:29], v[98:101], 0
	v_mfma_f32_16x16x32_bf16 v[188:191], v[30:33], v[102:105], v[6:9]
	v_mfma_f32_16x16x32_bf16 v[6:9], v[18:21], v[114:117], 0
	v_mfma_f32_16x16x32_bf16 v[192:195], v[22:25], v[118:121], v[6:9]
	v_mfma_f32_16x16x32_bf16 v[6:9], v[26:29], v[114:117], 0
	v_mfma_f32_16x16x32_bf16 v[196:199], v[30:33], v[118:121], v[6:9]
	v_mfma_f32_16x16x32_bf16 v[6:9], v[18:21], v[122:125], 0
	v_mfma_f32_16x16x32_bf16 v[200:203], v[22:25], v[126:129], v[6:9]
	v_mfma_f32_16x16x32_bf16 v[6:9], v[26:29], v[122:125], 0
	v_mfma_f32_16x16x32_bf16 v[204:207], v[30:33], v[126:129], v[6:9]
	s_barrier
	s_setprio 0
	s_add_i32 s47, 0, 0x18000
	s_add_i32 s56, 0, 0x1c000
	v_add_u32_e32 v138, s47, v162
	v_add_u32_e32 v148, s56, v162
	s_nop 0
	ds_read_b128 v[6:9], v138
	ds_read_b128 v[26:29], v138 offset:1024
	ds_read_b128 v[30:33], v138 offset:2048
	ds_read_b128 v[62:65], v138 offset:3072
	ds_read_b128 v[208:211], v148
	ds_read_b128 v[212:215], v148 offset:1024
	ds_read_b128 v[216:219], v148 offset:2048
	ds_read_b128 v[220:223], v148 offset:3072
	s_add_u32 s14, s80, 0x100100
	s_addc_u32 s15, s81, 0
	s_mov_b32 m0, s94
	v_lshl_add_u64 v[86:87], s[14:15], 0, v[136:137]
	ds_read_b128 v[18:21], v165 offset:32768
	ds_read_b128 v[22:25], v165 offset:33792
	ds_read_b128 v[224:227], v165 offset:34816
	ds_read_b128 v[228:231], v165 offset:35840
	ds_read_b128 v[232:235], v165 offset:36864
	ds_read_b128 v[236:239], v165 offset:37888
	ds_read_b128 v[240:243], v165 offset:38912
	ds_read_b128 v[244:247], v165 offset:39936
	global_load_lds_dwordx4 v[86:87], off
	v_lshl_add_u64 v[86:87], s[14:15], 0, v[132:133]
	s_mov_b32 m0, s95
	s_nop 0
	global_load_lds_dwordx4 v[86:87], off
	s_waitcnt vmcnt(8)
	s_waitcnt lgkmcnt(0)
	s_setprio 1
	s_barrier
	v_mfma_f32_16x16x32_bf16 v[66:69], v[6:9], v[18:21], v[66:69]
	v_mfma_f32_16x16x32_bf16 v[118:121], v[26:29], v[22:25], v[66:69]
	v_mfma_f32_16x16x32_bf16 v[66:69], v[30:33], v[18:21], v[70:73]
	v_mfma_f32_16x16x32_bf16 v[114:117], v[62:65], v[22:25], v[66:69]
	v_mfma_f32_16x16x32_bf16 v[66:69], v[6:9], v[224:227], v[74:77]
	v_mfma_f32_16x16x32_bf16 v[102:105], v[26:29], v[228:231], v[66:69]
	v_mfma_f32_16x16x32_bf16 v[66:69], v[30:33], v[224:227], v[78:81]
	v_mfma_f32_16x16x32_bf16 v[98:101], v[62:65], v[228:231], v[66:69]
	v_mfma_f32_16x16x32_bf16 v[66:69], v[6:9], v[232:235], v[82:85]
	v_mfma_f32_16x16x32_bf16 v[86:89], v[26:29], v[236:239], v[66:69]
	v_mfma_f32_16x16x32_bf16 v[66:69], v[30:33], v[232:235], v[90:93]
	v_mfma_f32_16x16x32_bf16 v[82:85], v[62:65], v[236:239], v[66:69]
	v_mfma_f32_16x16x32_bf16 v[66:69], v[6:9], v[240:243], v[94:97]
	v_mfma_f32_16x16x32_bf16 v[70:73], v[26:29], v[244:247], v[66:69]
	v_mfma_f32_16x16x32_bf16 v[66:69], v[30:33], v[240:243], v[106:109]
	v_mfma_f32_16x16x32_bf16 v[66:69], v[62:65], v[244:247], v[66:69]
	v_mfma_f32_16x16x32_bf16 v[74:77], v[208:211], v[18:21], v[110:113]
	v_mfma_f32_16x16x32_bf16 v[18:21], v[216:219], v[18:21], v[34:37]
	v_mfma_f32_16x16x32_bf16 v[122:125], v[220:223], v[22:25], v[18:21]
	v_mfma_f32_16x16x32_bf16 v[18:21], v[208:211], v[224:227], v[38:41]
	v_mfma_f32_16x16x32_bf16 v[110:113], v[212:215], v[228:231], v[18:21]
	v_mfma_f32_16x16x32_bf16 v[18:21], v[216:219], v[224:227], v[42:45]
	v_mfma_f32_16x16x32_bf16 v[106:109], v[220:223], v[228:231], v[18:21]
	v_mfma_f32_16x16x32_bf16 v[18:21], v[208:211], v[232:235], v[46:49]
	v_mfma_f32_16x16x32_bf16 v[94:97], v[212:215], v[236:239], v[18:21]
	v_mfma_f32_16x16x32_bf16 v[18:21], v[216:219], v[232:235], v[50:53]
	v_mfma_f32_16x16x32_bf16 v[90:93], v[220:223], v[236:239], v[18:21]
	v_mfma_f32_16x16x32_bf16 v[18:21], v[208:211], v[240:243], v[54:57]
	v_mfma_f32_16x16x32_bf16 v[78:81], v[212:215], v[244:247], v[18:21]
	v_mfma_f32_16x16x32_bf16 v[18:21], v[216:219], v[240:243], v[58:61]
	v_mfma_f32_16x16x32_bf16 v[126:129], v[212:215], v[22:25], v[74:77]
	v_mfma_f32_16x16x32_bf16 v[74:77], v[220:223], v[244:247], v[18:21]
	s_barrier
	s_setprio 0
	s_add_i32 s47, s47, s29
	s_add_i32 s91, s47, 0x2000
	s_nop 1
	v_lshl_add_u64 v[18:19], v[248:249], 0, s[68:69]
	s_mov_b32 m0, s47
	s_add_u32 s14, s6, 0x100180
	ds_read_b128 v[42:45], v165 offset:49152
	ds_read_b128 v[46:49], v165 offset:50176
	ds_read_b128 v[224:227], v165 offset:51200
	ds_read_b128 v[228:231], v165 offset:52224
	ds_read_b128 v[232:235], v165 offset:53248
	ds_read_b128 v[236:239], v165 offset:54272
	ds_read_b128 v[240:243], v165 offset:55296
	ds_read_b128 v[244:247], v165 offset:56320
	global_load_lds_dwordx4 v[18:19], off
	v_lshl_add_u64 v[18:19], v[250:251], 0, s[68:69]
	s_mov_b32 m0, s91
	s_addc_u32 s15, s7, 0
	s_add_i32 s56, s56, s29
	global_load_lds_dwordx4 v[18:19], off
	v_lshl_add_u64 v[18:19], s[14:15], 0, v[134:135]
	s_mov_b32 m0, s56
	s_add_i32 s57, s56, 0x2000
	global_load_lds_dwordx4 v[18:19], off
	v_lshl_add_u64 v[18:19], s[14:15], 0, v[130:131]
	s_mov_b32 m0, s57
	s_nop 0
	global_load_lds_dwordx4 v[18:19], off
	v_lshl_add_u64 v[18:19], v[252:253], 0, s[68:69]
	s_mov_b32 m0, s96
	s_nop 0
	global_load_lds_dwordx4 v[18:19], off
	v_lshl_add_u64 v[18:19], v[144:145], 0, s[68:69]
	s_mov_b32 m0, s97
	s_nop 0
	global_load_lds_dwordx4 v[18:19], off
	s_waitcnt vmcnt(8)
	s_waitcnt lgkmcnt(0)
	s_setprio 1
	s_barrier
	v_mfma_f32_16x16x32_bf16 v[18:21], v[6:9], v[42:45], v[150:153]
	v_mfma_f32_16x16x32_bf16 v[54:57], v[26:29], v[46:49], v[18:21]
	v_mfma_f32_16x16x32_bf16 v[18:21], v[30:33], v[42:45], v[154:157]
	v_mfma_f32_16x16x32_bf16 v[50:53], v[62:65], v[46:49], v[18:21]
	v_mfma_f32_16x16x32_bf16 v[18:21], v[6:9], v[224:227], v[158:161]
	v_mfma_f32_16x16x32_bf16 v[38:41], v[26:29], v[228:231], v[18:21]
	v_mfma_f32_16x16x32_bf16 v[18:21], v[30:33], v[224:227], v[168:171]
	v_mfma_f32_16x16x32_bf16 v[34:37], v[62:65], v[228:231], v[18:21]
	v_mfma_f32_16x16x32_bf16 v[18:21], v[6:9], v[232:235], v[172:175]
	v_mfma_f32_16x16x32_bf16 v[2:5], v[6:9], v[240:243], v[2:5]
	v_mfma_f32_16x16x32_bf16 v[22:25], v[26:29], v[236:239], v[18:21]
	v_mfma_f32_16x16x32_bf16 v[18:21], v[30:33], v[232:235], v[176:179]
	v_mfma_f32_16x16x32_bf16 v[6:9], v[26:29], v[244:247], v[2:5]
	v_mfma_f32_16x16x32_bf16 v[2:5], v[30:33], v[240:243], v[10:13]
	v_mfma_f32_16x16x32_bf16 v[18:21], v[62:65], v[236:239], v[18:21]
	v_mfma_f32_16x16x32_bf16 v[2:5], v[62:65], v[244:247], v[2:5]
	v_mfma_f32_16x16x32_bf16 v[10:13], v[208:211], v[42:45], v[14:17]
	v_mfma_f32_16x16x32_bf16 v[62:65], v[212:215], v[46:49], v[10:13]
	v_mfma_f32_16x16x32_bf16 v[10:13], v[216:219], v[42:45], v[180:183]
	v_mfma_f32_16x16x32_bf16 v[58:61], v[220:223], v[46:49], v[10:13]
	v_mfma_f32_16x16x32_bf16 v[10:13], v[208:211], v[224:227], v[184:187]
	v_mfma_f32_16x16x32_bf16 v[46:49], v[212:215], v[228:231], v[10:13]
	v_mfma_f32_16x16x32_bf16 v[10:13], v[216:219], v[224:227], v[188:191]
	v_mfma_f32_16x16x32_bf16 v[42:45], v[220:223], v[228:231], v[10:13]
	v_mfma_f32_16x16x32_bf16 v[10:13], v[208:211], v[232:235], v[192:195]
	v_mfma_f32_16x16x32_bf16 v[30:33], v[212:215], v[236:239], v[10:13]
	v_mfma_f32_16x16x32_bf16 v[10:13], v[216:219], v[232:235], v[196:199]
	v_mfma_f32_16x16x32_bf16 v[26:29], v[220:223], v[236:239], v[10:13]
	v_mfma_f32_16x16x32_bf16 v[10:13], v[208:211], v[240:243], v[200:203]
	v_mfma_f32_16x16x32_bf16 v[14:17], v[212:215], v[244:247], v[10:13]
	v_mfma_f32_16x16x32_bf16 v[10:13], v[216:219], v[240:243], v[204:207]
	v_mfma_f32_16x16x32_bf16 v[10:13], v[220:223], v[244:247], v[10:13]
	s_barrier
	s_setprio 0
	s_add_u32 s80, s80, 0x100180
	s_addc_u32 s81, s81, 0
	s_add_u32 s30, s6, 0x200
	s_addc_u32 s14, s7, 0
	s_mov_b32 s15, 0

.Lrb2_skip_11871:
	s_mov_b32 m0, s89
	ds_read_b128 v[188:191], v165
	ds_read_b128 v[192:195], v165 offset:1024
	ds_read_b128 v[196:199], v165 offset:2048
	ds_read_b128 v[200:203], v165 offset:3072
	ds_read_b128 v[204:207], v165 offset:4096
	ds_read_b128 v[208:211], v165 offset:5120
	ds_read_b128 v[212:215], v165 offset:6144
	ds_read_b128 v[216:219], v165 offset:7168
	global_load_lds_dwordx4 v140, s[80:81]
	s_mov_b32 m0, s92
	s_nop 0
	global_load_lds_dwordx4 v142, s[80:81]
	s_waitcnt vmcnt(8)
	s_waitcnt lgkmcnt(0)
	s_setprio 1
	s_barrier
	v_mfma_f32_16x16x32_bf16 v[118:121], v[150:153], v[188:191], v[118:121]
	v_mfma_f32_16x16x32_bf16 v[114:117], v[158:161], v[188:191], v[114:117]
	v_mfma_f32_16x16x32_bf16 v[102:105], v[150:153], v[196:199], v[102:105]
	v_mfma_f32_16x16x32_bf16 v[98:101], v[158:161], v[196:199], v[98:101]
	v_mfma_f32_16x16x32_bf16 v[86:89], v[150:153], v[204:207], v[86:89]
	v_mfma_f32_16x16x32_bf16 v[82:85], v[158:161], v[204:207], v[82:85]
	v_mfma_f32_16x16x32_bf16 v[70:73], v[150:153], v[212:215], v[70:73]
	v_mfma_f32_16x16x32_bf16 v[66:69], v[158:161], v[212:215], v[66:69]
	v_mfma_f32_16x16x32_bf16 v[118:121], v[154:157], v[192:195], v[118:121]
	v_mfma_f32_16x16x32_bf16 v[114:117], v[168:171], v[192:195], v[114:117]
	v_mfma_f32_16x16x32_bf16 v[102:105], v[154:157], v[200:203], v[102:105]
	v_mfma_f32_16x16x32_bf16 v[98:101], v[168:171], v[200:203], v[98:101]
	v_mfma_f32_16x16x32_bf16 v[86:89], v[154:157], v[208:211], v[86:89]
	v_mfma_f32_16x16x32_bf16 v[82:85], v[168:171], v[208:211], v[82:85]
	v_mfma_f32_16x16x32_bf16 v[70:73], v[154:157], v[216:219], v[70:73]
	v_mfma_f32_16x16x32_bf16 v[66:69], v[168:171], v[216:219], v[66:69]
	v_mfma_f32_16x16x32_bf16 v[126:129], v[172:175], v[188:191], v[126:129]
	v_mfma_f32_16x16x32_bf16 v[122:125], v[180:183], v[188:191], v[122:125]
	v_mfma_f32_16x16x32_bf16 v[110:113], v[172:175], v[196:199], v[110:113]
	v_mfma_f32_16x16x32_bf16 v[106:109], v[180:183], v[196:199], v[106:109]
	v_mfma_f32_16x16x32_bf16 v[94:97], v[172:175], v[204:207], v[94:97]
	v_mfma_f32_16x16x32_bf16 v[90:93], v[180:183], v[204:207], v[90:93]
	v_mfma_f32_16x16x32_bf16 v[78:81], v[172:175], v[212:215], v[78:81]
	v_mfma_f32_16x16x32_bf16 v[74:77], v[180:183], v[212:215], v[74:77]
	v_mfma_f32_16x16x32_bf16 v[126:129], v[176:179], v[192:195], v[126:129]
	v_mfma_f32_16x16x32_bf16 v[122:125], v[184:187], v[192:195], v[122:125]
	v_mfma_f32_16x16x32_bf16 v[110:113], v[176:179], v[200:203], v[110:113]
	v_mfma_f32_16x16x32_bf16 v[106:109], v[184:187], v[200:203], v[106:109]
	v_mfma_f32_16x16x32_bf16 v[94:97], v[176:179], v[208:211], v[94:97]
	v_mfma_f32_16x16x32_bf16 v[90:93], v[184:187], v[208:211], v[90:93]
	v_mfma_f32_16x16x32_bf16 v[78:81], v[176:179], v[216:219], v[78:81]
	v_mfma_f32_16x16x32_bf16 v[74:77], v[184:187], v[216:219], v[74:77]
	s_barrier
	s_setprio 0
	s_mov_b32 m0, vcc_hi
	s_mov_b64 s[98:99], s[6:7]
	s_add_u32 s16, s6, 0x100000
	ds_read_b128 v[188:191], v165 offset:16384
	ds_read_b128 v[192:195], v165 offset:17408
	ds_read_b128 v[196:199], v165 offset:18432
	ds_read_b128 v[200:203], v165 offset:19456
	ds_read_b128 v[204:207], v165 offset:20480
	ds_read_b128 v[208:211], v165 offset:21504
	ds_read_b128 v[212:215], v165 offset:22528
	ds_read_b128 v[216:219], v165 offset:23552
	global_load_lds_dwordx4 v134, s[6:7]
	s_mov_b32 m0, s84
	s_addc_u32 s17, s7, 0
	global_load_lds_dwordx4 v130, s[6:7]
	s_mov_b32 m0, s85
	s_mov_b64 s[100:101], s[82:83]
	global_load_lds_dwordx4 v134, s[16:17]
	s_mov_b32 m0, s46
	s_nop 0
	global_load_lds_dwordx4 v130, s[16:17]
	s_waitcnt vmcnt(6)
	s_waitcnt lgkmcnt(0)
	s_setprio 1
	s_barrier
	v_mfma_f32_16x16x32_bf16 v[54:57], v[150:153], v[188:191], v[54:57]
	v_mfma_f32_16x16x32_bf16 v[50:53], v[158:161], v[188:191], v[50:53]
	v_mfma_f32_16x16x32_bf16 v[38:41], v[150:153], v[196:199], v[38:41]
	v_mfma_f32_16x16x32_bf16 v[34:37], v[158:161], v[196:199], v[34:37]
	v_mfma_f32_16x16x32_bf16 v[22:25], v[150:153], v[204:207], v[22:25]
	v_mfma_f32_16x16x32_bf16 v[18:21], v[158:161], v[204:207], v[18:21]
	v_mfma_f32_16x16x32_bf16 v[6:9], v[150:153], v[212:215], v[6:9]
	v_mfma_f32_16x16x32_bf16 v[2:5], v[158:161], v[212:215], v[2:5]
	v_mfma_f32_16x16x32_bf16 v[54:57], v[154:157], v[192:195], v[54:57]
	v_mfma_f32_16x16x32_bf16 v[50:53], v[168:171], v[192:195], v[50:53]
	v_mfma_f32_16x16x32_bf16 v[38:41], v[154:157], v[200:203], v[38:41]
	v_mfma_f32_16x16x32_bf16 v[34:37], v[168:171], v[200:203], v[34:37]
	v_mfma_f32_16x16x32_bf16 v[22:25], v[154:157], v[208:211], v[22:25]
	v_mfma_f32_16x16x32_bf16 v[18:21], v[168:171], v[208:211], v[18:21]
	v_mfma_f32_16x16x32_bf16 v[6:9], v[154:157], v[216:219], v[6:9]
	v_mfma_f32_16x16x32_bf16 v[2:5], v[168:171], v[216:219], v[2:5]
	v_mfma_f32_16x16x32_bf16 v[62:65], v[172:175], v[188:191], v[62:65]
	v_mfma_f32_16x16x32_bf16 v[58:61], v[180:183], v[188:191], v[58:61]
	v_mfma_f32_16x16x32_bf16 v[46:49], v[172:175], v[196:199], v[46:49]
	v_mfma_f32_16x16x32_bf16 v[42:45], v[180:183], v[196:199], v[42:45]
	v_mfma_f32_16x16x32_bf16 v[30:33], v[172:175], v[204:207], v[30:33]
	v_mfma_f32_16x16x32_bf16 v[26:29], v[180:183], v[204:207], v[26:29]
	v_mfma_f32_16x16x32_bf16 v[14:17], v[172:175], v[212:215], v[14:17]
	v_mfma_f32_16x16x32_bf16 v[10:13], v[180:183], v[212:215], v[10:13]
	v_mfma_f32_16x16x32_bf16 v[62:65], v[176:179], v[192:195], v[62:65]
	v_mfma_f32_16x16x32_bf16 v[58:61], v[184:187], v[192:195], v[58:61]
	v_mfma_f32_16x16x32_bf16 v[46:49], v[176:179], v[200:203], v[46:49]
	v_mfma_f32_16x16x32_bf16 v[42:45], v[184:187], v[200:203], v[42:45]
	v_mfma_f32_16x16x32_bf16 v[30:33], v[176:179], v[208:211], v[30:33]
	v_mfma_f32_16x16x32_bf16 v[26:29], v[184:187], v[208:211], v[26:29]
	v_mfma_f32_16x16x32_bf16 v[14:17], v[176:179], v[216:219], v[14:17]
	v_mfma_f32_16x16x32_bf16 v[10:13], v[184:187], v[216:219], v[10:13]
	s_barrier
	s_setprio 0
	ds_read_b128 v[150:153], v138
	ds_read_b128 v[154:157], v138 offset:1024
	ds_read_b128 v[158:161], v138 offset:2048
	ds_read_b128 v[168:171], v138 offset:3072
	ds_read_b128 v[172:175], v148
	ds_read_b128 v[176:179], v148 offset:1024
	ds_read_b128 v[180:183], v148 offset:2048
	ds_read_b128 v[184:187], v148 offset:3072
	s_add_u32 s16, s82, 0x100000
	s_addc_u32 s17, s83, 0
	s_mov_b32 m0, s86
	s_nop 0
	global_load_lds_dwordx4 v136, s[100:101]
	s_mov_b32 m0, s93
	s_nop 0
	global_load_lds_dwordx4 v132, s[100:101]
	s_mov_b32 m0, s94
	ds_read_b128 v[188:191], v165 offset:32768
	ds_read_b128 v[192:195], v165 offset:33792
	ds_read_b128 v[196:199], v165 offset:34816
	ds_read_b128 v[200:203], v165 offset:35840
	ds_read_b128 v[204:207], v165 offset:36864
	ds_read_b128 v[208:211], v165 offset:37888
	ds_read_b128 v[212:215], v165 offset:38912
	ds_read_b128 v[216:219], v165 offset:39936
	global_load_lds_dwordx4 v136, s[16:17]
	s_mov_b32 m0, s95
	s_nop 0
	global_load_lds_dwordx4 v132, s[16:17]
	s_waitcnt vmcnt(8)
	s_waitcnt lgkmcnt(0)
	s_setprio 1
	s_barrier
	v_mfma_f32_16x16x32_bf16 v[118:121], v[150:153], v[188:191], v[118:121]
	v_mfma_f32_16x16x32_bf16 v[114:117], v[158:161], v[188:191], v[114:117]
	v_mfma_f32_16x16x32_bf16 v[102:105], v[150:153], v[196:199], v[102:105]
	v_mfma_f32_16x16x32_bf16 v[98:101], v[158:161], v[196:199], v[98:101]
	v_mfma_f32_16x16x32_bf16 v[86:89], v[150:153], v[204:207], v[86:89]
	v_mfma_f32_16x16x32_bf16 v[82:85], v[158:161], v[204:207], v[82:85]
	v_mfma_f32_16x16x32_bf16 v[70:73], v[150:153], v[212:215], v[70:73]
	v_mfma_f32_16x16x32_bf16 v[66:69], v[158:161], v[212:215], v[66:69]
	v_mfma_f32_16x16x32_bf16 v[118:121], v[154:157], v[192:195], v[118:121]
	v_mfma_f32_16x16x32_bf16 v[114:117], v[168:171], v[192:195], v[114:117]
	v_mfma_f32_16x16x32_bf16 v[102:105], v[154:157], v[200:203], v[102:105]
	v_mfma_f32_16x16x32_bf16 v[98:101], v[168:171], v[200:203], v[98:101]
	v_mfma_f32_16x16x32_bf16 v[86:89], v[154:157], v[208:211], v[86:89]
	v_mfma_f32_16x16x32_bf16 v[82:85], v[168:171], v[208:211], v[82:85]
	v_mfma_f32_16x16x32_bf16 v[70:73], v[154:157], v[216:219], v[70:73]
	v_mfma_f32_16x16x32_bf16 v[66:69], v[168:171], v[216:219], v[66:69]
	v_mfma_f32_16x16x32_bf16 v[126:129], v[172:175], v[188:191], v[126:129]
	v_mfma_f32_16x16x32_bf16 v[122:125], v[180:183], v[188:191], v[122:125]
	v_mfma_f32_16x16x32_bf16 v[110:113], v[172:175], v[196:199], v[110:113]
	v_mfma_f32_16x16x32_bf16 v[106:109], v[180:183], v[196:199], v[106:109]
	v_mfma_f32_16x16x32_bf16 v[94:97], v[172:175], v[204:207], v[94:97]
	v_mfma_f32_16x16x32_bf16 v[90:93], v[180:183], v[204:207], v[90:93]
	v_mfma_f32_16x16x32_bf16 v[78:81], v[172:175], v[212:215], v[78:81]
	v_mfma_f32_16x16x32_bf16 v[74:77], v[180:183], v[212:215], v[74:77]
	v_mfma_f32_16x16x32_bf16 v[126:129], v[176:179], v[192:195], v[126:129]
	v_mfma_f32_16x16x32_bf16 v[122:125], v[184:187], v[192:195], v[122:125]
	v_mfma_f32_16x16x32_bf16 v[110:113], v[176:179], v[200:203], v[110:113]
	v_mfma_f32_16x16x32_bf16 v[106:109], v[184:187], v[200:203], v[106:109]
	v_mfma_f32_16x16x32_bf16 v[94:97], v[176:179], v[208:211], v[94:97]
	v_mfma_f32_16x16x32_bf16 v[90:93], v[184:187], v[208:211], v[90:93]
	v_mfma_f32_16x16x32_bf16 v[78:81], v[176:179], v[216:219], v[78:81]
	v_mfma_f32_16x16x32_bf16 v[74:77], v[184:187], v[216:219], v[74:77]
	s_barrier
	s_setprio 0
	s_mov_b32 m0, s47
	s_add_u32 s98, s98, 0x80
	s_addc_u32 s99, s99, 0
	s_add_u32 s100, s100, 0x80
	s_addc_u32 s101, s101, 0
	s_add_u32 s6, s6, 0x100080
	ds_read_b128 v[188:191], v165 offset:49152
	ds_read_b128 v[192:195], v165 offset:50176
	ds_read_b128 v[196:199], v165 offset:51200
	ds_read_b128 v[200:203], v165 offset:52224
	ds_read_b128 v[204:207], v165 offset:53248
	ds_read_b128 v[208:211], v165 offset:54272
	ds_read_b128 v[212:215], v165 offset:55296
	ds_read_b128 v[216:219], v165 offset:56320
	global_load_lds_dwordx4 v134, s[98:99]
	s_mov_b32 m0, s91
	s_addc_u32 s7, s7, 0
	global_load_lds_dwordx4 v130, s[98:99]
	s_mov_b32 m0, s56
	s_nop 0
	global_load_lds_dwordx4 v134, s[6:7]
	s_mov_b32 m0, s57
	s_nop 0
	global_load_lds_dwordx4 v130, s[6:7]
	s_waitcnt vmcnt(6)
	s_waitcnt lgkmcnt(0)
	s_setprio 1
	s_barrier
	v_mfma_f32_16x16x32_bf16 v[54:57], v[150:153], v[188:191], v[54:57]
	v_mfma_f32_16x16x32_bf16 v[50:53], v[158:161], v[188:191], v[50:53]
	v_mfma_f32_16x16x32_bf16 v[38:41], v[150:153], v[196:199], v[38:41]
	v_mfma_f32_16x16x32_bf16 v[34:37], v[158:161], v[196:199], v[34:37]
	v_mfma_f32_16x16x32_bf16 v[22:25], v[150:153], v[204:207], v[22:25]
	v_mfma_f32_16x16x32_bf16 v[18:21], v[158:161], v[204:207], v[18:21]
	v_mfma_f32_16x16x32_bf16 v[6:9], v[150:153], v[212:215], v[6:9]
	v_mfma_f32_16x16x32_bf16 v[2:5], v[158:161], v[212:215], v[2:5]
	v_mfma_f32_16x16x32_bf16 v[54:57], v[154:157], v[192:195], v[54:57]
	v_mfma_f32_16x16x32_bf16 v[50:53], v[168:171], v[192:195], v[50:53]
	v_mfma_f32_16x16x32_bf16 v[38:41], v[154:157], v[200:203], v[38:41]
	v_mfma_f32_16x16x32_bf16 v[34:37], v[168:171], v[200:203], v[34:37]
	v_mfma_f32_16x16x32_bf16 v[22:25], v[154:157], v[208:211], v[22:25]
	v_mfma_f32_16x16x32_bf16 v[18:21], v[168:171], v[208:211], v[18:21]
	v_mfma_f32_16x16x32_bf16 v[6:9], v[154:157], v[216:219], v[6:9]
	v_mfma_f32_16x16x32_bf16 v[2:5], v[168:171], v[216:219], v[2:5]
	v_mfma_f32_16x16x32_bf16 v[62:65], v[172:175], v[188:191], v[62:65]
	v_mfma_f32_16x16x32_bf16 v[58:61], v[180:183], v[188:191], v[58:61]
	v_mfma_f32_16x16x32_bf16 v[46:49], v[172:175], v[196:199], v[46:49]
	v_mfma_f32_16x16x32_bf16 v[42:45], v[180:183], v[196:199], v[42:45]
	v_mfma_f32_16x16x32_bf16 v[30:33], v[172:175], v[204:207], v[30:33]
	v_mfma_f32_16x16x32_bf16 v[26:29], v[180:183], v[204:207], v[26:29]
	v_mfma_f32_16x16x32_bf16 v[14:17], v[172:175], v[212:215], v[14:17]
	v_mfma_f32_16x16x32_bf16 v[10:13], v[180:183], v[212:215], v[10:13]
	v_mfma_f32_16x16x32_bf16 v[62:65], v[176:179], v[192:195], v[62:65]
	v_mfma_f32_16x16x32_bf16 v[58:61], v[184:187], v[192:195], v[58:61]
	v_mfma_f32_16x16x32_bf16 v[46:49], v[176:179], v[200:203], v[46:49]
	v_mfma_f32_16x16x32_bf16 v[42:45], v[184:187], v[200:203], v[42:45]
	v_mfma_f32_16x16x32_bf16 v[30:33], v[176:179], v[208:211], v[30:33]
	v_mfma_f32_16x16x32_bf16 v[26:29], v[184:187], v[208:211], v[26:29]
	v_mfma_f32_16x16x32_bf16 v[14:17], v[176:179], v[216:219], v[14:17]
	v_mfma_f32_16x16x32_bf16 v[10:13], v[184:187], v[216:219], v[10:13]
	s_barrier
	s_setprio 0
	s_add_i32 s15, s15, 2
	s_add_u32 s80, s80, 0x100
	s_addc_u32 s81, s81, 0
	s_add_u32 s30, s30, 0x100
	s_addc_u32 s14, s14, 0
	s_cmp_gt_u32 s15, 61
	s_cbranch_scc0 .LBB0_415
	s_mov_b32 m0, s96
	s_nop 0
	global_load_lds_dwordx4 v136, s[100:101]
	s_mov_b32 m0, s97
	s_nop 0
	global_load_lds_dwordx4 v132, s[100:101]
	s_and_b64 vcc, exec, s[64:65]
	s_cbranch_vccz .LBB0_418
	s_barrier

;     __host__ __device__ bool next(int i, Unit& u) const { if (!StaticOrder::next(i >> 1, u)) return false; u.seg = i & 1; return true; }
;     ...
;         const bool has_next = S.next(ui + 1, nxt);
;         const char* nA = has_next ? PG8_APTR(nxt) : cA; const char* nB = has_next ? PG8_BPTR(nxt) : cB;
;         const char* pfc = PG8_PFPTR(cA, cB); const char* pfn = PG8_PFPTR(nA, nB);
;         PG8_KITER(0);
.LBB0_434:
	s_ashr_i32 s67, s66, 31
	ds_read_b128 v[2:5], v141
	ds_read_b128 v[6:9], v141 offset:1024
	ds_read_b128 v[10:13], v141 offset:2048
	ds_read_b128 v[14:17], v141 offset:3072
	ds_read_b128 v[18:21], v142
	ds_read_b128 v[22:25], v142 offset:1024
	ds_read_b128 v[26:29], v142 offset:2048
	ds_read_b128 v[30:33], v142 offset:3072
	s_lshl_b64 s[14:15], s[66:67], 21
	s_add_u32 s70, s11, s14
	s_addc_u32 s71, s12, s15
	s_and_b64 s[14:15], s[68:69], exec
	s_cselect_b32 s9, s71, s79
	s_cselect_b32 s67, s70, s78
	s_and_b32 s18, s94, 0x7fffffff
	s_lshl_b64 s[14:15], s[18:19], 21
	s_add_u32 s74, s13, s14
	s_addc_u32 s75, s29, s15
	s_and_b64 s[14:15], s[68:69], exec
	s_cselect_b32 s18, s75, s77
	s_cselect_b32 s95, s74, s76
	s_add_u32 s14, s78, 0x100080
	s_addc_u32 s15, s79, 0
	s_add_i32 s96, s59, 0xc000
	v_lshl_add_u64 v[66:67], s[14:15], 0, v[132:133]
	s_mov_b32 m0, s96
	s_add_i32 s97, s59, 0xe000
	ds_read_b128 v[34:37], v143
	ds_read_b128 v[38:41], v143 offset:1024
	ds_read_b128 v[42:45], v143 offset:2048
	ds_read_b128 v[46:49], v143 offset:3072
	ds_read_b128 v[50:53], v143 offset:4096
	ds_read_b128 v[54:57], v143 offset:5120
	ds_read_b128 v[58:61], v143 offset:6144
	ds_read_b128 v[62:65], v143 offset:7168
	global_load_lds_dwordx4 v[66:67], off
	v_lshl_add_u64 v[66:67], s[14:15], 0, v[130:131]
	s_mov_b32 m0, s97
	s_nop 0
	global_load_lds_dwordx4 v[66:67], off
	s_waitcnt vmcnt(8)
	s_waitcnt lgkmcnt(0)
	s_setprio 1
	s_barrier
	v_mfma_f32_16x16x32_bf16 v[66:69], v[2:5], v[34:37], 0
	v_mfma_f32_16x16x32_bf16 v[70:73], v[10:13], v[34:37], 0
	v_mfma_f32_16x16x32_bf16 v[74:77], v[2:5], v[42:45], 0
	v_mfma_f32_16x16x32_bf16 v[78:81], v[10:13], v[42:45], 0
	v_mfma_f32_16x16x32_bf16 v[82:85], v[2:5], v[50:53], 0
	v_mfma_f32_16x16x32_bf16 v[86:89], v[10:13], v[50:53], 0
	v_mfma_f32_16x16x32_bf16 v[90:93], v[2:5], v[58:61], 0
	v_mfma_f32_16x16x32_bf16 v[94:97], v[10:13], v[58:61], 0
	v_mfma_f32_16x16x32_bf16 v[66:69], v[6:9], v[38:41], v[66:69]
	v_mfma_f32_16x16x32_bf16 v[70:73], v[14:17], v[38:41], v[70:73]
	v_mfma_f32_16x16x32_bf16 v[74:77], v[6:9], v[46:49], v[74:77]
	v_mfma_f32_16x16x32_bf16 v[78:81], v[14:17], v[46:49], v[78:81]
	v_mfma_f32_16x16x32_bf16 v[82:85], v[6:9], v[54:57], v[82:85]
	v_mfma_f32_16x16x32_bf16 v[86:89], v[14:17], v[54:57], v[86:89]
	v_mfma_f32_16x16x32_bf16 v[90:93], v[6:9], v[62:65], v[90:93]
	v_mfma_f32_16x16x32_bf16 v[94:97], v[14:17], v[62:65], v[94:97]
	v_mfma_f32_16x16x32_bf16 v[98:101], v[18:21], v[34:37], 0
	v_mfma_f32_16x16x32_bf16 v[34:37], v[26:29], v[34:37], 0
	v_mfma_f32_16x16x32_bf16 v[102:105], v[30:33], v[38:41], v[34:37]
	v_mfma_f32_16x16x32_bf16 v[34:37], v[18:21], v[42:45], 0
	v_mfma_f32_16x16x32_bf16 v[106:109], v[22:25], v[46:49], v[34:37]
	v_mfma_f32_16x16x32_bf16 v[34:37], v[26:29], v[42:45], 0
	v_mfma_f32_16x16x32_bf16 v[42:45], v[30:33], v[46:49], v[34:37]
	v_mfma_f32_16x16x32_bf16 v[34:37], v[18:21], v[50:53], 0
	v_mfma_f32_16x16x32_bf16 v[46:49], v[22:25], v[54:57], v[34:37]
	v_mfma_f32_16x16x32_bf16 v[34:37], v[26:29], v[50:53], 0
	v_mfma_f32_16x16x32_bf16 v[50:53], v[30:33], v[54:57], v[34:37]
	v_mfma_f32_16x16x32_bf16 v[34:37], v[18:21], v[58:61], 0
	v_mfma_f32_16x16x32_bf16 v[110:113], v[22:25], v[62:65], v[34:37]
	v_mfma_f32_16x16x32_bf16 v[34:37], v[26:29], v[58:61], 0
	v_mfma_f32_16x16x32_bf16 v[98:101], v[22:25], v[38:41], v[98:101]
	v_mfma_f32_16x16x32_bf16 v[58:61], v[30:33], v[62:65], v[34:37]
	s_barrier
	s_setprio 0
	s_add_i32 vcc_lo, s91, s33
	v_lshl_add_u64 v[246:247], s[76:77], 0, v[132:133]
	s_add_i32 s84, vcc_lo, 0x2000
	v_lshl_add_u64 v[144:145], v[246:247], 0, s[62:63]
	s_mov_b32 m0, vcc_lo
	v_lshl_add_u64 v[248:249], s[76:77], 0, v[130:131]
	s_add_u32 s14, s76, 0x100100
	ds_read_b128 v[34:37], v143 offset:16384
	ds_read_b128 v[38:41], v143 offset:17408
	ds_read_b128 v[54:57], v143 offset:18432
	ds_read_b128 v[62:65], v143 offset:19456
	ds_read_b128 v[114:117], v143 offset:20480
	ds_read_b128 v[118:121], v143 offset:21504
	ds_read_b128 v[122:125], v143 offset:22528
	ds_read_b128 v[126:129], v143 offset:23552
	global_load_lds_dwordx4 v[144:145], off
	v_lshl_add_u64 v[144:145], v[248:249], 0, s[62:63]
	s_mov_b32 m0, s84
	s_addc_u32 s15, s77, 0
	s_add_i32 s85, s92, s33
	global_load_lds_dwordx4 v[144:145], off
	v_lshl_add_u64 v[144:145], s[14:15], 0, v[132:133]
	s_mov_b32 m0, s85
	s_add_i32 s46, s85, 0x2000
	global_load_lds_dwordx4 v[144:145], off
	v_lshl_add_u64 v[144:145], s[14:15], 0, v[130:131]
	s_mov_b32 m0, s46
	v_lshl_add_u64 v[250:251], s[78:79], 0, v[132:133]
	global_load_lds_dwordx4 v[144:145], off
	v_lshl_add_u64 v[144:145], v[250:251], 0, s[62:63]
	s_mov_b32 m0, s59
	v_lshl_add_u64 v[252:253], s[78:79], 0, v[130:131]
	global_load_lds_dwordx4 v[144:145], off
	v_lshl_add_u64 v[144:145], v[252:253], 0, s[62:63]
	s_mov_b32 m0, s82
	s_nop 0
	global_load_lds_dwordx4 v[144:145], off
	s_waitcnt vmcnt(8)
	s_waitcnt lgkmcnt(0)
	s_setprio 1
	s_barrier
	v_mfma_f32_16x16x32_bf16 v[144:147], v[2:5], v[34:37], 0
	v_mfma_f32_16x16x32_bf16 v[154:157], v[2:5], v[54:57], 0
	v_mfma_f32_16x16x32_bf16 v[162:165], v[2:5], v[114:117], 0
	v_mfma_f32_16x16x32_bf16 v[2:5], v[2:5], v[122:125], 0
	v_mfma_f32_16x16x32_bf16 v[150:153], v[10:13], v[34:37], 0
	v_mfma_f32_16x16x32_bf16 v[158:161], v[10:13], v[54:57], 0
	v_mfma_f32_16x16x32_bf16 v[166:169], v[10:13], v[114:117], 0
	v_mfma_f32_16x16x32_bf16 v[170:173], v[6:9], v[126:129], v[2:5]
	v_mfma_f32_16x16x32_bf16 v[2:5], v[10:13], v[122:125], 0
	v_mfma_f32_16x16x32_bf16 v[146:149], v[6:9], v[38:41], v[144:147]
	v_mfma_f32_16x16x32_bf16 v[150:153], v[14:17], v[38:41], v[150:153]
	v_mfma_f32_16x16x32_bf16 v[154:157], v[6:9], v[62:65], v[154:157]
	v_mfma_f32_16x16x32_bf16 v[158:161], v[14:17], v[62:65], v[158:161]
	v_mfma_f32_16x16x32_bf16 v[162:165], v[6:9], v[118:121], v[162:165]
	v_mfma_f32_16x16x32_bf16 v[166:169], v[14:17], v[118:121], v[166:169]
	v_mfma_f32_16x16x32_bf16 v[174:177], v[14:17], v[126:129], v[2:5]
	v_mfma_f32_16x16x32_bf16 v[2:5], v[18:21], v[34:37], 0
	v_mfma_f32_16x16x32_bf16 v[178:181], v[22:25], v[38:41], v[2:5]
	v_mfma_f32_16x16x32_bf16 v[2:5], v[26:29], v[34:37], 0
	v_mfma_f32_16x16x32_bf16 v[182:185], v[30:33], v[38:41], v[2:5]
	v_mfma_f32_16x16x32_bf16 v[2:5], v[18:21], v[54:57], 0
	v_mfma_f32_16x16x32_bf16 v[186:189], v[22:25], v[62:65], v[2:5]
	v_mfma_f32_16x16x32_bf16 v[2:5], v[26:29], v[54:57], 0
	v_mfma_f32_16x16x32_bf16 v[190:193], v[30:33], v[62:65], v[2:5]
	v_mfma_f32_16x16x32_bf16 v[2:5], v[18:21], v[114:117], 0
	v_mfma_f32_16x16x32_bf16 v[194:197], v[22:25], v[118:121], v[2:5]
	v_mfma_f32_16x16x32_bf16 v[2:5], v[26:29], v[114:117], 0
	v_mfma_f32_16x16x32_bf16 v[198:201], v[30:33], v[118:121], v[2:5]
	v_mfma_f32_16x16x32_bf16 v[2:5], v[18:21], v[122:125], 0
	v_mfma_f32_16x16x32_bf16 v[202:205], v[22:25], v[126:129], v[2:5]
	v_mfma_f32_16x16x32_bf16 v[2:5], v[26:29], v[122:125], 0
	v_mfma_f32_16x16x32_bf16 v[206:209], v[30:33], v[126:129], v[2:5]
	s_barrier
	s_setprio 0
	s_add_i32 s47, 0, 0x18000
	s_add_i32 s56, 0, 0x1c000
	v_add_u32_e32 v134, s47, v140
	v_add_u32_e32 v144, s56, v140
	ds_read_b128 v[114:117], v134
	ds_read_b128 v[118:121], v134 offset:1024
	ds_read_b128 v[122:125], v134 offset:2048
	ds_read_b128 v[126:129], v134 offset:3072
	ds_read_b128 v[210:213], v144
	ds_read_b128 v[214:217], v144 offset:1024
	ds_read_b128 v[218:221], v144 offset:2048
	ds_read_b128 v[222:225], v144 offset:3072
	s_add_u32 s14, s78, 0x100100
	s_addc_u32 s15, s79, 0
	s_mov_b32 m0, s83
	v_lshl_add_u64 v[2:3], s[14:15], 0, v[132:133]
	ds_read_b128 v[26:29], v143 offset:32768
	ds_read_b128 v[30:33], v143 offset:33792
	ds_read_b128 v[62:65], v143 offset:34816
	ds_read_b128 v[226:229], v143 offset:35840
	ds_read_b128 v[230:233], v143 offset:36864
	ds_read_b128 v[234:237], v143 offset:37888
	ds_read_b128 v[238:241], v143 offset:38912
	ds_read_b128 v[242:245], v143 offset:39936
	global_load_lds_dwordx4 v[2:3], off
	v_lshl_add_u64 v[2:3], s[14:15], 0, v[130:131]
	s_mov_b32 m0, s86
	s_nop 0
	global_load_lds_dwordx4 v[2:3], off
	s_waitcnt vmcnt(8)
	s_waitcnt lgkmcnt(0)
	s_setprio 1
	s_barrier
	v_mfma_f32_16x16x32_bf16 v[2:5], v[114:117], v[26:29], v[66:69]
	v_mfma_f32_16x16x32_bf16 v[34:37], v[118:121], v[30:33], v[2:5]
	v_mfma_f32_16x16x32_bf16 v[2:5], v[122:125], v[26:29], v[70:73]
	v_mfma_f32_16x16x32_bf16 v[38:41], v[126:129], v[30:33], v[2:5]
	v_mfma_f32_16x16x32_bf16 v[2:5], v[114:117], v[62:65], v[74:77]
	v_mfma_f32_16x16x32_bf16 v[18:21], v[118:121], v[226:229], v[2:5]
	v_mfma_f32_16x16x32_bf16 v[2:5], v[122:125], v[62:65], v[78:81]
	v_mfma_f32_16x16x32_bf16 v[22:25], v[126:129], v[226:229], v[2:5]
	v_mfma_f32_16x16x32_bf16 v[2:5], v[114:117], v[230:233], v[82:85]
	v_mfma_f32_16x16x32_bf16 v[10:13], v[118:121], v[234:237], v[2:5]
	v_mfma_f32_16x16x32_bf16 v[2:5], v[122:125], v[230:233], v[86:89]
	v_mfma_f32_16x16x32_bf16 v[14:17], v[126:129], v[234:237], v[2:5]
	v_mfma_f32_16x16x32_bf16 v[2:5], v[114:117], v[238:241], v[90:93]
	v_mfma_f32_16x16x32_bf16 v[6:9], v[122:125], v[238:241], v[94:97]
	v_mfma_f32_16x16x32_bf16 v[2:5], v[118:121], v[242:245], v[2:5]
	v_mfma_f32_16x16x32_bf16 v[6:9], v[126:129], v[242:245], v[6:9]
	v_mfma_f32_16x16x32_bf16 v[54:57], v[210:213], v[26:29], v[98:101]
	v_mfma_f32_16x16x32_bf16 v[26:29], v[218:221], v[26:29], v[102:105]
	v_mfma_f32_16x16x32_bf16 v[70:73], v[222:225], v[30:33], v[26:29]
	v_mfma_f32_16x16x32_bf16 v[26:29], v[210:213], v[62:65], v[106:109]
	v_mfma_f32_16x16x32_bf16 v[66:69], v[214:217], v[30:33], v[54:57]
	v_mfma_f32_16x16x32_bf16 v[54:57], v[214:217], v[226:229], v[26:29]
	v_mfma_f32_16x16x32_bf16 v[26:29], v[218:221], v[62:65], v[42:45]
	v_mfma_f32_16x16x32_bf16 v[62:65], v[222:225], v[226:229], v[26:29]
	v_mfma_f32_16x16x32_bf16 v[26:29], v[210:213], v[230:233], v[46:49]
	v_mfma_f32_16x16x32_bf16 v[42:45], v[214:217], v[234:237], v[26:29]
	v_mfma_f32_16x16x32_bf16 v[26:29], v[218:221], v[230:233], v[50:53]
	v_mfma_f32_16x16x32_bf16 v[46:49], v[222:225], v[234:237], v[26:29]
	v_mfma_f32_16x16x32_bf16 v[26:29], v[210:213], v[238:241], v[110:113]
	v_mfma_f32_16x16x32_bf16 v[30:33], v[218:221], v[238:241], v[58:61]
	v_mfma_f32_16x16x32_bf16 v[26:29], v[214:217], v[242:245], v[26:29]
	v_mfma_f32_16x16x32_bf16 v[30:33], v[222:225], v[242:245], v[30:33]
	s_barrier
	s_setprio 0
	s_add_i32 s47, s47, s33
	s_add_i32 vcc_hi, s47, 0x2000
	v_lshl_add_u64 v[50:51], v[246:247], 0, s[64:65]
	s_mov_b32 m0, s47
	s_add_u32 s14, s76, 0x100180
	ds_read_b128 v[82:85], v143 offset:49152
	ds_read_b128 v[86:89], v143 offset:50176
	ds_read_b128 v[98:101], v143 offset:51200
	ds_read_b128 v[106:109], v143 offset:52224
	ds_read_b128 v[226:229], v143 offset:53248
	ds_read_b128 v[230:233], v143 offset:54272
	ds_read_b128 v[234:237], v143 offset:55296
	ds_read_b128 v[238:241], v143 offset:56320
	global_load_lds_dwordx4 v[50:51], off
	v_lshl_add_u64 v[50:51], v[248:249], 0, s[64:65]
	s_mov_b32 m0, vcc_hi
	s_addc_u32 s15, s77, 0
	s_add_i32 s56, s56, s33
	global_load_lds_dwordx4 v[50:51], off
	v_lshl_add_u64 v[50:51], s[14:15], 0, v[132:133]
	s_mov_b32 m0, s56
	s_add_i32 s57, s56, 0x2000
	global_load_lds_dwordx4 v[50:51], off
	v_lshl_add_u64 v[50:51], s[14:15], 0, v[130:131]
	s_mov_b32 m0, s57
	s_nop 0
	global_load_lds_dwordx4 v[50:51], off
	v_lshl_add_u64 v[50:51], v[250:251], 0, s[64:65]
	s_mov_b32 m0, s88
	s_nop 0
	global_load_lds_dwordx4 v[50:51], off
	v_lshl_add_u64 v[50:51], v[252:253], 0, s[64:65]
	s_mov_b32 m0, s89
	s_nop 0
	global_load_lds_dwordx4 v[50:51], off
	s_waitcnt vmcnt(8)
	s_waitcnt lgkmcnt(0)
	s_setprio 1
	s_barrier
	v_mfma_f32_16x16x32_bf16 v[50:53], v[114:117], v[82:85], v[146:149]
	v_mfma_f32_16x16x32_bf16 v[102:105], v[118:121], v[86:89], v[50:53]
	v_mfma_f32_16x16x32_bf16 v[50:53], v[122:125], v[82:85], v[150:153]
	v_mfma_f32_16x16x32_bf16 v[110:113], v[126:129], v[86:89], v[50:53]
	v_mfma_f32_16x16x32_bf16 v[50:53], v[114:117], v[98:101], v[154:157]
	v_mfma_f32_16x16x32_bf16 v[90:93], v[118:121], v[106:109], v[50:53]
	v_mfma_f32_16x16x32_bf16 v[50:53], v[122:125], v[98:101], v[158:161]
	v_mfma_f32_16x16x32_bf16 v[94:97], v[126:129], v[106:109], v[50:53]
	v_mfma_f32_16x16x32_bf16 v[50:53], v[114:117], v[226:229], v[162:165]
	v_mfma_f32_16x16x32_bf16 v[74:77], v[118:121], v[230:233], v[50:53]
	v_mfma_f32_16x16x32_bf16 v[50:53], v[122:125], v[226:229], v[166:169]
	v_mfma_f32_16x16x32_bf16 v[78:81], v[126:129], v[230:233], v[50:53]
	v_mfma_f32_16x16x32_bf16 v[50:53], v[114:117], v[234:237], v[170:173]
	v_mfma_f32_16x16x32_bf16 v[58:61], v[122:125], v[234:237], v[174:177]
	v_mfma_f32_16x16x32_bf16 v[50:53], v[118:121], v[238:241], v[50:53]
	v_mfma_f32_16x16x32_bf16 v[58:61], v[126:129], v[238:241], v[58:61]
	v_mfma_f32_16x16x32_bf16 v[114:117], v[210:213], v[82:85], v[178:181]
	v_mfma_f32_16x16x32_bf16 v[82:85], v[218:221], v[82:85], v[182:185]
	v_mfma_f32_16x16x32_bf16 v[126:129], v[222:225], v[86:89], v[82:85]
	v_mfma_f32_16x16x32_bf16 v[82:85], v[210:213], v[98:101], v[186:189]
	v_mfma_f32_16x16x32_bf16 v[122:125], v[214:217], v[86:89], v[114:117]
	v_mfma_f32_16x16x32_bf16 v[114:117], v[214:217], v[106:109], v[82:85]
	v_mfma_f32_16x16x32_bf16 v[82:85], v[218:221], v[98:101], v[190:193]
	v_mfma_f32_16x16x32_bf16 v[118:121], v[222:225], v[106:109], v[82:85]
	v_mfma_f32_16x16x32_bf16 v[82:85], v[210:213], v[226:229], v[194:197]
	v_mfma_f32_16x16x32_bf16 v[98:101], v[214:217], v[230:233], v[82:85]
	v_mfma_f32_16x16x32_bf16 v[82:85], v[218:221], v[226:229], v[198:201]
	v_mfma_f32_16x16x32_bf16 v[106:109], v[222:225], v[230:233], v[82:85]
	v_mfma_f32_16x16x32_bf16 v[82:85], v[210:213], v[234:237], v[202:205]
	v_mfma_f32_16x16x32_bf16 v[86:89], v[218:221], v[234:237], v[206:209]
	v_mfma_f32_16x16x32_bf16 v[82:85], v[214:217], v[238:241], v[82:85]
	v_mfma_f32_16x16x32_bf16 v[86:89], v[222:225], v[238:241], v[86:89]
	s_barrier
	s_setprio 0
	s_add_u32 s78, s78, 0x100180
	s_addc_u32 s79, s79, 0
	s_add_u32 s14, s76, 0x200
	s_addc_u32 s15, s77, 0
	s_mov_b32 s16, 0

.Lrb2_skip_14078:
	s_mov_b32 m0, s96
	ds_read_b128 v[178:181], v143
	ds_read_b128 v[182:185], v143 offset:1024
	ds_read_b128 v[186:189], v143 offset:2048
	ds_read_b128 v[190:193], v143 offset:3072
	ds_read_b128 v[194:197], v143 offset:4096
	ds_read_b128 v[198:201], v143 offset:5120
	ds_read_b128 v[202:205], v143 offset:6144
	ds_read_b128 v[206:209], v143 offset:7168
	global_load_lds_dwordx4 v136, s[78:79]
	s_mov_b32 m0, s97
	s_nop 0
	global_load_lds_dwordx4 v138, s[78:79]
	s_waitcnt vmcnt(8)
	s_waitcnt lgkmcnt(0)
	s_setprio 1
	s_barrier
	v_mfma_f32_16x16x32_bf16 v[34:37], v[146:149], v[178:181], v[34:37]
	v_mfma_f32_16x16x32_bf16 v[38:41], v[154:157], v[178:181], v[38:41]
	v_mfma_f32_16x16x32_bf16 v[18:21], v[146:149], v[186:189], v[18:21]
	v_mfma_f32_16x16x32_bf16 v[22:25], v[154:157], v[186:189], v[22:25]
	v_mfma_f32_16x16x32_bf16 v[10:13], v[146:149], v[194:197], v[10:13]
	v_mfma_f32_16x16x32_bf16 v[14:17], v[154:157], v[194:197], v[14:17]
	v_mfma_f32_16x16x32_bf16 v[2:5], v[146:149], v[202:205], v[2:5]
	v_mfma_f32_16x16x32_bf16 v[6:9], v[154:157], v[202:205], v[6:9]
	v_mfma_f32_16x16x32_bf16 v[34:37], v[150:153], v[182:185], v[34:37]
	v_mfma_f32_16x16x32_bf16 v[38:41], v[158:161], v[182:185], v[38:41]
	v_mfma_f32_16x16x32_bf16 v[18:21], v[150:153], v[190:193], v[18:21]
	v_mfma_f32_16x16x32_bf16 v[22:25], v[158:161], v[190:193], v[22:25]
	v_mfma_f32_16x16x32_bf16 v[10:13], v[150:153], v[198:201], v[10:13]
	v_mfma_f32_16x16x32_bf16 v[14:17], v[158:161], v[198:201], v[14:17]
	v_mfma_f32_16x16x32_bf16 v[2:5], v[150:153], v[206:209], v[2:5]
	v_mfma_f32_16x16x32_bf16 v[6:9], v[158:161], v[206:209], v[6:9]
	v_mfma_f32_16x16x32_bf16 v[66:69], v[162:165], v[178:181], v[66:69]
	v_mfma_f32_16x16x32_bf16 v[70:73], v[170:173], v[178:181], v[70:73]
	v_mfma_f32_16x16x32_bf16 v[54:57], v[162:165], v[186:189], v[54:57]
	v_mfma_f32_16x16x32_bf16 v[62:65], v[170:173], v[186:189], v[62:65]
	v_mfma_f32_16x16x32_bf16 v[42:45], v[162:165], v[194:197], v[42:45]
	v_mfma_f32_16x16x32_bf16 v[46:49], v[170:173], v[194:197], v[46:49]
	v_mfma_f32_16x16x32_bf16 v[26:29], v[162:165], v[202:205], v[26:29]
	v_mfma_f32_16x16x32_bf16 v[30:33], v[170:173], v[202:205], v[30:33]
	v_mfma_f32_16x16x32_bf16 v[66:69], v[166:169], v[182:185], v[66:69]
	v_mfma_f32_16x16x32_bf16 v[70:73], v[174:177], v[182:185], v[70:73]
	v_mfma_f32_16x16x32_bf16 v[54:57], v[166:169], v[190:193], v[54:57]
	v_mfma_f32_16x16x32_bf16 v[62:65], v[174:177], v[190:193], v[62:65]
	v_mfma_f32_16x16x32_bf16 v[42:45], v[166:169], v[198:201], v[42:45]
	v_mfma_f32_16x16x32_bf16 v[46:49], v[174:177], v[198:201], v[46:49]
	v_mfma_f32_16x16x32_bf16 v[26:29], v[166:169], v[206:209], v[26:29]
	v_mfma_f32_16x16x32_bf16 v[30:33], v[174:177], v[206:209], v[30:33]
	s_barrier
	s_setprio 0
	s_mov_b32 m0, vcc_lo
	s_mov_b64 s[98:99], s[76:77]
	s_add_u32 s20, s76, 0x100000
	ds_read_b128 v[178:181], v143 offset:16384
	ds_read_b128 v[182:185], v143 offset:17408
	ds_read_b128 v[186:189], v143 offset:18432
	ds_read_b128 v[190:193], v143 offset:19456
	ds_read_b128 v[194:197], v143 offset:20480
	ds_read_b128 v[198:201], v143 offset:21504
	ds_read_b128 v[202:205], v143 offset:22528
	ds_read_b128 v[206:209], v143 offset:23552
	global_load_lds_dwordx4 v132, s[76:77]
	s_mov_b32 m0, s84
	s_addc_u32 s21, s77, 0
	global_load_lds_dwordx4 v130, s[76:77]
	s_mov_b32 m0, s85
	s_mov_b64 s[100:101], s[80:81]
	global_load_lds_dwordx4 v132, s[20:21]
	s_mov_b32 m0, s46
	s_nop 0
	global_load_lds_dwordx4 v130, s[20:21]
	s_waitcnt vmcnt(6)
	s_waitcnt lgkmcnt(0)
	s_setprio 1
	s_barrier
	v_mfma_f32_16x16x32_bf16 v[102:105], v[146:149], v[178:181], v[102:105]
	v_mfma_f32_16x16x32_bf16 v[110:113], v[154:157], v[178:181], v[110:113]
	v_mfma_f32_16x16x32_bf16 v[90:93], v[146:149], v[186:189], v[90:93]
	v_mfma_f32_16x16x32_bf16 v[94:97], v[154:157], v[186:189], v[94:97]
	v_mfma_f32_16x16x32_bf16 v[74:77], v[146:149], v[194:197], v[74:77]
	v_mfma_f32_16x16x32_bf16 v[78:81], v[154:157], v[194:197], v[78:81]
	v_mfma_f32_16x16x32_bf16 v[50:53], v[146:149], v[202:205], v[50:53]
	v_mfma_f32_16x16x32_bf16 v[58:61], v[154:157], v[202:205], v[58:61]
	v_mfma_f32_16x16x32_bf16 v[102:105], v[150:153], v[182:185], v[102:105]
	v_mfma_f32_16x16x32_bf16 v[110:113], v[158:161], v[182:185], v[110:113]
	v_mfma_f32_16x16x32_bf16 v[90:93], v[150:153], v[190:193], v[90:93]
	v_mfma_f32_16x16x32_bf16 v[94:97], v[158:161], v[190:193], v[94:97]
	v_mfma_f32_16x16x32_bf16 v[74:77], v[150:153], v[198:201], v[74:77]
	v_mfma_f32_16x16x32_bf16 v[78:81], v[158:161], v[198:201], v[78:81]
	v_mfma_f32_16x16x32_bf16 v[50:53], v[150:153], v[206:209], v[50:53]
	v_mfma_f32_16x16x32_bf16 v[58:61], v[158:161], v[206:209], v[58:61]
	v_mfma_f32_16x16x32_bf16 v[122:125], v[162:165], v[178:181], v[122:125]
	v_mfma_f32_16x16x32_bf16 v[126:129], v[170:173], v[178:181], v[126:129]
	v_mfma_f32_16x16x32_bf16 v[114:117], v[162:165], v[186:189], v[114:117]
	v_mfma_f32_16x16x32_bf16 v[118:121], v[170:173], v[186:189], v[118:121]
	v_mfma_f32_16x16x32_bf16 v[98:101], v[162:165], v[194:197], v[98:101]
	v_mfma_f32_16x16x32_bf16 v[106:109], v[170:173], v[194:197], v[106:109]
	v_mfma_f32_16x16x32_bf16 v[82:85], v[162:165], v[202:205], v[82:85]
	v_mfma_f32_16x16x32_bf16 v[86:89], v[170:173], v[202:205], v[86:89]
	v_mfma_f32_16x16x32_bf16 v[122:125], v[166:169], v[182:185], v[122:125]
	v_mfma_f32_16x16x32_bf16 v[126:129], v[174:177], v[182:185], v[126:129]
	v_mfma_f32_16x16x32_bf16 v[114:117], v[166:169], v[190:193], v[114:117]
	v_mfma_f32_16x16x32_bf16 v[118:121], v[174:177], v[190:193], v[118:121]
	v_mfma_f32_16x16x32_bf16 v[98:101], v[166:169], v[198:201], v[98:101]
	v_mfma_f32_16x16x32_bf16 v[106:109], v[174:177], v[198:201], v[106:109]
	v_mfma_f32_16x16x32_bf16 v[82:85], v[166:169], v[206:209], v[82:85]
	v_mfma_f32_16x16x32_bf16 v[86:89], v[174:177], v[206:209], v[86:89]
	s_barrier
;     ...
;         for (int t = 2; t < nt; t += 2) PG8_KITER(t);
	s_setprio 0
	ds_read_b128 v[146:149], v134
	ds_read_b128 v[150:153], v134 offset:1024
	ds_read_b128 v[154:157], v134 offset:2048
	ds_read_b128 v[158:161], v134 offset:3072
	ds_read_b128 v[162:165], v144
	ds_read_b128 v[166:169], v144 offset:1024
	ds_read_b128 v[170:173], v144 offset:2048
	ds_read_b128 v[174:177], v144 offset:3072
	s_add_u32 s20, s80, 0x100000
	s_addc_u32 s21, s81, 0
	s_mov_b32 m0, s59
	s_nop 0
	global_load_lds_dwordx4 v132, s[100:101]
	s_mov_b32 m0, s82
	s_nop 0
	global_load_lds_dwordx4 v130, s[100:101]
	s_mov_b32 m0, s83
	ds_read_b128 v[178:181], v143 offset:32768
	ds_read_b128 v[182:185], v143 offset:33792
	ds_read_b128 v[186:189], v143 offset:34816
	ds_read_b128 v[190:193], v143 offset:35840
	ds_read_b128 v[194:197], v143 offset:36864
	ds_read_b128 v[198:201], v143 offset:37888
	ds_read_b128 v[202:205], v143 offset:38912
	ds_read_b128 v[206:209], v143 offset:39936
	global_load_lds_dwordx4 v132, s[20:21]
	s_mov_b32 m0, s86
	s_nop 0
	global_load_lds_dwordx4 v130, s[20:21]
	s_waitcnt vmcnt(8)
	s_waitcnt lgkmcnt(0)
	s_setprio 1
	s_barrier
	v_mfma_f32_16x16x32_bf16 v[34:37], v[146:149], v[178:181], v[34:37]
	v_mfma_f32_16x16x32_bf16 v[38:41], v[154:157], v[178:181], v[38:41]
	v_mfma_f32_16x16x32_bf16 v[18:21], v[146:149], v[186:189], v[18:21]
	v_mfma_f32_16x16x32_bf16 v[22:25], v[154:157], v[186:189], v[22:25]
	v_mfma_f32_16x16x32_bf16 v[10:13], v[146:149], v[194:197], v[10:13]
	v_mfma_f32_16x16x32_bf16 v[14:17], v[154:157], v[194:197], v[14:17]
	v_mfma_f32_16x16x32_bf16 v[2:5], v[146:149], v[202:205], v[2:5]
	v_mfma_f32_16x16x32_bf16 v[6:9], v[154:157], v[202:205], v[6:9]
	v_mfma_f32_16x16x32_bf16 v[34:37], v[150:153], v[182:185], v[34:37]
	v_mfma_f32_16x16x32_bf16 v[38:41], v[158:161], v[182:185], v[38:41]
	v_mfma_f32_16x16x32_bf16 v[18:21], v[150:153], v[190:193], v[18:21]
	v_mfma_f32_16x16x32_bf16 v[22:25], v[158:161], v[190:193], v[22:25]
	v_mfma_f32_16x16x32_bf16 v[10:13], v[150:153], v[198:201], v[10:13]
	v_mfma_f32_16x16x32_bf16 v[14:17], v[158:161], v[198:201], v[14:17]
	v_mfma_f32_16x16x32_bf16 v[2:5], v[150:153], v[206:209], v[2:5]
	v_mfma_f32_16x16x32_bf16 v[6:9], v[158:161], v[206:209], v[6:9]
	v_mfma_f32_16x16x32_bf16 v[66:69], v[162:165], v[178:181], v[66:69]
	v_mfma_f32_16x16x32_bf16 v[70:73], v[170:173], v[178:181], v[70:73]
	v_mfma_f32_16x16x32_bf16 v[54:57], v[162:165], v[186:189], v[54:57]
	v_mfma_f32_16x16x32_bf16 v[62:65], v[170:173], v[186:189], v[62:65]
	v_mfma_f32_16x16x32_bf16 v[42:45], v[162:165], v[194:197], v[42:45]
	v_mfma_f32_16x16x32_bf16 v[46:49], v[170:173], v[194:197], v[46:49]
	v_mfma_f32_16x16x32_bf16 v[26:29], v[162:165], v[202:205], v[26:29]
	v_mfma_f32_16x16x32_bf16 v[30:33], v[170:173], v[202:205], v[30:33]
	v_mfma_f32_16x16x32_bf16 v[66:69], v[166:169], v[182:185], v[66:69]
	v_mfma_f32_16x16x32_bf16 v[70:73], v[174:177], v[182:185], v[70:73]
	v_mfma_f32_16x16x32_bf16 v[54:57], v[166:169], v[190:193], v[54:57]
	v_mfma_f32_16x16x32_bf16 v[62:65], v[174:177], v[190:193], v[62:65]
	v_mfma_f32_16x16x32_bf16 v[42:45], v[166:169], v[198:201], v[42:45]
	v_mfma_f32_16x16x32_bf16 v[46:49], v[174:177], v[198:201], v[46:49]
	v_mfma_f32_16x16x32_bf16 v[26:29], v[166:169], v[206:209], v[26:29]
	v_mfma_f32_16x16x32_bf16 v[30:33], v[174:177], v[206:209], v[30:33]
	s_barrier
	s_setprio 0
	s_mov_b32 m0, s47
	s_add_u32 s98, s98, 0x80
	s_addc_u32 s99, s99, 0
	s_add_u32 s100, s100, 0x80
	s_addc_u32 s101, s101, 0
	s_add_u32 s20, s76, 0x100080
	ds_read_b128 v[178:181], v143 offset:49152
	ds_read_b128 v[182:185], v143 offset:50176
	ds_read_b128 v[186:189], v143 offset:51200
	ds_read_b128 v[190:193], v143 offset:52224
	ds_read_b128 v[194:197], v143 offset:53248
	ds_read_b128 v[198:201], v143 offset:54272
	ds_read_b128 v[202:205], v143 offset:55296
	ds_read_b128 v[206:209], v143 offset:56320
	global_load_lds_dwordx4 v132, s[98:99]
	s_mov_b32 m0, vcc_hi
	s_addc_u32 s21, s77, 0
	global_load_lds_dwordx4 v130, s[98:99]
	s_mov_b32 m0, s56
	s_nop 0
	global_load_lds_dwordx4 v132, s[20:21]
	s_mov_b32 m0, s57
	s_nop 0
	global_load_lds_dwordx4 v130, s[20:21]
	s_waitcnt vmcnt(6)
	s_waitcnt lgkmcnt(0)
	s_setprio 1
	s_barrier
	v_mfma_f32_16x16x32_bf16 v[102:105], v[146:149], v[178:181], v[102:105]
	v_mfma_f32_16x16x32_bf16 v[110:113], v[154:157], v[178:181], v[110:113]
	v_mfma_f32_16x16x32_bf16 v[90:93], v[146:149], v[186:189], v[90:93]
	v_mfma_f32_16x16x32_bf16 v[94:97], v[154:157], v[186:189], v[94:97]
	v_mfma_f32_16x16x32_bf16 v[74:77], v[146:149], v[194:197], v[74:77]
	v_mfma_f32_16x16x32_bf16 v[78:81], v[154:157], v[194:197], v[78:81]
	v_mfma_f32_16x16x32_bf16 v[50:53], v[146:149], v[202:205], v[50:53]
	v_mfma_f32_16x16x32_bf16 v[58:61], v[154:157], v[202:205], v[58:61]
	v_mfma_f32_16x16x32_bf16 v[102:105], v[150:153], v[182:185], v[102:105]
	v_mfma_f32_16x16x32_bf16 v[110:113], v[158:161], v[182:185], v[110:113]
	v_mfma_f32_16x16x32_bf16 v[90:93], v[150:153], v[190:193], v[90:93]
	v_mfma_f32_16x16x32_bf16 v[94:97], v[158:161], v[190:193], v[94:97]
	v_mfma_f32_16x16x32_bf16 v[74:77], v[150:153], v[198:201], v[74:77]
	v_mfma_f32_16x16x32_bf16 v[78:81], v[158:161], v[198:201], v[78:81]
	v_mfma_f32_16x16x32_bf16 v[50:53], v[150:153], v[206:209], v[50:53]
	v_mfma_f32_16x16x32_bf16 v[58:61], v[158:161], v[206:209], v[58:61]
	v_mfma_f32_16x16x32_bf16 v[122:125], v[162:165], v[178:181], v[122:125]
	v_mfma_f32_16x16x32_bf16 v[126:129], v[170:173], v[178:181], v[126:129]
	v_mfma_f32_16x16x32_bf16 v[114:117], v[162:165], v[186:189], v[114:117]
	v_mfma_f32_16x16x32_bf16 v[118:121], v[170:173], v[186:189], v[118:121]
	v_mfma_f32_16x16x32_bf16 v[98:101], v[162:165], v[194:197], v[98:101]
	v_mfma_f32_16x16x32_bf16 v[106:109], v[170:173], v[194:197], v[106:109]
	v_mfma_f32_16x16x32_bf16 v[82:85], v[162:165], v[202:205], v[82:85]
	v_mfma_f32_16x16x32_bf16 v[86:89], v[170:173], v[202:205], v[86:89]
	v_mfma_f32_16x16x32_bf16 v[122:125], v[166:169], v[182:185], v[122:125]
	v_mfma_f32_16x16x32_bf16 v[126:129], v[174:177], v[182:185], v[126:129]
	v_mfma_f32_16x16x32_bf16 v[114:117], v[166:169], v[190:193], v[114:117]
	v_mfma_f32_16x16x32_bf16 v[118:121], v[174:177], v[190:193], v[118:121]
	v_mfma_f32_16x16x32_bf16 v[98:101], v[166:169], v[198:201], v[98:101]
	v_mfma_f32_16x16x32_bf16 v[106:109], v[174:177], v[198:201], v[106:109]
	v_mfma_f32_16x16x32_bf16 v[82:85], v[166:169], v[206:209], v[82:85]
	v_mfma_f32_16x16x32_bf16 v[86:89], v[174:177], v[206:209], v[86:89]
	s_barrier
	s_setprio 0
	s_add_i32 s16, s16, 2
	s_add_u32 s78, s78, 0x100
	s_addc_u32 s79, s79, 0
	s_add_u32 s14, s14, 0x100
	s_addc_u32 s15, s15, 0
	s_cmp_gt_u32 s16, 61
	s_cbranch_scc0 .LBB0_435
	s_mov_b32 m0, s88
	s_nop 0
	global_load_lds_dwordx4 v132, s[100:101]
	s_mov_b32 m0, s89
	s_nop 0
	global_load_lds_dwordx4 v130, s[100:101]
	s_and_b64 vcc, exec, s[30:31]
	s_cbranch_vccz .LBB0_438
	s_barrier

;     __host__ __device__ bool next(int i, Unit& u) const { if (!StaticOrder::next(i >> 1, u)) return false; u.seg = i & 1; return true; }
;     ...
;         const bool has_next = S.next(ui + 1, nxt);
;         const char* nA = has_next ? PG8_APTR(nxt) : cA; const char* nB = has_next ? PG8_BPTR(nxt) : cB;
;         const char* pfc = PG8_PFPTR(cA, cB); const char* pfn = PG8_PFPTR(nA, nB);
;         PG8_KITER(0);
.LBB0_643:
	s_ashr_i32 s23, s22, 31
	ds_read_b128 v[2:5], v1
	ds_read_b128 v[6:9], v1 offset:1024
	ds_read_b128 v[10:13], v1 offset:2048
	ds_read_b128 v[14:17], v1 offset:3072
	ds_read_b128 v[18:21], v150
	ds_read_b128 v[22:25], v150 offset:1024
	ds_read_b128 v[26:29], v150 offset:2048
	ds_read_b128 v[30:33], v150 offset:3072
	s_lshl_b64 s[14:15], s[22:23], 19
	s_add_u32 s28, s24, s14
	s_addc_u32 s29, s25, s15
	s_and_b64 s[14:15], s[4:5], exec
	s_cselect_b32 s23, s29, s63
	s_cselect_b32 s83, s28, s62
	s_and_b32 s0, s81, 0x7fffffff
	s_lshl_b64 s[14:15], s[0:1], 19
	s_add_u32 s30, s10, s14
	s_addc_u32 s31, s11, s15
	s_and_b64 s[14:15], s[4:5], exec
	s_cselect_b32 s0, s31, s55
	s_cselect_b32 s86, s30, s54
	s_add_u32 s14, s62, 0x40080
	s_addc_u32 s15, s63, 0
	s_mov_b32 m0, s69
	v_lshl_add_u64 v[66:67], s[14:15], 0, v[136:137]
	ds_read_b128 v[34:37], v151
	ds_read_b128 v[38:41], v151 offset:1024
	ds_read_b128 v[42:45], v151 offset:2048
	ds_read_b128 v[46:49], v151 offset:3072
	ds_read_b128 v[50:53], v151 offset:4096
	ds_read_b128 v[54:57], v151 offset:5120
	ds_read_b128 v[58:61], v151 offset:6144
	ds_read_b128 v[62:65], v151 offset:7168
	global_load_lds_dwordx4 v[66:67], off
	v_lshl_add_u64 v[66:67], s[14:15], 0, v[132:133]
	s_mov_b32 m0, s70
	s_nop 0
	global_load_lds_dwordx4 v[66:67], off
	s_waitcnt vmcnt(8)
	s_waitcnt lgkmcnt(0)
	s_setprio 1
	s_barrier
	v_mfma_f32_16x16x32_bf16 v[90:93], v[2:5], v[58:61], 0
	v_mfma_f32_16x16x32_bf16 v[66:69], v[2:5], v[34:37], 0
	v_mfma_f32_16x16x32_bf16 v[70:73], v[10:13], v[34:37], 0
	v_mfma_f32_16x16x32_bf16 v[74:77], v[2:5], v[42:45], 0
	v_mfma_f32_16x16x32_bf16 v[78:81], v[10:13], v[42:45], 0
	v_mfma_f32_16x16x32_bf16 v[82:85], v[2:5], v[50:53], 0
	v_mfma_f32_16x16x32_bf16 v[86:89], v[10:13], v[50:53], 0
	v_mfma_f32_16x16x32_bf16 v[94:97], v[6:9], v[62:65], v[90:93]
	v_mfma_f32_16x16x32_bf16 v[90:93], v[10:13], v[58:61], 0
	v_mfma_f32_16x16x32_bf16 v[66:69], v[6:9], v[38:41], v[66:69]
	v_mfma_f32_16x16x32_bf16 v[70:73], v[14:17], v[38:41], v[70:73]
	v_mfma_f32_16x16x32_bf16 v[74:77], v[6:9], v[46:49], v[74:77]
	v_mfma_f32_16x16x32_bf16 v[78:81], v[14:17], v[46:49], v[78:81]
	v_mfma_f32_16x16x32_bf16 v[82:85], v[6:9], v[54:57], v[82:85]
	v_mfma_f32_16x16x32_bf16 v[86:89], v[14:17], v[54:57], v[86:89]
	v_mfma_f32_16x16x32_bf16 v[102:105], v[14:17], v[62:65], v[90:93]
	v_mfma_f32_16x16x32_bf16 v[90:93], v[18:21], v[34:37], 0
	v_mfma_f32_16x16x32_bf16 v[34:37], v[26:29], v[34:37], 0
	v_mfma_f32_16x16x32_bf16 v[110:113], v[22:25], v[38:41], v[90:93]
	v_mfma_f32_16x16x32_bf16 v[34:37], v[30:33], v[38:41], v[34:37]
	v_mfma_f32_16x16x32_bf16 v[38:41], v[18:21], v[42:45], 0
	v_mfma_f32_16x16x32_bf16 v[42:45], v[26:29], v[42:45], 0
	v_mfma_f32_16x16x32_bf16 v[38:41], v[22:25], v[46:49], v[38:41]
	v_mfma_f32_16x16x32_bf16 v[42:45], v[30:33], v[46:49], v[42:45]
	v_mfma_f32_16x16x32_bf16 v[46:49], v[18:21], v[50:53], 0
	v_mfma_f32_16x16x32_bf16 v[50:53], v[26:29], v[50:53], 0
	v_mfma_f32_16x16x32_bf16 v[46:49], v[22:25], v[54:57], v[46:49]
	v_mfma_f32_16x16x32_bf16 v[54:57], v[30:33], v[54:57], v[50:53]
	v_mfma_f32_16x16x32_bf16 v[50:53], v[18:21], v[58:61], 0
	v_mfma_f32_16x16x32_bf16 v[146:149], v[22:25], v[62:65], v[50:53]
	v_mfma_f32_16x16x32_bf16 v[50:53], v[26:29], v[58:61], 0
	v_mfma_f32_16x16x32_bf16 v[154:157], v[30:33], v[62:65], v[50:53]
	s_barrier
	s_setprio 0
	v_lshl_add_u64 v[250:251], s[54:55], 0, v[134:135]
	s_mov_b32 m0, s72
	v_lshl_add_u64 v[122:123], v[250:251], 0, s[18:19]
	v_lshl_add_u64 v[252:253], s[54:55], 0, v[130:131]
	s_add_u32 s14, s54, 0x40100
	ds_read_b128 v[50:53], v151 offset:16384
	ds_read_b128 v[58:61], v151 offset:17408
	ds_read_b128 v[62:65], v151 offset:18432
	ds_read_b128 v[90:93], v151 offset:19456
	ds_read_b128 v[98:101], v151 offset:20480
	ds_read_b128 v[106:109], v151 offset:21504
	ds_read_b128 v[114:117], v151 offset:22528
	ds_read_b128 v[118:121], v151 offset:23552
	global_load_lds_dwordx4 v[122:123], off
	v_lshl_add_u64 v[122:123], v[252:253], 0, s[18:19]
	s_mov_b32 m0, s73
	s_addc_u32 s15, s55, 0
	global_load_lds_dwordx4 v[122:123], off
	v_lshl_add_u64 v[122:123], s[14:15], 0, v[134:135]
	s_mov_b32 m0, s74
	v_lshl_add_u64 v[142:143], s[62:63], 0, v[136:137]
	global_load_lds_dwordx4 v[122:123], off
	v_lshl_add_u64 v[122:123], s[14:15], 0, v[130:131]
	s_mov_b32 m0, s75
	v_lshl_add_u64 v[144:145], s[62:63], 0, v[132:133]
	global_load_lds_dwordx4 v[122:123], off
	v_lshl_add_u64 v[122:123], v[142:143], 0, s[18:19]
	s_mov_b32 m0, s33
	s_nop 0
	global_load_lds_dwordx4 v[122:123], off
	v_lshl_add_u64 v[122:123], v[144:145], 0, s[18:19]
	s_mov_b32 m0, s41
	s_nop 0
	global_load_lds_dwordx4 v[122:123], off
	s_waitcnt vmcnt(8)
	s_waitcnt lgkmcnt(0)
	s_setprio 1
	s_barrier
	v_mfma_f32_16x16x32_bf16 v[122:125], v[2:5], v[50:53], 0
	v_mfma_f32_16x16x32_bf16 v[158:161], v[6:9], v[58:61], v[122:125]
	v_mfma_f32_16x16x32_bf16 v[122:125], v[10:13], v[50:53], 0
	v_mfma_f32_16x16x32_bf16 v[162:165], v[14:17], v[58:61], v[122:125]
	v_mfma_f32_16x16x32_bf16 v[122:125], v[2:5], v[62:65], 0
	v_mfma_f32_16x16x32_bf16 v[166:169], v[6:9], v[90:93], v[122:125]
	v_mfma_f32_16x16x32_bf16 v[122:125], v[10:13], v[62:65], 0
	v_mfma_f32_16x16x32_bf16 v[170:173], v[14:17], v[90:93], v[122:125]
	v_mfma_f32_16x16x32_bf16 v[122:125], v[2:5], v[98:101], 0
	v_mfma_f32_16x16x32_bf16 v[2:5], v[2:5], v[114:117], 0
	v_mfma_f32_16x16x32_bf16 v[174:177], v[6:9], v[106:109], v[122:125]
	v_mfma_f32_16x16x32_bf16 v[2:5], v[6:9], v[118:121], v[2:5]
	v_mfma_f32_16x16x32_bf16 v[6:9], v[10:13], v[114:117], 0
	v_mfma_f32_16x16x32_bf16 v[122:125], v[10:13], v[98:101], 0
	v_mfma_f32_16x16x32_bf16 v[6:9], v[14:17], v[118:121], v[6:9]
	v_mfma_f32_16x16x32_bf16 v[178:181], v[14:17], v[106:109], v[122:125]
	v_mfma_f32_16x16x32_bf16 v[10:13], v[18:21], v[50:53], 0
	v_mfma_f32_16x16x32_bf16 v[14:17], v[22:25], v[58:61], v[10:13]
	v_mfma_f32_16x16x32_bf16 v[10:13], v[26:29], v[50:53], 0
	v_mfma_f32_16x16x32_bf16 v[182:185], v[30:33], v[58:61], v[10:13]
	v_mfma_f32_16x16x32_bf16 v[10:13], v[18:21], v[62:65], 0
	v_mfma_f32_16x16x32_bf16 v[186:189], v[22:25], v[90:93], v[10:13]
	v_mfma_f32_16x16x32_bf16 v[10:13], v[26:29], v[62:65], 0
	v_mfma_f32_16x16x32_bf16 v[190:193], v[30:33], v[90:93], v[10:13]
	v_mfma_f32_16x16x32_bf16 v[10:13], v[18:21], v[98:101], 0
	v_mfma_f32_16x16x32_bf16 v[194:197], v[22:25], v[106:109], v[10:13]
	v_mfma_f32_16x16x32_bf16 v[10:13], v[26:29], v[98:101], 0
	v_mfma_f32_16x16x32_bf16 v[198:201], v[30:33], v[106:109], v[10:13]
	v_mfma_f32_16x16x32_bf16 v[10:13], v[18:21], v[114:117], 0
	v_mfma_f32_16x16x32_bf16 v[202:205], v[22:25], v[118:121], v[10:13]
	v_mfma_f32_16x16x32_bf16 v[10:13], v[26:29], v[114:117], 0
	v_mfma_f32_16x16x32_bf16 v[206:209], v[30:33], v[118:121], v[10:13]
	s_barrier
	s_setprio 0
	s_nop 4
	ds_read_b128 v[10:13], v152
	ds_read_b128 v[22:25], v152 offset:1024
	ds_read_b128 v[30:33], v152 offset:2048
	ds_read_b128 v[210:213], v152 offset:3072
	ds_read_b128 v[214:217], v153
	ds_read_b128 v[218:221], v153 offset:1024
	ds_read_b128 v[222:225], v153 offset:2048
	ds_read_b128 v[226:229], v153 offset:3072
	s_add_u32 s14, s62, 0x40100
	s_addc_u32 s15, s63, 0
	s_mov_b32 m0, s58
	v_lshl_add_u64 v[50:51], s[14:15], 0, v[136:137]
	ds_read_b128 v[18:21], v151 offset:32768
	ds_read_b128 v[26:29], v151 offset:33792
	ds_read_b128 v[62:65], v151 offset:34816
	ds_read_b128 v[230:233], v151 offset:35840
	ds_read_b128 v[234:237], v151 offset:36864
	ds_read_b128 v[238:241], v151 offset:37888
	ds_read_b128 v[242:245], v151 offset:38912
	ds_read_b128 v[246:249], v151 offset:39936
	global_load_lds_dwordx4 v[50:51], off
	v_lshl_add_u64 v[50:51], s[14:15], 0, v[132:133]
	s_mov_b32 m0, s59
	s_nop 0
	global_load_lds_dwordx4 v[50:51], off
	s_waitcnt vmcnt(8)
	s_waitcnt lgkmcnt(0)
	s_setprio 1
	s_barrier
	v_mfma_f32_16x16x32_bf16 v[50:53], v[10:13], v[18:21], v[66:69]
	v_mfma_f32_16x16x32_bf16 v[122:125], v[22:25], v[26:29], v[50:53]
	v_mfma_f32_16x16x32_bf16 v[50:53], v[30:33], v[18:21], v[70:73]
	v_mfma_f32_16x16x32_bf16 v[114:117], v[210:213], v[26:29], v[50:53]
	v_mfma_f32_16x16x32_bf16 v[50:53], v[10:13], v[62:65], v[74:77]
	v_mfma_f32_16x16x32_bf16 v[106:109], v[22:25], v[230:233], v[50:53]
	v_mfma_f32_16x16x32_bf16 v[50:53], v[30:33], v[62:65], v[78:81]
	v_mfma_f32_16x16x32_bf16 v[98:101], v[210:213], v[230:233], v[50:53]
	v_mfma_f32_16x16x32_bf16 v[50:53], v[10:13], v[234:237], v[82:85]
	v_mfma_f32_16x16x32_bf16 v[90:93], v[22:25], v[238:241], v[50:53]
	v_mfma_f32_16x16x32_bf16 v[50:53], v[30:33], v[234:237], v[86:89]
	v_mfma_f32_16x16x32_bf16 v[82:85], v[210:213], v[238:241], v[50:53]
	v_mfma_f32_16x16x32_bf16 v[50:53], v[10:13], v[242:245], v[94:97]
	v_mfma_f32_16x16x32_bf16 v[58:61], v[22:25], v[246:249], v[50:53]
	v_mfma_f32_16x16x32_bf16 v[50:53], v[30:33], v[242:245], v[102:105]
	v_mfma_f32_16x16x32_bf16 v[50:53], v[210:213], v[246:249], v[50:53]
	v_mfma_f32_16x16x32_bf16 v[66:69], v[214:217], v[18:21], v[110:113]
	v_mfma_f32_16x16x32_bf16 v[18:21], v[222:225], v[18:21], v[34:37]
	v_mfma_f32_16x16x32_bf16 v[118:121], v[226:229], v[26:29], v[18:21]
	v_mfma_f32_16x16x32_bf16 v[18:21], v[214:217], v[62:65], v[38:41]
	v_mfma_f32_16x16x32_bf16 v[110:113], v[218:221], v[230:233], v[18:21]
	v_mfma_f32_16x16x32_bf16 v[18:21], v[222:225], v[62:65], v[42:45]
	v_mfma_f32_16x16x32_bf16 v[102:105], v[226:229], v[230:233], v[18:21]
	v_mfma_f32_16x16x32_bf16 v[18:21], v[214:217], v[234:237], v[46:49]
	v_mfma_f32_16x16x32_bf16 v[94:97], v[218:221], v[238:241], v[18:21]
	v_mfma_f32_16x16x32_bf16 v[18:21], v[222:225], v[234:237], v[54:57]
	v_mfma_f32_16x16x32_bf16 v[86:89], v[226:229], v[238:241], v[18:21]
	v_mfma_f32_16x16x32_bf16 v[18:21], v[214:217], v[242:245], v[146:149]
	v_mfma_f32_16x16x32_bf16 v[62:65], v[218:221], v[246:249], v[18:21]
	v_mfma_f32_16x16x32_bf16 v[18:21], v[222:225], v[242:245], v[154:157]
	v_mfma_f32_16x16x32_bf16 v[126:129], v[218:221], v[26:29], v[66:69]
	v_mfma_f32_16x16x32_bf16 v[54:57], v[226:229], v[246:249], v[18:21]
	s_barrier
	s_setprio 0
	s_mov_b32 m0, s76
	s_nop 2
	v_lshl_add_u64 v[18:19], v[250:251], 0, s[20:21]
	s_add_u32 s14, s54, 0x40180
	ds_read_b128 v[38:41], v151 offset:49152
	ds_read_b128 v[46:49], v151 offset:50176
	ds_read_b128 v[146:149], v151 offset:51200
	ds_read_b128 v[154:157], v151 offset:52224
	ds_read_b128 v[230:233], v151 offset:53248
	ds_read_b128 v[234:237], v151 offset:54272
	ds_read_b128 v[238:241], v151 offset:55296
	ds_read_b128 v[242:245], v151 offset:56320
	global_load_lds_dwordx4 v[18:19], off
	v_lshl_add_u64 v[18:19], v[252:253], 0, s[20:21]
	s_mov_b32 m0, s77
	s_addc_u32 s15, s55, 0
	global_load_lds_dwordx4 v[18:19], off
	v_lshl_add_u64 v[18:19], s[14:15], 0, v[134:135]
	s_mov_b32 m0, s78
	s_nop 0
	global_load_lds_dwordx4 v[18:19], off
	v_lshl_add_u64 v[18:19], s[14:15], 0, v[130:131]
	s_mov_b32 m0, s79
	s_nop 0
	global_load_lds_dwordx4 v[18:19], off
	v_lshl_add_u64 v[18:19], v[142:143], 0, s[20:21]
	s_mov_b32 m0, s66
	s_nop 0
	global_load_lds_dwordx4 v[18:19], off
	v_lshl_add_u64 v[18:19], v[144:145], 0, s[20:21]
	s_mov_b32 m0, s67
	s_nop 0
	global_load_lds_dwordx4 v[18:19], off
	s_waitcnt vmcnt(8)
	s_waitcnt lgkmcnt(0)
	s_setprio 1
	s_barrier
	v_mfma_f32_16x16x32_bf16 v[18:21], v[10:13], v[38:41], v[158:161]
	v_mfma_f32_16x16x32_bf16 v[74:77], v[22:25], v[46:49], v[18:21]
	v_mfma_f32_16x16x32_bf16 v[18:21], v[30:33], v[38:41], v[162:165]
	v_mfma_f32_16x16x32_bf16 v[66:69], v[210:213], v[46:49], v[18:21]
	v_mfma_f32_16x16x32_bf16 v[18:21], v[10:13], v[146:149], v[166:169]
	v_mfma_f32_16x16x32_bf16 v[42:45], v[22:25], v[154:157], v[18:21]
	v_mfma_f32_16x16x32_bf16 v[18:21], v[30:33], v[146:149], v[170:173]
	v_mfma_f32_16x16x32_bf16 v[34:37], v[210:213], v[154:157], v[18:21]
	v_mfma_f32_16x16x32_bf16 v[18:21], v[10:13], v[230:233], v[174:177]
	v_mfma_f32_16x16x32_bf16 v[2:5], v[10:13], v[238:241], v[2:5]
	v_mfma_f32_16x16x32_bf16 v[26:29], v[22:25], v[234:237], v[18:21]
	v_mfma_f32_16x16x32_bf16 v[18:21], v[30:33], v[230:233], v[178:181]
	v_mfma_f32_16x16x32_bf16 v[10:13], v[22:25], v[242:245], v[2:5]
	v_mfma_f32_16x16x32_bf16 v[2:5], v[30:33], v[238:241], v[6:9]
	v_mfma_f32_16x16x32_bf16 v[18:21], v[210:213], v[234:237], v[18:21]
	v_mfma_f32_16x16x32_bf16 v[2:5], v[210:213], v[242:245], v[2:5]
	v_mfma_f32_16x16x32_bf16 v[6:9], v[214:217], v[38:41], v[14:17]
	v_mfma_f32_16x16x32_bf16 v[78:81], v[218:221], v[46:49], v[6:9]
	v_mfma_f32_16x16x32_bf16 v[6:9], v[222:225], v[38:41], v[182:185]
	v_mfma_f32_16x16x32_bf16 v[70:73], v[226:229], v[46:49], v[6:9]
	v_mfma_f32_16x16x32_bf16 v[6:9], v[214:217], v[146:149], v[186:189]
	v_mfma_f32_16x16x32_bf16 v[46:49], v[218:221], v[154:157], v[6:9]
	v_mfma_f32_16x16x32_bf16 v[6:9], v[222:225], v[146:149], v[190:193]
	v_mfma_f32_16x16x32_bf16 v[38:41], v[226:229], v[154:157], v[6:9]
	v_mfma_f32_16x16x32_bf16 v[6:9], v[214:217], v[230:233], v[194:197]
	v_mfma_f32_16x16x32_bf16 v[30:33], v[218:221], v[234:237], v[6:9]
	v_mfma_f32_16x16x32_bf16 v[6:9], v[222:225], v[230:233], v[198:201]
	v_mfma_f32_16x16x32_bf16 v[22:25], v[226:229], v[234:237], v[6:9]
	v_mfma_f32_16x16x32_bf16 v[6:9], v[214:217], v[238:241], v[202:205]
	v_mfma_f32_16x16x32_bf16 v[14:17], v[218:221], v[242:245], v[6:9]
	v_mfma_f32_16x16x32_bf16 v[6:9], v[222:225], v[238:241], v[206:209]
	v_mfma_f32_16x16x32_bf16 v[6:9], v[226:229], v[242:245], v[6:9]
	s_barrier
	s_setprio 0
	s_add_u32 s62, s62, 0x40180
	s_addc_u32 s63, s63, 0
	s_add_u32 s14, s54, 0x200
	s_addc_u32 s15, s55, 0
	s_mov_b32 s26, 0

.Lrb2_skip_18937:
	s_mov_b32 m0, s69
	ds_read_b128 v[182:185], v151
	ds_read_b128 v[186:189], v151 offset:1024
	ds_read_b128 v[190:193], v151 offset:2048
	ds_read_b128 v[194:197], v151 offset:3072
	ds_read_b128 v[198:201], v151 offset:4096
	ds_read_b128 v[202:205], v151 offset:5120
	ds_read_b128 v[206:209], v151 offset:6144
	ds_read_b128 v[210:213], v151 offset:7168
	global_load_lds_dwordx4 v138, s[62:63]
	s_mov_b32 m0, s70
	s_nop 0
	global_load_lds_dwordx4 v140, s[62:63]
	s_waitcnt vmcnt(8)
	s_waitcnt lgkmcnt(0)
	s_setprio 1
	s_barrier
	v_mfma_f32_16x16x32_bf16 v[122:125], v[146:149], v[182:185], v[122:125]
	v_mfma_f32_16x16x32_bf16 v[114:117], v[158:161], v[182:185], v[114:117]
	v_mfma_f32_16x16x32_bf16 v[106:109], v[146:149], v[190:193], v[106:109]
	v_mfma_f32_16x16x32_bf16 v[98:101], v[158:161], v[190:193], v[98:101]
	v_mfma_f32_16x16x32_bf16 v[90:93], v[146:149], v[198:201], v[90:93]
	v_mfma_f32_16x16x32_bf16 v[82:85], v[158:161], v[198:201], v[82:85]
	v_mfma_f32_16x16x32_bf16 v[58:61], v[146:149], v[206:209], v[58:61]
	v_mfma_f32_16x16x32_bf16 v[50:53], v[158:161], v[206:209], v[50:53]
	v_mfma_f32_16x16x32_bf16 v[122:125], v[154:157], v[186:189], v[122:125]
	v_mfma_f32_16x16x32_bf16 v[114:117], v[162:165], v[186:189], v[114:117]
	v_mfma_f32_16x16x32_bf16 v[106:109], v[154:157], v[194:197], v[106:109]
	v_mfma_f32_16x16x32_bf16 v[98:101], v[162:165], v[194:197], v[98:101]
	v_mfma_f32_16x16x32_bf16 v[90:93], v[154:157], v[202:205], v[90:93]
	v_mfma_f32_16x16x32_bf16 v[82:85], v[162:165], v[202:205], v[82:85]
	v_mfma_f32_16x16x32_bf16 v[58:61], v[154:157], v[210:213], v[58:61]
	v_mfma_f32_16x16x32_bf16 v[50:53], v[162:165], v[210:213], v[50:53]
	v_mfma_f32_16x16x32_bf16 v[126:129], v[166:169], v[182:185], v[126:129]
	v_mfma_f32_16x16x32_bf16 v[118:121], v[174:177], v[182:185], v[118:121]
	v_mfma_f32_16x16x32_bf16 v[110:113], v[166:169], v[190:193], v[110:113]
	v_mfma_f32_16x16x32_bf16 v[102:105], v[174:177], v[190:193], v[102:105]
	v_mfma_f32_16x16x32_bf16 v[94:97], v[166:169], v[198:201], v[94:97]
	v_mfma_f32_16x16x32_bf16 v[86:89], v[174:177], v[198:201], v[86:89]
	v_mfma_f32_16x16x32_bf16 v[62:65], v[166:169], v[206:209], v[62:65]
	v_mfma_f32_16x16x32_bf16 v[54:57], v[174:177], v[206:209], v[54:57]
	v_mfma_f32_16x16x32_bf16 v[126:129], v[170:173], v[186:189], v[126:129]
	v_mfma_f32_16x16x32_bf16 v[118:121], v[178:181], v[186:189], v[118:121]
	v_mfma_f32_16x16x32_bf16 v[110:113], v[170:173], v[194:197], v[110:113]
	v_mfma_f32_16x16x32_bf16 v[102:105], v[178:181], v[194:197], v[102:105]
	v_mfma_f32_16x16x32_bf16 v[94:97], v[170:173], v[202:205], v[94:97]
	v_mfma_f32_16x16x32_bf16 v[86:89], v[178:181], v[202:205], v[86:89]
	v_mfma_f32_16x16x32_bf16 v[62:65], v[170:173], v[210:213], v[62:65]
	v_mfma_f32_16x16x32_bf16 v[54:57], v[178:181], v[210:213], v[54:57]
	s_barrier
	s_setprio 0
	s_mov_b32 m0, s72
	s_mov_b64 s[98:99], s[54:55]
	s_add_u32 s46, s54, 0x40000
	ds_read_b128 v[182:185], v151 offset:16384
	ds_read_b128 v[186:189], v151 offset:17408
	ds_read_b128 v[190:193], v151 offset:18432
	ds_read_b128 v[194:197], v151 offset:19456
	ds_read_b128 v[198:201], v151 offset:20480
	ds_read_b128 v[202:205], v151 offset:21504
	ds_read_b128 v[206:209], v151 offset:22528
	ds_read_b128 v[210:213], v151 offset:23552
	global_load_lds_dwordx4 v134, s[54:55]
	s_mov_b32 m0, s73
	s_addc_u32 s47, s55, 0
	global_load_lds_dwordx4 v130, s[54:55]
	s_mov_b32 m0, s74
	s_mov_b64 s[100:101], s[64:65]
	global_load_lds_dwordx4 v134, s[46:47]
	s_mov_b32 m0, s75
	s_nop 0
	global_load_lds_dwordx4 v130, s[46:47]
	s_waitcnt vmcnt(6)
	s_waitcnt lgkmcnt(0)
	s_setprio 1
	s_barrier
	v_mfma_f32_16x16x32_bf16 v[74:77], v[146:149], v[182:185], v[74:77]
	v_mfma_f32_16x16x32_bf16 v[66:69], v[158:161], v[182:185], v[66:69]
	v_mfma_f32_16x16x32_bf16 v[42:45], v[146:149], v[190:193], v[42:45]
	v_mfma_f32_16x16x32_bf16 v[34:37], v[158:161], v[190:193], v[34:37]
	v_mfma_f32_16x16x32_bf16 v[26:29], v[146:149], v[198:201], v[26:29]
	v_mfma_f32_16x16x32_bf16 v[18:21], v[158:161], v[198:201], v[18:21]
	v_mfma_f32_16x16x32_bf16 v[10:13], v[146:149], v[206:209], v[10:13]
	v_mfma_f32_16x16x32_bf16 v[2:5], v[158:161], v[206:209], v[2:5]
	v_mfma_f32_16x16x32_bf16 v[74:77], v[154:157], v[186:189], v[74:77]
	v_mfma_f32_16x16x32_bf16 v[66:69], v[162:165], v[186:189], v[66:69]
	v_mfma_f32_16x16x32_bf16 v[42:45], v[154:157], v[194:197], v[42:45]
	v_mfma_f32_16x16x32_bf16 v[34:37], v[162:165], v[194:197], v[34:37]
	v_mfma_f32_16x16x32_bf16 v[26:29], v[154:157], v[202:205], v[26:29]
	v_mfma_f32_16x16x32_bf16 v[18:21], v[162:165], v[202:205], v[18:21]
	v_mfma_f32_16x16x32_bf16 v[10:13], v[154:157], v[210:213], v[10:13]
	v_mfma_f32_16x16x32_bf16 v[2:5], v[162:165], v[210:213], v[2:5]
	v_mfma_f32_16x16x32_bf16 v[78:81], v[166:169], v[182:185], v[78:81]
	v_mfma_f32_16x16x32_bf16 v[70:73], v[174:177], v[182:185], v[70:73]
	v_mfma_f32_16x16x32_bf16 v[46:49], v[166:169], v[190:193], v[46:49]
	v_mfma_f32_16x16x32_bf16 v[38:41], v[174:177], v[190:193], v[38:41]
	v_mfma_f32_16x16x32_bf16 v[30:33], v[166:169], v[198:201], v[30:33]
	v_mfma_f32_16x16x32_bf16 v[22:25], v[174:177], v[198:201], v[22:25]
	v_mfma_f32_16x16x32_bf16 v[14:17], v[166:169], v[206:209], v[14:17]
	v_mfma_f32_16x16x32_bf16 v[6:9], v[174:177], v[206:209], v[6:9]
	v_mfma_f32_16x16x32_bf16 v[78:81], v[170:173], v[186:189], v[78:81]
	v_mfma_f32_16x16x32_bf16 v[70:73], v[178:181], v[186:189], v[70:73]
	v_mfma_f32_16x16x32_bf16 v[46:49], v[170:173], v[194:197], v[46:49]
	v_mfma_f32_16x16x32_bf16 v[38:41], v[178:181], v[194:197], v[38:41]
	v_mfma_f32_16x16x32_bf16 v[30:33], v[170:173], v[202:205], v[30:33]
	v_mfma_f32_16x16x32_bf16 v[22:25], v[178:181], v[202:205], v[22:25]
	v_mfma_f32_16x16x32_bf16 v[14:17], v[170:173], v[210:213], v[14:17]
	v_mfma_f32_16x16x32_bf16 v[6:9], v[178:181], v[210:213], v[6:9]
	s_barrier
;     ...
;         for (int t = 2; t < nt; t += 2) PG8_KITER(t);
	s_setprio 0
	ds_read_b128 v[146:149], v152
	ds_read_b128 v[154:157], v152 offset:1024
	ds_read_b128 v[158:161], v152 offset:2048
	ds_read_b128 v[162:165], v152 offset:3072
	ds_read_b128 v[166:169], v153
	ds_read_b128 v[170:173], v153 offset:1024
	ds_read_b128 v[174:177], v153 offset:2048
	ds_read_b128 v[178:181], v153 offset:3072
	s_add_u32 s46, s64, 0x40000
	s_addc_u32 s47, s65, 0
	s_mov_b32 m0, s33
	s_nop 0
	global_load_lds_dwordx4 v136, s[100:101]
	s_mov_b32 m0, s41
	s_nop 0
	global_load_lds_dwordx4 v132, s[100:101]
	s_mov_b32 m0, s58
	ds_read_b128 v[182:185], v151 offset:32768
	ds_read_b128 v[186:189], v151 offset:33792
	ds_read_b128 v[190:193], v151 offset:34816
	ds_read_b128 v[194:197], v151 offset:35840
	ds_read_b128 v[198:201], v151 offset:36864
	ds_read_b128 v[202:205], v151 offset:37888
	ds_read_b128 v[206:209], v151 offset:38912
	ds_read_b128 v[210:213], v151 offset:39936
	global_load_lds_dwordx4 v136, s[46:47]
	s_mov_b32 m0, s59
	s_nop 0
	global_load_lds_dwordx4 v132, s[46:47]
	s_waitcnt vmcnt(8)
	s_waitcnt lgkmcnt(0)
	s_setprio 1
	s_barrier
	v_mfma_f32_16x16x32_bf16 v[122:125], v[146:149], v[182:185], v[122:125]
	v_mfma_f32_16x16x32_bf16 v[114:117], v[158:161], v[182:185], v[114:117]
	v_mfma_f32_16x16x32_bf16 v[106:109], v[146:149], v[190:193], v[106:109]
	v_mfma_f32_16x16x32_bf16 v[98:101], v[158:161], v[190:193], v[98:101]
	v_mfma_f32_16x16x32_bf16 v[90:93], v[146:149], v[198:201], v[90:93]
	v_mfma_f32_16x16x32_bf16 v[82:85], v[158:161], v[198:201], v[82:85]
	v_mfma_f32_16x16x32_bf16 v[58:61], v[146:149], v[206:209], v[58:61]
	v_mfma_f32_16x16x32_bf16 v[50:53], v[158:161], v[206:209], v[50:53]
	v_mfma_f32_16x16x32_bf16 v[122:125], v[154:157], v[186:189], v[122:125]
	v_mfma_f32_16x16x32_bf16 v[114:117], v[162:165], v[186:189], v[114:117]
	v_mfma_f32_16x16x32_bf16 v[106:109], v[154:157], v[194:197], v[106:109]
	v_mfma_f32_16x16x32_bf16 v[98:101], v[162:165], v[194:197], v[98:101]
	v_mfma_f32_16x16x32_bf16 v[90:93], v[154:157], v[202:205], v[90:93]
	v_mfma_f32_16x16x32_bf16 v[82:85], v[162:165], v[202:205], v[82:85]
	v_mfma_f32_16x16x32_bf16 v[58:61], v[154:157], v[210:213], v[58:61]
	v_mfma_f32_16x16x32_bf16 v[50:53], v[162:165], v[210:213], v[50:53]
	v_mfma_f32_16x16x32_bf16 v[126:129], v[166:169], v[182:185], v[126:129]
	v_mfma_f32_16x16x32_bf16 v[118:121], v[174:177], v[182:185], v[118:121]
	v_mfma_f32_16x16x32_bf16 v[110:113], v[166:169], v[190:193], v[110:113]
	v_mfma_f32_16x16x32_bf16 v[102:105], v[174:177], v[190:193], v[102:105]
	v_mfma_f32_16x16x32_bf16 v[94:97], v[166:169], v[198:201], v[94:97]
	v_mfma_f32_16x16x32_bf16 v[86:89], v[174:177], v[198:201], v[86:89]
	v_mfma_f32_16x16x32_bf16 v[62:65], v[166:169], v[206:209], v[62:65]
	v_mfma_f32_16x16x32_bf16 v[54:57], v[174:177], v[206:209], v[54:57]
	v_mfma_f32_16x16x32_bf16 v[126:129], v[170:173], v[186:189], v[126:129]
	v_mfma_f32_16x16x32_bf16 v[118:121], v[178:181], v[186:189], v[118:121]
	v_mfma_f32_16x16x32_bf16 v[110:113], v[170:173], v[194:197], v[110:113]
	v_mfma_f32_16x16x32_bf16 v[102:105], v[178:181], v[194:197], v[102:105]
	v_mfma_f32_16x16x32_bf16 v[94:97], v[170:173], v[202:205], v[94:97]
	v_mfma_f32_16x16x32_bf16 v[86:89], v[178:181], v[202:205], v[86:89]
	v_mfma_f32_16x16x32_bf16 v[62:65], v[170:173], v[210:213], v[62:65]
	v_mfma_f32_16x16x32_bf16 v[54:57], v[178:181], v[210:213], v[54:57]
	s_barrier
	s_setprio 0
	s_mov_b32 m0, s76
	s_add_u32 s98, s98, 0x80
	s_addc_u32 s99, s99, 0
	s_add_u32 s100, s100, 0x80
	s_addc_u32 s101, s101, 0
	s_add_u32 s46, s54, 0x40080
	ds_read_b128 v[182:185], v151 offset:49152
	ds_read_b128 v[186:189], v151 offset:50176
	ds_read_b128 v[190:193], v151 offset:51200
	ds_read_b128 v[194:197], v151 offset:52224
	ds_read_b128 v[198:201], v151 offset:53248
	ds_read_b128 v[202:205], v151 offset:54272
	ds_read_b128 v[206:209], v151 offset:55296
	ds_read_b128 v[210:213], v151 offset:56320
	global_load_lds_dwordx4 v134, s[98:99]
	s_mov_b32 m0, s77
	s_addc_u32 s47, s55, 0
	global_load_lds_dwordx4 v130, s[98:99]
	s_mov_b32 m0, s78
	s_nop 0
	global_load_lds_dwordx4 v134, s[46:47]
	s_mov_b32 m0, s79
	s_nop 0
	global_load_lds_dwordx4 v130, s[46:47]
	s_waitcnt vmcnt(6)
	s_waitcnt lgkmcnt(0)
	s_setprio 1
	s_barrier
	v_mfma_f32_16x16x32_bf16 v[74:77], v[146:149], v[182:185], v[74:77]
	v_mfma_f32_16x16x32_bf16 v[66:69], v[158:161], v[182:185], v[66:69]
	v_mfma_f32_16x16x32_bf16 v[42:45], v[146:149], v[190:193], v[42:45]
	v_mfma_f32_16x16x32_bf16 v[34:37], v[158:161], v[190:193], v[34:37]
	v_mfma_f32_16x16x32_bf16 v[26:29], v[146:149], v[198:201], v[26:29]
	v_mfma_f32_16x16x32_bf16 v[18:21], v[158:161], v[198:201], v[18:21]
	v_mfma_f32_16x16x32_bf16 v[10:13], v[146:149], v[206:209], v[10:13]
	v_mfma_f32_16x16x32_bf16 v[2:5], v[158:161], v[206:209], v[2:5]
	v_mfma_f32_16x16x32_bf16 v[74:77], v[154:157], v[186:189], v[74:77]
	v_mfma_f32_16x16x32_bf16 v[66:69], v[162:165], v[186:189], v[66:69]
	v_mfma_f32_16x16x32_bf16 v[42:45], v[154:157], v[194:197], v[42:45]
	v_mfma_f32_16x16x32_bf16 v[34:37], v[162:165], v[194:197], v[34:37]
	v_mfma_f32_16x16x32_bf16 v[26:29], v[154:157], v[202:205], v[26:29]
	v_mfma_f32_16x16x32_bf16 v[18:21], v[162:165], v[202:205], v[18:21]
	v_mfma_f32_16x16x32_bf16 v[10:13], v[154:157], v[210:213], v[10:13]
	v_mfma_f32_16x16x32_bf16 v[2:5], v[162:165], v[210:213], v[2:5]
	v_mfma_f32_16x16x32_bf16 v[78:81], v[166:169], v[182:185], v[78:81]
	v_mfma_f32_16x16x32_bf16 v[70:73], v[174:177], v[182:185], v[70:73]
	v_mfma_f32_16x16x32_bf16 v[46:49], v[166:169], v[190:193], v[46:49]
	v_mfma_f32_16x16x32_bf16 v[38:41], v[174:177], v[190:193], v[38:41]
	v_mfma_f32_16x16x32_bf16 v[30:33], v[166:169], v[198:201], v[30:33]
	v_mfma_f32_16x16x32_bf16 v[22:25], v[174:177], v[198:201], v[22:25]
	v_mfma_f32_16x16x32_bf16 v[14:17], v[166:169], v[206:209], v[14:17]
	v_mfma_f32_16x16x32_bf16 v[6:9], v[174:177], v[206:209], v[6:9]
	v_mfma_f32_16x16x32_bf16 v[78:81], v[170:173], v[186:189], v[78:81]
	v_mfma_f32_16x16x32_bf16 v[70:73], v[178:181], v[186:189], v[70:73]
	v_mfma_f32_16x16x32_bf16 v[46:49], v[170:173], v[194:197], v[46:49]
	v_mfma_f32_16x16x32_bf16 v[38:41], v[178:181], v[194:197], v[38:41]
	v_mfma_f32_16x16x32_bf16 v[30:33], v[170:173], v[202:205], v[30:33]
	v_mfma_f32_16x16x32_bf16 v[22:25], v[178:181], v[202:205], v[22:25]
	v_mfma_f32_16x16x32_bf16 v[14:17], v[170:173], v[210:213], v[14:17]
	v_mfma_f32_16x16x32_bf16 v[6:9], v[178:181], v[210:213], v[6:9]
	s_barrier
	s_setprio 0
	s_add_i32 s26, s26, 2
	s_add_u32 s62, s62, 0x100
	s_addc_u32 s63, s63, 0
	s_add_u32 s14, s14, 0x100
	s_addc_u32 s15, s15, 0
	s_cmp_gt_u32 s26, 13
	s_cbranch_scc0 .LBB0_644
	s_mov_b32 m0, s66
	s_nop 0
	global_load_lds_dwordx4 v136, s[100:101]
	s_mov_b32 m0, s67
	s_nop 0
	global_load_lds_dwordx4 v132, s[100:101]
	s_and_b64 vcc, exec, s[16:17]
	s_cbranch_vccz .LBB0_647
	s_barrier

;     __host__ __device__ bool next(int i, Unit& u) const { if (!StaticOrder::next(i >> 1, u)) return false; u.seg = i & 1; return true; }
;     ...
;         const bool has_next = S.next(ui + 1, nxt);
;         const char* nA = has_next ? PG8_APTR(nxt) : cA; const char* nB = has_next ? PG8_BPTR(nxt) : cB;
;         const char* pfc = PG8_PFPTR(cA, cB); const char* pfn = PG8_PFPTR(nA, nB);
;         PG8_KITER(0);
.LBB0_669:
	s_ashr_i32 s29, s28, 31
	ds_read_b128 v[2:5], v158
	ds_read_b128 v[6:9], v158 offset:1024
	ds_read_b128 v[10:13], v158 offset:2048
	ds_read_b128 v[14:17], v158 offset:3072
	ds_read_b128 v[18:21], v159
	ds_read_b128 v[22:25], v159 offset:1024
	ds_read_b128 v[26:29], v159 offset:2048
	ds_read_b128 v[30:33], v159 offset:3072
	s_lshl_b64 s[14:15], s[28:29], 18
	s_add_u32 s30, s10, s14
	s_addc_u32 s31, s11, s15
	s_and_b64 s[14:15], s[4:5], exec
	s_cselect_b32 s29, s31, s65
	s_cselect_b32 s79, s30, s64
	s_and_b32 s0, s77, 0x7fffffff
	s_lshl_b64 s[14:15], s[0:1], 18
	s_add_u32 s40, s12, s14
	s_addc_u32 s41, s13, s15
	s_and_b64 s[14:15], s[4:5], exec
	s_cselect_b32 s0, s41, s7
	s_cselect_b32 s80, s40, s6
	s_add_u32 s14, s64, 0x20080
	s_addc_u32 s15, s65, 0
	s_add_i32 s81, s58, 0xc000
	v_lshl_add_u64 v[66:67], s[14:15], 0, v[138:139]
	s_mov_b32 m0, s81
	s_add_i32 s82, s58, 0xe000
	ds_read_b128 v[34:37], v160
	ds_read_b128 v[38:41], v160 offset:1024
	ds_read_b128 v[42:45], v160 offset:2048
	ds_read_b128 v[46:49], v160 offset:3072
	ds_read_b128 v[50:53], v160 offset:4096
	ds_read_b128 v[54:57], v160 offset:5120
	ds_read_b128 v[58:61], v160 offset:6144
	ds_read_b128 v[62:65], v160 offset:7168
	global_load_lds_dwordx4 v[66:67], off
	v_lshl_add_u64 v[66:67], s[14:15], 0, v[142:143]
	s_mov_b32 m0, s82
	s_nop 0
	global_load_lds_dwordx4 v[66:67], off
	s_waitcnt vmcnt(8)
	s_waitcnt lgkmcnt(0)
	s_setprio 1
	s_barrier
	v_mfma_f32_16x16x32_bf16 v[90:93], v[2:5], v[58:61], 0
	v_mfma_f32_16x16x32_bf16 v[66:69], v[2:5], v[34:37], 0
	v_mfma_f32_16x16x32_bf16 v[70:73], v[10:13], v[34:37], 0
	v_mfma_f32_16x16x32_bf16 v[74:77], v[2:5], v[42:45], 0
	v_mfma_f32_16x16x32_bf16 v[78:81], v[10:13], v[42:45], 0
	v_mfma_f32_16x16x32_bf16 v[82:85], v[2:5], v[50:53], 0
	v_mfma_f32_16x16x32_bf16 v[86:89], v[10:13], v[50:53], 0
	v_mfma_f32_16x16x32_bf16 v[102:105], v[6:9], v[62:65], v[90:93]
	v_mfma_f32_16x16x32_bf16 v[90:93], v[10:13], v[58:61], 0
	v_mfma_f32_16x16x32_bf16 v[66:69], v[6:9], v[38:41], v[66:69]
	v_mfma_f32_16x16x32_bf16 v[70:73], v[14:17], v[38:41], v[70:73]
	v_mfma_f32_16x16x32_bf16 v[74:77], v[6:9], v[46:49], v[74:77]
	v_mfma_f32_16x16x32_bf16 v[78:81], v[14:17], v[46:49], v[78:81]
	v_mfma_f32_16x16x32_bf16 v[82:85], v[6:9], v[54:57], v[82:85]
	v_mfma_f32_16x16x32_bf16 v[86:89], v[14:17], v[54:57], v[86:89]
	v_mfma_f32_16x16x32_bf16 v[106:109], v[14:17], v[62:65], v[90:93]
	v_mfma_f32_16x16x32_bf16 v[90:93], v[18:21], v[34:37], 0
	v_mfma_f32_16x16x32_bf16 v[34:37], v[26:29], v[34:37], 0
	v_mfma_f32_16x16x32_bf16 v[122:125], v[22:25], v[38:41], v[90:93]
	v_mfma_f32_16x16x32_bf16 v[34:37], v[30:33], v[38:41], v[34:37]
	v_mfma_f32_16x16x32_bf16 v[38:41], v[18:21], v[42:45], 0
	v_mfma_f32_16x16x32_bf16 v[42:45], v[26:29], v[42:45], 0
	v_mfma_f32_16x16x32_bf16 v[38:41], v[22:25], v[46:49], v[38:41]
	v_mfma_f32_16x16x32_bf16 v[42:45], v[30:33], v[46:49], v[42:45]
	v_mfma_f32_16x16x32_bf16 v[46:49], v[18:21], v[50:53], 0
	v_mfma_f32_16x16x32_bf16 v[50:53], v[26:29], v[50:53], 0
	v_mfma_f32_16x16x32_bf16 v[46:49], v[22:25], v[54:57], v[46:49]
	v_mfma_f32_16x16x32_bf16 v[50:53], v[30:33], v[54:57], v[50:53]
	v_mfma_f32_16x16x32_bf16 v[54:57], v[18:21], v[58:61], 0
	v_mfma_f32_16x16x32_bf16 v[58:61], v[26:29], v[58:61], 0
	v_mfma_f32_16x16x32_bf16 v[54:57], v[22:25], v[62:65], v[54:57]
	v_mfma_f32_16x16x32_bf16 v[58:61], v[30:33], v[62:65], v[58:61]
	s_barrier
	s_setprio 0
	s_add_i32 s83, s73, s33
	v_lshl_add_u64 v[136:137], s[6:7], 0, v[140:141]
	s_add_i32 s84, s83, 0x2000
	v_lshl_add_u64 v[130:131], v[136:137], 0, s[20:21]
	s_mov_b32 m0, s83
	v_lshl_add_u64 v[250:251], s[6:7], 0, v[144:145]
	s_add_u32 s14, s6, 0x20100
	ds_read_b128 v[62:65], v160 offset:16384
	ds_read_b128 v[90:93], v160 offset:17408
	ds_read_b128 v[94:97], v160 offset:18432
	ds_read_b128 v[98:101], v160 offset:19456
	ds_read_b128 v[110:113], v160 offset:20480
	ds_read_b128 v[114:117], v160 offset:21504
	ds_read_b128 v[118:121], v160 offset:22528
	ds_read_b128 v[126:129], v160 offset:23552
	global_load_lds_dwordx4 v[130:131], off
	v_lshl_add_u64 v[130:131], v[250:251], 0, s[20:21]
	s_mov_b32 m0, s84
	s_addc_u32 s15, s7, 0
	s_add_i32 s85, s74, s33
	global_load_lds_dwordx4 v[130:131], off
	v_lshl_add_u64 v[130:131], s[14:15], 0, v[140:141]
	s_mov_b32 m0, s85
	s_add_i32 s46, s85, 0x2000
	global_load_lds_dwordx4 v[130:131], off
	v_lshl_add_u64 v[130:131], s[14:15], 0, v[144:145]
	s_mov_b32 m0, s46
	v_lshl_add_u64 v[252:253], s[64:65], 0, v[138:139]
	global_load_lds_dwordx4 v[130:131], off
	v_lshl_add_u64 v[130:131], v[252:253], 0, s[20:21]
	s_mov_b32 m0, s58
	v_lshl_add_u64 v[150:151], s[64:65], 0, v[142:143]
	global_load_lds_dwordx4 v[130:131], off
	v_lshl_add_u64 v[130:131], v[150:151], 0, s[20:21]
	s_mov_b32 m0, s59
	s_nop 0
	global_load_lds_dwordx4 v[130:131], off
	s_waitcnt vmcnt(8)
	s_waitcnt lgkmcnt(0)
	s_setprio 1
	s_barrier
	v_mfma_f32_16x16x32_bf16 v[130:133], v[2:5], v[62:65], 0
	v_mfma_f32_16x16x32_bf16 v[162:165], v[2:5], v[94:97], 0
	v_mfma_f32_16x16x32_bf16 v[170:173], v[2:5], v[110:113], 0
	v_mfma_f32_16x16x32_bf16 v[2:5], v[2:5], v[118:121], 0
	v_mfma_f32_16x16x32_bf16 v[132:135], v[6:9], v[90:93], v[130:133]
	v_mfma_f32_16x16x32_bf16 v[162:165], v[6:9], v[98:101], v[162:165]
	v_mfma_f32_16x16x32_bf16 v[170:173], v[6:9], v[114:117], v[170:173]
	v_mfma_f32_16x16x32_bf16 v[2:5], v[6:9], v[126:129], v[2:5]
	v_mfma_f32_16x16x32_bf16 v[6:9], v[10:13], v[118:121], 0
	v_mfma_f32_16x16x32_bf16 v[154:157], v[10:13], v[62:65], 0
	v_mfma_f32_16x16x32_bf16 v[166:169], v[10:13], v[94:97], 0
	v_mfma_f32_16x16x32_bf16 v[174:177], v[10:13], v[110:113], 0
	v_mfma_f32_16x16x32_bf16 v[6:9], v[14:17], v[126:129], v[6:9]
	v_mfma_f32_16x16x32_bf16 v[154:157], v[14:17], v[90:93], v[154:157]
	v_mfma_f32_16x16x32_bf16 v[166:169], v[14:17], v[98:101], v[166:169]
	v_mfma_f32_16x16x32_bf16 v[174:177], v[14:17], v[114:117], v[174:177]
	v_mfma_f32_16x16x32_bf16 v[10:13], v[18:21], v[62:65], 0
	v_mfma_f32_16x16x32_bf16 v[178:181], v[22:25], v[90:93], v[10:13]
	v_mfma_f32_16x16x32_bf16 v[10:13], v[26:29], v[62:65], 0
	v_mfma_f32_16x16x32_bf16 v[182:185], v[30:33], v[90:93], v[10:13]
	v_mfma_f32_16x16x32_bf16 v[10:13], v[18:21], v[94:97], 0
	v_mfma_f32_16x16x32_bf16 v[186:189], v[22:25], v[98:101], v[10:13]
	v_mfma_f32_16x16x32_bf16 v[10:13], v[26:29], v[94:97], 0
	v_mfma_f32_16x16x32_bf16 v[190:193], v[30:33], v[98:101], v[10:13]
	v_mfma_f32_16x16x32_bf16 v[10:13], v[18:21], v[110:113], 0
	v_mfma_f32_16x16x32_bf16 v[194:197], v[22:25], v[114:117], v[10:13]
	v_mfma_f32_16x16x32_bf16 v[10:13], v[26:29], v[110:113], 0
	v_mfma_f32_16x16x32_bf16 v[198:201], v[30:33], v[114:117], v[10:13]
	v_mfma_f32_16x16x32_bf16 v[10:13], v[18:21], v[118:121], 0
	v_mfma_f32_16x16x32_bf16 v[202:205], v[22:25], v[126:129], v[10:13]
	v_mfma_f32_16x16x32_bf16 v[10:13], v[26:29], v[118:121], 0
	v_mfma_f32_16x16x32_bf16 v[206:209], v[30:33], v[126:129], v[10:13]
	s_barrier
	s_setprio 0
	s_add_i32 s47, 0, 0x18000
	s_add_i32 s56, 0, 0x1c000
	v_add_u32_e32 v130, s47, v1
	v_add_u32_e32 v131, s56, v1
	s_nop 0
	ds_read_b128 v[10:13], v130
	ds_read_b128 v[14:17], v130 offset:1024
	ds_read_b128 v[18:21], v130 offset:2048
	ds_read_b128 v[22:25], v130 offset:3072
	ds_read_b128 v[210:213], v131
	ds_read_b128 v[214:217], v131 offset:1024
	ds_read_b128 v[218:221], v131 offset:2048
	ds_read_b128 v[222:225], v131 offset:3072
	s_add_u32 s14, s64, 0x20100
	s_addc_u32 s15, s65, 0
	s_mov_b32 m0, s63
	v_lshl_add_u64 v[90:91], s[14:15], 0, v[138:139]
	ds_read_b128 v[26:29], v160 offset:32768
	ds_read_b128 v[30:33], v160 offset:33792
	ds_read_b128 v[62:65], v160 offset:34816
	ds_read_b128 v[226:229], v160 offset:35840
	ds_read_b128 v[230:233], v160 offset:36864
	ds_read_b128 v[234:237], v160 offset:37888
	ds_read_b128 v[238:241], v160 offset:38912
	ds_read_b128 v[242:245], v160 offset:39936
	global_load_lds_dwordx4 v[90:91], off
	v_lshl_add_u64 v[90:91], s[14:15], 0, v[142:143]
	s_mov_b32 m0, s68
	s_nop 0
	global_load_lds_dwordx4 v[90:91], off
	s_waitcnt vmcnt(8)
	s_waitcnt lgkmcnt(0)
	s_setprio 1
	s_barrier
	v_mfma_f32_16x16x32_bf16 v[66:69], v[10:13], v[26:29], v[66:69]
	v_mfma_f32_16x16x32_bf16 v[118:121], v[14:17], v[30:33], v[66:69]
	v_mfma_f32_16x16x32_bf16 v[66:69], v[18:21], v[26:29], v[70:73]
	v_mfma_f32_16x16x32_bf16 v[114:117], v[22:25], v[30:33], v[66:69]
	v_mfma_f32_16x16x32_bf16 v[66:69], v[10:13], v[62:65], v[74:77]
	v_mfma_f32_16x16x32_bf16 v[110:113], v[14:17], v[226:229], v[66:69]
	v_mfma_f32_16x16x32_bf16 v[66:69], v[18:21], v[62:65], v[78:81]
	v_mfma_f32_16x16x32_bf16 v[98:101], v[22:25], v[226:229], v[66:69]
	v_mfma_f32_16x16x32_bf16 v[66:69], v[10:13], v[230:233], v[82:85]
	v_mfma_f32_16x16x32_bf16 v[94:97], v[14:17], v[234:237], v[66:69]
	v_mfma_f32_16x16x32_bf16 v[66:69], v[18:21], v[230:233], v[86:89]
	v_mfma_f32_16x16x32_bf16 v[90:93], v[22:25], v[234:237], v[66:69]
	v_mfma_f32_16x16x32_bf16 v[66:69], v[10:13], v[238:241], v[102:105]
	v_mfma_f32_16x16x32_bf16 v[78:81], v[14:17], v[242:245], v[66:69]
	v_mfma_f32_16x16x32_bf16 v[66:69], v[18:21], v[238:241], v[106:109]
	v_mfma_f32_16x16x32_bf16 v[70:73], v[22:25], v[242:245], v[66:69]
	v_mfma_f32_16x16x32_bf16 v[66:69], v[210:213], v[26:29], v[122:125]
	v_mfma_f32_16x16x32_bf16 v[26:29], v[218:221], v[26:29], v[34:37]
	v_mfma_f32_16x16x32_bf16 v[122:125], v[222:225], v[30:33], v[26:29]
	v_mfma_f32_16x16x32_bf16 v[26:29], v[210:213], v[62:65], v[38:41]
	v_mfma_f32_16x16x32_bf16 v[106:109], v[214:217], v[226:229], v[26:29]
	v_mfma_f32_16x16x32_bf16 v[26:29], v[218:221], v[62:65], v[42:45]
	v_mfma_f32_16x16x32_bf16 v[102:105], v[222:225], v[226:229], v[26:29]
	v_mfma_f32_16x16x32_bf16 v[26:29], v[210:213], v[230:233], v[46:49]
	v_mfma_f32_16x16x32_bf16 v[86:89], v[214:217], v[234:237], v[26:29]
	v_mfma_f32_16x16x32_bf16 v[26:29], v[218:221], v[230:233], v[50:53]
	v_mfma_f32_16x16x32_bf16 v[82:85], v[222:225], v[234:237], v[26:29]
	v_mfma_f32_16x16x32_bf16 v[26:29], v[210:213], v[238:241], v[54:57]
	v_mfma_f32_16x16x32_bf16 v[62:65], v[214:217], v[242:245], v[26:29]
	v_mfma_f32_16x16x32_bf16 v[26:29], v[218:221], v[238:241], v[58:61]
	v_mfma_f32_16x16x32_bf16 v[126:129], v[214:217], v[30:33], v[66:69]
	v_mfma_f32_16x16x32_bf16 v[58:61], v[222:225], v[242:245], v[26:29]
	s_barrier
	s_setprio 0
	s_add_i32 s47, s47, s33
	s_add_i32 s86, s47, 0x2000
	s_nop 1
	v_lshl_add_u64 v[26:27], v[136:137], 0, s[22:23]
	s_mov_b32 m0, s47
	s_add_u32 s14, s6, 0x20180
	ds_read_b128 v[34:37], v160 offset:49152
	ds_read_b128 v[38:41], v160 offset:50176
	ds_read_b128 v[226:229], v160 offset:51200
	ds_read_b128 v[230:233], v160 offset:52224
	ds_read_b128 v[234:237], v160 offset:53248
	ds_read_b128 v[238:241], v160 offset:54272
	ds_read_b128 v[242:245], v160 offset:55296
	ds_read_b128 v[246:249], v160 offset:56320
	global_load_lds_dwordx4 v[26:27], off
	v_lshl_add_u64 v[26:27], v[250:251], 0, s[22:23]
	s_mov_b32 m0, s86
	s_addc_u32 s15, s7, 0
	s_add_i32 s56, s56, s33
	global_load_lds_dwordx4 v[26:27], off
	v_lshl_add_u64 v[26:27], s[14:15], 0, v[140:141]
	s_mov_b32 m0, s56
	s_add_i32 s57, s56, 0x2000
	global_load_lds_dwordx4 v[26:27], off
	v_lshl_add_u64 v[26:27], s[14:15], 0, v[144:145]
	s_mov_b32 m0, s57
	s_nop 0
	global_load_lds_dwordx4 v[26:27], off
	v_lshl_add_u64 v[26:27], v[252:253], 0, s[22:23]
	s_mov_b32 m0, s69
	s_nop 0
	global_load_lds_dwordx4 v[26:27], off
	v_lshl_add_u64 v[26:27], v[150:151], 0, s[22:23]
	s_mov_b32 m0, s70
	s_nop 0
	global_load_lds_dwordx4 v[26:27], off
	s_waitcnt vmcnt(8)
	s_waitcnt lgkmcnt(0)
	s_setprio 1
	s_barrier
	v_mfma_f32_16x16x32_bf16 v[26:29], v[10:13], v[34:37], v[132:135]
	v_mfma_f32_16x16x32_bf16 v[74:77], v[14:17], v[38:41], v[26:29]
	v_mfma_f32_16x16x32_bf16 v[26:29], v[18:21], v[34:37], v[154:157]
	v_mfma_f32_16x16x32_bf16 v[66:69], v[22:25], v[38:41], v[26:29]
	v_mfma_f32_16x16x32_bf16 v[26:29], v[10:13], v[226:229], v[162:165]
	v_mfma_f32_16x16x32_bf16 v[46:49], v[14:17], v[230:233], v[26:29]
	v_mfma_f32_16x16x32_bf16 v[26:29], v[18:21], v[226:229], v[166:169]
	v_mfma_f32_16x16x32_bf16 v[42:45], v[22:25], v[230:233], v[26:29]
	v_mfma_f32_16x16x32_bf16 v[26:29], v[10:13], v[234:237], v[170:173]
	v_mfma_f32_16x16x32_bf16 v[2:5], v[10:13], v[242:245], v[2:5]
	v_mfma_f32_16x16x32_bf16 v[30:33], v[14:17], v[238:241], v[26:29]
	v_mfma_f32_16x16x32_bf16 v[26:29], v[18:21], v[234:237], v[174:177]
	v_mfma_f32_16x16x32_bf16 v[14:17], v[14:17], v[246:249], v[2:5]
	v_mfma_f32_16x16x32_bf16 v[2:5], v[18:21], v[242:245], v[6:9]
	v_mfma_f32_16x16x32_bf16 v[26:29], v[22:25], v[238:241], v[26:29]
	v_mfma_f32_16x16x32_bf16 v[10:13], v[22:25], v[246:249], v[2:5]
	v_mfma_f32_16x16x32_bf16 v[2:5], v[210:213], v[34:37], v[178:181]
	v_mfma_f32_16x16x32_bf16 v[54:57], v[214:217], v[38:41], v[2:5]
	v_mfma_f32_16x16x32_bf16 v[2:5], v[218:221], v[34:37], v[182:185]
	v_mfma_f32_16x16x32_bf16 v[50:53], v[222:225], v[38:41], v[2:5]
	v_mfma_f32_16x16x32_bf16 v[2:5], v[210:213], v[226:229], v[186:189]
	v_mfma_f32_16x16x32_bf16 v[38:41], v[214:217], v[230:233], v[2:5]
	v_mfma_f32_16x16x32_bf16 v[2:5], v[218:221], v[226:229], v[190:193]
	v_mfma_f32_16x16x32_bf16 v[34:37], v[222:225], v[230:233], v[2:5]
	v_mfma_f32_16x16x32_bf16 v[2:5], v[210:213], v[234:237], v[194:197]
	v_mfma_f32_16x16x32_bf16 v[22:25], v[214:217], v[238:241], v[2:5]
	v_mfma_f32_16x16x32_bf16 v[2:5], v[218:221], v[234:237], v[198:201]
	v_mfma_f32_16x16x32_bf16 v[18:21], v[222:225], v[238:241], v[2:5]
	v_mfma_f32_16x16x32_bf16 v[2:5], v[210:213], v[242:245], v[202:205]
	v_mfma_f32_16x16x32_bf16 v[6:9], v[214:217], v[246:249], v[2:5]
	v_mfma_f32_16x16x32_bf16 v[2:5], v[218:221], v[242:245], v[206:209]
	v_mfma_f32_16x16x32_bf16 v[2:5], v[222:225], v[246:249], v[2:5]
	s_barrier
	s_setprio 0
	s_add_u32 s64, s64, 0x20180
	s_addc_u32 s65, s65, 0
	s_add_u32 s14, s6, 0x200
	s_addc_u32 s15, s7, 0
	s_mov_b32 s26, 0

.Lrb2_skip_20202:
	s_mov_b32 m0, s81
	ds_read_b128 v[186:189], v160
	ds_read_b128 v[190:193], v160 offset:1024
	ds_read_b128 v[194:197], v160 offset:2048
	ds_read_b128 v[198:201], v160 offset:3072
	ds_read_b128 v[202:205], v160 offset:4096
	ds_read_b128 v[206:209], v160 offset:5120
	ds_read_b128 v[210:213], v160 offset:6144
	ds_read_b128 v[214:217], v160 offset:7168
	global_load_lds_dwordx4 v146, s[64:65]
	s_mov_b32 m0, s82
	s_nop 0
	global_load_lds_dwordx4 v148, s[64:65]
	s_waitcnt vmcnt(8)
	s_waitcnt lgkmcnt(0)
	s_setprio 1
	s_barrier
	v_mfma_f32_16x16x32_bf16 v[118:121], v[132:135], v[186:189], v[118:121]
	v_mfma_f32_16x16x32_bf16 v[114:117], v[162:165], v[186:189], v[114:117]
	v_mfma_f32_16x16x32_bf16 v[110:113], v[132:135], v[194:197], v[110:113]
	v_mfma_f32_16x16x32_bf16 v[98:101], v[162:165], v[194:197], v[98:101]
	v_mfma_f32_16x16x32_bf16 v[94:97], v[132:135], v[202:205], v[94:97]
	v_mfma_f32_16x16x32_bf16 v[90:93], v[162:165], v[202:205], v[90:93]
	v_mfma_f32_16x16x32_bf16 v[78:81], v[132:135], v[210:213], v[78:81]
	v_mfma_f32_16x16x32_bf16 v[70:73], v[162:165], v[210:213], v[70:73]
	v_mfma_f32_16x16x32_bf16 v[118:121], v[154:157], v[190:193], v[118:121]
	v_mfma_f32_16x16x32_bf16 v[114:117], v[166:169], v[190:193], v[114:117]
	v_mfma_f32_16x16x32_bf16 v[110:113], v[154:157], v[198:201], v[110:113]
	v_mfma_f32_16x16x32_bf16 v[98:101], v[166:169], v[198:201], v[98:101]
	v_mfma_f32_16x16x32_bf16 v[94:97], v[154:157], v[206:209], v[94:97]
	v_mfma_f32_16x16x32_bf16 v[90:93], v[166:169], v[206:209], v[90:93]
	v_mfma_f32_16x16x32_bf16 v[78:81], v[154:157], v[214:217], v[78:81]
	v_mfma_f32_16x16x32_bf16 v[70:73], v[166:169], v[214:217], v[70:73]
	v_mfma_f32_16x16x32_bf16 v[126:129], v[170:173], v[186:189], v[126:129]
	v_mfma_f32_16x16x32_bf16 v[122:125], v[178:181], v[186:189], v[122:125]
	v_mfma_f32_16x16x32_bf16 v[106:109], v[170:173], v[194:197], v[106:109]
	v_mfma_f32_16x16x32_bf16 v[102:105], v[178:181], v[194:197], v[102:105]
	v_mfma_f32_16x16x32_bf16 v[86:89], v[170:173], v[202:205], v[86:89]
	v_mfma_f32_16x16x32_bf16 v[82:85], v[178:181], v[202:205], v[82:85]
	v_mfma_f32_16x16x32_bf16 v[62:65], v[170:173], v[210:213], v[62:65]
	v_mfma_f32_16x16x32_bf16 v[58:61], v[178:181], v[210:213], v[58:61]
	v_mfma_f32_16x16x32_bf16 v[126:129], v[174:177], v[190:193], v[126:129]
	v_mfma_f32_16x16x32_bf16 v[122:125], v[182:185], v[190:193], v[122:125]
	v_mfma_f32_16x16x32_bf16 v[106:109], v[174:177], v[198:201], v[106:109]
	v_mfma_f32_16x16x32_bf16 v[102:105], v[182:185], v[198:201], v[102:105]
	v_mfma_f32_16x16x32_bf16 v[86:89], v[174:177], v[206:209], v[86:89]
	v_mfma_f32_16x16x32_bf16 v[82:85], v[182:185], v[206:209], v[82:85]
	v_mfma_f32_16x16x32_bf16 v[62:65], v[174:177], v[214:217], v[62:65]
	v_mfma_f32_16x16x32_bf16 v[58:61], v[182:185], v[214:217], v[58:61]
	s_barrier
	s_setprio 0
	s_mov_b32 m0, s83
	s_mov_b64 s[98:99], s[6:7]
	s_add_u32 s88, s6, 0x20000
	ds_read_b128 v[186:189], v160 offset:16384
	ds_read_b128 v[190:193], v160 offset:17408
	ds_read_b128 v[194:197], v160 offset:18432
	ds_read_b128 v[198:201], v160 offset:19456
	ds_read_b128 v[202:205], v160 offset:20480
	ds_read_b128 v[206:209], v160 offset:21504
	ds_read_b128 v[210:213], v160 offset:22528
	ds_read_b128 v[214:217], v160 offset:23552
	global_load_lds_dwordx4 v140, s[6:7]
	s_mov_b32 m0, s84
	s_addc_u32 s89, s7, 0
	global_load_lds_dwordx4 v144, s[6:7]
	s_mov_b32 m0, s85
	s_mov_b64 s[100:101], s[66:67]
	global_load_lds_dwordx4 v140, s[88:89]
	s_mov_b32 m0, s46
	s_nop 0
	global_load_lds_dwordx4 v144, s[88:89]
	s_waitcnt vmcnt(6)
	s_waitcnt lgkmcnt(0)
	s_setprio 1
	s_barrier
	v_mfma_f32_16x16x32_bf16 v[74:77], v[132:135], v[186:189], v[74:77]
	v_mfma_f32_16x16x32_bf16 v[66:69], v[162:165], v[186:189], v[66:69]
	v_mfma_f32_16x16x32_bf16 v[46:49], v[132:135], v[194:197], v[46:49]
	v_mfma_f32_16x16x32_bf16 v[42:45], v[162:165], v[194:197], v[42:45]
	v_mfma_f32_16x16x32_bf16 v[30:33], v[132:135], v[202:205], v[30:33]
	v_mfma_f32_16x16x32_bf16 v[26:29], v[162:165], v[202:205], v[26:29]
	v_mfma_f32_16x16x32_bf16 v[14:17], v[132:135], v[210:213], v[14:17]
	v_mfma_f32_16x16x32_bf16 v[10:13], v[162:165], v[210:213], v[10:13]
	v_mfma_f32_16x16x32_bf16 v[74:77], v[154:157], v[190:193], v[74:77]
	v_mfma_f32_16x16x32_bf16 v[66:69], v[166:169], v[190:193], v[66:69]
	v_mfma_f32_16x16x32_bf16 v[46:49], v[154:157], v[198:201], v[46:49]
	v_mfma_f32_16x16x32_bf16 v[42:45], v[166:169], v[198:201], v[42:45]
	v_mfma_f32_16x16x32_bf16 v[30:33], v[154:157], v[206:209], v[30:33]
	v_mfma_f32_16x16x32_bf16 v[26:29], v[166:169], v[206:209], v[26:29]
	v_mfma_f32_16x16x32_bf16 v[14:17], v[154:157], v[214:217], v[14:17]
	v_mfma_f32_16x16x32_bf16 v[10:13], v[166:169], v[214:217], v[10:13]
	v_mfma_f32_16x16x32_bf16 v[54:57], v[170:173], v[186:189], v[54:57]
	v_mfma_f32_16x16x32_bf16 v[50:53], v[178:181], v[186:189], v[50:53]
	v_mfma_f32_16x16x32_bf16 v[38:41], v[170:173], v[194:197], v[38:41]
	v_mfma_f32_16x16x32_bf16 v[34:37], v[178:181], v[194:197], v[34:37]
	v_mfma_f32_16x16x32_bf16 v[22:25], v[170:173], v[202:205], v[22:25]
	v_mfma_f32_16x16x32_bf16 v[18:21], v[178:181], v[202:205], v[18:21]
	v_mfma_f32_16x16x32_bf16 v[6:9], v[170:173], v[210:213], v[6:9]
	v_mfma_f32_16x16x32_bf16 v[2:5], v[178:181], v[210:213], v[2:5]
	v_mfma_f32_16x16x32_bf16 v[54:57], v[174:177], v[190:193], v[54:57]
	v_mfma_f32_16x16x32_bf16 v[50:53], v[182:185], v[190:193], v[50:53]
	v_mfma_f32_16x16x32_bf16 v[38:41], v[174:177], v[198:201], v[38:41]
	v_mfma_f32_16x16x32_bf16 v[34:37], v[182:185], v[198:201], v[34:37]
	v_mfma_f32_16x16x32_bf16 v[22:25], v[174:177], v[206:209], v[22:25]
	v_mfma_f32_16x16x32_bf16 v[18:21], v[182:185], v[206:209], v[18:21]
	v_mfma_f32_16x16x32_bf16 v[6:9], v[174:177], v[214:217], v[6:9]
	v_mfma_f32_16x16x32_bf16 v[2:5], v[182:185], v[214:217], v[2:5]
	s_barrier
;     ...
;         for (int t = 2; t < nt; t += 2) PG8_KITER(t);
	s_setprio 0
	ds_read_b128 v[132:135], v130
	ds_read_b128 v[154:157], v130 offset:1024
	ds_read_b128 v[162:165], v130 offset:2048
	ds_read_b128 v[166:169], v130 offset:3072
	ds_read_b128 v[170:173], v131
	ds_read_b128 v[174:177], v131 offset:1024
	ds_read_b128 v[178:181], v131 offset:2048
	ds_read_b128 v[182:185], v131 offset:3072
	s_add_u32 s66, s66, 0x20000
	s_addc_u32 s67, s67, 0
	s_mov_b32 m0, s58
	s_nop 0
	global_load_lds_dwordx4 v138, s[100:101]
	s_mov_b32 m0, s59
	s_nop 0
	global_load_lds_dwordx4 v142, s[100:101]
	s_mov_b32 m0, s63
	ds_read_b128 v[186:189], v160 offset:32768
	ds_read_b128 v[190:193], v160 offset:33792
	ds_read_b128 v[194:197], v160 offset:34816
	ds_read_b128 v[198:201], v160 offset:35840
	ds_read_b128 v[202:205], v160 offset:36864
	ds_read_b128 v[206:209], v160 offset:37888
	ds_read_b128 v[210:213], v160 offset:38912
	ds_read_b128 v[214:217], v160 offset:39936
	global_load_lds_dwordx4 v138, s[66:67]
	s_mov_b32 m0, s68
	s_nop 0
	global_load_lds_dwordx4 v142, s[66:67]
	s_waitcnt vmcnt(8)
	s_waitcnt lgkmcnt(0)
	s_setprio 1
	s_barrier
	v_mfma_f32_16x16x32_bf16 v[118:121], v[132:135], v[186:189], v[118:121]
	v_mfma_f32_16x16x32_bf16 v[114:117], v[162:165], v[186:189], v[114:117]
	v_mfma_f32_16x16x32_bf16 v[110:113], v[132:135], v[194:197], v[110:113]
	v_mfma_f32_16x16x32_bf16 v[98:101], v[162:165], v[194:197], v[98:101]
	v_mfma_f32_16x16x32_bf16 v[94:97], v[132:135], v[202:205], v[94:97]
	v_mfma_f32_16x16x32_bf16 v[90:93], v[162:165], v[202:205], v[90:93]
	v_mfma_f32_16x16x32_bf16 v[78:81], v[132:135], v[210:213], v[78:81]
	v_mfma_f32_16x16x32_bf16 v[70:73], v[162:165], v[210:213], v[70:73]
	v_mfma_f32_16x16x32_bf16 v[118:121], v[154:157], v[190:193], v[118:121]
	v_mfma_f32_16x16x32_bf16 v[114:117], v[166:169], v[190:193], v[114:117]
	v_mfma_f32_16x16x32_bf16 v[110:113], v[154:157], v[198:201], v[110:113]
	v_mfma_f32_16x16x32_bf16 v[98:101], v[166:169], v[198:201], v[98:101]
	v_mfma_f32_16x16x32_bf16 v[94:97], v[154:157], v[206:209], v[94:97]
	v_mfma_f32_16x16x32_bf16 v[90:93], v[166:169], v[206:209], v[90:93]
	v_mfma_f32_16x16x32_bf16 v[78:81], v[154:157], v[214:217], v[78:81]
	v_mfma_f32_16x16x32_bf16 v[70:73], v[166:169], v[214:217], v[70:73]
	v_mfma_f32_16x16x32_bf16 v[126:129], v[170:173], v[186:189], v[126:129]
	v_mfma_f32_16x16x32_bf16 v[122:125], v[178:181], v[186:189], v[122:125]
	v_mfma_f32_16x16x32_bf16 v[106:109], v[170:173], v[194:197], v[106:109]
	v_mfma_f32_16x16x32_bf16 v[102:105], v[178:181], v[194:197], v[102:105]
	v_mfma_f32_16x16x32_bf16 v[86:89], v[170:173], v[202:205], v[86:89]
	v_mfma_f32_16x16x32_bf16 v[82:85], v[178:181], v[202:205], v[82:85]
	v_mfma_f32_16x16x32_bf16 v[62:65], v[170:173], v[210:213], v[62:65]
	v_mfma_f32_16x16x32_bf16 v[58:61], v[178:181], v[210:213], v[58:61]
	v_mfma_f32_16x16x32_bf16 v[126:129], v[174:177], v[190:193], v[126:129]
	v_mfma_f32_16x16x32_bf16 v[122:125], v[182:185], v[190:193], v[122:125]
	v_mfma_f32_16x16x32_bf16 v[106:109], v[174:177], v[198:201], v[106:109]
	v_mfma_f32_16x16x32_bf16 v[102:105], v[182:185], v[198:201], v[102:105]
	v_mfma_f32_16x16x32_bf16 v[86:89], v[174:177], v[206:209], v[86:89]
	v_mfma_f32_16x16x32_bf16 v[82:85], v[182:185], v[206:209], v[82:85]
	v_mfma_f32_16x16x32_bf16 v[62:65], v[174:177], v[214:217], v[62:65]
	v_mfma_f32_16x16x32_bf16 v[58:61], v[182:185], v[214:217], v[58:61]
	s_barrier
	s_setprio 0
	s_mov_b32 m0, s47
	s_add_u32 s98, s98, 0x80
	s_addc_u32 s99, s99, 0
	s_add_u32 s100, s100, 0x80
	s_addc_u32 s101, s101, 0
	s_add_u32 s6, s6, 0x20080
	ds_read_b128 v[186:189], v160 offset:49152
	ds_read_b128 v[190:193], v160 offset:50176
	ds_read_b128 v[194:197], v160 offset:51200
	ds_read_b128 v[198:201], v160 offset:52224
	ds_read_b128 v[202:205], v160 offset:53248
	ds_read_b128 v[206:209], v160 offset:54272
	ds_read_b128 v[210:213], v160 offset:55296
	ds_read_b128 v[214:217], v160 offset:56320
	global_load_lds_dwordx4 v140, s[98:99]
	s_mov_b32 m0, s86
	s_addc_u32 s7, s7, 0
	global_load_lds_dwordx4 v144, s[98:99]
	s_mov_b32 m0, s56
	s_nop 0
	global_load_lds_dwordx4 v140, s[6:7]
	s_mov_b32 m0, s57
	s_nop 0
	global_load_lds_dwordx4 v144, s[6:7]
	s_waitcnt vmcnt(6)
	s_waitcnt lgkmcnt(0)
	s_setprio 1
	s_barrier
	v_mfma_f32_16x16x32_bf16 v[74:77], v[132:135], v[186:189], v[74:77]
	v_mfma_f32_16x16x32_bf16 v[66:69], v[162:165], v[186:189], v[66:69]
	v_mfma_f32_16x16x32_bf16 v[46:49], v[132:135], v[194:197], v[46:49]
	v_mfma_f32_16x16x32_bf16 v[42:45], v[162:165], v[194:197], v[42:45]
	v_mfma_f32_16x16x32_bf16 v[30:33], v[132:135], v[202:205], v[30:33]
	v_mfma_f32_16x16x32_bf16 v[26:29], v[162:165], v[202:205], v[26:29]
	v_mfma_f32_16x16x32_bf16 v[14:17], v[132:135], v[210:213], v[14:17]
	v_mfma_f32_16x16x32_bf16 v[10:13], v[162:165], v[210:213], v[10:13]
	v_mfma_f32_16x16x32_bf16 v[74:77], v[154:157], v[190:193], v[74:77]
	v_mfma_f32_16x16x32_bf16 v[66:69], v[166:169], v[190:193], v[66:69]
	v_mfma_f32_16x16x32_bf16 v[46:49], v[154:157], v[198:201], v[46:49]
	v_mfma_f32_16x16x32_bf16 v[42:45], v[166:169], v[198:201], v[42:45]
	v_mfma_f32_16x16x32_bf16 v[30:33], v[154:157], v[206:209], v[30:33]
	v_mfma_f32_16x16x32_bf16 v[26:29], v[166:169], v[206:209], v[26:29]
	v_mfma_f32_16x16x32_bf16 v[14:17], v[154:157], v[214:217], v[14:17]
	v_mfma_f32_16x16x32_bf16 v[10:13], v[166:169], v[214:217], v[10:13]
	v_mfma_f32_16x16x32_bf16 v[54:57], v[170:173], v[186:189], v[54:57]
	v_mfma_f32_16x16x32_bf16 v[50:53], v[178:181], v[186:189], v[50:53]
	v_mfma_f32_16x16x32_bf16 v[38:41], v[170:173], v[194:197], v[38:41]
	v_mfma_f32_16x16x32_bf16 v[34:37], v[178:181], v[194:197], v[34:37]
	v_mfma_f32_16x16x32_bf16 v[22:25], v[170:173], v[202:205], v[22:25]
	v_mfma_f32_16x16x32_bf16 v[18:21], v[178:181], v[202:205], v[18:21]
	v_mfma_f32_16x16x32_bf16 v[6:9], v[170:173], v[210:213], v[6:9]
	v_mfma_f32_16x16x32_bf16 v[2:5], v[178:181], v[210:213], v[2:5]
	v_mfma_f32_16x16x32_bf16 v[54:57], v[174:177], v[190:193], v[54:57]
	v_mfma_f32_16x16x32_bf16 v[50:53], v[182:185], v[190:193], v[50:53]
	v_mfma_f32_16x16x32_bf16 v[38:41], v[174:177], v[198:201], v[38:41]
	v_mfma_f32_16x16x32_bf16 v[34:37], v[182:185], v[198:201], v[34:37]
	v_mfma_f32_16x16x32_bf16 v[22:25], v[174:177], v[206:209], v[22:25]
	v_mfma_f32_16x16x32_bf16 v[18:21], v[182:185], v[206:209], v[18:21]
	v_mfma_f32_16x16x32_bf16 v[6:9], v[174:177], v[214:217], v[6:9]
	v_mfma_f32_16x16x32_bf16 v[2:5], v[182:185], v[214:217], v[2:5]
	s_barrier
	s_setprio 0
	s_add_i32 s26, s26, 2
	s_add_u32 s64, s64, 0x100
	s_addc_u32 s65, s65, 0
	s_add_u32 s14, s14, 0x100
	s_addc_u32 s15, s15, 0
	s_cmp_gt_u32 s26, 5
	s_cbranch_scc0 .LBB0_670
	s_mov_b32 m0, s69
	s_nop 0
	global_load_lds_dwordx4 v138, s[100:101]
	s_mov_b32 m0, s70
	s_nop 0
	global_load_lds_dwordx4 v142, s[100:101]
	s_and_b64 vcc, exec, s[18:19]
	s_cbranch_vccz .LBB0_673
	s_barrier

.LBB0_715:
	ds_read_b128 v[2:5], v164
	ds_read_b128 v[6:9], v164 offset:1024
	ds_read_b128 v[10:13], v164 offset:2048
	ds_read_b128 v[14:17], v164 offset:3072
	ds_read_b128 v[18:21], v165
	ds_read_b128 v[22:25], v165 offset:1024
	ds_read_b128 v[26:29], v165 offset:2048
	ds_read_b128 v[30:33], v165 offset:3072
	s_add_u32 s14, s62, 0x80080
	s_addc_u32 s15, s63, 0
	s_add_i32 s23, s59, 0xc000
	v_lshl_add_u64 v[66:67], s[14:15], 0, v[146:147]
	s_mov_b32 m0, s23
	s_add_i32 s77, s59, 0xe000
	ds_read_b128 v[34:37], v166
	ds_read_b128 v[38:41], v166 offset:1024
	ds_read_b128 v[42:45], v166 offset:2048
	ds_read_b128 v[46:49], v166 offset:3072
	ds_read_b128 v[50:53], v166 offset:4096
	ds_read_b128 v[54:57], v166 offset:5120
	ds_read_b128 v[58:61], v166 offset:6144
	ds_read_b128 v[62:65], v166 offset:7168
	global_load_lds_dwordx4 v[66:67], off
	v_lshl_add_u64 v[66:67], s[14:15], 0, v[150:151]
	s_mov_b32 m0, s77
	s_nop 0
	global_load_lds_dwordx4 v[66:67], off
	s_waitcnt vmcnt(8)
	s_waitcnt lgkmcnt(0)
	s_setprio 1
	s_barrier
	v_mfma_f32_16x16x32_bf16 v[86:89], v[10:13], v[50:53], 0
	v_mfma_f32_16x16x32_bf16 v[106:109], v[14:17], v[54:57], v[86:89]
	v_mfma_f32_16x16x32_bf16 v[86:89], v[2:5], v[58:61], 0
	v_mfma_f32_16x16x32_bf16 v[66:69], v[2:5], v[34:37], 0
	v_mfma_f32_16x16x32_bf16 v[70:73], v[10:13], v[34:37], 0
	v_mfma_f32_16x16x32_bf16 v[74:77], v[2:5], v[42:45], 0
	v_mfma_f32_16x16x32_bf16 v[78:81], v[10:13], v[42:45], 0
	v_mfma_f32_16x16x32_bf16 v[82:85], v[2:5], v[50:53], 0
	v_mfma_f32_16x16x32_bf16 v[110:113], v[6:9], v[62:65], v[86:89]
	v_mfma_f32_16x16x32_bf16 v[86:89], v[10:13], v[58:61], 0
	v_mfma_f32_16x16x32_bf16 v[66:69], v[6:9], v[38:41], v[66:69]
	v_mfma_f32_16x16x32_bf16 v[70:73], v[14:17], v[38:41], v[70:73]
	v_mfma_f32_16x16x32_bf16 v[74:77], v[6:9], v[46:49], v[74:77]
	v_mfma_f32_16x16x32_bf16 v[78:81], v[14:17], v[46:49], v[78:81]
	v_mfma_f32_16x16x32_bf16 v[82:85], v[6:9], v[54:57], v[82:85]
	v_mfma_f32_16x16x32_bf16 v[114:117], v[14:17], v[62:65], v[86:89]
	v_mfma_f32_16x16x32_bf16 v[86:89], v[18:21], v[34:37], 0
	v_mfma_f32_16x16x32_bf16 v[34:37], v[26:29], v[34:37], 0
	v_mfma_f32_16x16x32_bf16 v[118:121], v[22:25], v[38:41], v[86:89]
	v_mfma_f32_16x16x32_bf16 v[34:37], v[30:33], v[38:41], v[34:37]
	v_mfma_f32_16x16x32_bf16 v[38:41], v[18:21], v[42:45], 0
	v_mfma_f32_16x16x32_bf16 v[42:45], v[26:29], v[42:45], 0
	v_mfma_f32_16x16x32_bf16 v[38:41], v[22:25], v[46:49], v[38:41]
	v_mfma_f32_16x16x32_bf16 v[42:45], v[30:33], v[46:49], v[42:45]
	v_mfma_f32_16x16x32_bf16 v[46:49], v[18:21], v[50:53], 0
	v_mfma_f32_16x16x32_bf16 v[50:53], v[26:29], v[50:53], 0
	v_mfma_f32_16x16x32_bf16 v[46:49], v[22:25], v[54:57], v[46:49]
	v_mfma_f32_16x16x32_bf16 v[50:53], v[30:33], v[54:57], v[50:53]
	v_mfma_f32_16x16x32_bf16 v[54:57], v[18:21], v[58:61], 0
	v_mfma_f32_16x16x32_bf16 v[58:61], v[26:29], v[58:61], 0
	v_mfma_f32_16x16x32_bf16 v[54:57], v[22:25], v[62:65], v[54:57]
	v_mfma_f32_16x16x32_bf16 v[58:61], v[30:33], v[62:65], v[58:61]
	s_barrier
	s_setprio 0
	s_add_i32 s78, s72, s58
	v_lshl_add_u64 v[144:145], s[50:51], 0, v[148:149]
	s_add_i32 s79, s78, 0x2000
	v_lshl_add_u64 v[130:131], v[144:145], 0, s[18:19]
	s_mov_b32 m0, s78
	v_lshl_add_u64 v[162:163], s[50:51], 0, v[152:153]
	s_add_u32 s14, s50, 0x80100
	ds_read_b128 v[62:65], v166 offset:16384
	ds_read_b128 v[86:89], v166 offset:17408
	ds_read_b128 v[90:93], v166 offset:18432
	ds_read_b128 v[94:97], v166 offset:19456
	ds_read_b128 v[98:101], v166 offset:20480
	ds_read_b128 v[102:105], v166 offset:21504
	ds_read_b128 v[122:125], v166 offset:22528
	ds_read_b128 v[126:129], v166 offset:23552
	global_load_lds_dwordx4 v[130:131], off
	v_lshl_add_u64 v[130:131], v[162:163], 0, s[18:19]
	s_mov_b32 m0, s79
	s_addc_u32 s15, s51, 0
	s_add_i32 s80, s73, s58
	global_load_lds_dwordx4 v[130:131], off
	v_lshl_add_u64 v[130:131], s[14:15], 0, v[148:149]
	s_mov_b32 m0, s80
	s_add_i32 s46, s80, 0x2000
	global_load_lds_dwordx4 v[130:131], off
	v_lshl_add_u64 v[130:131], s[14:15], 0, v[152:153]
	s_mov_b32 m0, s46
	v_lshl_add_u64 v[252:253], s[62:63], 0, v[146:147]
	global_load_lds_dwordx4 v[130:131], off
	v_lshl_add_u64 v[130:131], v[252:253], 0, s[18:19]
	s_mov_b32 m0, s59
	v_lshl_add_u64 v[158:159], s[62:63], 0, v[150:151]
	global_load_lds_dwordx4 v[130:131], off
	v_lshl_add_u64 v[130:131], v[158:159], 0, s[18:19]
	s_mov_b32 m0, s31
	s_nop 0
	global_load_lds_dwordx4 v[130:131], off
	s_waitcnt vmcnt(8)
	s_waitcnt lgkmcnt(0)
	s_setprio 1
	s_barrier
	v_mfma_f32_16x16x32_bf16 v[130:133], v[2:5], v[62:65], 0
	v_mfma_f32_16x16x32_bf16 v[140:143], v[2:5], v[90:93], 0
	v_mfma_f32_16x16x32_bf16 v[172:175], v[2:5], v[98:101], 0
	v_mfma_f32_16x16x32_bf16 v[2:5], v[2:5], v[122:125], 0
	v_mfma_f32_16x16x32_bf16 v[132:135], v[6:9], v[86:89], v[130:133]
	v_mfma_f32_16x16x32_bf16 v[140:143], v[6:9], v[94:97], v[140:143]
	v_mfma_f32_16x16x32_bf16 v[172:175], v[6:9], v[102:105], v[172:175]
	v_mfma_f32_16x16x32_bf16 v[2:5], v[6:9], v[126:129], v[2:5]
	v_mfma_f32_16x16x32_bf16 v[6:9], v[10:13], v[122:125], 0
	v_mfma_f32_16x16x32_bf16 v[136:139], v[10:13], v[62:65], 0
	v_mfma_f32_16x16x32_bf16 v[168:171], v[10:13], v[90:93], 0
	v_mfma_f32_16x16x32_bf16 v[176:179], v[10:13], v[98:101], 0
	v_mfma_f32_16x16x32_bf16 v[6:9], v[14:17], v[126:129], v[6:9]
	v_mfma_f32_16x16x32_bf16 v[136:139], v[14:17], v[86:89], v[136:139]
	v_mfma_f32_16x16x32_bf16 v[168:171], v[14:17], v[94:97], v[168:171]
	v_mfma_f32_16x16x32_bf16 v[176:179], v[14:17], v[102:105], v[176:179]
	v_mfma_f32_16x16x32_bf16 v[10:13], v[18:21], v[62:65], 0
	v_mfma_f32_16x16x32_bf16 v[180:183], v[22:25], v[86:89], v[10:13]
	v_mfma_f32_16x16x32_bf16 v[10:13], v[26:29], v[62:65], 0
	v_mfma_f32_16x16x32_bf16 v[184:187], v[30:33], v[86:89], v[10:13]
	v_mfma_f32_16x16x32_bf16 v[10:13], v[18:21], v[90:93], 0
	v_mfma_f32_16x16x32_bf16 v[188:191], v[22:25], v[94:97], v[10:13]
	v_mfma_f32_16x16x32_bf16 v[10:13], v[26:29], v[90:93], 0
	v_mfma_f32_16x16x32_bf16 v[192:195], v[30:33], v[94:97], v[10:13]
	v_mfma_f32_16x16x32_bf16 v[10:13], v[18:21], v[98:101], 0
	v_mfma_f32_16x16x32_bf16 v[196:199], v[22:25], v[102:105], v[10:13]
	v_mfma_f32_16x16x32_bf16 v[10:13], v[26:29], v[98:101], 0
	v_mfma_f32_16x16x32_bf16 v[200:203], v[30:33], v[102:105], v[10:13]
	v_mfma_f32_16x16x32_bf16 v[10:13], v[18:21], v[122:125], 0
	v_mfma_f32_16x16x32_bf16 v[204:207], v[22:25], v[126:129], v[10:13]
	v_mfma_f32_16x16x32_bf16 v[10:13], v[26:29], v[122:125], 0
	v_mfma_f32_16x16x32_bf16 v[208:211], v[30:33], v[126:129], v[10:13]
	s_barrier
	s_setprio 0
	s_add_i32 s47, 0, 0x18000
	s_add_i32 s56, 0, 0x1c000
	v_add_u32_e32 v130, s47, v1
	v_add_u32_e32 v131, s56, v1
	s_nop 0
	ds_read_b128 v[10:13], v130
	ds_read_b128 v[14:17], v130 offset:1024
	ds_read_b128 v[18:21], v130 offset:2048
	ds_read_b128 v[22:25], v130 offset:3072
	ds_read_b128 v[212:215], v131
	ds_read_b128 v[216:219], v131 offset:1024
	ds_read_b128 v[220:223], v131 offset:2048
	ds_read_b128 v[224:227], v131 offset:3072
	s_add_u32 s14, s62, 0x80100
	s_addc_u32 s15, s63, 0
	s_mov_b32 m0, s66
	v_lshl_add_u64 v[62:63], s[14:15], 0, v[146:147]
	ds_read_b128 v[26:29], v166 offset:32768
	ds_read_b128 v[30:33], v166 offset:33792
	ds_read_b128 v[228:231], v166 offset:34816
	ds_read_b128 v[232:235], v166 offset:35840
	ds_read_b128 v[236:239], v166 offset:36864
	ds_read_b128 v[240:243], v166 offset:37888
	ds_read_b128 v[244:247], v166 offset:38912
	ds_read_b128 v[248:251], v166 offset:39936
	global_load_lds_dwordx4 v[62:63], off
	v_lshl_add_u64 v[62:63], s[14:15], 0, v[150:151]
	s_mov_b32 m0, s67
	s_nop 0
	global_load_lds_dwordx4 v[62:63], off
	s_waitcnt vmcnt(8)
	s_waitcnt lgkmcnt(0)
	s_setprio 1
	s_barrier
	v_mfma_f32_16x16x32_bf16 v[62:65], v[10:13], v[26:29], v[66:69]
	v_mfma_f32_16x16x32_bf16 v[102:105], v[14:17], v[30:33], v[62:65]
	v_mfma_f32_16x16x32_bf16 v[62:65], v[18:21], v[26:29], v[70:73]
	v_mfma_f32_16x16x32_bf16 v[98:101], v[22:25], v[30:33], v[62:65]
	v_mfma_f32_16x16x32_bf16 v[62:65], v[10:13], v[228:231], v[74:77]
	v_mfma_f32_16x16x32_bf16 v[94:97], v[14:17], v[232:235], v[62:65]
	v_mfma_f32_16x16x32_bf16 v[62:65], v[18:21], v[228:231], v[78:81]
	v_mfma_f32_16x16x32_bf16 v[90:93], v[22:25], v[232:235], v[62:65]
	v_mfma_f32_16x16x32_bf16 v[62:65], v[10:13], v[236:239], v[82:85]
	v_mfma_f32_16x16x32_bf16 v[86:89], v[14:17], v[240:243], v[62:65]
	v_mfma_f32_16x16x32_bf16 v[62:65], v[18:21], v[236:239], v[106:109]
	v_mfma_f32_16x16x32_bf16 v[82:85], v[22:25], v[240:243], v[62:65]
	v_mfma_f32_16x16x32_bf16 v[62:65], v[10:13], v[244:247], v[110:113]
	v_mfma_f32_16x16x32_bf16 v[78:81], v[14:17], v[248:251], v[62:65]
	v_mfma_f32_16x16x32_bf16 v[62:65], v[18:21], v[244:247], v[114:117]
	v_mfma_f32_16x16x32_bf16 v[62:65], v[22:25], v[248:251], v[62:65]
	v_mfma_f32_16x16x32_bf16 v[66:69], v[212:215], v[26:29], v[118:121]
	v_mfma_f32_16x16x32_bf16 v[26:29], v[220:223], v[26:29], v[34:37]
	v_mfma_f32_16x16x32_bf16 v[122:125], v[224:227], v[30:33], v[26:29]
	v_mfma_f32_16x16x32_bf16 v[26:29], v[212:215], v[228:231], v[38:41]
	v_mfma_f32_16x16x32_bf16 v[118:121], v[216:219], v[232:235], v[26:29]
	v_mfma_f32_16x16x32_bf16 v[26:29], v[220:223], v[228:231], v[42:45]
	v_mfma_f32_16x16x32_bf16 v[114:117], v[224:227], v[232:235], v[26:29]
	v_mfma_f32_16x16x32_bf16 v[26:29], v[212:215], v[236:239], v[46:49]
	v_mfma_f32_16x16x32_bf16 v[110:113], v[216:219], v[240:243], v[26:29]
	v_mfma_f32_16x16x32_bf16 v[26:29], v[220:223], v[236:239], v[50:53]
	v_mfma_f32_16x16x32_bf16 v[106:109], v[224:227], v[240:243], v[26:29]
	v_mfma_f32_16x16x32_bf16 v[26:29], v[212:215], v[244:247], v[54:57]
	v_mfma_f32_16x16x32_bf16 v[54:57], v[216:219], v[248:251], v[26:29]
	v_mfma_f32_16x16x32_bf16 v[26:29], v[220:223], v[244:247], v[58:61]
	v_mfma_f32_16x16x32_bf16 v[126:129], v[216:219], v[30:33], v[66:69]
	v_mfma_f32_16x16x32_bf16 v[50:53], v[224:227], v[248:251], v[26:29]
	s_barrier
	s_setprio 0
	s_add_i32 s47, s47, s58
	s_add_i32 s81, s47, 0x2000
	s_nop 1
	v_lshl_add_u64 v[26:27], v[144:145], 0, s[20:21]
	s_mov_b32 m0, s47
	s_add_u32 s14, s50, 0x80180
	ds_read_b128 v[34:37], v166 offset:49152
	ds_read_b128 v[38:41], v166 offset:50176
	ds_read_b128 v[228:231], v166 offset:51200
	ds_read_b128 v[232:235], v166 offset:52224
	ds_read_b128 v[236:239], v166 offset:53248
	ds_read_b128 v[240:243], v166 offset:54272
	ds_read_b128 v[244:247], v166 offset:55296
	ds_read_b128 v[248:251], v166 offset:56320
	global_load_lds_dwordx4 v[26:27], off
	v_lshl_add_u64 v[26:27], v[162:163], 0, s[20:21]
	s_mov_b32 m0, s81
	s_addc_u32 s15, s51, 0
	s_add_i32 s56, s56, s58
	global_load_lds_dwordx4 v[26:27], off
	v_lshl_add_u64 v[26:27], s[14:15], 0, v[148:149]
	s_mov_b32 m0, s56
	s_add_i32 s57, s56, 0x2000
	global_load_lds_dwordx4 v[26:27], off
	v_lshl_add_u64 v[26:27], s[14:15], 0, v[152:153]
	s_mov_b32 m0, s57
	s_nop 0
	global_load_lds_dwordx4 v[26:27], off
	v_lshl_add_u64 v[26:27], v[252:253], 0, s[20:21]
	s_mov_b32 m0, s69
	s_nop 0
	global_load_lds_dwordx4 v[26:27], off
	v_lshl_add_u64 v[26:27], v[158:159], 0, s[20:21]
	s_mov_b32 m0, s70
	s_nop 0
	global_load_lds_dwordx4 v[26:27], off
	s_waitcnt vmcnt(8)
	s_waitcnt lgkmcnt(0)
	s_setprio 1
	s_barrier
	v_mfma_f32_16x16x32_bf16 v[26:29], v[10:13], v[34:37], v[132:135]
	v_mfma_f32_16x16x32_bf16 v[74:77], v[14:17], v[38:41], v[26:29]
	v_mfma_f32_16x16x32_bf16 v[26:29], v[18:21], v[34:37], v[136:139]
	v_mfma_f32_16x16x32_bf16 v[70:73], v[22:25], v[38:41], v[26:29]
	v_mfma_f32_16x16x32_bf16 v[26:29], v[10:13], v[228:231], v[140:143]
	v_mfma_f32_16x16x32_bf16 v[46:49], v[14:17], v[232:235], v[26:29]
	v_mfma_f32_16x16x32_bf16 v[26:29], v[18:21], v[228:231], v[168:171]
	v_mfma_f32_16x16x32_bf16 v[42:45], v[22:25], v[232:235], v[26:29]
	v_mfma_f32_16x16x32_bf16 v[26:29], v[10:13], v[236:239], v[172:175]
	v_mfma_f32_16x16x32_bf16 v[2:5], v[10:13], v[244:247], v[2:5]
	v_mfma_f32_16x16x32_bf16 v[30:33], v[14:17], v[240:243], v[26:29]
	v_mfma_f32_16x16x32_bf16 v[26:29], v[18:21], v[236:239], v[176:179]
	v_mfma_f32_16x16x32_bf16 v[14:17], v[14:17], v[248:251], v[2:5]
	v_mfma_f32_16x16x32_bf16 v[2:5], v[18:21], v[244:247], v[6:9]
	v_mfma_f32_16x16x32_bf16 v[26:29], v[22:25], v[240:243], v[26:29]
	v_mfma_f32_16x16x32_bf16 v[10:13], v[22:25], v[248:251], v[2:5]
	v_mfma_f32_16x16x32_bf16 v[2:5], v[212:215], v[34:37], v[180:183]
	v_mfma_f32_16x16x32_bf16 v[66:69], v[216:219], v[38:41], v[2:5]
	v_mfma_f32_16x16x32_bf16 v[2:5], v[220:223], v[34:37], v[184:187]
	v_mfma_f32_16x16x32_bf16 v[58:61], v[224:227], v[38:41], v[2:5]
	v_mfma_f32_16x16x32_bf16 v[2:5], v[212:215], v[228:231], v[188:191]
	v_mfma_f32_16x16x32_bf16 v[38:41], v[216:219], v[232:235], v[2:5]
	v_mfma_f32_16x16x32_bf16 v[2:5], v[220:223], v[228:231], v[192:195]
	v_mfma_f32_16x16x32_bf16 v[34:37], v[224:227], v[232:235], v[2:5]
	v_mfma_f32_16x16x32_bf16 v[2:5], v[212:215], v[236:239], v[196:199]
	v_mfma_f32_16x16x32_bf16 v[22:25], v[216:219], v[240:243], v[2:5]
	v_mfma_f32_16x16x32_bf16 v[2:5], v[220:223], v[236:239], v[200:203]
	v_mfma_f32_16x16x32_bf16 v[18:21], v[224:227], v[240:243], v[2:5]
	v_mfma_f32_16x16x32_bf16 v[2:5], v[212:215], v[244:247], v[204:207]
	v_mfma_f32_16x16x32_bf16 v[6:9], v[216:219], v[248:251], v[2:5]
	v_mfma_f32_16x16x32_bf16 v[2:5], v[220:223], v[244:247], v[208:211]
	v_mfma_f32_16x16x32_bf16 v[2:5], v[224:227], v[248:251], v[2:5]
	s_barrier
	s_setprio 0
	s_add_u32 s62, s62, 0x80180
	s_addc_u32 s63, s63, 0
	s_add_u32 s14, s50, 0x200
	s_addc_u32 s15, s51, 0
	s_mov_b32 s26, 0

.Lrb2_skip_21903:
	s_mov_b32 m0, s23
	ds_read_b128 v[188:191], v166
	ds_read_b128 v[192:195], v166 offset:1024
	ds_read_b128 v[196:199], v166 offset:2048
	ds_read_b128 v[200:203], v166 offset:3072
	ds_read_b128 v[204:207], v166 offset:4096
	ds_read_b128 v[208:211], v166 offset:5120
	ds_read_b128 v[212:215], v166 offset:6144
	ds_read_b128 v[216:219], v166 offset:7168
	global_load_lds_dwordx4 v154, s[62:63]
	s_mov_b32 m0, s77
	s_nop 0
	global_load_lds_dwordx4 v156, s[62:63]
	s_waitcnt vmcnt(8)
	s_waitcnt lgkmcnt(0)
	s_setprio 1
	s_barrier
	v_mfma_f32_16x16x32_bf16 v[102:105], v[132:135], v[188:191], v[102:105]
	v_mfma_f32_16x16x32_bf16 v[98:101], v[140:143], v[188:191], v[98:101]
	v_mfma_f32_16x16x32_bf16 v[94:97], v[132:135], v[196:199], v[94:97]
	v_mfma_f32_16x16x32_bf16 v[90:93], v[140:143], v[196:199], v[90:93]
	v_mfma_f32_16x16x32_bf16 v[86:89], v[132:135], v[204:207], v[86:89]
	v_mfma_f32_16x16x32_bf16 v[82:85], v[140:143], v[204:207], v[82:85]
	v_mfma_f32_16x16x32_bf16 v[78:81], v[132:135], v[212:215], v[78:81]
	v_mfma_f32_16x16x32_bf16 v[62:65], v[140:143], v[212:215], v[62:65]
	v_mfma_f32_16x16x32_bf16 v[102:105], v[136:139], v[192:195], v[102:105]
	v_mfma_f32_16x16x32_bf16 v[98:101], v[168:171], v[192:195], v[98:101]
	v_mfma_f32_16x16x32_bf16 v[94:97], v[136:139], v[200:203], v[94:97]
	v_mfma_f32_16x16x32_bf16 v[90:93], v[168:171], v[200:203], v[90:93]
	v_mfma_f32_16x16x32_bf16 v[86:89], v[136:139], v[208:211], v[86:89]
	v_mfma_f32_16x16x32_bf16 v[82:85], v[168:171], v[208:211], v[82:85]
	v_mfma_f32_16x16x32_bf16 v[78:81], v[136:139], v[216:219], v[78:81]
	v_mfma_f32_16x16x32_bf16 v[62:65], v[168:171], v[216:219], v[62:65]
	v_mfma_f32_16x16x32_bf16 v[126:129], v[172:175], v[188:191], v[126:129]
	v_mfma_f32_16x16x32_bf16 v[122:125], v[180:183], v[188:191], v[122:125]
	v_mfma_f32_16x16x32_bf16 v[118:121], v[172:175], v[196:199], v[118:121]
	v_mfma_f32_16x16x32_bf16 v[114:117], v[180:183], v[196:199], v[114:117]
	v_mfma_f32_16x16x32_bf16 v[110:113], v[172:175], v[204:207], v[110:113]
	v_mfma_f32_16x16x32_bf16 v[106:109], v[180:183], v[204:207], v[106:109]
	v_mfma_f32_16x16x32_bf16 v[54:57], v[172:175], v[212:215], v[54:57]
	v_mfma_f32_16x16x32_bf16 v[50:53], v[180:183], v[212:215], v[50:53]
	v_mfma_f32_16x16x32_bf16 v[126:129], v[176:179], v[192:195], v[126:129]
	v_mfma_f32_16x16x32_bf16 v[122:125], v[184:187], v[192:195], v[122:125]
	v_mfma_f32_16x16x32_bf16 v[118:121], v[176:179], v[200:203], v[118:121]
	v_mfma_f32_16x16x32_bf16 v[114:117], v[184:187], v[200:203], v[114:117]
	v_mfma_f32_16x16x32_bf16 v[110:113], v[176:179], v[208:211], v[110:113]
	v_mfma_f32_16x16x32_bf16 v[106:109], v[184:187], v[208:211], v[106:109]
	v_mfma_f32_16x16x32_bf16 v[54:57], v[176:179], v[216:219], v[54:57]
	v_mfma_f32_16x16x32_bf16 v[50:53], v[184:187], v[216:219], v[50:53]
	s_barrier
	s_setprio 0
	s_mov_b32 m0, s78
	s_mov_b64 s[98:99], s[50:51]
	s_add_u32 s82, s50, 0x80000
	ds_read_b128 v[188:191], v166 offset:16384
	ds_read_b128 v[192:195], v166 offset:17408
	ds_read_b128 v[196:199], v166 offset:18432
	ds_read_b128 v[200:203], v166 offset:19456
	ds_read_b128 v[204:207], v166 offset:20480
	ds_read_b128 v[208:211], v166 offset:21504
	ds_read_b128 v[212:215], v166 offset:22528
	ds_read_b128 v[216:219], v166 offset:23552
	global_load_lds_dwordx4 v148, s[50:51]
	s_mov_b32 m0, s79
	s_addc_u32 s83, s51, 0
	global_load_lds_dwordx4 v152, s[50:51]
	s_mov_b32 m0, s80
	s_mov_b64 s[100:101], s[64:65]
	global_load_lds_dwordx4 v148, s[82:83]
	s_mov_b32 m0, s46
	s_nop 0
	global_load_lds_dwordx4 v152, s[82:83]
	s_waitcnt vmcnt(6)
	s_waitcnt lgkmcnt(0)
	s_setprio 1
	s_barrier
	v_mfma_f32_16x16x32_bf16 v[74:77], v[132:135], v[188:191], v[74:77]
	v_mfma_f32_16x16x32_bf16 v[70:73], v[140:143], v[188:191], v[70:73]
	v_mfma_f32_16x16x32_bf16 v[46:49], v[132:135], v[196:199], v[46:49]
	v_mfma_f32_16x16x32_bf16 v[42:45], v[140:143], v[196:199], v[42:45]
	v_mfma_f32_16x16x32_bf16 v[30:33], v[132:135], v[204:207], v[30:33]
	v_mfma_f32_16x16x32_bf16 v[26:29], v[140:143], v[204:207], v[26:29]
	v_mfma_f32_16x16x32_bf16 v[14:17], v[132:135], v[212:215], v[14:17]
	v_mfma_f32_16x16x32_bf16 v[10:13], v[140:143], v[212:215], v[10:13]
	v_mfma_f32_16x16x32_bf16 v[74:77], v[136:139], v[192:195], v[74:77]
	v_mfma_f32_16x16x32_bf16 v[70:73], v[168:171], v[192:195], v[70:73]
	v_mfma_f32_16x16x32_bf16 v[46:49], v[136:139], v[200:203], v[46:49]
	v_mfma_f32_16x16x32_bf16 v[42:45], v[168:171], v[200:203], v[42:45]
	v_mfma_f32_16x16x32_bf16 v[30:33], v[136:139], v[208:211], v[30:33]
	v_mfma_f32_16x16x32_bf16 v[26:29], v[168:171], v[208:211], v[26:29]
	v_mfma_f32_16x16x32_bf16 v[14:17], v[136:139], v[216:219], v[14:17]
	v_mfma_f32_16x16x32_bf16 v[10:13], v[168:171], v[216:219], v[10:13]
	v_mfma_f32_16x16x32_bf16 v[66:69], v[172:175], v[188:191], v[66:69]
	v_mfma_f32_16x16x32_bf16 v[58:61], v[180:183], v[188:191], v[58:61]
	v_mfma_f32_16x16x32_bf16 v[38:41], v[172:175], v[196:199], v[38:41]
	v_mfma_f32_16x16x32_bf16 v[34:37], v[180:183], v[196:199], v[34:37]
	v_mfma_f32_16x16x32_bf16 v[22:25], v[172:175], v[204:207], v[22:25]
	v_mfma_f32_16x16x32_bf16 v[18:21], v[180:183], v[204:207], v[18:21]
	v_mfma_f32_16x16x32_bf16 v[6:9], v[172:175], v[212:215], v[6:9]
	v_mfma_f32_16x16x32_bf16 v[2:5], v[180:183], v[212:215], v[2:5]
	v_mfma_f32_16x16x32_bf16 v[66:69], v[176:179], v[192:195], v[66:69]
	v_mfma_f32_16x16x32_bf16 v[58:61], v[184:187], v[192:195], v[58:61]
	v_mfma_f32_16x16x32_bf16 v[38:41], v[176:179], v[200:203], v[38:41]
	v_mfma_f32_16x16x32_bf16 v[34:37], v[184:187], v[200:203], v[34:37]
	v_mfma_f32_16x16x32_bf16 v[22:25], v[176:179], v[208:211], v[22:25]
	v_mfma_f32_16x16x32_bf16 v[18:21], v[184:187], v[208:211], v[18:21]
	v_mfma_f32_16x16x32_bf16 v[6:9], v[176:179], v[216:219], v[6:9]
	v_mfma_f32_16x16x32_bf16 v[2:5], v[184:187], v[216:219], v[2:5]
	s_barrier
;     ...
;         for (int t = 2; t < nt; t += 2) PG8_KITER(t);
	s_setprio 0
	ds_read_b128 v[132:135], v130
	ds_read_b128 v[136:139], v130 offset:1024
	ds_read_b128 v[140:143], v130 offset:2048
	ds_read_b128 v[168:171], v130 offset:3072
	ds_read_b128 v[172:175], v131
	ds_read_b128 v[176:179], v131 offset:1024
	ds_read_b128 v[180:183], v131 offset:2048
	ds_read_b128 v[184:187], v131 offset:3072
	s_add_u32 s64, s64, 0x80000
	s_addc_u32 s65, s65, 0
	s_mov_b32 m0, s59
	s_nop 0
	global_load_lds_dwordx4 v146, s[100:101]
	s_mov_b32 m0, s31
	s_nop 0
	global_load_lds_dwordx4 v150, s[100:101]
	s_mov_b32 m0, s66
	ds_read_b128 v[188:191], v166 offset:32768
	ds_read_b128 v[192:195], v166 offset:33792
	ds_read_b128 v[196:199], v166 offset:34816
	ds_read_b128 v[200:203], v166 offset:35840
	ds_read_b128 v[204:207], v166 offset:36864
	ds_read_b128 v[208:211], v166 offset:37888
	ds_read_b128 v[212:215], v166 offset:38912
	ds_read_b128 v[216:219], v166 offset:39936
	global_load_lds_dwordx4 v146, s[64:65]
	s_mov_b32 m0, s67
	s_nop 0
	global_load_lds_dwordx4 v150, s[64:65]
	s_waitcnt vmcnt(8)
	s_waitcnt lgkmcnt(0)
	s_setprio 1
	s_barrier
	v_mfma_f32_16x16x32_bf16 v[102:105], v[132:135], v[188:191], v[102:105]
	v_mfma_f32_16x16x32_bf16 v[98:101], v[140:143], v[188:191], v[98:101]
	v_mfma_f32_16x16x32_bf16 v[94:97], v[132:135], v[196:199], v[94:97]
	v_mfma_f32_16x16x32_bf16 v[90:93], v[140:143], v[196:199], v[90:93]
	v_mfma_f32_16x16x32_bf16 v[86:89], v[132:135], v[204:207], v[86:89]
	v_mfma_f32_16x16x32_bf16 v[82:85], v[140:143], v[204:207], v[82:85]
	v_mfma_f32_16x16x32_bf16 v[78:81], v[132:135], v[212:215], v[78:81]
	v_mfma_f32_16x16x32_bf16 v[62:65], v[140:143], v[212:215], v[62:65]
	v_mfma_f32_16x16x32_bf16 v[102:105], v[136:139], v[192:195], v[102:105]
	v_mfma_f32_16x16x32_bf16 v[98:101], v[168:171], v[192:195], v[98:101]
	v_mfma_f32_16x16x32_bf16 v[94:97], v[136:139], v[200:203], v[94:97]
	v_mfma_f32_16x16x32_bf16 v[90:93], v[168:171], v[200:203], v[90:93]
	v_mfma_f32_16x16x32_bf16 v[86:89], v[136:139], v[208:211], v[86:89]
	v_mfma_f32_16x16x32_bf16 v[82:85], v[168:171], v[208:211], v[82:85]
	v_mfma_f32_16x16x32_bf16 v[78:81], v[136:139], v[216:219], v[78:81]
	v_mfma_f32_16x16x32_bf16 v[62:65], v[168:171], v[216:219], v[62:65]
	v_mfma_f32_16x16x32_bf16 v[126:129], v[172:175], v[188:191], v[126:129]
	v_mfma_f32_16x16x32_bf16 v[122:125], v[180:183], v[188:191], v[122:125]
	v_mfma_f32_16x16x32_bf16 v[118:121], v[172:175], v[196:199], v[118:121]
	v_mfma_f32_16x16x32_bf16 v[114:117], v[180:183], v[196:199], v[114:117]
	v_mfma_f32_16x16x32_bf16 v[110:113], v[172:175], v[204:207], v[110:113]
	v_mfma_f32_16x16x32_bf16 v[106:109], v[180:183], v[204:207], v[106:109]
	v_mfma_f32_16x16x32_bf16 v[54:57], v[172:175], v[212:215], v[54:57]
	v_mfma_f32_16x16x32_bf16 v[50:53], v[180:183], v[212:215], v[50:53]
	v_mfma_f32_16x16x32_bf16 v[126:129], v[176:179], v[192:195], v[126:129]
	v_mfma_f32_16x16x32_bf16 v[122:125], v[184:187], v[192:195], v[122:125]
	v_mfma_f32_16x16x32_bf16 v[118:121], v[176:179], v[200:203], v[118:121]
	v_mfma_f32_16x16x32_bf16 v[114:117], v[184:187], v[200:203], v[114:117]
	v_mfma_f32_16x16x32_bf16 v[110:113], v[176:179], v[208:211], v[110:113]
	v_mfma_f32_16x16x32_bf16 v[106:109], v[184:187], v[208:211], v[106:109]
	v_mfma_f32_16x16x32_bf16 v[54:57], v[176:179], v[216:219], v[54:57]
	v_mfma_f32_16x16x32_bf16 v[50:53], v[184:187], v[216:219], v[50:53]
	s_barrier
	s_setprio 0
	s_mov_b32 m0, s47
	s_add_u32 s98, s98, 0x80
	s_addc_u32 s99, s99, 0
	s_add_u32 s100, s100, 0x80
	s_addc_u32 s101, s101, 0
	s_add_u32 s50, s50, 0x80080
	ds_read_b128 v[188:191], v166 offset:49152
	ds_read_b128 v[192:195], v166 offset:50176
	ds_read_b128 v[196:199], v166 offset:51200
	ds_read_b128 v[200:203], v166 offset:52224
	ds_read_b128 v[204:207], v166 offset:53248
	ds_read_b128 v[208:211], v166 offset:54272
	ds_read_b128 v[212:215], v166 offset:55296
	ds_read_b128 v[216:219], v166 offset:56320
	global_load_lds_dwordx4 v148, s[98:99]
	s_mov_b32 m0, s81
	s_addc_u32 s51, s51, 0
	global_load_lds_dwordx4 v152, s[98:99]
	s_mov_b32 m0, s56
	s_nop 0
	global_load_lds_dwordx4 v148, s[50:51]
	s_mov_b32 m0, s57
	s_nop 0
	global_load_lds_dwordx4 v152, s[50:51]
	s_waitcnt vmcnt(6)
	s_waitcnt lgkmcnt(0)
	s_setprio 1
	s_barrier
	v_mfma_f32_16x16x32_bf16 v[74:77], v[132:135], v[188:191], v[74:77]
	v_mfma_f32_16x16x32_bf16 v[70:73], v[140:143], v[188:191], v[70:73]
	v_mfma_f32_16x16x32_bf16 v[46:49], v[132:135], v[196:199], v[46:49]
	v_mfma_f32_16x16x32_bf16 v[42:45], v[140:143], v[196:199], v[42:45]
	v_mfma_f32_16x16x32_bf16 v[30:33], v[132:135], v[204:207], v[30:33]
	v_mfma_f32_16x16x32_bf16 v[26:29], v[140:143], v[204:207], v[26:29]
	v_mfma_f32_16x16x32_bf16 v[14:17], v[132:135], v[212:215], v[14:17]
	v_mfma_f32_16x16x32_bf16 v[10:13], v[140:143], v[212:215], v[10:13]
	v_mfma_f32_16x16x32_bf16 v[74:77], v[136:139], v[192:195], v[74:77]
	v_mfma_f32_16x16x32_bf16 v[70:73], v[168:171], v[192:195], v[70:73]
	v_mfma_f32_16x16x32_bf16 v[46:49], v[136:139], v[200:203], v[46:49]
	v_mfma_f32_16x16x32_bf16 v[42:45], v[168:171], v[200:203], v[42:45]
	v_mfma_f32_16x16x32_bf16 v[30:33], v[136:139], v[208:211], v[30:33]
	v_mfma_f32_16x16x32_bf16 v[26:29], v[168:171], v[208:211], v[26:29]
	v_mfma_f32_16x16x32_bf16 v[14:17], v[136:139], v[216:219], v[14:17]
	v_mfma_f32_16x16x32_bf16 v[10:13], v[168:171], v[216:219], v[10:13]
	v_mfma_f32_16x16x32_bf16 v[66:69], v[172:175], v[188:191], v[66:69]
	v_mfma_f32_16x16x32_bf16 v[58:61], v[180:183], v[188:191], v[58:61]
	v_mfma_f32_16x16x32_bf16 v[38:41], v[172:175], v[196:199], v[38:41]
	v_mfma_f32_16x16x32_bf16 v[34:37], v[180:183], v[196:199], v[34:37]
	v_mfma_f32_16x16x32_bf16 v[22:25], v[172:175], v[204:207], v[22:25]
	v_mfma_f32_16x16x32_bf16 v[18:21], v[180:183], v[204:207], v[18:21]
	v_mfma_f32_16x16x32_bf16 v[6:9], v[172:175], v[212:215], v[6:9]
	v_mfma_f32_16x16x32_bf16 v[2:5], v[180:183], v[212:215], v[2:5]
	v_mfma_f32_16x16x32_bf16 v[66:69], v[176:179], v[192:195], v[66:69]
	v_mfma_f32_16x16x32_bf16 v[58:61], v[184:187], v[192:195], v[58:61]
	v_mfma_f32_16x16x32_bf16 v[38:41], v[176:179], v[200:203], v[38:41]
	v_mfma_f32_16x16x32_bf16 v[34:37], v[184:187], v[200:203], v[34:37]
	v_mfma_f32_16x16x32_bf16 v[22:25], v[176:179], v[208:211], v[22:25]
	v_mfma_f32_16x16x32_bf16 v[18:21], v[184:187], v[208:211], v[18:21]
	v_mfma_f32_16x16x32_bf16 v[6:9], v[176:179], v[216:219], v[6:9]
	v_mfma_f32_16x16x32_bf16 v[2:5], v[184:187], v[216:219], v[2:5]
	s_barrier
	s_setprio 0
	s_add_i32 s26, s26, 2
	s_add_u32 s62, s62, 0x100
	s_addc_u32 s63, s63, 0
	s_add_u32 s14, s14, 0x100
	s_addc_u32 s15, s15, 0
	s_cmp_gt_u32 s26, 5
	s_cbranch_scc0 .LBB0_716
	s_mov_b32 m0, s69
	s_nop 0
	global_load_lds_dwordx4 v146, s[100:101]
	s_mov_b32 m0, s70
	s_nop 0
	global_load_lds_dwordx4 v150, s[100:101]
	s_and_b64 vcc, exec, s[16:17]
	s_cbranch_vccz .LBB0_719
	s_barrier

.LBB0_929:
	v_add_u32_e32 v130, s79, v1
	v_add_u32_e32 v131, s80, v1
	ds_read_b128 v[132:135], v130
	ds_read_b128 v[136:139], v130 offset:1024
	ds_read_b128 v[140:143], v130 offset:2048
	ds_read_b128 v[144:147], v130 offset:3072
	ds_read_b128 v[168:171], v131
	ds_read_b128 v[174:177], v131 offset:1024
	ds_read_b128 v[178:181], v131 offset:2048
	ds_read_b128 v[182:185], v131 offset:3072
	s_add_u32 s12, s62, 0x80080
	s_addc_u32 s13, s63, 0
	s_add_i32 s0, s69, 0xc000
	v_lshl_add_u64 v[148:149], s[12:13], 0, v[150:151]
	s_mov_b32 m0, s0
	s_add_i32 s11, s69, 0xe000
	ds_read_b128 v[186:189], v172
	ds_read_b128 v[190:193], v172 offset:1024
	ds_read_b128 v[194:197], v172 offset:2048
	ds_read_b128 v[198:201], v172 offset:3072
	ds_read_b128 v[202:205], v172 offset:4096
	ds_read_b128 v[206:209], v172 offset:5120
	ds_read_b128 v[210:213], v172 offset:6144
	ds_read_b128 v[214:217], v172 offset:7168
	global_load_lds_dwordx4 v[148:149], off
	v_lshl_add_u64 v[148:149], s[12:13], 0, v[154:155]
	s_mov_b32 m0, s11
	s_nop 0
	global_load_lds_dwordx4 v[148:149], off
	s_waitcnt vmcnt(8)
	s_waitcnt lgkmcnt(0)
	s_setprio 1
	s_barrier
	v_mfma_f32_16x16x32_bf16 v[126:129], v[132:135], v[186:189], v[126:129]
	v_mfma_f32_16x16x32_bf16 v[122:125], v[140:143], v[186:189], v[122:125]
	v_mfma_f32_16x16x32_bf16 v[118:121], v[132:135], v[194:197], v[118:121]
	v_mfma_f32_16x16x32_bf16 v[114:117], v[140:143], v[194:197], v[114:117]
	v_mfma_f32_16x16x32_bf16 v[110:113], v[132:135], v[202:205], v[110:113]
	v_mfma_f32_16x16x32_bf16 v[106:109], v[140:143], v[202:205], v[106:109]
	v_mfma_f32_16x16x32_bf16 v[102:105], v[132:135], v[210:213], v[102:105]
	v_mfma_f32_16x16x32_bf16 v[98:101], v[140:143], v[210:213], v[98:101]
	v_mfma_f32_16x16x32_bf16 v[126:129], v[136:139], v[190:193], v[126:129]
	v_mfma_f32_16x16x32_bf16 v[122:125], v[144:147], v[190:193], v[122:125]
	v_mfma_f32_16x16x32_bf16 v[118:121], v[136:139], v[198:201], v[118:121]
	v_mfma_f32_16x16x32_bf16 v[114:117], v[144:147], v[198:201], v[114:117]
	v_mfma_f32_16x16x32_bf16 v[110:113], v[136:139], v[206:209], v[110:113]
	v_mfma_f32_16x16x32_bf16 v[106:109], v[144:147], v[206:209], v[106:109]
	v_mfma_f32_16x16x32_bf16 v[102:105], v[136:139], v[214:217], v[102:105]
	v_mfma_f32_16x16x32_bf16 v[98:101], v[144:147], v[214:217], v[98:101]
	v_mfma_f32_16x16x32_bf16 v[94:97], v[168:171], v[186:189], v[94:97]
	v_mfma_f32_16x16x32_bf16 v[90:93], v[178:181], v[186:189], v[90:93]
	v_mfma_f32_16x16x32_bf16 v[86:89], v[168:171], v[194:197], v[86:89]
	v_mfma_f32_16x16x32_bf16 v[82:85], v[178:181], v[194:197], v[82:85]
	v_mfma_f32_16x16x32_bf16 v[78:81], v[168:171], v[202:205], v[78:81]
	v_mfma_f32_16x16x32_bf16 v[74:77], v[178:181], v[202:205], v[74:77]
	v_mfma_f32_16x16x32_bf16 v[70:73], v[168:171], v[210:213], v[70:73]
	v_mfma_f32_16x16x32_bf16 v[66:69], v[178:181], v[210:213], v[66:69]
	v_mfma_f32_16x16x32_bf16 v[94:97], v[174:177], v[190:193], v[94:97]
	v_mfma_f32_16x16x32_bf16 v[90:93], v[182:185], v[190:193], v[90:93]
	v_mfma_f32_16x16x32_bf16 v[86:89], v[174:177], v[198:201], v[86:89]
	v_mfma_f32_16x16x32_bf16 v[82:85], v[182:185], v[198:201], v[82:85]
	v_mfma_f32_16x16x32_bf16 v[78:81], v[174:177], v[206:209], v[78:81]
	v_mfma_f32_16x16x32_bf16 v[74:77], v[182:185], v[206:209], v[74:77]
	v_mfma_f32_16x16x32_bf16 v[70:73], v[174:177], v[214:217], v[70:73]
	v_mfma_f32_16x16x32_bf16 v[66:69], v[182:185], v[214:217], v[66:69]
	s_barrier
	s_setprio 0
	s_add_i32 s12, s79, s68
	v_lshl_add_u64 v[218:219], s[50:51], 0, v[152:153]
	s_add_i32 s13, s12, 0x2000
	v_lshl_add_u64 v[148:149], v[218:219], 0, s[22:23]
	s_mov_b32 m0, s12
	v_lshl_add_u64 v[220:221], s[50:51], 0, v[156:157]
	s_add_u32 s14, s50, 0x80100
	ds_read_b128 v[186:189], v172 offset:16384
	ds_read_b128 v[190:193], v172 offset:17408
	ds_read_b128 v[194:197], v172 offset:18432
	ds_read_b128 v[198:201], v172 offset:19456
	ds_read_b128 v[202:205], v172 offset:20480
	ds_read_b128 v[206:209], v172 offset:21504
	ds_read_b128 v[210:213], v172 offset:22528
	ds_read_b128 v[214:217], v172 offset:23552
	global_load_lds_dwordx4 v[148:149], off
	v_lshl_add_u64 v[148:149], v[220:221], 0, s[22:23]
	s_mov_b32 m0, s13
	s_addc_u32 s15, s51, 0
	s_add_i32 s43, s80, s68
	global_load_lds_dwordx4 v[148:149], off
	v_lshl_add_u64 v[148:149], s[14:15], 0, v[152:153]
	s_mov_b32 m0, s43
	s_add_i32 s46, s43, 0x2000
	global_load_lds_dwordx4 v[148:149], off
	v_lshl_add_u64 v[148:149], s[14:15], 0, v[156:157]
	s_mov_b32 m0, s46
	v_lshl_add_u64 v[222:223], s[62:63], 0, v[150:151]
	global_load_lds_dwordx4 v[148:149], off
	v_lshl_add_u64 v[148:149], v[222:223], 0, s[22:23]
	s_mov_b32 m0, s69
	v_lshl_add_u64 v[224:225], s[62:63], 0, v[154:155]
	global_load_lds_dwordx4 v[148:149], off
	v_lshl_add_u64 v[148:149], v[224:225], 0, s[22:23]
	s_mov_b32 m0, s70
	s_nop 0
	global_load_lds_dwordx4 v[148:149], off
	s_waitcnt vmcnt(8)
	s_waitcnt lgkmcnt(0)
	s_setprio 1
	s_barrier
	v_mfma_f32_16x16x32_bf16 v[62:65], v[132:135], v[186:189], v[62:65]
	v_mfma_f32_16x16x32_bf16 v[58:61], v[140:143], v[186:189], v[58:61]
	v_mfma_f32_16x16x32_bf16 v[54:57], v[132:135], v[194:197], v[54:57]
	v_mfma_f32_16x16x32_bf16 v[50:53], v[140:143], v[194:197], v[50:53]
	v_mfma_f32_16x16x32_bf16 v[46:49], v[132:135], v[202:205], v[46:49]
	v_mfma_f32_16x16x32_bf16 v[42:45], v[140:143], v[202:205], v[42:45]
	v_mfma_f32_16x16x32_bf16 v[38:41], v[132:135], v[210:213], v[38:41]
	v_mfma_f32_16x16x32_bf16 v[34:37], v[140:143], v[210:213], v[34:37]
	v_mfma_f32_16x16x32_bf16 v[62:65], v[136:139], v[190:193], v[62:65]
	v_mfma_f32_16x16x32_bf16 v[58:61], v[144:147], v[190:193], v[58:61]
	v_mfma_f32_16x16x32_bf16 v[54:57], v[136:139], v[198:201], v[54:57]
	v_mfma_f32_16x16x32_bf16 v[50:53], v[144:147], v[198:201], v[50:53]
	v_mfma_f32_16x16x32_bf16 v[46:49], v[136:139], v[206:209], v[46:49]
	v_mfma_f32_16x16x32_bf16 v[42:45], v[144:147], v[206:209], v[42:45]
	v_mfma_f32_16x16x32_bf16 v[38:41], v[136:139], v[214:217], v[38:41]
	v_mfma_f32_16x16x32_bf16 v[34:37], v[144:147], v[214:217], v[34:37]
	v_mfma_f32_16x16x32_bf16 v[30:33], v[168:171], v[186:189], v[30:33]
	v_mfma_f32_16x16x32_bf16 v[26:29], v[178:181], v[186:189], v[26:29]
	v_mfma_f32_16x16x32_bf16 v[22:25], v[168:171], v[194:197], v[22:25]
	v_mfma_f32_16x16x32_bf16 v[18:21], v[178:181], v[194:197], v[18:21]
	v_mfma_f32_16x16x32_bf16 v[14:17], v[168:171], v[202:205], v[14:17]
	v_mfma_f32_16x16x32_bf16 v[10:13], v[178:181], v[202:205], v[10:13]
	v_mfma_f32_16x16x32_bf16 v[6:9], v[168:171], v[210:213], v[6:9]
	v_mfma_f32_16x16x32_bf16 v[2:5], v[178:181], v[210:213], v[2:5]
	v_mfma_f32_16x16x32_bf16 v[30:33], v[174:177], v[190:193], v[30:33]
	v_mfma_f32_16x16x32_bf16 v[26:29], v[182:185], v[190:193], v[26:29]
	v_mfma_f32_16x16x32_bf16 v[22:25], v[174:177], v[198:201], v[22:25]
	v_mfma_f32_16x16x32_bf16 v[18:21], v[182:185], v[198:201], v[18:21]
	v_mfma_f32_16x16x32_bf16 v[14:17], v[174:177], v[206:209], v[14:17]
	v_mfma_f32_16x16x32_bf16 v[10:13], v[182:185], v[206:209], v[10:13]
	v_mfma_f32_16x16x32_bf16 v[6:9], v[174:177], v[214:217], v[6:9]
	v_mfma_f32_16x16x32_bf16 v[2:5], v[182:185], v[214:217], v[2:5]
	s_barrier
	s_setprio 0
	s_add_i32 s47, 0, 0x18000
	s_add_i32 s55, 0, 0x1c000
	v_add_u32_e32 v132, s47, v1
	v_add_u32_e32 v133, s55, v1
	ds_read_b128 v[134:137], v132
	ds_read_b128 v[138:141], v132 offset:1024
	ds_read_b128 v[142:145], v132 offset:2048
	ds_read_b128 v[146:149], v132 offset:3072
	ds_read_b128 v[168:171], v133
	ds_read_b128 v[174:177], v133 offset:1024
	ds_read_b128 v[178:181], v133 offset:2048
	ds_read_b128 v[182:185], v133 offset:3072
	s_add_u32 s14, s62, 0x80100
	s_addc_u32 s15, s63, 0
	s_mov_b32 m0, s71
	v_lshl_add_u64 v[226:227], s[14:15], 0, v[150:151]
	ds_read_b128 v[186:189], v172 offset:32768
	ds_read_b128 v[190:193], v172 offset:33792
	ds_read_b128 v[194:197], v172 offset:34816
	ds_read_b128 v[198:201], v172 offset:35840
	ds_read_b128 v[202:205], v172 offset:36864
	ds_read_b128 v[206:209], v172 offset:37888
	ds_read_b128 v[210:213], v172 offset:38912
	ds_read_b128 v[214:217], v172 offset:39936
	global_load_lds_dwordx4 v[226:227], off
	v_lshl_add_u64 v[226:227], s[14:15], 0, v[154:155]
	s_mov_b32 m0, s72
	s_nop 0
	global_load_lds_dwordx4 v[226:227], off
	s_waitcnt vmcnt(8)
	s_waitcnt lgkmcnt(0)
	s_setprio 1
	s_barrier
	v_mfma_f32_16x16x32_bf16 v[126:129], v[134:137], v[186:189], v[126:129]
	v_mfma_f32_16x16x32_bf16 v[122:125], v[142:145], v[186:189], v[122:125]
	v_mfma_f32_16x16x32_bf16 v[118:121], v[134:137], v[194:197], v[118:121]
	v_mfma_f32_16x16x32_bf16 v[114:117], v[142:145], v[194:197], v[114:117]
	v_mfma_f32_16x16x32_bf16 v[110:113], v[134:137], v[202:205], v[110:113]
	v_mfma_f32_16x16x32_bf16 v[106:109], v[142:145], v[202:205], v[106:109]
	v_mfma_f32_16x16x32_bf16 v[102:105], v[134:137], v[210:213], v[102:105]
	v_mfma_f32_16x16x32_bf16 v[98:101], v[142:145], v[210:213], v[98:101]
	v_mfma_f32_16x16x32_bf16 v[126:129], v[138:141], v[190:193], v[126:129]
	v_mfma_f32_16x16x32_bf16 v[122:125], v[146:149], v[190:193], v[122:125]
	v_mfma_f32_16x16x32_bf16 v[118:121], v[138:141], v[198:201], v[118:121]
	v_mfma_f32_16x16x32_bf16 v[114:117], v[146:149], v[198:201], v[114:117]
	v_mfma_f32_16x16x32_bf16 v[110:113], v[138:141], v[206:209], v[110:113]
	v_mfma_f32_16x16x32_bf16 v[106:109], v[146:149], v[206:209], v[106:109]
	v_mfma_f32_16x16x32_bf16 v[102:105], v[138:141], v[214:217], v[102:105]
	v_mfma_f32_16x16x32_bf16 v[98:101], v[146:149], v[214:217], v[98:101]
	v_mfma_f32_16x16x32_bf16 v[94:97], v[168:171], v[186:189], v[94:97]
	v_mfma_f32_16x16x32_bf16 v[90:93], v[178:181], v[186:189], v[90:93]
	v_mfma_f32_16x16x32_bf16 v[86:89], v[168:171], v[194:197], v[86:89]
	v_mfma_f32_16x16x32_bf16 v[82:85], v[178:181], v[194:197], v[82:85]
	v_mfma_f32_16x16x32_bf16 v[78:81], v[168:171], v[202:205], v[78:81]
	v_mfma_f32_16x16x32_bf16 v[74:77], v[178:181], v[202:205], v[74:77]
	v_mfma_f32_16x16x32_bf16 v[70:73], v[168:171], v[210:213], v[70:73]
	v_mfma_f32_16x16x32_bf16 v[66:69], v[178:181], v[210:213], v[66:69]
	v_mfma_f32_16x16x32_bf16 v[94:97], v[174:177], v[190:193], v[94:97]
	v_mfma_f32_16x16x32_bf16 v[90:93], v[182:185], v[190:193], v[90:93]
	v_mfma_f32_16x16x32_bf16 v[86:89], v[174:177], v[198:201], v[86:89]
	v_mfma_f32_16x16x32_bf16 v[82:85], v[182:185], v[198:201], v[82:85]
	v_mfma_f32_16x16x32_bf16 v[78:81], v[174:177], v[206:209], v[78:81]
	v_mfma_f32_16x16x32_bf16 v[74:77], v[182:185], v[206:209], v[74:77]
	v_mfma_f32_16x16x32_bf16 v[70:73], v[174:177], v[214:217], v[70:73]
	v_mfma_f32_16x16x32_bf16 v[66:69], v[182:185], v[214:217], v[66:69]
	s_barrier
	s_setprio 0
	s_add_i32 s47, s47, s68
	s_add_i32 s53, s47, 0x2000
	v_lshl_add_u64 v[218:219], v[218:219], 0, s[28:29]
	s_mov_b32 m0, s47
	s_add_u32 s14, s50, 0x80180
	ds_read_b128 v[186:189], v172 offset:49152
	ds_read_b128 v[190:193], v172 offset:50176
	ds_read_b128 v[194:197], v172 offset:51200
	ds_read_b128 v[198:201], v172 offset:52224
	ds_read_b128 v[202:205], v172 offset:53248
	ds_read_b128 v[206:209], v172 offset:54272
	ds_read_b128 v[210:213], v172 offset:55296
	ds_read_b128 v[214:217], v172 offset:56320
	global_load_lds_dwordx4 v[218:219], off
	v_lshl_add_u64 v[218:219], v[220:221], 0, s[28:29]
	s_mov_b32 m0, s53
	s_addc_u32 s15, s51, 0
	s_add_i32 s55, s55, s68
	global_load_lds_dwordx4 v[218:219], off
	v_lshl_add_u64 v[218:219], s[14:15], 0, v[152:153]
	s_mov_b32 m0, s55
	s_add_i32 s56, s55, 0x2000
	global_load_lds_dwordx4 v[218:219], off
	v_lshl_add_u64 v[218:219], s[14:15], 0, v[156:157]
	s_mov_b32 m0, s56
	s_nop 0
	global_load_lds_dwordx4 v[218:219], off
	v_lshl_add_u64 v[218:219], v[222:223], 0, s[28:29]
	s_mov_b32 m0, s77
	s_nop 0
	global_load_lds_dwordx4 v[218:219], off
	v_lshl_add_u64 v[218:219], v[224:225], 0, s[28:29]
	s_mov_b32 m0, s78
	s_nop 0
	global_load_lds_dwordx4 v[218:219], off
	s_waitcnt vmcnt(8)
	s_waitcnt lgkmcnt(0)
	s_setprio 1
	s_barrier
	v_mfma_f32_16x16x32_bf16 v[62:65], v[134:137], v[186:189], v[62:65]
	v_mfma_f32_16x16x32_bf16 v[58:61], v[142:145], v[186:189], v[58:61]
	v_mfma_f32_16x16x32_bf16 v[54:57], v[134:137], v[194:197], v[54:57]
	v_mfma_f32_16x16x32_bf16 v[50:53], v[142:145], v[194:197], v[50:53]
	v_mfma_f32_16x16x32_bf16 v[46:49], v[134:137], v[202:205], v[46:49]
	v_mfma_f32_16x16x32_bf16 v[42:45], v[142:145], v[202:205], v[42:45]
	v_mfma_f32_16x16x32_bf16 v[38:41], v[134:137], v[210:213], v[38:41]
	v_mfma_f32_16x16x32_bf16 v[34:37], v[142:145], v[210:213], v[34:37]
	v_mfma_f32_16x16x32_bf16 v[62:65], v[138:141], v[190:193], v[62:65]
	v_mfma_f32_16x16x32_bf16 v[58:61], v[146:149], v[190:193], v[58:61]
	v_mfma_f32_16x16x32_bf16 v[54:57], v[138:141], v[198:201], v[54:57]
	v_mfma_f32_16x16x32_bf16 v[50:53], v[146:149], v[198:201], v[50:53]
	v_mfma_f32_16x16x32_bf16 v[46:49], v[138:141], v[206:209], v[46:49]
	v_mfma_f32_16x16x32_bf16 v[42:45], v[146:149], v[206:209], v[42:45]
	v_mfma_f32_16x16x32_bf16 v[38:41], v[138:141], v[214:217], v[38:41]
	v_mfma_f32_16x16x32_bf16 v[34:37], v[146:149], v[214:217], v[34:37]
	v_mfma_f32_16x16x32_bf16 v[30:33], v[168:171], v[186:189], v[30:33]
	v_mfma_f32_16x16x32_bf16 v[26:29], v[178:181], v[186:189], v[26:29]
	v_mfma_f32_16x16x32_bf16 v[22:25], v[168:171], v[194:197], v[22:25]
	v_mfma_f32_16x16x32_bf16 v[18:21], v[178:181], v[194:197], v[18:21]
	v_mfma_f32_16x16x32_bf16 v[14:17], v[168:171], v[202:205], v[14:17]
	v_mfma_f32_16x16x32_bf16 v[10:13], v[178:181], v[202:205], v[10:13]
	v_mfma_f32_16x16x32_bf16 v[6:9], v[168:171], v[210:213], v[6:9]
	v_mfma_f32_16x16x32_bf16 v[2:5], v[178:181], v[210:213], v[2:5]
	v_mfma_f32_16x16x32_bf16 v[30:33], v[174:177], v[190:193], v[30:33]
	v_mfma_f32_16x16x32_bf16 v[26:29], v[182:185], v[190:193], v[26:29]
	v_mfma_f32_16x16x32_bf16 v[22:25], v[174:177], v[198:201], v[22:25]
	v_mfma_f32_16x16x32_bf16 v[18:21], v[182:185], v[198:201], v[18:21]
	v_mfma_f32_16x16x32_bf16 v[14:17], v[174:177], v[206:209], v[14:17]
	v_mfma_f32_16x16x32_bf16 v[10:13], v[182:185], v[206:209], v[10:13]
	v_mfma_f32_16x16x32_bf16 v[6:9], v[174:177], v[214:217], v[6:9]
	v_mfma_f32_16x16x32_bf16 v[2:5], v[182:185], v[214:217], v[2:5]
	s_barrier
	s_setprio 0
	s_add_u32 s62, s62, 0x80180
	s_addc_u32 s63, s63, 0
	s_add_u32 s14, s50, 0x200
	s_addc_u32 s15, s51, 0
	s_mov_b32 s26, 0

.Lrb2_skip_28568:
	s_mov_b32 m0, s0
	ds_read_b128 v[186:189], v172
	ds_read_b128 v[190:193], v172 offset:1024
	ds_read_b128 v[194:197], v172 offset:2048
	ds_read_b128 v[198:201], v172 offset:3072
	ds_read_b128 v[202:205], v172 offset:4096
	ds_read_b128 v[206:209], v172 offset:5120
	ds_read_b128 v[210:213], v172 offset:6144
	ds_read_b128 v[214:217], v172 offset:7168
	global_load_lds_dwordx4 v160, s[62:63]
	s_mov_b32 m0, s11
	s_nop 0
	global_load_lds_dwordx4 v162, s[62:63]
	s_waitcnt vmcnt(8)
	s_waitcnt lgkmcnt(0)
	s_setprio 1
	s_barrier
	v_mfma_f32_16x16x32_bf16 v[126:129], v[134:137], v[186:189], v[126:129]
	v_mfma_f32_16x16x32_bf16 v[122:125], v[142:145], v[186:189], v[122:125]
	v_mfma_f32_16x16x32_bf16 v[118:121], v[134:137], v[194:197], v[118:121]
	v_mfma_f32_16x16x32_bf16 v[114:117], v[142:145], v[194:197], v[114:117]
	v_mfma_f32_16x16x32_bf16 v[110:113], v[134:137], v[202:205], v[110:113]
	v_mfma_f32_16x16x32_bf16 v[106:109], v[142:145], v[202:205], v[106:109]
	v_mfma_f32_16x16x32_bf16 v[102:105], v[134:137], v[210:213], v[102:105]
	v_mfma_f32_16x16x32_bf16 v[98:101], v[142:145], v[210:213], v[98:101]
	v_mfma_f32_16x16x32_bf16 v[126:129], v[138:141], v[190:193], v[126:129]
	v_mfma_f32_16x16x32_bf16 v[122:125], v[146:149], v[190:193], v[122:125]
	v_mfma_f32_16x16x32_bf16 v[118:121], v[138:141], v[198:201], v[118:121]
	v_mfma_f32_16x16x32_bf16 v[114:117], v[146:149], v[198:201], v[114:117]
	v_mfma_f32_16x16x32_bf16 v[110:113], v[138:141], v[206:209], v[110:113]
	v_mfma_f32_16x16x32_bf16 v[106:109], v[146:149], v[206:209], v[106:109]
	v_mfma_f32_16x16x32_bf16 v[102:105], v[138:141], v[214:217], v[102:105]
	v_mfma_f32_16x16x32_bf16 v[98:101], v[146:149], v[214:217], v[98:101]
	v_mfma_f32_16x16x32_bf16 v[94:97], v[168:171], v[186:189], v[94:97]
	v_mfma_f32_16x16x32_bf16 v[90:93], v[178:181], v[186:189], v[90:93]
	v_mfma_f32_16x16x32_bf16 v[86:89], v[168:171], v[194:197], v[86:89]
	v_mfma_f32_16x16x32_bf16 v[82:85], v[178:181], v[194:197], v[82:85]
	v_mfma_f32_16x16x32_bf16 v[78:81], v[168:171], v[202:205], v[78:81]
	v_mfma_f32_16x16x32_bf16 v[74:77], v[178:181], v[202:205], v[74:77]
	v_mfma_f32_16x16x32_bf16 v[70:73], v[168:171], v[210:213], v[70:73]
	v_mfma_f32_16x16x32_bf16 v[66:69], v[178:181], v[210:213], v[66:69]
	v_mfma_f32_16x16x32_bf16 v[94:97], v[174:177], v[190:193], v[94:97]
	v_mfma_f32_16x16x32_bf16 v[90:93], v[182:185], v[190:193], v[90:93]
	v_mfma_f32_16x16x32_bf16 v[86:89], v[174:177], v[198:201], v[86:89]
	v_mfma_f32_16x16x32_bf16 v[82:85], v[182:185], v[198:201], v[82:85]
	v_mfma_f32_16x16x32_bf16 v[78:81], v[174:177], v[206:209], v[78:81]
	v_mfma_f32_16x16x32_bf16 v[74:77], v[182:185], v[206:209], v[74:77]
	v_mfma_f32_16x16x32_bf16 v[70:73], v[174:177], v[214:217], v[70:73]
	v_mfma_f32_16x16x32_bf16 v[66:69], v[182:185], v[214:217], v[66:69]
	s_barrier
	s_setprio 0
	s_mov_b32 m0, s12
	s_mov_b64 s[98:99], s[50:51]
	s_add_u32 s58, s50, 0x80000
	ds_read_b128 v[186:189], v172 offset:16384
	ds_read_b128 v[190:193], v172 offset:17408
	ds_read_b128 v[194:197], v172 offset:18432
	ds_read_b128 v[198:201], v172 offset:19456
	ds_read_b128 v[202:205], v172 offset:20480
	ds_read_b128 v[206:209], v172 offset:21504
	ds_read_b128 v[210:213], v172 offset:22528
	ds_read_b128 v[214:217], v172 offset:23552
	global_load_lds_dwordx4 v152, s[50:51]
	s_mov_b32 m0, s13
	s_addc_u32 s59, s51, 0
	global_load_lds_dwordx4 v156, s[50:51]
	s_mov_b32 m0, s43
	s_mov_b64 s[100:101], s[64:65]
	global_load_lds_dwordx4 v152, s[58:59]
	s_mov_b32 m0, s46
	s_nop 0
	global_load_lds_dwordx4 v156, s[58:59]
	s_waitcnt vmcnt(6)
	s_waitcnt lgkmcnt(0)
	s_setprio 1
	s_barrier
	v_mfma_f32_16x16x32_bf16 v[62:65], v[134:137], v[186:189], v[62:65]
	v_mfma_f32_16x16x32_bf16 v[58:61], v[142:145], v[186:189], v[58:61]
	v_mfma_f32_16x16x32_bf16 v[54:57], v[134:137], v[194:197], v[54:57]
	v_mfma_f32_16x16x32_bf16 v[50:53], v[142:145], v[194:197], v[50:53]
	v_mfma_f32_16x16x32_bf16 v[46:49], v[134:137], v[202:205], v[46:49]
	v_mfma_f32_16x16x32_bf16 v[42:45], v[142:145], v[202:205], v[42:45]
	v_mfma_f32_16x16x32_bf16 v[38:41], v[134:137], v[210:213], v[38:41]
	v_mfma_f32_16x16x32_bf16 v[34:37], v[142:145], v[210:213], v[34:37]
	v_mfma_f32_16x16x32_bf16 v[62:65], v[138:141], v[190:193], v[62:65]
	v_mfma_f32_16x16x32_bf16 v[58:61], v[146:149], v[190:193], v[58:61]
	v_mfma_f32_16x16x32_bf16 v[54:57], v[138:141], v[198:201], v[54:57]
	v_mfma_f32_16x16x32_bf16 v[50:53], v[146:149], v[198:201], v[50:53]
	v_mfma_f32_16x16x32_bf16 v[46:49], v[138:141], v[206:209], v[46:49]
	v_mfma_f32_16x16x32_bf16 v[42:45], v[146:149], v[206:209], v[42:45]
	v_mfma_f32_16x16x32_bf16 v[38:41], v[138:141], v[214:217], v[38:41]
	v_mfma_f32_16x16x32_bf16 v[34:37], v[146:149], v[214:217], v[34:37]
	v_mfma_f32_16x16x32_bf16 v[30:33], v[168:171], v[186:189], v[30:33]
	v_mfma_f32_16x16x32_bf16 v[26:29], v[178:181], v[186:189], v[26:29]
	v_mfma_f32_16x16x32_bf16 v[22:25], v[168:171], v[194:197], v[22:25]
	v_mfma_f32_16x16x32_bf16 v[18:21], v[178:181], v[194:197], v[18:21]
	v_mfma_f32_16x16x32_bf16 v[14:17], v[168:171], v[202:205], v[14:17]
	v_mfma_f32_16x16x32_bf16 v[10:13], v[178:181], v[202:205], v[10:13]
	v_mfma_f32_16x16x32_bf16 v[6:9], v[168:171], v[210:213], v[6:9]
	v_mfma_f32_16x16x32_bf16 v[2:5], v[178:181], v[210:213], v[2:5]
	v_mfma_f32_16x16x32_bf16 v[30:33], v[174:177], v[190:193], v[30:33]
	v_mfma_f32_16x16x32_bf16 v[26:29], v[182:185], v[190:193], v[26:29]
	v_mfma_f32_16x16x32_bf16 v[22:25], v[174:177], v[198:201], v[22:25]
	v_mfma_f32_16x16x32_bf16 v[18:21], v[182:185], v[198:201], v[18:21]
	v_mfma_f32_16x16x32_bf16 v[14:17], v[174:177], v[206:209], v[14:17]
	v_mfma_f32_16x16x32_bf16 v[10:13], v[182:185], v[206:209], v[10:13]
	v_mfma_f32_16x16x32_bf16 v[6:9], v[174:177], v[214:217], v[6:9]
	v_mfma_f32_16x16x32_bf16 v[2:5], v[182:185], v[214:217], v[2:5]
	s_barrier
; #define PG8_BAR __builtin_amdgcn_s_barrier()
;     ...
;         for (int t = 2; t < nt; t += 2) PG8_KITER(t);
;         if constexpr (ALIGN_EPI) { if (wr == 0) PG8_BAR; }
	s_setprio 0
	ds_read_b128 v[134:137], v132
	ds_read_b128 v[138:141], v132 offset:1024
	ds_read_b128 v[142:145], v132 offset:2048
	ds_read_b128 v[146:149], v132 offset:3072
	ds_read_b128 v[168:171], v133
	ds_read_b128 v[174:177], v133 offset:1024
	ds_read_b128 v[178:181], v133 offset:2048
	ds_read_b128 v[182:185], v133 offset:3072
	s_add_u32 s58, s64, 0x80000
	s_addc_u32 s59, s65, 0
	s_mov_b32 m0, s69
	s_nop 0
	global_load_lds_dwordx4 v150, s[100:101]
	s_mov_b32 m0, s70
	s_nop 0
	global_load_lds_dwordx4 v154, s[100:101]
	s_mov_b32 m0, s71
	ds_read_b128 v[186:189], v172 offset:32768
	ds_read_b128 v[190:193], v172 offset:33792
	ds_read_b128 v[194:197], v172 offset:34816
	ds_read_b128 v[198:201], v172 offset:35840
	ds_read_b128 v[202:205], v172 offset:36864
	ds_read_b128 v[206:209], v172 offset:37888
	ds_read_b128 v[210:213], v172 offset:38912
	ds_read_b128 v[214:217], v172 offset:39936
	global_load_lds_dwordx4 v150, s[58:59]
	s_mov_b32 m0, s72
	s_nop 0
	global_load_lds_dwordx4 v154, s[58:59]
	s_waitcnt vmcnt(8)
	s_waitcnt lgkmcnt(0)
	s_setprio 1
	s_barrier
	v_mfma_f32_16x16x32_bf16 v[126:129], v[134:137], v[186:189], v[126:129]
	v_mfma_f32_16x16x32_bf16 v[122:125], v[142:145], v[186:189], v[122:125]
	v_mfma_f32_16x16x32_bf16 v[118:121], v[134:137], v[194:197], v[118:121]
	v_mfma_f32_16x16x32_bf16 v[114:117], v[142:145], v[194:197], v[114:117]
	v_mfma_f32_16x16x32_bf16 v[110:113], v[134:137], v[202:205], v[110:113]
	v_mfma_f32_16x16x32_bf16 v[106:109], v[142:145], v[202:205], v[106:109]
	v_mfma_f32_16x16x32_bf16 v[102:105], v[134:137], v[210:213], v[102:105]
	v_mfma_f32_16x16x32_bf16 v[98:101], v[142:145], v[210:213], v[98:101]
	v_mfma_f32_16x16x32_bf16 v[126:129], v[138:141], v[190:193], v[126:129]
	v_mfma_f32_16x16x32_bf16 v[122:125], v[146:149], v[190:193], v[122:125]
	v_mfma_f32_16x16x32_bf16 v[118:121], v[138:141], v[198:201], v[118:121]
	v_mfma_f32_16x16x32_bf16 v[114:117], v[146:149], v[198:201], v[114:117]
	v_mfma_f32_16x16x32_bf16 v[110:113], v[138:141], v[206:209], v[110:113]
	v_mfma_f32_16x16x32_bf16 v[106:109], v[146:149], v[206:209], v[106:109]
	v_mfma_f32_16x16x32_bf16 v[102:105], v[138:141], v[214:217], v[102:105]
	v_mfma_f32_16x16x32_bf16 v[98:101], v[146:149], v[214:217], v[98:101]
	v_mfma_f32_16x16x32_bf16 v[94:97], v[168:171], v[186:189], v[94:97]
	v_mfma_f32_16x16x32_bf16 v[90:93], v[178:181], v[186:189], v[90:93]
	v_mfma_f32_16x16x32_bf16 v[86:89], v[168:171], v[194:197], v[86:89]
	v_mfma_f32_16x16x32_bf16 v[82:85], v[178:181], v[194:197], v[82:85]
	v_mfma_f32_16x16x32_bf16 v[78:81], v[168:171], v[202:205], v[78:81]
	v_mfma_f32_16x16x32_bf16 v[74:77], v[178:181], v[202:205], v[74:77]
	v_mfma_f32_16x16x32_bf16 v[70:73], v[168:171], v[210:213], v[70:73]
	v_mfma_f32_16x16x32_bf16 v[66:69], v[178:181], v[210:213], v[66:69]
	v_mfma_f32_16x16x32_bf16 v[94:97], v[174:177], v[190:193], v[94:97]
	v_mfma_f32_16x16x32_bf16 v[90:93], v[182:185], v[190:193], v[90:93]
	v_mfma_f32_16x16x32_bf16 v[86:89], v[174:177], v[198:201], v[86:89]
	v_mfma_f32_16x16x32_bf16 v[82:85], v[182:185], v[198:201], v[82:85]
	v_mfma_f32_16x16x32_bf16 v[78:81], v[174:177], v[206:209], v[78:81]
	v_mfma_f32_16x16x32_bf16 v[74:77], v[182:185], v[206:209], v[74:77]
	v_mfma_f32_16x16x32_bf16 v[70:73], v[174:177], v[214:217], v[70:73]
	v_mfma_f32_16x16x32_bf16 v[66:69], v[182:185], v[214:217], v[66:69]
	s_barrier
	s_setprio 0
	s_mov_b32 m0, s47
	s_add_u32 s98, s98, 0x80
	s_addc_u32 s99, s99, 0
	s_add_u32 s100, s100, 0x80
	s_addc_u32 s101, s101, 0
	s_add_u32 s50, s50, 0x80080
	ds_read_b128 v[186:189], v172 offset:49152
	ds_read_b128 v[190:193], v172 offset:50176
	ds_read_b128 v[194:197], v172 offset:51200
	ds_read_b128 v[198:201], v172 offset:52224
	ds_read_b128 v[202:205], v172 offset:53248
	ds_read_b128 v[206:209], v172 offset:54272
	ds_read_b128 v[210:213], v172 offset:55296
	ds_read_b128 v[214:217], v172 offset:56320
	global_load_lds_dwordx4 v152, s[98:99]
	s_mov_b32 m0, s53
	s_addc_u32 s51, s51, 0
	global_load_lds_dwordx4 v156, s[98:99]
	s_mov_b32 m0, s55
	s_nop 0
	global_load_lds_dwordx4 v152, s[50:51]
	s_mov_b32 m0, s56
	s_nop 0
	global_load_lds_dwordx4 v156, s[50:51]
	s_waitcnt vmcnt(6)
	s_waitcnt lgkmcnt(0)
	s_setprio 1
	s_barrier
	v_mfma_f32_16x16x32_bf16 v[62:65], v[134:137], v[186:189], v[62:65]
	v_mfma_f32_16x16x32_bf16 v[58:61], v[142:145], v[186:189], v[58:61]
	v_mfma_f32_16x16x32_bf16 v[54:57], v[134:137], v[194:197], v[54:57]
	v_mfma_f32_16x16x32_bf16 v[50:53], v[142:145], v[194:197], v[50:53]
	v_mfma_f32_16x16x32_bf16 v[46:49], v[134:137], v[202:205], v[46:49]
	v_mfma_f32_16x16x32_bf16 v[42:45], v[142:145], v[202:205], v[42:45]
	v_mfma_f32_16x16x32_bf16 v[38:41], v[134:137], v[210:213], v[38:41]
	v_mfma_f32_16x16x32_bf16 v[34:37], v[142:145], v[210:213], v[34:37]
	v_mfma_f32_16x16x32_bf16 v[62:65], v[138:141], v[190:193], v[62:65]
	v_mfma_f32_16x16x32_bf16 v[58:61], v[146:149], v[190:193], v[58:61]
	v_mfma_f32_16x16x32_bf16 v[54:57], v[138:141], v[198:201], v[54:57]
	v_mfma_f32_16x16x32_bf16 v[50:53], v[146:149], v[198:201], v[50:53]
	v_mfma_f32_16x16x32_bf16 v[46:49], v[138:141], v[206:209], v[46:49]
	v_mfma_f32_16x16x32_bf16 v[42:45], v[146:149], v[206:209], v[42:45]
	v_mfma_f32_16x16x32_bf16 v[38:41], v[138:141], v[214:217], v[38:41]
	v_mfma_f32_16x16x32_bf16 v[34:37], v[146:149], v[214:217], v[34:37]
	v_mfma_f32_16x16x32_bf16 v[30:33], v[168:171], v[186:189], v[30:33]
	v_mfma_f32_16x16x32_bf16 v[26:29], v[178:181], v[186:189], v[26:29]
	v_mfma_f32_16x16x32_bf16 v[22:25], v[168:171], v[194:197], v[22:25]
	v_mfma_f32_16x16x32_bf16 v[18:21], v[178:181], v[194:197], v[18:21]
	v_mfma_f32_16x16x32_bf16 v[14:17], v[168:171], v[202:205], v[14:17]
	v_mfma_f32_16x16x32_bf16 v[10:13], v[178:181], v[202:205], v[10:13]
	v_mfma_f32_16x16x32_bf16 v[6:9], v[168:171], v[210:213], v[6:9]
	v_mfma_f32_16x16x32_bf16 v[2:5], v[178:181], v[210:213], v[2:5]
	v_mfma_f32_16x16x32_bf16 v[30:33], v[174:177], v[190:193], v[30:33]
	v_mfma_f32_16x16x32_bf16 v[26:29], v[182:185], v[190:193], v[26:29]
	v_mfma_f32_16x16x32_bf16 v[22:25], v[174:177], v[198:201], v[22:25]
	v_mfma_f32_16x16x32_bf16 v[18:21], v[182:185], v[198:201], v[18:21]
	v_mfma_f32_16x16x32_bf16 v[14:17], v[174:177], v[206:209], v[14:17]
	v_mfma_f32_16x16x32_bf16 v[10:13], v[182:185], v[206:209], v[10:13]
	v_mfma_f32_16x16x32_bf16 v[6:9], v[174:177], v[214:217], v[6:9]
	v_mfma_f32_16x16x32_bf16 v[2:5], v[182:185], v[214:217], v[2:5]
	s_barrier
	s_setprio 0
	s_add_i32 s26, s26, 2
	s_add_u32 s62, s62, 0x100
	s_addc_u32 s63, s63, 0
	s_add_u32 s14, s14, 0x100
	s_addc_u32 s15, s15, 0
	s_cmp_gt_u32 s26, 29
	s_cbranch_scc0 .LBB0_930
	s_mov_b32 m0, s77
	s_nop 0
	global_load_lds_dwordx4 v150, s[100:101]
	s_mov_b32 m0, s78
	s_nop 0
	global_load_lds_dwordx4 v154, s[100:101]
	s_and_b64 vcc, exec, s[18:19]
	s_cbranch_vccz .LBB0_933
	s_barrier

;     __host__ __device__ bool next(int i, Unit& u) const { if (!StaticOrder::next(i >> 1, u)) return false; u.seg = i & 1; return true; }
;     ...
;         const bool has_next = S.next(ui + 1, nxt);
;         const char* nA = has_next ? PG8_APTR(nxt) : cA; const char* nB = has_next ? PG8_BPTR(nxt) : cB;
.LBB0_1013:
	s_ashr_i32 s29, s28, 31
	ds_read_b128 v[2:5], v182
	ds_read_b128 v[6:9], v182 offset:1024
	ds_read_b128 v[10:13], v182 offset:2048
	ds_read_b128 v[14:17], v182 offset:3072
	ds_read_b128 v[18:21], v183
	ds_read_b128 v[22:25], v183 offset:1024
	ds_read_b128 v[26:29], v183 offset:2048
	ds_read_b128 v[30:33], v183 offset:3072
	s_lshl_b64 s[14:15], s[28:29], 21
	s_add_u32 s30, s24, s14
	s_addc_u32 s31, s25, s15
	s_and_b64 s[14:15], s[4:5], exec
	s_cselect_b32 s29, s31, s49
	s_cselect_b32 s41, s30, s48
	s_and_b32 s0, s66, 0x7fffffff
	s_lshl_b64 s[14:15], s[0:1], 21
	s_add_u32 s38, s10, s14
	s_addc_u32 s39, s11, s15
	s_and_b64 s[14:15], s[4:5], exec
	s_cselect_b32 s0, s39, s43
	s_cselect_b32 s68, s38, s42
	s_add_u32 s14, s48, 0x100080
	s_addc_u32 s15, s49, 0
	s_mov_b32 m0, s61
	v_lshl_add_u64 v[66:67], s[14:15], 0, v[154:155]
	ds_read_b128 v[34:37], v184
	ds_read_b128 v[38:41], v184 offset:1024
	ds_read_b128 v[42:45], v184 offset:2048
	ds_read_b128 v[46:49], v184 offset:3072
	ds_read_b128 v[50:53], v184 offset:4096
	ds_read_b128 v[54:57], v184 offset:5120
	ds_read_b128 v[58:61], v184 offset:6144
	ds_read_b128 v[62:65], v184 offset:7168
	global_load_lds_dwordx4 v[66:67], off
	v_lshl_add_u64 v[66:67], s[14:15], 0, v[158:159]
	s_mov_b32 m0, s62
	s_nop 0
	global_load_lds_dwordx4 v[66:67], off
	s_waitcnt vmcnt(8)
	s_waitcnt lgkmcnt(0)
	s_setprio 1
	s_barrier
	v_mfma_f32_16x16x32_bf16 v[90:93], v[2:5], v[58:61], 0
	v_mfma_f32_16x16x32_bf16 v[66:69], v[2:5], v[34:37], 0
	v_mfma_f32_16x16x32_bf16 v[70:73], v[10:13], v[34:37], 0
	v_mfma_f32_16x16x32_bf16 v[74:77], v[2:5], v[42:45], 0
	v_mfma_f32_16x16x32_bf16 v[78:81], v[10:13], v[42:45], 0
	v_mfma_f32_16x16x32_bf16 v[82:85], v[2:5], v[50:53], 0
	v_mfma_f32_16x16x32_bf16 v[86:89], v[10:13], v[50:53], 0
	v_mfma_f32_16x16x32_bf16 v[98:101], v[6:9], v[62:65], v[90:93]
	v_mfma_f32_16x16x32_bf16 v[90:93], v[10:13], v[58:61], 0
	v_mfma_f32_16x16x32_bf16 v[66:69], v[6:9], v[38:41], v[66:69]
	v_mfma_f32_16x16x32_bf16 v[70:73], v[14:17], v[38:41], v[70:73]
	v_mfma_f32_16x16x32_bf16 v[74:77], v[6:9], v[46:49], v[74:77]
	v_mfma_f32_16x16x32_bf16 v[78:81], v[14:17], v[46:49], v[78:81]
	v_mfma_f32_16x16x32_bf16 v[82:85], v[6:9], v[54:57], v[82:85]
	v_mfma_f32_16x16x32_bf16 v[86:89], v[14:17], v[54:57], v[86:89]
	v_mfma_f32_16x16x32_bf16 v[102:105], v[14:17], v[62:65], v[90:93]
	v_mfma_f32_16x16x32_bf16 v[90:93], v[18:21], v[34:37], 0
	v_mfma_f32_16x16x32_bf16 v[34:37], v[26:29], v[34:37], 0
	v_mfma_f32_16x16x32_bf16 v[114:117], v[22:25], v[38:41], v[90:93]
	v_mfma_f32_16x16x32_bf16 v[34:37], v[30:33], v[38:41], v[34:37]
	v_mfma_f32_16x16x32_bf16 v[38:41], v[18:21], v[42:45], 0
	v_mfma_f32_16x16x32_bf16 v[42:45], v[26:29], v[42:45], 0
	v_mfma_f32_16x16x32_bf16 v[38:41], v[22:25], v[46:49], v[38:41]
	v_mfma_f32_16x16x32_bf16 v[42:45], v[30:33], v[46:49], v[42:45]
	v_mfma_f32_16x16x32_bf16 v[46:49], v[18:21], v[50:53], 0
	v_mfma_f32_16x16x32_bf16 v[50:53], v[26:29], v[50:53], 0
	v_mfma_f32_16x16x32_bf16 v[46:49], v[22:25], v[54:57], v[46:49]
	v_mfma_f32_16x16x32_bf16 v[50:53], v[30:33], v[54:57], v[50:53]
	v_mfma_f32_16x16x32_bf16 v[54:57], v[18:21], v[58:61], 0
	v_mfma_f32_16x16x32_bf16 v[58:61], v[26:29], v[58:61], 0
	v_mfma_f32_16x16x32_bf16 v[54:57], v[22:25], v[62:65], v[54:57]
	v_mfma_f32_16x16x32_bf16 v[58:61], v[30:33], v[62:65], v[58:61]
	s_barrier
	s_setprio 0
	v_lshl_add_u64 v[152:153], s[42:43], 0, v[156:157]
	s_mov_b32 m0, s63
	v_lshl_add_u64 v[130:131], v[152:153], 0, s[20:21]
	v_lshl_add_u64 v[250:251], s[42:43], 0, v[160:161]
	s_add_u32 s14, s42, 0x100100
	ds_read_b128 v[62:65], v184 offset:16384
	ds_read_b128 v[90:93], v184 offset:17408
	ds_read_b128 v[94:97], v184 offset:18432
	ds_read_b128 v[106:109], v184 offset:19456
	ds_read_b128 v[110:113], v184 offset:20480
	ds_read_b128 v[118:121], v184 offset:21504
	ds_read_b128 v[122:125], v184 offset:22528
	ds_read_b128 v[126:129], v184 offset:23552
	global_load_lds_dwordx4 v[130:131], off
	v_lshl_add_u64 v[130:131], v[250:251], 0, s[20:21]
	s_mov_b32 m0, s64
	s_addc_u32 s15, s43, 0
	s_add_i32 s69, s60, s12
	global_load_lds_dwordx4 v[130:131], off
	v_lshl_add_u64 v[130:131], s[14:15], 0, v[156:157]
	s_mov_b32 m0, s69
	s_add_i32 s46, s69, 0x2000
	global_load_lds_dwordx4 v[130:131], off
	v_lshl_add_u64 v[130:131], s[14:15], 0, v[160:161]
	s_mov_b32 m0, s46
	v_lshl_add_u64 v[252:253], s[48:49], 0, v[154:155]
	global_load_lds_dwordx4 v[130:131], off
	v_lshl_add_u64 v[130:131], v[252:253], 0, s[20:21]
	s_mov_b32 m0, s13
	v_lshl_add_u64 v[166:167], s[48:49], 0, v[158:159]
	global_load_lds_dwordx4 v[130:131], off
	v_lshl_add_u64 v[130:131], v[166:167], 0, s[20:21]
	s_mov_b32 m0, s33
	s_nop 0
	global_load_lds_dwordx4 v[130:131], off
	s_waitcnt vmcnt(8)
	s_waitcnt lgkmcnt(0)
	s_setprio 1
	s_barrier
	v_mfma_f32_16x16x32_bf16 v[130:133], v[2:5], v[62:65], 0
	v_mfma_f32_16x16x32_bf16 v[140:143], v[2:5], v[94:97], 0
	v_mfma_f32_16x16x32_bf16 v[148:151], v[2:5], v[110:113], 0
	v_mfma_f32_16x16x32_bf16 v[2:5], v[2:5], v[122:125], 0
	v_mfma_f32_16x16x32_bf16 v[132:135], v[6:9], v[90:93], v[130:133]
	v_mfma_f32_16x16x32_bf16 v[140:143], v[6:9], v[106:109], v[140:143]
	v_mfma_f32_16x16x32_bf16 v[148:151], v[6:9], v[118:121], v[148:151]
	v_mfma_f32_16x16x32_bf16 v[2:5], v[6:9], v[126:129], v[2:5]
	v_mfma_f32_16x16x32_bf16 v[6:9], v[10:13], v[122:125], 0
	v_mfma_f32_16x16x32_bf16 v[136:139], v[10:13], v[62:65], 0
	v_mfma_f32_16x16x32_bf16 v[144:147], v[10:13], v[94:97], 0
	v_mfma_f32_16x16x32_bf16 v[170:173], v[10:13], v[110:113], 0
	v_mfma_f32_16x16x32_bf16 v[6:9], v[14:17], v[126:129], v[6:9]
	v_mfma_f32_16x16x32_bf16 v[136:139], v[14:17], v[90:93], v[136:139]
	v_mfma_f32_16x16x32_bf16 v[144:147], v[14:17], v[106:109], v[144:147]
	v_mfma_f32_16x16x32_bf16 v[170:173], v[14:17], v[118:121], v[170:173]
	v_mfma_f32_16x16x32_bf16 v[10:13], v[18:21], v[62:65], 0
	v_mfma_f32_16x16x32_bf16 v[174:177], v[22:25], v[90:93], v[10:13]
	v_mfma_f32_16x16x32_bf16 v[10:13], v[26:29], v[62:65], 0
	v_mfma_f32_16x16x32_bf16 v[178:181], v[30:33], v[90:93], v[10:13]
	v_mfma_f32_16x16x32_bf16 v[10:13], v[18:21], v[94:97], 0
	v_mfma_f32_16x16x32_bf16 v[186:189], v[22:25], v[106:109], v[10:13]
	v_mfma_f32_16x16x32_bf16 v[10:13], v[26:29], v[94:97], 0
	v_mfma_f32_16x16x32_bf16 v[190:193], v[30:33], v[106:109], v[10:13]
	v_mfma_f32_16x16x32_bf16 v[10:13], v[18:21], v[110:113], 0
	v_mfma_f32_16x16x32_bf16 v[194:197], v[22:25], v[118:121], v[10:13]
	v_mfma_f32_16x16x32_bf16 v[10:13], v[26:29], v[110:113], 0
	v_mfma_f32_16x16x32_bf16 v[198:201], v[30:33], v[118:121], v[10:13]
	v_mfma_f32_16x16x32_bf16 v[10:13], v[18:21], v[122:125], 0
	v_mfma_f32_16x16x32_bf16 v[202:205], v[22:25], v[126:129], v[10:13]
	v_mfma_f32_16x16x32_bf16 v[10:13], v[26:29], v[122:125], 0
	v_mfma_f32_16x16x32_bf16 v[206:209], v[30:33], v[126:129], v[10:13]
	s_barrier
	s_setprio 0
	s_add_i32 s47, 0, 0x18000
	s_add_i32 s56, 0, 0x1c000
	v_add_u32_e32 v130, s47, v1
	v_add_u32_e32 v131, s56, v1
	s_nop 0
	ds_read_b128 v[10:13], v130
	ds_read_b128 v[14:17], v130 offset:1024
	ds_read_b128 v[18:21], v130 offset:2048
	ds_read_b128 v[22:25], v130 offset:3072
	ds_read_b128 v[210:213], v131
	ds_read_b128 v[214:217], v131 offset:1024
	ds_read_b128 v[218:221], v131 offset:2048
	ds_read_b128 v[222:225], v131 offset:3072
	s_add_u32 s14, s48, 0x100100
	s_addc_u32 s15, s49, 0
	s_mov_b32 m0, s52
	v_lshl_add_u64 v[90:91], s[14:15], 0, v[154:155]
	ds_read_b128 v[26:29], v184 offset:32768
	ds_read_b128 v[30:33], v184 offset:33792
	ds_read_b128 v[62:65], v184 offset:34816
	ds_read_b128 v[226:229], v184 offset:35840
	ds_read_b128 v[230:233], v184 offset:36864
	ds_read_b128 v[234:237], v184 offset:37888
	ds_read_b128 v[238:241], v184 offset:38912
	ds_read_b128 v[242:245], v184 offset:39936
	global_load_lds_dwordx4 v[90:91], off
	v_lshl_add_u64 v[90:91], s[14:15], 0, v[158:159]
	s_mov_b32 m0, s53
	s_nop 0
	global_load_lds_dwordx4 v[90:91], off
	s_waitcnt vmcnt(8)
	s_waitcnt lgkmcnt(0)
	s_setprio 1
	s_barrier
	v_mfma_f32_16x16x32_bf16 v[66:69], v[10:13], v[26:29], v[66:69]
	v_mfma_f32_16x16x32_bf16 v[122:125], v[14:17], v[30:33], v[66:69]
	v_mfma_f32_16x16x32_bf16 v[66:69], v[18:21], v[26:29], v[70:73]
	v_mfma_f32_16x16x32_bf16 v[118:121], v[22:25], v[30:33], v[66:69]
	v_mfma_f32_16x16x32_bf16 v[66:69], v[10:13], v[62:65], v[74:77]
	v_mfma_f32_16x16x32_bf16 v[110:113], v[14:17], v[226:229], v[66:69]
	v_mfma_f32_16x16x32_bf16 v[66:69], v[18:21], v[62:65], v[78:81]
	v_mfma_f32_16x16x32_bf16 v[106:109], v[22:25], v[226:229], v[66:69]
	v_mfma_f32_16x16x32_bf16 v[66:69], v[10:13], v[230:233], v[82:85]
	v_mfma_f32_16x16x32_bf16 v[94:97], v[14:17], v[234:237], v[66:69]
	v_mfma_f32_16x16x32_bf16 v[66:69], v[18:21], v[230:233], v[86:89]
	v_mfma_f32_16x16x32_bf16 v[90:93], v[22:25], v[234:237], v[66:69]
	v_mfma_f32_16x16x32_bf16 v[66:69], v[10:13], v[238:241], v[98:101]
	v_mfma_f32_16x16x32_bf16 v[78:81], v[14:17], v[242:245], v[66:69]
	v_mfma_f32_16x16x32_bf16 v[66:69], v[18:21], v[238:241], v[102:105]
	v_mfma_f32_16x16x32_bf16 v[74:77], v[22:25], v[242:245], v[66:69]
	v_mfma_f32_16x16x32_bf16 v[66:69], v[210:213], v[26:29], v[114:117]
	v_mfma_f32_16x16x32_bf16 v[26:29], v[218:221], v[26:29], v[34:37]
	v_mfma_f32_16x16x32_bf16 v[114:117], v[222:225], v[30:33], v[26:29]
	v_mfma_f32_16x16x32_bf16 v[26:29], v[210:213], v[62:65], v[38:41]
	v_mfma_f32_16x16x32_bf16 v[102:105], v[214:217], v[226:229], v[26:29]
	v_mfma_f32_16x16x32_bf16 v[26:29], v[218:221], v[62:65], v[42:45]
	v_mfma_f32_16x16x32_bf16 v[98:101], v[222:225], v[226:229], v[26:29]
	v_mfma_f32_16x16x32_bf16 v[26:29], v[210:213], v[230:233], v[46:49]
	v_mfma_f32_16x16x32_bf16 v[86:89], v[214:217], v[234:237], v[26:29]
	v_mfma_f32_16x16x32_bf16 v[26:29], v[218:221], v[230:233], v[50:53]
	v_mfma_f32_16x16x32_bf16 v[82:85], v[222:225], v[234:237], v[26:29]
	v_mfma_f32_16x16x32_bf16 v[26:29], v[210:213], v[238:241], v[54:57]
	v_mfma_f32_16x16x32_bf16 v[70:73], v[214:217], v[242:245], v[26:29]
	v_mfma_f32_16x16x32_bf16 v[26:29], v[218:221], v[238:241], v[58:61]
	v_mfma_f32_16x16x32_bf16 v[126:129], v[214:217], v[30:33], v[66:69]
	v_mfma_f32_16x16x32_bf16 v[66:69], v[222:225], v[242:245], v[26:29]
	s_barrier
	s_setprio 0
	s_add_i32 s47, s47, s12
	s_add_i32 s70, s47, 0x2000
	s_nop 1
	v_lshl_add_u64 v[26:27], v[152:153], 0, s[22:23]
	s_mov_b32 m0, s47
	s_add_u32 s14, s42, 0x100180
	ds_read_b128 v[34:37], v184 offset:49152
	ds_read_b128 v[38:41], v184 offset:50176
	ds_read_b128 v[226:229], v184 offset:51200
	ds_read_b128 v[230:233], v184 offset:52224
	ds_read_b128 v[234:237], v184 offset:53248
	ds_read_b128 v[238:241], v184 offset:54272
	ds_read_b128 v[242:245], v184 offset:55296
	ds_read_b128 v[246:249], v184 offset:56320
	global_load_lds_dwordx4 v[26:27], off
	v_lshl_add_u64 v[26:27], v[250:251], 0, s[22:23]
	s_mov_b32 m0, s70
	s_addc_u32 s15, s43, 0
	s_add_i32 s56, s56, s12
	global_load_lds_dwordx4 v[26:27], off
	v_lshl_add_u64 v[26:27], s[14:15], 0, v[156:157]
	s_mov_b32 m0, s56
	s_add_i32 s57, s56, 0x2000
	global_load_lds_dwordx4 v[26:27], off
	v_lshl_add_u64 v[26:27], s[14:15], 0, v[160:161]
	s_mov_b32 m0, s57
	s_nop 0
	global_load_lds_dwordx4 v[26:27], off
	v_lshl_add_u64 v[26:27], v[252:253], 0, s[22:23]
	s_mov_b32 m0, s54
	s_nop 0
	global_load_lds_dwordx4 v[26:27], off
	v_lshl_add_u64 v[26:27], v[166:167], 0, s[22:23]
	s_mov_b32 m0, s55
	s_nop 0
	global_load_lds_dwordx4 v[26:27], off
	s_waitcnt vmcnt(8)
	s_waitcnt lgkmcnt(0)
	s_setprio 1
	s_barrier
	v_mfma_f32_16x16x32_bf16 v[26:29], v[10:13], v[34:37], v[132:135]
	v_mfma_f32_16x16x32_bf16 v[58:61], v[14:17], v[38:41], v[26:29]
	v_mfma_f32_16x16x32_bf16 v[26:29], v[18:21], v[34:37], v[136:139]
	v_mfma_f32_16x16x32_bf16 v[54:57], v[22:25], v[38:41], v[26:29]
	v_mfma_f32_16x16x32_bf16 v[26:29], v[10:13], v[226:229], v[140:143]
	v_mfma_f32_16x16x32_bf16 v[46:49], v[14:17], v[230:233], v[26:29]
	v_mfma_f32_16x16x32_bf16 v[26:29], v[18:21], v[226:229], v[144:147]
	v_mfma_f32_16x16x32_bf16 v[42:45], v[22:25], v[230:233], v[26:29]
	v_mfma_f32_16x16x32_bf16 v[26:29], v[10:13], v[234:237], v[148:151]
	v_mfma_f32_16x16x32_bf16 v[2:5], v[10:13], v[242:245], v[2:5]
	v_mfma_f32_16x16x32_bf16 v[30:33], v[14:17], v[238:241], v[26:29]
	v_mfma_f32_16x16x32_bf16 v[26:29], v[18:21], v[234:237], v[170:173]
	v_mfma_f32_16x16x32_bf16 v[14:17], v[14:17], v[246:249], v[2:5]
	v_mfma_f32_16x16x32_bf16 v[2:5], v[18:21], v[242:245], v[6:9]
	v_mfma_f32_16x16x32_bf16 v[26:29], v[22:25], v[238:241], v[26:29]
	v_mfma_f32_16x16x32_bf16 v[10:13], v[22:25], v[246:249], v[2:5]
	v_mfma_f32_16x16x32_bf16 v[2:5], v[210:213], v[34:37], v[174:177]
	v_mfma_f32_16x16x32_bf16 v[62:65], v[214:217], v[38:41], v[2:5]
	v_mfma_f32_16x16x32_bf16 v[2:5], v[218:221], v[34:37], v[178:181]
	v_mfma_f32_16x16x32_bf16 v[50:53], v[222:225], v[38:41], v[2:5]
	v_mfma_f32_16x16x32_bf16 v[2:5], v[210:213], v[226:229], v[186:189]
	v_mfma_f32_16x16x32_bf16 v[38:41], v[214:217], v[230:233], v[2:5]
	v_mfma_f32_16x16x32_bf16 v[2:5], v[218:221], v[226:229], v[190:193]
	v_mfma_f32_16x16x32_bf16 v[34:37], v[222:225], v[230:233], v[2:5]
	v_mfma_f32_16x16x32_bf16 v[2:5], v[210:213], v[234:237], v[194:197]
	v_mfma_f32_16x16x32_bf16 v[22:25], v[214:217], v[238:241], v[2:5]
	v_mfma_f32_16x16x32_bf16 v[2:5], v[218:221], v[234:237], v[198:201]
	v_mfma_f32_16x16x32_bf16 v[18:21], v[222:225], v[238:241], v[2:5]
	v_mfma_f32_16x16x32_bf16 v[2:5], v[210:213], v[242:245], v[202:205]
	v_mfma_f32_16x16x32_bf16 v[6:9], v[214:217], v[246:249], v[2:5]
	v_mfma_f32_16x16x32_bf16 v[2:5], v[218:221], v[242:245], v[206:209]
	v_mfma_f32_16x16x32_bf16 v[2:5], v[222:225], v[246:249], v[2:5]
	s_barrier
	s_setprio 0
	s_add_u32 s48, s48, 0x100180
	s_addc_u32 s49, s49, 0
	s_add_u32 s14, s42, 0x200
	s_addc_u32 s15, s43, 0
	s_mov_b32 s26, 0

.Lrb2_skip_31798:
	s_mov_b32 m0, s61
	ds_read_b128 v[186:189], v184
	ds_read_b128 v[190:193], v184 offset:1024
	ds_read_b128 v[194:197], v184 offset:2048
	ds_read_b128 v[198:201], v184 offset:3072
	ds_read_b128 v[202:205], v184 offset:4096
	ds_read_b128 v[206:209], v184 offset:5120
	ds_read_b128 v[210:213], v184 offset:6144
	ds_read_b128 v[214:217], v184 offset:7168
	global_load_lds_dwordx4 v162, s[48:49]
	s_mov_b32 m0, s62
	s_nop 0
	global_load_lds_dwordx4 v164, s[48:49]
	s_waitcnt vmcnt(8)
	s_waitcnt lgkmcnt(0)
	s_setprio 1
	s_barrier
	v_mfma_f32_16x16x32_bf16 v[122:125], v[132:135], v[186:189], v[122:125]
	v_mfma_f32_16x16x32_bf16 v[118:121], v[140:143], v[186:189], v[118:121]
	v_mfma_f32_16x16x32_bf16 v[110:113], v[132:135], v[194:197], v[110:113]
	v_mfma_f32_16x16x32_bf16 v[106:109], v[140:143], v[194:197], v[106:109]
	v_mfma_f32_16x16x32_bf16 v[94:97], v[132:135], v[202:205], v[94:97]
	v_mfma_f32_16x16x32_bf16 v[90:93], v[140:143], v[202:205], v[90:93]
	v_mfma_f32_16x16x32_bf16 v[78:81], v[132:135], v[210:213], v[78:81]
	v_mfma_f32_16x16x32_bf16 v[74:77], v[140:143], v[210:213], v[74:77]
	v_mfma_f32_16x16x32_bf16 v[122:125], v[136:139], v[190:193], v[122:125]
	v_mfma_f32_16x16x32_bf16 v[118:121], v[144:147], v[190:193], v[118:121]
	v_mfma_f32_16x16x32_bf16 v[110:113], v[136:139], v[198:201], v[110:113]
	v_mfma_f32_16x16x32_bf16 v[106:109], v[144:147], v[198:201], v[106:109]
	v_mfma_f32_16x16x32_bf16 v[94:97], v[136:139], v[206:209], v[94:97]
	v_mfma_f32_16x16x32_bf16 v[90:93], v[144:147], v[206:209], v[90:93]
	v_mfma_f32_16x16x32_bf16 v[78:81], v[136:139], v[214:217], v[78:81]
	v_mfma_f32_16x16x32_bf16 v[74:77], v[144:147], v[214:217], v[74:77]
	v_mfma_f32_16x16x32_bf16 v[126:129], v[148:151], v[186:189], v[126:129]
	v_mfma_f32_16x16x32_bf16 v[114:117], v[174:177], v[186:189], v[114:117]
	v_mfma_f32_16x16x32_bf16 v[102:105], v[148:151], v[194:197], v[102:105]
	v_mfma_f32_16x16x32_bf16 v[98:101], v[174:177], v[194:197], v[98:101]
	v_mfma_f32_16x16x32_bf16 v[86:89], v[148:151], v[202:205], v[86:89]
	v_mfma_f32_16x16x32_bf16 v[82:85], v[174:177], v[202:205], v[82:85]
	v_mfma_f32_16x16x32_bf16 v[70:73], v[148:151], v[210:213], v[70:73]
	v_mfma_f32_16x16x32_bf16 v[66:69], v[174:177], v[210:213], v[66:69]
	v_mfma_f32_16x16x32_bf16 v[126:129], v[170:173], v[190:193], v[126:129]
	v_mfma_f32_16x16x32_bf16 v[114:117], v[178:181], v[190:193], v[114:117]
	v_mfma_f32_16x16x32_bf16 v[102:105], v[170:173], v[198:201], v[102:105]
	v_mfma_f32_16x16x32_bf16 v[98:101], v[178:181], v[198:201], v[98:101]
	v_mfma_f32_16x16x32_bf16 v[86:89], v[170:173], v[206:209], v[86:89]
	v_mfma_f32_16x16x32_bf16 v[82:85], v[178:181], v[206:209], v[82:85]
	v_mfma_f32_16x16x32_bf16 v[70:73], v[170:173], v[214:217], v[70:73]
	v_mfma_f32_16x16x32_bf16 v[66:69], v[178:181], v[214:217], v[66:69]
	s_barrier
	s_setprio 0
	s_mov_b32 m0, s63
	s_mov_b64 s[98:99], s[42:43]
	s_add_u32 s72, s42, 0x100000
	ds_read_b128 v[186:189], v184 offset:16384
	ds_read_b128 v[190:193], v184 offset:17408
	ds_read_b128 v[194:197], v184 offset:18432
	ds_read_b128 v[198:201], v184 offset:19456
	ds_read_b128 v[202:205], v184 offset:20480
	ds_read_b128 v[206:209], v184 offset:21504
	ds_read_b128 v[210:213], v184 offset:22528
	ds_read_b128 v[214:217], v184 offset:23552
	global_load_lds_dwordx4 v156, s[42:43]
	s_mov_b32 m0, s64
	s_addc_u32 s73, s43, 0
	global_load_lds_dwordx4 v160, s[42:43]
	s_mov_b32 m0, s69
	s_mov_b64 s[100:101], s[50:51]
	global_load_lds_dwordx4 v156, s[72:73]
	s_mov_b32 m0, s46
	s_nop 0
	global_load_lds_dwordx4 v160, s[72:73]
	s_waitcnt vmcnt(6)
	s_waitcnt lgkmcnt(0)
	s_setprio 1
	s_barrier
	v_mfma_f32_16x16x32_bf16 v[58:61], v[132:135], v[186:189], v[58:61]
	v_mfma_f32_16x16x32_bf16 v[54:57], v[140:143], v[186:189], v[54:57]
	v_mfma_f32_16x16x32_bf16 v[46:49], v[132:135], v[194:197], v[46:49]
	v_mfma_f32_16x16x32_bf16 v[42:45], v[140:143], v[194:197], v[42:45]
	v_mfma_f32_16x16x32_bf16 v[30:33], v[132:135], v[202:205], v[30:33]
	v_mfma_f32_16x16x32_bf16 v[26:29], v[140:143], v[202:205], v[26:29]
	v_mfma_f32_16x16x32_bf16 v[14:17], v[132:135], v[210:213], v[14:17]
	v_mfma_f32_16x16x32_bf16 v[10:13], v[140:143], v[210:213], v[10:13]
	v_mfma_f32_16x16x32_bf16 v[58:61], v[136:139], v[190:193], v[58:61]
	v_mfma_f32_16x16x32_bf16 v[54:57], v[144:147], v[190:193], v[54:57]
	v_mfma_f32_16x16x32_bf16 v[46:49], v[136:139], v[198:201], v[46:49]
	v_mfma_f32_16x16x32_bf16 v[42:45], v[144:147], v[198:201], v[42:45]
	v_mfma_f32_16x16x32_bf16 v[30:33], v[136:139], v[206:209], v[30:33]
	v_mfma_f32_16x16x32_bf16 v[26:29], v[144:147], v[206:209], v[26:29]
	v_mfma_f32_16x16x32_bf16 v[14:17], v[136:139], v[214:217], v[14:17]
	v_mfma_f32_16x16x32_bf16 v[10:13], v[144:147], v[214:217], v[10:13]
	v_mfma_f32_16x16x32_bf16 v[62:65], v[148:151], v[186:189], v[62:65]
	v_mfma_f32_16x16x32_bf16 v[50:53], v[174:177], v[186:189], v[50:53]
	v_mfma_f32_16x16x32_bf16 v[38:41], v[148:151], v[194:197], v[38:41]
	v_mfma_f32_16x16x32_bf16 v[34:37], v[174:177], v[194:197], v[34:37]
	v_mfma_f32_16x16x32_bf16 v[22:25], v[148:151], v[202:205], v[22:25]
	v_mfma_f32_16x16x32_bf16 v[18:21], v[174:177], v[202:205], v[18:21]
	v_mfma_f32_16x16x32_bf16 v[6:9], v[148:151], v[210:213], v[6:9]
	v_mfma_f32_16x16x32_bf16 v[2:5], v[174:177], v[210:213], v[2:5]
	v_mfma_f32_16x16x32_bf16 v[62:65], v[170:173], v[190:193], v[62:65]
	v_mfma_f32_16x16x32_bf16 v[50:53], v[178:181], v[190:193], v[50:53]
	v_mfma_f32_16x16x32_bf16 v[38:41], v[170:173], v[198:201], v[38:41]
	v_mfma_f32_16x16x32_bf16 v[34:37], v[178:181], v[198:201], v[34:37]
	v_mfma_f32_16x16x32_bf16 v[22:25], v[170:173], v[206:209], v[22:25]
	v_mfma_f32_16x16x32_bf16 v[18:21], v[178:181], v[206:209], v[18:21]
	v_mfma_f32_16x16x32_bf16 v[6:9], v[170:173], v[214:217], v[6:9]
	v_mfma_f32_16x16x32_bf16 v[2:5], v[178:181], v[214:217], v[2:5]
	s_barrier
; #define PG8_BAR __builtin_amdgcn_s_barrier()
;     ...
;         for (int t = 2; t < nt; t += 2) PG8_KITER(t);
;         if constexpr (ALIGN_EPI) { if (wr == 0) PG8_BAR; }
	s_setprio 0
	ds_read_b128 v[132:135], v130
	ds_read_b128 v[136:139], v130 offset:1024
	ds_read_b128 v[140:143], v130 offset:2048
	ds_read_b128 v[144:147], v130 offset:3072
	ds_read_b128 v[148:151], v131
	ds_read_b128 v[170:173], v131 offset:1024
	ds_read_b128 v[174:177], v131 offset:2048
	ds_read_b128 v[178:181], v131 offset:3072
	s_add_u32 s50, s50, 0x100000
	s_addc_u32 s51, s51, 0
	s_mov_b32 m0, s13
	s_nop 0
	global_load_lds_dwordx4 v154, s[100:101]
	s_mov_b32 m0, s33
	s_nop 0
	global_load_lds_dwordx4 v158, s[100:101]
	s_mov_b32 m0, s52
	ds_read_b128 v[186:189], v184 offset:32768
	ds_read_b128 v[190:193], v184 offset:33792
	ds_read_b128 v[194:197], v184 offset:34816
	ds_read_b128 v[198:201], v184 offset:35840
	ds_read_b128 v[202:205], v184 offset:36864
	ds_read_b128 v[206:209], v184 offset:37888
	ds_read_b128 v[210:213], v184 offset:38912
	ds_read_b128 v[214:217], v184 offset:39936
	global_load_lds_dwordx4 v154, s[50:51]
	s_mov_b32 m0, s53
	s_nop 0
	global_load_lds_dwordx4 v158, s[50:51]
	s_waitcnt vmcnt(8)
	s_waitcnt lgkmcnt(0)
	s_setprio 1
	s_barrier
	v_mfma_f32_16x16x32_bf16 v[122:125], v[132:135], v[186:189], v[122:125]
	v_mfma_f32_16x16x32_bf16 v[118:121], v[140:143], v[186:189], v[118:121]
	v_mfma_f32_16x16x32_bf16 v[110:113], v[132:135], v[194:197], v[110:113]
	v_mfma_f32_16x16x32_bf16 v[106:109], v[140:143], v[194:197], v[106:109]
	v_mfma_f32_16x16x32_bf16 v[94:97], v[132:135], v[202:205], v[94:97]
	v_mfma_f32_16x16x32_bf16 v[90:93], v[140:143], v[202:205], v[90:93]
	v_mfma_f32_16x16x32_bf16 v[78:81], v[132:135], v[210:213], v[78:81]
	v_mfma_f32_16x16x32_bf16 v[74:77], v[140:143], v[210:213], v[74:77]
	v_mfma_f32_16x16x32_bf16 v[122:125], v[136:139], v[190:193], v[122:125]
	v_mfma_f32_16x16x32_bf16 v[118:121], v[144:147], v[190:193], v[118:121]
	v_mfma_f32_16x16x32_bf16 v[110:113], v[136:139], v[198:201], v[110:113]
	v_mfma_f32_16x16x32_bf16 v[106:109], v[144:147], v[198:201], v[106:109]
	v_mfma_f32_16x16x32_bf16 v[94:97], v[136:139], v[206:209], v[94:97]
	v_mfma_f32_16x16x32_bf16 v[90:93], v[144:147], v[206:209], v[90:93]
	v_mfma_f32_16x16x32_bf16 v[78:81], v[136:139], v[214:217], v[78:81]
	v_mfma_f32_16x16x32_bf16 v[74:77], v[144:147], v[214:217], v[74:77]
	v_mfma_f32_16x16x32_bf16 v[126:129], v[148:151], v[186:189], v[126:129]
	v_mfma_f32_16x16x32_bf16 v[114:117], v[174:177], v[186:189], v[114:117]
	v_mfma_f32_16x16x32_bf16 v[102:105], v[148:151], v[194:197], v[102:105]
	v_mfma_f32_16x16x32_bf16 v[98:101], v[174:177], v[194:197], v[98:101]
	v_mfma_f32_16x16x32_bf16 v[86:89], v[148:151], v[202:205], v[86:89]
	v_mfma_f32_16x16x32_bf16 v[82:85], v[174:177], v[202:205], v[82:85]
	v_mfma_f32_16x16x32_bf16 v[70:73], v[148:151], v[210:213], v[70:73]
	v_mfma_f32_16x16x32_bf16 v[66:69], v[174:177], v[210:213], v[66:69]
	v_mfma_f32_16x16x32_bf16 v[126:129], v[170:173], v[190:193], v[126:129]
	v_mfma_f32_16x16x32_bf16 v[114:117], v[178:181], v[190:193], v[114:117]
	v_mfma_f32_16x16x32_bf16 v[102:105], v[170:173], v[198:201], v[102:105]
	v_mfma_f32_16x16x32_bf16 v[98:101], v[178:181], v[198:201], v[98:101]
	v_mfma_f32_16x16x32_bf16 v[86:89], v[170:173], v[206:209], v[86:89]
	v_mfma_f32_16x16x32_bf16 v[82:85], v[178:181], v[206:209], v[82:85]
	v_mfma_f32_16x16x32_bf16 v[70:73], v[170:173], v[214:217], v[70:73]
	v_mfma_f32_16x16x32_bf16 v[66:69], v[178:181], v[214:217], v[66:69]
	s_barrier
	s_setprio 0
	s_mov_b32 m0, s47
	s_add_u32 s98, s98, 0x80
	s_addc_u32 s99, s99, 0
	s_add_u32 s100, s100, 0x80
	s_addc_u32 s101, s101, 0
	s_add_u32 s42, s42, 0x100080
	ds_read_b128 v[186:189], v184 offset:49152
	ds_read_b128 v[190:193], v184 offset:50176
	ds_read_b128 v[194:197], v184 offset:51200
	ds_read_b128 v[198:201], v184 offset:52224
	ds_read_b128 v[202:205], v184 offset:53248
	ds_read_b128 v[206:209], v184 offset:54272
	ds_read_b128 v[210:213], v184 offset:55296
	ds_read_b128 v[214:217], v184 offset:56320
	global_load_lds_dwordx4 v156, s[98:99]
	s_mov_b32 m0, s70
	s_addc_u32 s43, s43, 0
	global_load_lds_dwordx4 v160, s[98:99]
	s_mov_b32 m0, s56
	s_nop 0
	global_load_lds_dwordx4 v156, s[42:43]
	s_mov_b32 m0, s57
	s_nop 0
	global_load_lds_dwordx4 v160, s[42:43]
	s_waitcnt vmcnt(6)
	s_waitcnt lgkmcnt(0)
	s_setprio 1
	s_barrier
	v_mfma_f32_16x16x32_bf16 v[58:61], v[132:135], v[186:189], v[58:61]
	v_mfma_f32_16x16x32_bf16 v[54:57], v[140:143], v[186:189], v[54:57]
	v_mfma_f32_16x16x32_bf16 v[46:49], v[132:135], v[194:197], v[46:49]
	v_mfma_f32_16x16x32_bf16 v[42:45], v[140:143], v[194:197], v[42:45]
	v_mfma_f32_16x16x32_bf16 v[30:33], v[132:135], v[202:205], v[30:33]
	v_mfma_f32_16x16x32_bf16 v[26:29], v[140:143], v[202:205], v[26:29]
	v_mfma_f32_16x16x32_bf16 v[14:17], v[132:135], v[210:213], v[14:17]
	v_mfma_f32_16x16x32_bf16 v[10:13], v[140:143], v[210:213], v[10:13]
	v_mfma_f32_16x16x32_bf16 v[58:61], v[136:139], v[190:193], v[58:61]
	v_mfma_f32_16x16x32_bf16 v[54:57], v[144:147], v[190:193], v[54:57]
	v_mfma_f32_16x16x32_bf16 v[46:49], v[136:139], v[198:201], v[46:49]
	v_mfma_f32_16x16x32_bf16 v[42:45], v[144:147], v[198:201], v[42:45]
	v_mfma_f32_16x16x32_bf16 v[30:33], v[136:139], v[206:209], v[30:33]
	v_mfma_f32_16x16x32_bf16 v[26:29], v[144:147], v[206:209], v[26:29]
	v_mfma_f32_16x16x32_bf16 v[14:17], v[136:139], v[214:217], v[14:17]
	v_mfma_f32_16x16x32_bf16 v[10:13], v[144:147], v[214:217], v[10:13]
	v_mfma_f32_16x16x32_bf16 v[62:65], v[148:151], v[186:189], v[62:65]
	v_mfma_f32_16x16x32_bf16 v[50:53], v[174:177], v[186:189], v[50:53]
	v_mfma_f32_16x16x32_bf16 v[38:41], v[148:151], v[194:197], v[38:41]
	v_mfma_f32_16x16x32_bf16 v[34:37], v[174:177], v[194:197], v[34:37]
	v_mfma_f32_16x16x32_bf16 v[22:25], v[148:151], v[202:205], v[22:25]
	v_mfma_f32_16x16x32_bf16 v[18:21], v[174:177], v[202:205], v[18:21]
	v_mfma_f32_16x16x32_bf16 v[6:9], v[148:151], v[210:213], v[6:9]
	v_mfma_f32_16x16x32_bf16 v[2:5], v[174:177], v[210:213], v[2:5]
	v_mfma_f32_16x16x32_bf16 v[62:65], v[170:173], v[190:193], v[62:65]
	v_mfma_f32_16x16x32_bf16 v[50:53], v[178:181], v[190:193], v[50:53]
	v_mfma_f32_16x16x32_bf16 v[38:41], v[170:173], v[198:201], v[38:41]
	v_mfma_f32_16x16x32_bf16 v[34:37], v[178:181], v[198:201], v[34:37]
	v_mfma_f32_16x16x32_bf16 v[22:25], v[170:173], v[206:209], v[22:25]
	v_mfma_f32_16x16x32_bf16 v[18:21], v[178:181], v[206:209], v[18:21]
	v_mfma_f32_16x16x32_bf16 v[6:9], v[170:173], v[214:217], v[6:9]
	v_mfma_f32_16x16x32_bf16 v[2:5], v[178:181], v[214:217], v[2:5]
	s_barrier
	s_setprio 0
	s_add_i32 s26, s26, 2
	s_add_u32 s48, s48, 0x100
	s_addc_u32 s49, s49, 0
	s_add_u32 s14, s14, 0x100
	s_addc_u32 s15, s15, 0
	s_cmp_gt_u32 s26, 61
	s_cbranch_scc0 .LBB0_1014
	s_mov_b32 m0, s54
	s_nop 0
	global_load_lds_dwordx4 v154, s[100:101]
	s_mov_b32 m0, s55
	s_nop 0
	global_load_lds_dwordx4 v158, s[100:101]
	s_and_b64 vcc, exec, s[18:19]
	s_cbranch_vccz .LBB0_1017
	s_barrier

.LBB0_1109:
	ds_read_b128 v[2:5], v148
	ds_read_b128 v[6:9], v148 offset:1024
	ds_read_b128 v[10:13], v148 offset:2048
	ds_read_b128 v[14:17], v148 offset:3072
	ds_read_b128 v[18:21], v149
	ds_read_b128 v[22:25], v149 offset:1024
	ds_read_b128 v[26:29], v149 offset:2048
	ds_read_b128 v[30:33], v149 offset:3072
	s_add_u32 s0, s54, 0x100080
	s_addc_u32 s1, s55, 0
	s_add_i32 s41, s33, 0xc000
	v_lshl_add_u64 v[66:67], s[0:1], 0, v[130:131]
	s_mov_b32 m0, s41
	s_add_i32 s73, s33, 0xe000
	ds_read_b128 v[34:37], v150
	ds_read_b128 v[38:41], v150 offset:1024
	ds_read_b128 v[42:45], v150 offset:2048
	ds_read_b128 v[46:49], v150 offset:3072
	ds_read_b128 v[50:53], v150 offset:4096
	ds_read_b128 v[54:57], v150 offset:5120
	ds_read_b128 v[58:61], v150 offset:6144
	ds_read_b128 v[62:65], v150 offset:7168
	global_load_lds_dwordx4 v[66:67], off
	v_lshl_add_u64 v[66:67], s[0:1], 0, v[132:133]
	s_mov_b32 m0, s73
	s_nop 0
	global_load_lds_dwordx4 v[66:67], off
	s_waitcnt vmcnt(8)
	s_waitcnt lgkmcnt(0)
	s_setprio 1
	s_barrier
	v_mfma_f32_16x16x32_bf16 v[86:89], v[10:13], v[50:53], 0
	v_mfma_f32_16x16x32_bf16 v[90:93], v[14:17], v[54:57], v[86:89]
	v_mfma_f32_16x16x32_bf16 v[86:89], v[2:5], v[58:61], 0
	v_mfma_f32_16x16x32_bf16 v[66:69], v[2:5], v[34:37], 0
	v_mfma_f32_16x16x32_bf16 v[70:73], v[10:13], v[34:37], 0
	v_mfma_f32_16x16x32_bf16 v[74:77], v[2:5], v[42:45], 0
	v_mfma_f32_16x16x32_bf16 v[78:81], v[10:13], v[42:45], 0
	v_mfma_f32_16x16x32_bf16 v[82:85], v[2:5], v[50:53], 0
	v_mfma_f32_16x16x32_bf16 v[94:97], v[6:9], v[62:65], v[86:89]
	v_mfma_f32_16x16x32_bf16 v[86:89], v[10:13], v[58:61], 0
	v_mfma_f32_16x16x32_bf16 v[66:69], v[6:9], v[38:41], v[66:69]
	v_mfma_f32_16x16x32_bf16 v[70:73], v[14:17], v[38:41], v[70:73]
	v_mfma_f32_16x16x32_bf16 v[74:77], v[6:9], v[46:49], v[74:77]
	v_mfma_f32_16x16x32_bf16 v[78:81], v[14:17], v[46:49], v[78:81]
	v_mfma_f32_16x16x32_bf16 v[82:85], v[6:9], v[54:57], v[82:85]
	v_mfma_f32_16x16x32_bf16 v[106:109], v[14:17], v[62:65], v[86:89]
	v_mfma_f32_16x16x32_bf16 v[86:89], v[18:21], v[34:37], 0
	v_mfma_f32_16x16x32_bf16 v[34:37], v[26:29], v[34:37], 0
	v_mfma_f32_16x16x32_bf16 v[110:113], v[22:25], v[38:41], v[86:89]
	v_mfma_f32_16x16x32_bf16 v[34:37], v[30:33], v[38:41], v[34:37]
	v_mfma_f32_16x16x32_bf16 v[38:41], v[18:21], v[42:45], 0
	v_mfma_f32_16x16x32_bf16 v[42:45], v[26:29], v[42:45], 0
	v_mfma_f32_16x16x32_bf16 v[38:41], v[22:25], v[46:49], v[38:41]
	v_mfma_f32_16x16x32_bf16 v[42:45], v[30:33], v[46:49], v[42:45]
	v_mfma_f32_16x16x32_bf16 v[46:49], v[18:21], v[50:53], 0
	v_mfma_f32_16x16x32_bf16 v[50:53], v[26:29], v[50:53], 0
	v_mfma_f32_16x16x32_bf16 v[46:49], v[22:25], v[54:57], v[46:49]
	v_mfma_f32_16x16x32_bf16 v[50:53], v[30:33], v[54:57], v[50:53]
	v_mfma_f32_16x16x32_bf16 v[54:57], v[18:21], v[58:61], 0
	v_mfma_f32_16x16x32_bf16 v[152:155], v[22:25], v[62:65], v[54:57]
	v_mfma_f32_16x16x32_bf16 v[54:57], v[26:29], v[58:61], 0
	v_mfma_f32_16x16x32_bf16 v[58:61], v[30:33], v[62:65], v[54:57]
	s_barrier
	s_setprio 0
	s_add_i32 s74, s64, s13
	v_lshl_add_u64 v[146:147], s[52:53], 0, v[130:131]
	s_add_i32 s75, s74, 0x2000
	v_lshl_add_u64 v[126:127], v[146:147], 0, s[20:21]
	s_mov_b32 m0, s74
	v_lshl_add_u64 v[248:249], s[52:53], 0, v[132:133]
	s_add_u32 s0, s52, 0x100100
	ds_read_b128 v[54:57], v150 offset:16384
	ds_read_b128 v[62:65], v150 offset:17408
	ds_read_b128 v[86:89], v150 offset:18432
	ds_read_b128 v[98:101], v150 offset:19456
	ds_read_b128 v[102:105], v150 offset:20480
	ds_read_b128 v[114:117], v150 offset:21504
	ds_read_b128 v[118:121], v150 offset:22528
	ds_read_b128 v[122:125], v150 offset:23552
	global_load_lds_dwordx4 v[126:127], off
	v_lshl_add_u64 v[126:127], v[248:249], 0, s[20:21]
	s_mov_b32 m0, s75
	s_addc_u32 s1, s53, 0
	s_add_i32 s76, s65, s13
	global_load_lds_dwordx4 v[126:127], off
	v_lshl_add_u64 v[126:127], s[0:1], 0, v[130:131]
	s_mov_b32 m0, s76
	s_add_i32 s46, s76, 0x2000
	global_load_lds_dwordx4 v[126:127], off
	v_lshl_add_u64 v[126:127], s[0:1], 0, v[132:133]
	s_mov_b32 m0, s46
	v_lshl_add_u64 v[250:251], s[54:55], 0, v[130:131]
	global_load_lds_dwordx4 v[126:127], off
	v_lshl_add_u64 v[126:127], v[250:251], 0, s[20:21]
	s_mov_b32 m0, s33
	v_lshl_add_u64 v[252:253], s[54:55], 0, v[132:133]
	global_load_lds_dwordx4 v[126:127], off
	v_lshl_add_u64 v[126:127], v[252:253], 0, s[20:21]
	s_mov_b32 m0, s51
	s_nop 0
	global_load_lds_dwordx4 v[126:127], off
	s_waitcnt vmcnt(8)
	s_waitcnt lgkmcnt(0)
	s_setprio 1
	s_barrier
	v_mfma_f32_16x16x32_bf16 v[126:129], v[2:5], v[54:57], 0
	v_mfma_f32_16x16x32_bf16 v[156:159], v[6:9], v[62:65], v[126:129]
	v_mfma_f32_16x16x32_bf16 v[126:129], v[10:13], v[54:57], 0
	v_mfma_f32_16x16x32_bf16 v[160:163], v[14:17], v[62:65], v[126:129]
	v_mfma_f32_16x16x32_bf16 v[126:129], v[2:5], v[86:89], 0
	v_mfma_f32_16x16x32_bf16 v[164:167], v[6:9], v[98:101], v[126:129]
	v_mfma_f32_16x16x32_bf16 v[126:129], v[10:13], v[86:89], 0
	v_mfma_f32_16x16x32_bf16 v[168:171], v[14:17], v[98:101], v[126:129]
	v_mfma_f32_16x16x32_bf16 v[126:129], v[2:5], v[102:105], 0
	v_mfma_f32_16x16x32_bf16 v[2:5], v[2:5], v[118:121], 0
	v_mfma_f32_16x16x32_bf16 v[172:175], v[6:9], v[114:117], v[126:129]
	v_mfma_f32_16x16x32_bf16 v[2:5], v[6:9], v[122:125], v[2:5]
	v_mfma_f32_16x16x32_bf16 v[6:9], v[10:13], v[118:121], 0
	v_mfma_f32_16x16x32_bf16 v[126:129], v[10:13], v[102:105], 0
	v_mfma_f32_16x16x32_bf16 v[10:13], v[14:17], v[122:125], v[6:9]
	v_mfma_f32_16x16x32_bf16 v[176:179], v[14:17], v[114:117], v[126:129]
	v_mfma_f32_16x16x32_bf16 v[6:9], v[18:21], v[54:57], 0
	v_mfma_f32_16x16x32_bf16 v[14:17], v[22:25], v[62:65], v[6:9]
	v_mfma_f32_16x16x32_bf16 v[6:9], v[26:29], v[54:57], 0
	v_mfma_f32_16x16x32_bf16 v[180:183], v[30:33], v[62:65], v[6:9]
	v_mfma_f32_16x16x32_bf16 v[6:9], v[18:21], v[86:89], 0
	v_mfma_f32_16x16x32_bf16 v[184:187], v[22:25], v[98:101], v[6:9]
	v_mfma_f32_16x16x32_bf16 v[6:9], v[26:29], v[86:89], 0
	v_mfma_f32_16x16x32_bf16 v[188:191], v[30:33], v[98:101], v[6:9]
	v_mfma_f32_16x16x32_bf16 v[6:9], v[18:21], v[102:105], 0
	v_mfma_f32_16x16x32_bf16 v[192:195], v[22:25], v[114:117], v[6:9]
	v_mfma_f32_16x16x32_bf16 v[6:9], v[26:29], v[102:105], 0
	v_mfma_f32_16x16x32_bf16 v[196:199], v[30:33], v[114:117], v[6:9]
	v_mfma_f32_16x16x32_bf16 v[6:9], v[18:21], v[118:121], 0
	v_mfma_f32_16x16x32_bf16 v[200:203], v[22:25], v[122:125], v[6:9]
	v_mfma_f32_16x16x32_bf16 v[6:9], v[26:29], v[118:121], 0
	v_mfma_f32_16x16x32_bf16 v[204:207], v[30:33], v[122:125], v[6:9]
	s_barrier
	s_setprio 0
	s_add_i32 s47, 0, 0x18000
	s_add_i32 s56, 0, 0x1c000
	v_add_u32_e32 v134, s47, v1
	v_add_u32_e32 v144, s56, v1
	s_nop 0
	ds_read_b128 v[6:9], v134
	ds_read_b128 v[18:21], v134 offset:1024
	ds_read_b128 v[30:33], v134 offset:2048
	ds_read_b128 v[208:211], v134 offset:3072
	ds_read_b128 v[212:215], v144
	ds_read_b128 v[216:219], v144 offset:1024
	ds_read_b128 v[220:223], v144 offset:2048
	ds_read_b128 v[224:227], v144 offset:3072
	s_add_u32 s0, s54, 0x100100
	s_addc_u32 s1, s55, 0
	s_mov_b32 m0, s58
	v_lshl_add_u64 v[54:55], s[0:1], 0, v[130:131]
	ds_read_b128 v[22:25], v150 offset:32768
	ds_read_b128 v[26:29], v150 offset:33792
	ds_read_b128 v[62:65], v150 offset:34816
	ds_read_b128 v[228:231], v150 offset:35840
	ds_read_b128 v[232:235], v150 offset:36864
	ds_read_b128 v[236:239], v150 offset:37888
	ds_read_b128 v[240:243], v150 offset:38912
	ds_read_b128 v[244:247], v150 offset:39936
	global_load_lds_dwordx4 v[54:55], off
	v_lshl_add_u64 v[54:55], s[0:1], 0, v[132:133]
	s_mov_b32 m0, s59
	s_nop 0
	global_load_lds_dwordx4 v[54:55], off
	s_waitcnt vmcnt(8)
	s_waitcnt lgkmcnt(0)
	s_setprio 1
	s_barrier
	v_mfma_f32_16x16x32_bf16 v[54:57], v[6:9], v[22:25], v[66:69]
	v_mfma_f32_16x16x32_bf16 v[118:121], v[18:21], v[26:29], v[54:57]
	v_mfma_f32_16x16x32_bf16 v[54:57], v[30:33], v[22:25], v[70:73]
	v_mfma_f32_16x16x32_bf16 v[114:117], v[208:211], v[26:29], v[54:57]
	v_mfma_f32_16x16x32_bf16 v[54:57], v[6:9], v[62:65], v[74:77]
	v_mfma_f32_16x16x32_bf16 v[102:105], v[18:21], v[228:231], v[54:57]
	v_mfma_f32_16x16x32_bf16 v[54:57], v[30:33], v[62:65], v[78:81]
	v_mfma_f32_16x16x32_bf16 v[98:101], v[208:211], v[228:231], v[54:57]
	v_mfma_f32_16x16x32_bf16 v[54:57], v[6:9], v[232:235], v[82:85]
	v_mfma_f32_16x16x32_bf16 v[86:89], v[18:21], v[236:239], v[54:57]
	v_mfma_f32_16x16x32_bf16 v[54:57], v[30:33], v[232:235], v[90:93]
	v_mfma_f32_16x16x32_bf16 v[82:85], v[208:211], v[236:239], v[54:57]
	v_mfma_f32_16x16x32_bf16 v[54:57], v[6:9], v[240:243], v[94:97]
	v_mfma_f32_16x16x32_bf16 v[74:77], v[18:21], v[244:247], v[54:57]
	v_mfma_f32_16x16x32_bf16 v[54:57], v[30:33], v[240:243], v[106:109]
	v_mfma_f32_16x16x32_bf16 v[54:57], v[208:211], v[244:247], v[54:57]
	v_mfma_f32_16x16x32_bf16 v[66:69], v[212:215], v[22:25], v[110:113]
	v_mfma_f32_16x16x32_bf16 v[22:25], v[220:223], v[22:25], v[34:37]
	v_mfma_f32_16x16x32_bf16 v[122:125], v[224:227], v[26:29], v[22:25]
	v_mfma_f32_16x16x32_bf16 v[22:25], v[212:215], v[62:65], v[38:41]
	v_mfma_f32_16x16x32_bf16 v[110:113], v[216:219], v[228:231], v[22:25]
	v_mfma_f32_16x16x32_bf16 v[22:25], v[220:223], v[62:65], v[42:45]
	v_mfma_f32_16x16x32_bf16 v[106:109], v[224:227], v[228:231], v[22:25]
	v_mfma_f32_16x16x32_bf16 v[22:25], v[212:215], v[232:235], v[46:49]
	v_mfma_f32_16x16x32_bf16 v[94:97], v[216:219], v[236:239], v[22:25]
	v_mfma_f32_16x16x32_bf16 v[22:25], v[220:223], v[232:235], v[50:53]
	v_mfma_f32_16x16x32_bf16 v[90:93], v[224:227], v[236:239], v[22:25]
	v_mfma_f32_16x16x32_bf16 v[22:25], v[212:215], v[240:243], v[152:155]
	v_mfma_f32_16x16x32_bf16 v[70:73], v[216:219], v[244:247], v[22:25]
	v_mfma_f32_16x16x32_bf16 v[22:25], v[220:223], v[240:243], v[58:61]
	v_mfma_f32_16x16x32_bf16 v[126:129], v[216:219], v[26:29], v[66:69]
	v_mfma_f32_16x16x32_bf16 v[50:53], v[224:227], v[244:247], v[22:25]
	s_barrier
	s_setprio 0
	s_add_i32 s47, s47, s13
	s_add_i32 s77, s47, 0x2000
	s_nop 1
	v_lshl_add_u64 v[22:23], v[146:147], 0, s[22:23]
	s_mov_b32 m0, s47
	s_add_u32 s0, s52, 0x100180
	ds_read_b128 v[34:37], v150 offset:49152
	ds_read_b128 v[46:49], v150 offset:50176
	ds_read_b128 v[152:155], v150 offset:51200
	ds_read_b128 v[228:231], v150 offset:52224
	ds_read_b128 v[232:235], v150 offset:53248
	ds_read_b128 v[236:239], v150 offset:54272
	ds_read_b128 v[240:243], v150 offset:55296
	ds_read_b128 v[244:247], v150 offset:56320
	global_load_lds_dwordx4 v[22:23], off
	v_lshl_add_u64 v[22:23], v[248:249], 0, s[22:23]
	s_mov_b32 m0, s77
	s_addc_u32 s1, s53, 0
	s_add_i32 s56, s56, s13
	global_load_lds_dwordx4 v[22:23], off
	v_lshl_add_u64 v[22:23], s[0:1], 0, v[130:131]
	s_mov_b32 m0, s56
	s_add_i32 s57, s56, 0x2000
	global_load_lds_dwordx4 v[22:23], off
	v_lshl_add_u64 v[22:23], s[0:1], 0, v[132:133]
	s_mov_b32 m0, s57
	s_nop 0
	global_load_lds_dwordx4 v[22:23], off
	v_lshl_add_u64 v[22:23], v[250:251], 0, s[22:23]
	s_mov_b32 m0, s61
	s_nop 0
	global_load_lds_dwordx4 v[22:23], off
	v_lshl_add_u64 v[22:23], v[252:253], 0, s[22:23]
	s_mov_b32 m0, s62
	s_nop 0
	global_load_lds_dwordx4 v[22:23], off
	s_waitcnt vmcnt(8)
	s_waitcnt lgkmcnt(0)
	s_setprio 1
	s_barrier
	v_mfma_f32_16x16x32_bf16 v[22:25], v[6:9], v[34:37], v[156:159]
	v_mfma_f32_16x16x32_bf16 v[66:69], v[18:21], v[46:49], v[22:25]
	v_mfma_f32_16x16x32_bf16 v[22:25], v[30:33], v[34:37], v[160:163]
	v_mfma_f32_16x16x32_bf16 v[62:65], v[208:211], v[46:49], v[22:25]
	v_mfma_f32_16x16x32_bf16 v[22:25], v[6:9], v[152:155], v[164:167]
	v_mfma_f32_16x16x32_bf16 v[42:45], v[18:21], v[228:231], v[22:25]
	v_mfma_f32_16x16x32_bf16 v[22:25], v[30:33], v[152:155], v[168:171]
	v_mfma_f32_16x16x32_bf16 v[38:41], v[208:211], v[228:231], v[22:25]
	v_mfma_f32_16x16x32_bf16 v[22:25], v[6:9], v[232:235], v[172:175]
	v_mfma_f32_16x16x32_bf16 v[2:5], v[6:9], v[240:243], v[2:5]
	v_mfma_f32_16x16x32_bf16 v[26:29], v[18:21], v[236:239], v[22:25]
	v_mfma_f32_16x16x32_bf16 v[22:25], v[30:33], v[232:235], v[176:179]
	v_mfma_f32_16x16x32_bf16 v[6:9], v[18:21], v[244:247], v[2:5]
	v_mfma_f32_16x16x32_bf16 v[2:5], v[30:33], v[240:243], v[10:13]
	v_mfma_f32_16x16x32_bf16 v[22:25], v[208:211], v[236:239], v[22:25]
	v_mfma_f32_16x16x32_bf16 v[2:5], v[208:211], v[244:247], v[2:5]
	v_mfma_f32_16x16x32_bf16 v[10:13], v[212:215], v[34:37], v[14:17]
	v_mfma_f32_16x16x32_bf16 v[78:81], v[216:219], v[46:49], v[10:13]
	v_mfma_f32_16x16x32_bf16 v[10:13], v[220:223], v[34:37], v[180:183]
	v_mfma_f32_16x16x32_bf16 v[58:61], v[224:227], v[46:49], v[10:13]
	v_mfma_f32_16x16x32_bf16 v[10:13], v[212:215], v[152:155], v[184:187]
	v_mfma_f32_16x16x32_bf16 v[46:49], v[216:219], v[228:231], v[10:13]
	v_mfma_f32_16x16x32_bf16 v[10:13], v[220:223], v[152:155], v[188:191]
	v_mfma_f32_16x16x32_bf16 v[34:37], v[224:227], v[228:231], v[10:13]
	v_mfma_f32_16x16x32_bf16 v[10:13], v[212:215], v[232:235], v[192:195]
	v_mfma_f32_16x16x32_bf16 v[30:33], v[216:219], v[236:239], v[10:13]
	v_mfma_f32_16x16x32_bf16 v[10:13], v[220:223], v[232:235], v[196:199]
	v_mfma_f32_16x16x32_bf16 v[18:21], v[224:227], v[236:239], v[10:13]
	v_mfma_f32_16x16x32_bf16 v[10:13], v[212:215], v[240:243], v[200:203]
	v_mfma_f32_16x16x32_bf16 v[14:17], v[216:219], v[244:247], v[10:13]
	v_mfma_f32_16x16x32_bf16 v[10:13], v[220:223], v[240:243], v[204:207]
	v_mfma_f32_16x16x32_bf16 v[10:13], v[224:227], v[244:247], v[10:13]
	s_barrier
	s_setprio 0
	s_add_u32 s0, s54, 0x100180
	s_addc_u32 s1, s55, 0
	s_add_u32 s14, s52, 0x200
	s_addc_u32 s15, s53, 0
	s_mov_b32 s26, 0

.Lrb2_skip_34078:
	s_mov_b32 m0, s41
	ds_read_b128 v[184:187], v150
	ds_read_b128 v[188:191], v150 offset:1024
	ds_read_b128 v[192:195], v150 offset:2048
	ds_read_b128 v[196:199], v150 offset:3072
	ds_read_b128 v[200:203], v150 offset:4096
	ds_read_b128 v[204:207], v150 offset:5120
	ds_read_b128 v[208:211], v150 offset:6144
	ds_read_b128 v[212:215], v150 offset:7168
	global_load_lds_dwordx4 v136, s[0:1]
	s_mov_b32 m0, s73
	s_nop 0
	global_load_lds_dwordx4 v138, s[0:1]
	s_waitcnt vmcnt(8)
	s_waitcnt lgkmcnt(0)
	s_setprio 1
	s_barrier
	v_mfma_f32_16x16x32_bf16 v[118:121], v[152:155], v[184:187], v[118:121]
	v_mfma_f32_16x16x32_bf16 v[114:117], v[160:163], v[184:187], v[114:117]
	v_mfma_f32_16x16x32_bf16 v[102:105], v[152:155], v[192:195], v[102:105]
	v_mfma_f32_16x16x32_bf16 v[98:101], v[160:163], v[192:195], v[98:101]
	v_mfma_f32_16x16x32_bf16 v[86:89], v[152:155], v[200:203], v[86:89]
	v_mfma_f32_16x16x32_bf16 v[82:85], v[160:163], v[200:203], v[82:85]
	v_mfma_f32_16x16x32_bf16 v[74:77], v[152:155], v[208:211], v[74:77]
	v_mfma_f32_16x16x32_bf16 v[54:57], v[160:163], v[208:211], v[54:57]
	v_mfma_f32_16x16x32_bf16 v[118:121], v[156:159], v[188:191], v[118:121]
	v_mfma_f32_16x16x32_bf16 v[114:117], v[164:167], v[188:191], v[114:117]
	v_mfma_f32_16x16x32_bf16 v[102:105], v[156:159], v[196:199], v[102:105]
	v_mfma_f32_16x16x32_bf16 v[98:101], v[164:167], v[196:199], v[98:101]
	v_mfma_f32_16x16x32_bf16 v[86:89], v[156:159], v[204:207], v[86:89]
	v_mfma_f32_16x16x32_bf16 v[82:85], v[164:167], v[204:207], v[82:85]
	v_mfma_f32_16x16x32_bf16 v[74:77], v[156:159], v[212:215], v[74:77]
	v_mfma_f32_16x16x32_bf16 v[54:57], v[164:167], v[212:215], v[54:57]
	v_mfma_f32_16x16x32_bf16 v[126:129], v[168:171], v[184:187], v[126:129]
	v_mfma_f32_16x16x32_bf16 v[122:125], v[176:179], v[184:187], v[122:125]
	v_mfma_f32_16x16x32_bf16 v[110:113], v[168:171], v[192:195], v[110:113]
	v_mfma_f32_16x16x32_bf16 v[106:109], v[176:179], v[192:195], v[106:109]
	v_mfma_f32_16x16x32_bf16 v[94:97], v[168:171], v[200:203], v[94:97]
	v_mfma_f32_16x16x32_bf16 v[90:93], v[176:179], v[200:203], v[90:93]
	v_mfma_f32_16x16x32_bf16 v[70:73], v[168:171], v[208:211], v[70:73]
	v_mfma_f32_16x16x32_bf16 v[50:53], v[176:179], v[208:211], v[50:53]
	v_mfma_f32_16x16x32_bf16 v[126:129], v[172:175], v[188:191], v[126:129]
	v_mfma_f32_16x16x32_bf16 v[122:125], v[180:183], v[188:191], v[122:125]
	v_mfma_f32_16x16x32_bf16 v[110:113], v[172:175], v[196:199], v[110:113]
	v_mfma_f32_16x16x32_bf16 v[106:109], v[180:183], v[196:199], v[106:109]
	v_mfma_f32_16x16x32_bf16 v[94:97], v[172:175], v[204:207], v[94:97]
	v_mfma_f32_16x16x32_bf16 v[90:93], v[180:183], v[204:207], v[90:93]
	v_mfma_f32_16x16x32_bf16 v[70:73], v[172:175], v[212:215], v[70:73]
	v_mfma_f32_16x16x32_bf16 v[50:53], v[180:183], v[212:215], v[50:53]
	s_barrier
	s_setprio 0
	s_mov_b32 m0, s74
	s_mov_b64 s[98:99], s[52:53]
	s_add_u32 s78, s52, 0x100000
	ds_read_b128 v[184:187], v150 offset:16384
	ds_read_b128 v[188:191], v150 offset:17408
	ds_read_b128 v[192:195], v150 offset:18432
	ds_read_b128 v[196:199], v150 offset:19456
	ds_read_b128 v[200:203], v150 offset:20480
	ds_read_b128 v[204:207], v150 offset:21504
	ds_read_b128 v[208:211], v150 offset:22528
	ds_read_b128 v[212:215], v150 offset:23552
	global_load_lds_dwordx4 v130, s[52:53]
	s_mov_b32 m0, s75
	s_addc_u32 s79, s53, 0
	global_load_lds_dwordx4 v132, s[52:53]
	s_mov_b32 m0, s76
	s_mov_b64 s[100:101], s[54:55]
	global_load_lds_dwordx4 v130, s[78:79]
	s_mov_b32 m0, s46
	s_nop 0
	global_load_lds_dwordx4 v132, s[78:79]
	s_waitcnt vmcnt(6)
	s_waitcnt lgkmcnt(0)
	s_setprio 1
	s_barrier
	v_mfma_f32_16x16x32_bf16 v[66:69], v[152:155], v[184:187], v[66:69]
	v_mfma_f32_16x16x32_bf16 v[62:65], v[160:163], v[184:187], v[62:65]
	v_mfma_f32_16x16x32_bf16 v[42:45], v[152:155], v[192:195], v[42:45]
	v_mfma_f32_16x16x32_bf16 v[38:41], v[160:163], v[192:195], v[38:41]
	v_mfma_f32_16x16x32_bf16 v[26:29], v[152:155], v[200:203], v[26:29]
	v_mfma_f32_16x16x32_bf16 v[22:25], v[160:163], v[200:203], v[22:25]
	v_mfma_f32_16x16x32_bf16 v[6:9], v[152:155], v[208:211], v[6:9]
	v_mfma_f32_16x16x32_bf16 v[2:5], v[160:163], v[208:211], v[2:5]
	v_mfma_f32_16x16x32_bf16 v[66:69], v[156:159], v[188:191], v[66:69]
	v_mfma_f32_16x16x32_bf16 v[62:65], v[164:167], v[188:191], v[62:65]
	v_mfma_f32_16x16x32_bf16 v[42:45], v[156:159], v[196:199], v[42:45]
	v_mfma_f32_16x16x32_bf16 v[38:41], v[164:167], v[196:199], v[38:41]
	v_mfma_f32_16x16x32_bf16 v[26:29], v[156:159], v[204:207], v[26:29]
	v_mfma_f32_16x16x32_bf16 v[22:25], v[164:167], v[204:207], v[22:25]
	v_mfma_f32_16x16x32_bf16 v[6:9], v[156:159], v[212:215], v[6:9]
	v_mfma_f32_16x16x32_bf16 v[2:5], v[164:167], v[212:215], v[2:5]
	v_mfma_f32_16x16x32_bf16 v[78:81], v[168:171], v[184:187], v[78:81]
	v_mfma_f32_16x16x32_bf16 v[58:61], v[176:179], v[184:187], v[58:61]
	v_mfma_f32_16x16x32_bf16 v[46:49], v[168:171], v[192:195], v[46:49]
	v_mfma_f32_16x16x32_bf16 v[34:37], v[176:179], v[192:195], v[34:37]
	v_mfma_f32_16x16x32_bf16 v[30:33], v[168:171], v[200:203], v[30:33]
	v_mfma_f32_16x16x32_bf16 v[18:21], v[176:179], v[200:203], v[18:21]
	v_mfma_f32_16x16x32_bf16 v[14:17], v[168:171], v[208:211], v[14:17]
	v_mfma_f32_16x16x32_bf16 v[10:13], v[176:179], v[208:211], v[10:13]
	v_mfma_f32_16x16x32_bf16 v[78:81], v[172:175], v[188:191], v[78:81]
	v_mfma_f32_16x16x32_bf16 v[58:61], v[180:183], v[188:191], v[58:61]
	v_mfma_f32_16x16x32_bf16 v[46:49], v[172:175], v[196:199], v[46:49]
	v_mfma_f32_16x16x32_bf16 v[34:37], v[180:183], v[196:199], v[34:37]
	v_mfma_f32_16x16x32_bf16 v[30:33], v[172:175], v[204:207], v[30:33]
	v_mfma_f32_16x16x32_bf16 v[18:21], v[180:183], v[204:207], v[18:21]
	v_mfma_f32_16x16x32_bf16 v[14:17], v[172:175], v[212:215], v[14:17]
	v_mfma_f32_16x16x32_bf16 v[10:13], v[180:183], v[212:215], v[10:13]
	s_barrier
; #define PG8_BAR __builtin_amdgcn_s_barrier()
;     ...
;         for (int t = 2; t < nt; t += 2) PG8_KITER(t);
;         if constexpr (ALIGN_EPI) { if (wr == 0) PG8_BAR; }
	s_setprio 0
	ds_read_b128 v[152:155], v134
	ds_read_b128 v[156:159], v134 offset:1024
	ds_read_b128 v[160:163], v134 offset:2048
	ds_read_b128 v[164:167], v134 offset:3072
	ds_read_b128 v[168:171], v144
	ds_read_b128 v[172:175], v144 offset:1024
	ds_read_b128 v[176:179], v144 offset:2048
	ds_read_b128 v[180:183], v144 offset:3072
	s_add_u32 s54, s54, 0x100000
	s_addc_u32 s55, s55, 0
	s_mov_b32 m0, s33
	s_nop 0
	global_load_lds_dwordx4 v130, s[100:101]
	s_mov_b32 m0, s51
	s_nop 0
	global_load_lds_dwordx4 v132, s[100:101]
	s_mov_b32 m0, s58
	ds_read_b128 v[184:187], v150 offset:32768
	ds_read_b128 v[188:191], v150 offset:33792
	ds_read_b128 v[192:195], v150 offset:34816
	ds_read_b128 v[196:199], v150 offset:35840
	ds_read_b128 v[200:203], v150 offset:36864
	ds_read_b128 v[204:207], v150 offset:37888
	ds_read_b128 v[208:211], v150 offset:38912
	ds_read_b128 v[212:215], v150 offset:39936
	global_load_lds_dwordx4 v130, s[54:55]
	s_mov_b32 m0, s59
	s_nop 0
	global_load_lds_dwordx4 v132, s[54:55]
	s_waitcnt vmcnt(8)
	s_waitcnt lgkmcnt(0)
	s_setprio 1
	s_barrier
	v_mfma_f32_16x16x32_bf16 v[118:121], v[152:155], v[184:187], v[118:121]
	v_mfma_f32_16x16x32_bf16 v[114:117], v[160:163], v[184:187], v[114:117]
	v_mfma_f32_16x16x32_bf16 v[102:105], v[152:155], v[192:195], v[102:105]
	v_mfma_f32_16x16x32_bf16 v[98:101], v[160:163], v[192:195], v[98:101]
	v_mfma_f32_16x16x32_bf16 v[86:89], v[152:155], v[200:203], v[86:89]
	v_mfma_f32_16x16x32_bf16 v[82:85], v[160:163], v[200:203], v[82:85]
	v_mfma_f32_16x16x32_bf16 v[74:77], v[152:155], v[208:211], v[74:77]
	v_mfma_f32_16x16x32_bf16 v[54:57], v[160:163], v[208:211], v[54:57]
	v_mfma_f32_16x16x32_bf16 v[118:121], v[156:159], v[188:191], v[118:121]
	v_mfma_f32_16x16x32_bf16 v[114:117], v[164:167], v[188:191], v[114:117]
	v_mfma_f32_16x16x32_bf16 v[102:105], v[156:159], v[196:199], v[102:105]
	v_mfma_f32_16x16x32_bf16 v[98:101], v[164:167], v[196:199], v[98:101]
	v_mfma_f32_16x16x32_bf16 v[86:89], v[156:159], v[204:207], v[86:89]
	v_mfma_f32_16x16x32_bf16 v[82:85], v[164:167], v[204:207], v[82:85]
	v_mfma_f32_16x16x32_bf16 v[74:77], v[156:159], v[212:215], v[74:77]
	v_mfma_f32_16x16x32_bf16 v[54:57], v[164:167], v[212:215], v[54:57]
	v_mfma_f32_16x16x32_bf16 v[126:129], v[168:171], v[184:187], v[126:129]
	v_mfma_f32_16x16x32_bf16 v[122:125], v[176:179], v[184:187], v[122:125]
	v_mfma_f32_16x16x32_bf16 v[110:113], v[168:171], v[192:195], v[110:113]
	v_mfma_f32_16x16x32_bf16 v[106:109], v[176:179], v[192:195], v[106:109]
	v_mfma_f32_16x16x32_bf16 v[94:97], v[168:171], v[200:203], v[94:97]
	v_mfma_f32_16x16x32_bf16 v[90:93], v[176:179], v[200:203], v[90:93]
	v_mfma_f32_16x16x32_bf16 v[70:73], v[168:171], v[208:211], v[70:73]
	v_mfma_f32_16x16x32_bf16 v[50:53], v[176:179], v[208:211], v[50:53]
	v_mfma_f32_16x16x32_bf16 v[126:129], v[172:175], v[188:191], v[126:129]
	v_mfma_f32_16x16x32_bf16 v[122:125], v[180:183], v[188:191], v[122:125]
	v_mfma_f32_16x16x32_bf16 v[110:113], v[172:175], v[196:199], v[110:113]
	v_mfma_f32_16x16x32_bf16 v[106:109], v[180:183], v[196:199], v[106:109]
	v_mfma_f32_16x16x32_bf16 v[94:97], v[172:175], v[204:207], v[94:97]
	v_mfma_f32_16x16x32_bf16 v[90:93], v[180:183], v[204:207], v[90:93]
	v_mfma_f32_16x16x32_bf16 v[70:73], v[172:175], v[212:215], v[70:73]
	v_mfma_f32_16x16x32_bf16 v[50:53], v[180:183], v[212:215], v[50:53]
	s_barrier
	s_setprio 0
	s_mov_b32 m0, s47
	s_add_u32 s98, s98, 0x80
	s_addc_u32 s99, s99, 0
	s_add_u32 s100, s100, 0x80
	s_addc_u32 s101, s101, 0
	s_add_u32 s52, s52, 0x100080
	ds_read_b128 v[184:187], v150 offset:49152
	ds_read_b128 v[188:191], v150 offset:50176
	ds_read_b128 v[192:195], v150 offset:51200
	ds_read_b128 v[196:199], v150 offset:52224
	ds_read_b128 v[200:203], v150 offset:53248
	ds_read_b128 v[204:207], v150 offset:54272
	ds_read_b128 v[208:211], v150 offset:55296
	ds_read_b128 v[212:215], v150 offset:56320
	global_load_lds_dwordx4 v130, s[98:99]
	s_mov_b32 m0, s77
	s_addc_u32 s53, s53, 0
	global_load_lds_dwordx4 v132, s[98:99]
	s_mov_b32 m0, s56
	s_nop 0
	global_load_lds_dwordx4 v130, s[52:53]
	s_mov_b32 m0, s57
	s_nop 0
	global_load_lds_dwordx4 v132, s[52:53]
	s_waitcnt vmcnt(6)
	s_waitcnt lgkmcnt(0)
	s_setprio 1
	s_barrier
	v_mfma_f32_16x16x32_bf16 v[66:69], v[152:155], v[184:187], v[66:69]
	v_mfma_f32_16x16x32_bf16 v[62:65], v[160:163], v[184:187], v[62:65]
	v_mfma_f32_16x16x32_bf16 v[42:45], v[152:155], v[192:195], v[42:45]
	v_mfma_f32_16x16x32_bf16 v[38:41], v[160:163], v[192:195], v[38:41]
	v_mfma_f32_16x16x32_bf16 v[26:29], v[152:155], v[200:203], v[26:29]
	v_mfma_f32_16x16x32_bf16 v[22:25], v[160:163], v[200:203], v[22:25]
	v_mfma_f32_16x16x32_bf16 v[6:9], v[152:155], v[208:211], v[6:9]
	v_mfma_f32_16x16x32_bf16 v[2:5], v[160:163], v[208:211], v[2:5]
	v_mfma_f32_16x16x32_bf16 v[66:69], v[156:159], v[188:191], v[66:69]
	v_mfma_f32_16x16x32_bf16 v[62:65], v[164:167], v[188:191], v[62:65]
	v_mfma_f32_16x16x32_bf16 v[42:45], v[156:159], v[196:199], v[42:45]
	v_mfma_f32_16x16x32_bf16 v[38:41], v[164:167], v[196:199], v[38:41]
	v_mfma_f32_16x16x32_bf16 v[26:29], v[156:159], v[204:207], v[26:29]
	v_mfma_f32_16x16x32_bf16 v[22:25], v[164:167], v[204:207], v[22:25]
	v_mfma_f32_16x16x32_bf16 v[6:9], v[156:159], v[212:215], v[6:9]
	v_mfma_f32_16x16x32_bf16 v[2:5], v[164:167], v[212:215], v[2:5]
	v_mfma_f32_16x16x32_bf16 v[78:81], v[168:171], v[184:187], v[78:81]
	v_mfma_f32_16x16x32_bf16 v[58:61], v[176:179], v[184:187], v[58:61]
	v_mfma_f32_16x16x32_bf16 v[46:49], v[168:171], v[192:195], v[46:49]
	v_mfma_f32_16x16x32_bf16 v[34:37], v[176:179], v[192:195], v[34:37]
	v_mfma_f32_16x16x32_bf16 v[30:33], v[168:171], v[200:203], v[30:33]
	v_mfma_f32_16x16x32_bf16 v[18:21], v[176:179], v[200:203], v[18:21]
	v_mfma_f32_16x16x32_bf16 v[14:17], v[168:171], v[208:211], v[14:17]
	v_mfma_f32_16x16x32_bf16 v[10:13], v[176:179], v[208:211], v[10:13]
	v_mfma_f32_16x16x32_bf16 v[78:81], v[172:175], v[188:191], v[78:81]
	v_mfma_f32_16x16x32_bf16 v[58:61], v[180:183], v[188:191], v[58:61]
	v_mfma_f32_16x16x32_bf16 v[46:49], v[172:175], v[196:199], v[46:49]
	v_mfma_f32_16x16x32_bf16 v[34:37], v[180:183], v[196:199], v[34:37]
	v_mfma_f32_16x16x32_bf16 v[30:33], v[172:175], v[204:207], v[30:33]
	v_mfma_f32_16x16x32_bf16 v[18:21], v[180:183], v[204:207], v[18:21]
	v_mfma_f32_16x16x32_bf16 v[14:17], v[172:175], v[212:215], v[14:17]
	v_mfma_f32_16x16x32_bf16 v[10:13], v[180:183], v[212:215], v[10:13]
	s_barrier
	s_setprio 0
	s_add_i32 s26, s26, 2
	s_add_u32 s0, s0, 0x100
	s_addc_u32 s1, s1, 0
	s_add_u32 s14, s14, 0x100
	s_addc_u32 s15, s15, 0
	s_cmp_gt_u32 s26, 29
	s_cbranch_scc0 .LBB0_1110
	s_mov_b32 m0, s61
	s_nop 0
	global_load_lds_dwordx4 v130, s[100:101]
	s_mov_b32 m0, s62
	s_nop 0
	global_load_lds_dwordx4 v132, s[100:101]
	s_and_b64 vcc, exec, s[18:19]
	s_cbranch_vccz .LBB0_1113
	s_barrier

;     __host__ __device__ bool next(int i, Unit& u) const { if (!StaticOrder::next(i >> 1, u)) return false; u.seg = i & 1; return true; }
;     ...
;         const bool has_next = S.next(ui + 1, nxt);
;         const char* nA = has_next ? PG8_APTR(nxt) : cA; const char* nB = has_next ? PG8_BPTR(nxt) : cB;
.LBB0_1260:
	s_ashr_i32 s23, s22, 31
	ds_read_b128 v[2:5], v182
	ds_read_b128 v[6:9], v182 offset:1024
	ds_read_b128 v[10:13], v182 offset:2048
	ds_read_b128 v[14:17], v182 offset:3072
	ds_read_b128 v[18:21], v183
	ds_read_b128 v[22:25], v183 offset:1024
	ds_read_b128 v[26:29], v183 offset:2048
	ds_read_b128 v[30:33], v183 offset:3072
	s_lshl_b64 s[24:25], s[22:23], 18
	s_add_u32 s24, s10, s24
	s_addc_u32 s25, s11, s25
	s_and_b64 s[26:27], s[4:5], exec
	s_cselect_b32 s23, s25, s41
	s_cselect_b32 s31, s24, s40
	s_and_b32 s0, s64, 0x7fffffff
	s_lshl_b64 s[26:27], s[0:1], 18
	s_add_u32 s28, s12, s26
	s_addc_u32 s29, s13, s27
	s_and_b64 s[26:27], s[4:5], exec
	s_cselect_b32 s0, s29, s39
	s_cselect_b32 s66, s28, s38
	s_add_u32 s26, s40, 0x20080
	s_addc_u32 s27, s41, 0
	s_mov_b32 m0, s59
	v_lshl_add_u64 v[66:67], s[26:27], 0, v[154:155]
	ds_read_b128 v[34:37], v184
	ds_read_b128 v[38:41], v184 offset:1024
	ds_read_b128 v[42:45], v184 offset:2048
	ds_read_b128 v[46:49], v184 offset:3072
	ds_read_b128 v[50:53], v184 offset:4096
	ds_read_b128 v[54:57], v184 offset:5120
	ds_read_b128 v[58:61], v184 offset:6144
	ds_read_b128 v[62:65], v184 offset:7168
	global_load_lds_dwordx4 v[66:67], off
	v_lshl_add_u64 v[66:67], s[26:27], 0, v[158:159]
	s_mov_b32 m0, s60
	s_nop 0
	global_load_lds_dwordx4 v[66:67], off
	s_waitcnt vmcnt(8)
	s_waitcnt lgkmcnt(0)
	s_setprio 1
	s_barrier
	v_mfma_f32_16x16x32_bf16 v[90:93], v[2:5], v[58:61], 0
	v_mfma_f32_16x16x32_bf16 v[66:69], v[2:5], v[34:37], 0
	v_mfma_f32_16x16x32_bf16 v[70:73], v[10:13], v[34:37], 0
	v_mfma_f32_16x16x32_bf16 v[74:77], v[2:5], v[42:45], 0
	v_mfma_f32_16x16x32_bf16 v[78:81], v[10:13], v[42:45], 0
	v_mfma_f32_16x16x32_bf16 v[82:85], v[2:5], v[50:53], 0
	v_mfma_f32_16x16x32_bf16 v[86:89], v[10:13], v[50:53], 0
	v_mfma_f32_16x16x32_bf16 v[98:101], v[6:9], v[62:65], v[90:93]
	v_mfma_f32_16x16x32_bf16 v[90:93], v[10:13], v[58:61], 0
	v_mfma_f32_16x16x32_bf16 v[66:69], v[6:9], v[38:41], v[66:69]
	v_mfma_f32_16x16x32_bf16 v[70:73], v[14:17], v[38:41], v[70:73]
	v_mfma_f32_16x16x32_bf16 v[74:77], v[6:9], v[46:49], v[74:77]
	v_mfma_f32_16x16x32_bf16 v[78:81], v[14:17], v[46:49], v[78:81]
	v_mfma_f32_16x16x32_bf16 v[82:85], v[6:9], v[54:57], v[82:85]
	v_mfma_f32_16x16x32_bf16 v[86:89], v[14:17], v[54:57], v[86:89]
	v_mfma_f32_16x16x32_bf16 v[102:105], v[14:17], v[62:65], v[90:93]
	v_mfma_f32_16x16x32_bf16 v[90:93], v[18:21], v[34:37], 0
	v_mfma_f32_16x16x32_bf16 v[34:37], v[26:29], v[34:37], 0
	v_mfma_f32_16x16x32_bf16 v[114:117], v[22:25], v[38:41], v[90:93]
	v_mfma_f32_16x16x32_bf16 v[34:37], v[30:33], v[38:41], v[34:37]
	v_mfma_f32_16x16x32_bf16 v[38:41], v[18:21], v[42:45], 0
	v_mfma_f32_16x16x32_bf16 v[42:45], v[26:29], v[42:45], 0
	v_mfma_f32_16x16x32_bf16 v[38:41], v[22:25], v[46:49], v[38:41]
	v_mfma_f32_16x16x32_bf16 v[42:45], v[30:33], v[46:49], v[42:45]
	v_mfma_f32_16x16x32_bf16 v[46:49], v[18:21], v[50:53], 0
	v_mfma_f32_16x16x32_bf16 v[50:53], v[26:29], v[50:53], 0
	v_mfma_f32_16x16x32_bf16 v[46:49], v[22:25], v[54:57], v[46:49]
	v_mfma_f32_16x16x32_bf16 v[50:53], v[30:33], v[54:57], v[50:53]
	v_mfma_f32_16x16x32_bf16 v[54:57], v[18:21], v[58:61], 0
	v_mfma_f32_16x16x32_bf16 v[58:61], v[26:29], v[58:61], 0
	v_mfma_f32_16x16x32_bf16 v[54:57], v[22:25], v[62:65], v[54:57]
	v_mfma_f32_16x16x32_bf16 v[58:61], v[30:33], v[62:65], v[58:61]
	s_barrier
	s_setprio 0
	v_lshl_add_u64 v[152:153], s[38:39], 0, v[156:157]
	s_mov_b32 m0, s61
	v_lshl_add_u64 v[130:131], v[152:153], 0, s[18:19]
	v_lshl_add_u64 v[250:251], s[38:39], 0, v[160:161]
	s_add_u32 s26, s38, 0x20100
	ds_read_b128 v[62:65], v184 offset:16384
	ds_read_b128 v[90:93], v184 offset:17408
	ds_read_b128 v[94:97], v184 offset:18432
	ds_read_b128 v[106:109], v184 offset:19456
	ds_read_b128 v[110:113], v184 offset:20480
	ds_read_b128 v[118:121], v184 offset:21504
	ds_read_b128 v[122:125], v184 offset:22528
	ds_read_b128 v[126:129], v184 offset:23552
	global_load_lds_dwordx4 v[130:131], off
	v_lshl_add_u64 v[130:131], v[250:251], 0, s[18:19]
	s_mov_b32 m0, s62
	s_addc_u32 s27, s39, 0
	s_add_i32 s67, s58, s33
	global_load_lds_dwordx4 v[130:131], off
	v_lshl_add_u64 v[130:131], s[26:27], 0, v[156:157]
	s_mov_b32 m0, s67
	s_add_i32 s46, s67, 0x2000
	global_load_lds_dwordx4 v[130:131], off
	v_lshl_add_u64 v[130:131], s[26:27], 0, v[160:161]
	s_mov_b32 m0, s46
	v_lshl_add_u64 v[252:253], s[40:41], 0, v[154:155]
	global_load_lds_dwordx4 v[130:131], off
	v_lshl_add_u64 v[130:131], v[252:253], 0, s[18:19]
	s_mov_b32 m0, s48
	v_lshl_add_u64 v[166:167], s[40:41], 0, v[158:159]
	global_load_lds_dwordx4 v[130:131], off
	v_lshl_add_u64 v[130:131], v[166:167], 0, s[18:19]
	s_mov_b32 m0, s49
	s_nop 0
	global_load_lds_dwordx4 v[130:131], off
	s_waitcnt vmcnt(8)
	s_waitcnt lgkmcnt(0)
	s_setprio 1
	s_barrier
	v_mfma_f32_16x16x32_bf16 v[130:133], v[2:5], v[62:65], 0
	v_mfma_f32_16x16x32_bf16 v[140:143], v[2:5], v[94:97], 0
	v_mfma_f32_16x16x32_bf16 v[148:151], v[2:5], v[110:113], 0
	v_mfma_f32_16x16x32_bf16 v[2:5], v[2:5], v[122:125], 0
	v_mfma_f32_16x16x32_bf16 v[132:135], v[6:9], v[90:93], v[130:133]
	v_mfma_f32_16x16x32_bf16 v[140:143], v[6:9], v[106:109], v[140:143]
	v_mfma_f32_16x16x32_bf16 v[148:151], v[6:9], v[118:121], v[148:151]
	v_mfma_f32_16x16x32_bf16 v[2:5], v[6:9], v[126:129], v[2:5]
	v_mfma_f32_16x16x32_bf16 v[6:9], v[10:13], v[122:125], 0
	v_mfma_f32_16x16x32_bf16 v[136:139], v[10:13], v[62:65], 0
	v_mfma_f32_16x16x32_bf16 v[144:147], v[10:13], v[94:97], 0
	v_mfma_f32_16x16x32_bf16 v[170:173], v[10:13], v[110:113], 0
	v_mfma_f32_16x16x32_bf16 v[6:9], v[14:17], v[126:129], v[6:9]
	v_mfma_f32_16x16x32_bf16 v[136:139], v[14:17], v[90:93], v[136:139]
	v_mfma_f32_16x16x32_bf16 v[144:147], v[14:17], v[106:109], v[144:147]
	v_mfma_f32_16x16x32_bf16 v[170:173], v[14:17], v[118:121], v[170:173]
	v_mfma_f32_16x16x32_bf16 v[10:13], v[18:21], v[62:65], 0
	v_mfma_f32_16x16x32_bf16 v[174:177], v[22:25], v[90:93], v[10:13]
	v_mfma_f32_16x16x32_bf16 v[10:13], v[26:29], v[62:65], 0
	v_mfma_f32_16x16x32_bf16 v[178:181], v[30:33], v[90:93], v[10:13]
	v_mfma_f32_16x16x32_bf16 v[10:13], v[18:21], v[94:97], 0
	v_mfma_f32_16x16x32_bf16 v[186:189], v[22:25], v[106:109], v[10:13]
	v_mfma_f32_16x16x32_bf16 v[10:13], v[26:29], v[94:97], 0
	v_mfma_f32_16x16x32_bf16 v[190:193], v[30:33], v[106:109], v[10:13]
	v_mfma_f32_16x16x32_bf16 v[10:13], v[18:21], v[110:113], 0
	v_mfma_f32_16x16x32_bf16 v[194:197], v[22:25], v[118:121], v[10:13]
	v_mfma_f32_16x16x32_bf16 v[10:13], v[26:29], v[110:113], 0
	v_mfma_f32_16x16x32_bf16 v[198:201], v[30:33], v[118:121], v[10:13]
	v_mfma_f32_16x16x32_bf16 v[10:13], v[18:21], v[122:125], 0
	v_mfma_f32_16x16x32_bf16 v[202:205], v[22:25], v[126:129], v[10:13]
	v_mfma_f32_16x16x32_bf16 v[10:13], v[26:29], v[122:125], 0
	v_mfma_f32_16x16x32_bf16 v[206:209], v[30:33], v[126:129], v[10:13]
	s_barrier
	s_setprio 0
	s_add_i32 s47, 0, 0x18000
	s_add_i32 s56, 0, 0x1c000
	v_add_u32_e32 v130, s47, v1
	v_add_u32_e32 v131, s56, v1
	s_nop 0
	ds_read_b128 v[10:13], v130
	ds_read_b128 v[14:17], v130 offset:1024
	ds_read_b128 v[18:21], v130 offset:2048
	ds_read_b128 v[22:25], v130 offset:3072
	ds_read_b128 v[210:213], v131
	ds_read_b128 v[214:217], v131 offset:1024
	ds_read_b128 v[218:221], v131 offset:2048
	ds_read_b128 v[222:225], v131 offset:3072
	s_add_u32 s26, s40, 0x20100
	s_addc_u32 s27, s41, 0
	s_mov_b32 m0, s50
	v_lshl_add_u64 v[90:91], s[26:27], 0, v[154:155]
	ds_read_b128 v[26:29], v184 offset:32768
	ds_read_b128 v[30:33], v184 offset:33792
	ds_read_b128 v[62:65], v184 offset:34816
	ds_read_b128 v[226:229], v184 offset:35840
	ds_read_b128 v[230:233], v184 offset:36864
	ds_read_b128 v[234:237], v184 offset:37888
	ds_read_b128 v[238:241], v184 offset:38912
	ds_read_b128 v[242:245], v184 offset:39936
	global_load_lds_dwordx4 v[90:91], off
	v_lshl_add_u64 v[90:91], s[26:27], 0, v[158:159]
	s_mov_b32 m0, s51
	s_nop 0
	global_load_lds_dwordx4 v[90:91], off
	s_waitcnt vmcnt(8)
	s_waitcnt lgkmcnt(0)
	s_setprio 1
	s_barrier
	v_mfma_f32_16x16x32_bf16 v[66:69], v[10:13], v[26:29], v[66:69]
	v_mfma_f32_16x16x32_bf16 v[122:125], v[14:17], v[30:33], v[66:69]
	v_mfma_f32_16x16x32_bf16 v[66:69], v[18:21], v[26:29], v[70:73]
	v_mfma_f32_16x16x32_bf16 v[118:121], v[22:25], v[30:33], v[66:69]
	v_mfma_f32_16x16x32_bf16 v[66:69], v[10:13], v[62:65], v[74:77]
	v_mfma_f32_16x16x32_bf16 v[110:113], v[14:17], v[226:229], v[66:69]
	v_mfma_f32_16x16x32_bf16 v[66:69], v[18:21], v[62:65], v[78:81]
	v_mfma_f32_16x16x32_bf16 v[106:109], v[22:25], v[226:229], v[66:69]
	v_mfma_f32_16x16x32_bf16 v[66:69], v[10:13], v[230:233], v[82:85]
	v_mfma_f32_16x16x32_bf16 v[94:97], v[14:17], v[234:237], v[66:69]
	v_mfma_f32_16x16x32_bf16 v[66:69], v[18:21], v[230:233], v[86:89]
	v_mfma_f32_16x16x32_bf16 v[90:93], v[22:25], v[234:237], v[66:69]
	v_mfma_f32_16x16x32_bf16 v[66:69], v[10:13], v[238:241], v[98:101]
	v_mfma_f32_16x16x32_bf16 v[78:81], v[14:17], v[242:245], v[66:69]
	v_mfma_f32_16x16x32_bf16 v[66:69], v[18:21], v[238:241], v[102:105]
	v_mfma_f32_16x16x32_bf16 v[74:77], v[22:25], v[242:245], v[66:69]
	v_mfma_f32_16x16x32_bf16 v[66:69], v[210:213], v[26:29], v[114:117]
	v_mfma_f32_16x16x32_bf16 v[26:29], v[218:221], v[26:29], v[34:37]
	v_mfma_f32_16x16x32_bf16 v[114:117], v[222:225], v[30:33], v[26:29]
	v_mfma_f32_16x16x32_bf16 v[26:29], v[210:213], v[62:65], v[38:41]
	v_mfma_f32_16x16x32_bf16 v[102:105], v[214:217], v[226:229], v[26:29]
	v_mfma_f32_16x16x32_bf16 v[26:29], v[218:221], v[62:65], v[42:45]
	v_mfma_f32_16x16x32_bf16 v[98:101], v[222:225], v[226:229], v[26:29]
	v_mfma_f32_16x16x32_bf16 v[26:29], v[210:213], v[230:233], v[46:49]
	v_mfma_f32_16x16x32_bf16 v[86:89], v[214:217], v[234:237], v[26:29]
	v_mfma_f32_16x16x32_bf16 v[26:29], v[218:221], v[230:233], v[50:53]
	v_mfma_f32_16x16x32_bf16 v[82:85], v[222:225], v[234:237], v[26:29]
	v_mfma_f32_16x16x32_bf16 v[26:29], v[210:213], v[238:241], v[54:57]
	v_mfma_f32_16x16x32_bf16 v[70:73], v[214:217], v[242:245], v[26:29]
	v_mfma_f32_16x16x32_bf16 v[26:29], v[218:221], v[238:241], v[58:61]
	v_mfma_f32_16x16x32_bf16 v[126:129], v[214:217], v[30:33], v[66:69]
	v_mfma_f32_16x16x32_bf16 v[66:69], v[222:225], v[242:245], v[26:29]
	s_barrier
	s_setprio 0
	s_add_i32 s47, s47, s33
	s_add_i32 s68, s47, 0x2000
	s_nop 1
	v_lshl_add_u64 v[26:27], v[152:153], 0, s[20:21]
	s_mov_b32 m0, s47
	s_add_u32 s26, s38, 0x20180
	ds_read_b128 v[34:37], v184 offset:49152
	ds_read_b128 v[38:41], v184 offset:50176
	ds_read_b128 v[226:229], v184 offset:51200
	ds_read_b128 v[230:233], v184 offset:52224
	ds_read_b128 v[234:237], v184 offset:53248
	ds_read_b128 v[238:241], v184 offset:54272
	ds_read_b128 v[242:245], v184 offset:55296
	ds_read_b128 v[246:249], v184 offset:56320
	global_load_lds_dwordx4 v[26:27], off
	v_lshl_add_u64 v[26:27], v[250:251], 0, s[20:21]
	s_mov_b32 m0, s68
	s_addc_u32 s27, s39, 0
	s_add_i32 s56, s56, s33
	global_load_lds_dwordx4 v[26:27], off
	v_lshl_add_u64 v[26:27], s[26:27], 0, v[156:157]
	s_mov_b32 m0, s56
	s_add_i32 s57, s56, 0x2000
	global_load_lds_dwordx4 v[26:27], off
	v_lshl_add_u64 v[26:27], s[26:27], 0, v[160:161]
	s_mov_b32 m0, s57
	s_nop 0
	global_load_lds_dwordx4 v[26:27], off
	v_lshl_add_u64 v[26:27], v[252:253], 0, s[20:21]
	s_mov_b32 m0, s52
	s_nop 0
	global_load_lds_dwordx4 v[26:27], off
	v_lshl_add_u64 v[26:27], v[166:167], 0, s[20:21]
	s_mov_b32 m0, s53
	s_nop 0
	global_load_lds_dwordx4 v[26:27], off
	s_waitcnt vmcnt(8)
	s_waitcnt lgkmcnt(0)
	s_setprio 1
	s_barrier
	v_mfma_f32_16x16x32_bf16 v[26:29], v[10:13], v[34:37], v[132:135]
	v_mfma_f32_16x16x32_bf16 v[58:61], v[14:17], v[38:41], v[26:29]
	v_mfma_f32_16x16x32_bf16 v[26:29], v[18:21], v[34:37], v[136:139]
	v_mfma_f32_16x16x32_bf16 v[54:57], v[22:25], v[38:41], v[26:29]
	v_mfma_f32_16x16x32_bf16 v[26:29], v[10:13], v[226:229], v[140:143]
	v_mfma_f32_16x16x32_bf16 v[46:49], v[14:17], v[230:233], v[26:29]
	v_mfma_f32_16x16x32_bf16 v[26:29], v[18:21], v[226:229], v[144:147]
	v_mfma_f32_16x16x32_bf16 v[42:45], v[22:25], v[230:233], v[26:29]
	v_mfma_f32_16x16x32_bf16 v[26:29], v[10:13], v[234:237], v[148:151]
	v_mfma_f32_16x16x32_bf16 v[2:5], v[10:13], v[242:245], v[2:5]
	v_mfma_f32_16x16x32_bf16 v[30:33], v[14:17], v[238:241], v[26:29]
	v_mfma_f32_16x16x32_bf16 v[26:29], v[18:21], v[234:237], v[170:173]
	v_mfma_f32_16x16x32_bf16 v[14:17], v[14:17], v[246:249], v[2:5]
	v_mfma_f32_16x16x32_bf16 v[2:5], v[18:21], v[242:245], v[6:9]
	v_mfma_f32_16x16x32_bf16 v[26:29], v[22:25], v[238:241], v[26:29]
	v_mfma_f32_16x16x32_bf16 v[10:13], v[22:25], v[246:249], v[2:5]
	v_mfma_f32_16x16x32_bf16 v[2:5], v[210:213], v[34:37], v[174:177]
	v_mfma_f32_16x16x32_bf16 v[62:65], v[214:217], v[38:41], v[2:5]
	v_mfma_f32_16x16x32_bf16 v[2:5], v[218:221], v[34:37], v[178:181]
	v_mfma_f32_16x16x32_bf16 v[50:53], v[222:225], v[38:41], v[2:5]
	v_mfma_f32_16x16x32_bf16 v[2:5], v[210:213], v[226:229], v[186:189]
	v_mfma_f32_16x16x32_bf16 v[38:41], v[214:217], v[230:233], v[2:5]
	v_mfma_f32_16x16x32_bf16 v[2:5], v[218:221], v[226:229], v[190:193]
	v_mfma_f32_16x16x32_bf16 v[34:37], v[222:225], v[230:233], v[2:5]
	v_mfma_f32_16x16x32_bf16 v[2:5], v[210:213], v[234:237], v[194:197]
	v_mfma_f32_16x16x32_bf16 v[22:25], v[214:217], v[238:241], v[2:5]
	v_mfma_f32_16x16x32_bf16 v[2:5], v[218:221], v[234:237], v[198:201]
	v_mfma_f32_16x16x32_bf16 v[18:21], v[222:225], v[238:241], v[2:5]
	v_mfma_f32_16x16x32_bf16 v[2:5], v[210:213], v[242:245], v[202:205]
	v_mfma_f32_16x16x32_bf16 v[6:9], v[214:217], v[246:249], v[2:5]
	v_mfma_f32_16x16x32_bf16 v[2:5], v[218:221], v[242:245], v[206:209]
	v_mfma_f32_16x16x32_bf16 v[2:5], v[222:225], v[246:249], v[2:5]
	s_barrier
	s_setprio 0
	s_add_u32 s40, s40, 0x20180
	s_addc_u32 s41, s41, 0
	s_add_u32 s26, s38, 0x200
	s_addc_u32 s27, s39, 0
	s_mov_b32 s69, 0

.Lrb2_skip_38305:
	s_mov_b32 m0, s59
	ds_read_b128 v[186:189], v184
	ds_read_b128 v[190:193], v184 offset:1024
	ds_read_b128 v[194:197], v184 offset:2048
	ds_read_b128 v[198:201], v184 offset:3072
	ds_read_b128 v[202:205], v184 offset:4096
	ds_read_b128 v[206:209], v184 offset:5120
	ds_read_b128 v[210:213], v184 offset:6144
	ds_read_b128 v[214:217], v184 offset:7168
	global_load_lds_dwordx4 v162, s[40:41]
	s_mov_b32 m0, s60
	s_nop 0
	global_load_lds_dwordx4 v164, s[40:41]
	s_waitcnt vmcnt(8)
	s_waitcnt lgkmcnt(0)
	s_setprio 1
	s_barrier
	v_mfma_f32_16x16x32_bf16 v[122:125], v[132:135], v[186:189], v[122:125]
	v_mfma_f32_16x16x32_bf16 v[118:121], v[140:143], v[186:189], v[118:121]
	v_mfma_f32_16x16x32_bf16 v[110:113], v[132:135], v[194:197], v[110:113]
	v_mfma_f32_16x16x32_bf16 v[106:109], v[140:143], v[194:197], v[106:109]
	v_mfma_f32_16x16x32_bf16 v[94:97], v[132:135], v[202:205], v[94:97]
	v_mfma_f32_16x16x32_bf16 v[90:93], v[140:143], v[202:205], v[90:93]
	v_mfma_f32_16x16x32_bf16 v[78:81], v[132:135], v[210:213], v[78:81]
	v_mfma_f32_16x16x32_bf16 v[74:77], v[140:143], v[210:213], v[74:77]
	v_mfma_f32_16x16x32_bf16 v[122:125], v[136:139], v[190:193], v[122:125]
	v_mfma_f32_16x16x32_bf16 v[118:121], v[144:147], v[190:193], v[118:121]
	v_mfma_f32_16x16x32_bf16 v[110:113], v[136:139], v[198:201], v[110:113]
	v_mfma_f32_16x16x32_bf16 v[106:109], v[144:147], v[198:201], v[106:109]
	v_mfma_f32_16x16x32_bf16 v[94:97], v[136:139], v[206:209], v[94:97]
	v_mfma_f32_16x16x32_bf16 v[90:93], v[144:147], v[206:209], v[90:93]
	v_mfma_f32_16x16x32_bf16 v[78:81], v[136:139], v[214:217], v[78:81]
	v_mfma_f32_16x16x32_bf16 v[74:77], v[144:147], v[214:217], v[74:77]
	v_mfma_f32_16x16x32_bf16 v[126:129], v[148:151], v[186:189], v[126:129]
	v_mfma_f32_16x16x32_bf16 v[114:117], v[174:177], v[186:189], v[114:117]
	v_mfma_f32_16x16x32_bf16 v[102:105], v[148:151], v[194:197], v[102:105]
	v_mfma_f32_16x16x32_bf16 v[98:101], v[174:177], v[194:197], v[98:101]
	v_mfma_f32_16x16x32_bf16 v[86:89], v[148:151], v[202:205], v[86:89]
	v_mfma_f32_16x16x32_bf16 v[82:85], v[174:177], v[202:205], v[82:85]
	v_mfma_f32_16x16x32_bf16 v[70:73], v[148:151], v[210:213], v[70:73]
	v_mfma_f32_16x16x32_bf16 v[66:69], v[174:177], v[210:213], v[66:69]
	v_mfma_f32_16x16x32_bf16 v[126:129], v[170:173], v[190:193], v[126:129]
	v_mfma_f32_16x16x32_bf16 v[114:117], v[178:181], v[190:193], v[114:117]
	v_mfma_f32_16x16x32_bf16 v[102:105], v[170:173], v[198:201], v[102:105]
	v_mfma_f32_16x16x32_bf16 v[98:101], v[178:181], v[198:201], v[98:101]
	v_mfma_f32_16x16x32_bf16 v[86:89], v[170:173], v[206:209], v[86:89]
	v_mfma_f32_16x16x32_bf16 v[82:85], v[178:181], v[206:209], v[82:85]
	v_mfma_f32_16x16x32_bf16 v[70:73], v[170:173], v[214:217], v[70:73]
	v_mfma_f32_16x16x32_bf16 v[66:69], v[178:181], v[214:217], v[66:69]
	s_barrier
	s_setprio 0
	s_mov_b32 m0, s61
	s_mov_b64 s[98:99], s[38:39]
	s_add_u32 s70, s38, 0x20000
	ds_read_b128 v[186:189], v184 offset:16384
	ds_read_b128 v[190:193], v184 offset:17408
	ds_read_b128 v[194:197], v184 offset:18432
	ds_read_b128 v[198:201], v184 offset:19456
	ds_read_b128 v[202:205], v184 offset:20480
	ds_read_b128 v[206:209], v184 offset:21504
	ds_read_b128 v[210:213], v184 offset:22528
	ds_read_b128 v[214:217], v184 offset:23552
	global_load_lds_dwordx4 v156, s[38:39]
	s_mov_b32 m0, s62
	s_addc_u32 s71, s39, 0
	global_load_lds_dwordx4 v160, s[38:39]
	s_mov_b32 m0, s67
	s_mov_b64 s[100:101], s[42:43]
	global_load_lds_dwordx4 v156, s[70:71]
	s_mov_b32 m0, s46
	s_nop 0
	global_load_lds_dwordx4 v160, s[70:71]
	s_waitcnt vmcnt(6)
	s_waitcnt lgkmcnt(0)
	s_setprio 1
	s_barrier
	v_mfma_f32_16x16x32_bf16 v[58:61], v[132:135], v[186:189], v[58:61]
	v_mfma_f32_16x16x32_bf16 v[54:57], v[140:143], v[186:189], v[54:57]
	v_mfma_f32_16x16x32_bf16 v[46:49], v[132:135], v[194:197], v[46:49]
	v_mfma_f32_16x16x32_bf16 v[42:45], v[140:143], v[194:197], v[42:45]
	v_mfma_f32_16x16x32_bf16 v[30:33], v[132:135], v[202:205], v[30:33]
	v_mfma_f32_16x16x32_bf16 v[26:29], v[140:143], v[202:205], v[26:29]
	v_mfma_f32_16x16x32_bf16 v[14:17], v[132:135], v[210:213], v[14:17]
	v_mfma_f32_16x16x32_bf16 v[10:13], v[140:143], v[210:213], v[10:13]
	v_mfma_f32_16x16x32_bf16 v[58:61], v[136:139], v[190:193], v[58:61]
	v_mfma_f32_16x16x32_bf16 v[54:57], v[144:147], v[190:193], v[54:57]
	v_mfma_f32_16x16x32_bf16 v[46:49], v[136:139], v[198:201], v[46:49]
	v_mfma_f32_16x16x32_bf16 v[42:45], v[144:147], v[198:201], v[42:45]
	v_mfma_f32_16x16x32_bf16 v[30:33], v[136:139], v[206:209], v[30:33]
	v_mfma_f32_16x16x32_bf16 v[26:29], v[144:147], v[206:209], v[26:29]
	v_mfma_f32_16x16x32_bf16 v[14:17], v[136:139], v[214:217], v[14:17]
	v_mfma_f32_16x16x32_bf16 v[10:13], v[144:147], v[214:217], v[10:13]
	v_mfma_f32_16x16x32_bf16 v[62:65], v[148:151], v[186:189], v[62:65]
	v_mfma_f32_16x16x32_bf16 v[50:53], v[174:177], v[186:189], v[50:53]
	v_mfma_f32_16x16x32_bf16 v[38:41], v[148:151], v[194:197], v[38:41]
	v_mfma_f32_16x16x32_bf16 v[34:37], v[174:177], v[194:197], v[34:37]
	v_mfma_f32_16x16x32_bf16 v[22:25], v[148:151], v[202:205], v[22:25]
	v_mfma_f32_16x16x32_bf16 v[18:21], v[174:177], v[202:205], v[18:21]
	v_mfma_f32_16x16x32_bf16 v[6:9], v[148:151], v[210:213], v[6:9]
	v_mfma_f32_16x16x32_bf16 v[2:5], v[174:177], v[210:213], v[2:5]
	v_mfma_f32_16x16x32_bf16 v[62:65], v[170:173], v[190:193], v[62:65]
	v_mfma_f32_16x16x32_bf16 v[50:53], v[178:181], v[190:193], v[50:53]
	v_mfma_f32_16x16x32_bf16 v[38:41], v[170:173], v[198:201], v[38:41]
	v_mfma_f32_16x16x32_bf16 v[34:37], v[178:181], v[198:201], v[34:37]
	v_mfma_f32_16x16x32_bf16 v[22:25], v[170:173], v[206:209], v[22:25]
	v_mfma_f32_16x16x32_bf16 v[18:21], v[178:181], v[206:209], v[18:21]
	v_mfma_f32_16x16x32_bf16 v[6:9], v[170:173], v[214:217], v[6:9]
	v_mfma_f32_16x16x32_bf16 v[2:5], v[178:181], v[214:217], v[2:5]
	s_barrier
; #define PG8_BAR __builtin_amdgcn_s_barrier()
;     ...
;         for (int t = 2; t < nt; t += 2) PG8_KITER(t);
;         if constexpr (ALIGN_EPI) { if (wr == 0) PG8_BAR; }
	s_setprio 0
	ds_read_b128 v[132:135], v130
	ds_read_b128 v[136:139], v130 offset:1024
	ds_read_b128 v[140:143], v130 offset:2048
	ds_read_b128 v[144:147], v130 offset:3072
	ds_read_b128 v[148:151], v131
	ds_read_b128 v[170:173], v131 offset:1024
	ds_read_b128 v[174:177], v131 offset:2048
	ds_read_b128 v[178:181], v131 offset:3072
	s_add_u32 s42, s42, 0x20000
	s_addc_u32 s43, s43, 0
	s_mov_b32 m0, s48
	s_nop 0
	global_load_lds_dwordx4 v154, s[100:101]
	s_mov_b32 m0, s49
	s_nop 0
	global_load_lds_dwordx4 v158, s[100:101]
	s_mov_b32 m0, s50
	ds_read_b128 v[186:189], v184 offset:32768
	ds_read_b128 v[190:193], v184 offset:33792
	ds_read_b128 v[194:197], v184 offset:34816
	ds_read_b128 v[198:201], v184 offset:35840
	ds_read_b128 v[202:205], v184 offset:36864
	ds_read_b128 v[206:209], v184 offset:37888
	ds_read_b128 v[210:213], v184 offset:38912
	ds_read_b128 v[214:217], v184 offset:39936
	global_load_lds_dwordx4 v154, s[42:43]
	s_mov_b32 m0, s51
	s_nop 0
	global_load_lds_dwordx4 v158, s[42:43]
	s_waitcnt vmcnt(8)
	s_waitcnt lgkmcnt(0)
	s_setprio 1
	s_barrier
	v_mfma_f32_16x16x32_bf16 v[122:125], v[132:135], v[186:189], v[122:125]
	v_mfma_f32_16x16x32_bf16 v[118:121], v[140:143], v[186:189], v[118:121]
	v_mfma_f32_16x16x32_bf16 v[110:113], v[132:135], v[194:197], v[110:113]
	v_mfma_f32_16x16x32_bf16 v[106:109], v[140:143], v[194:197], v[106:109]
	v_mfma_f32_16x16x32_bf16 v[94:97], v[132:135], v[202:205], v[94:97]
	v_mfma_f32_16x16x32_bf16 v[90:93], v[140:143], v[202:205], v[90:93]
	v_mfma_f32_16x16x32_bf16 v[78:81], v[132:135], v[210:213], v[78:81]
	v_mfma_f32_16x16x32_bf16 v[74:77], v[140:143], v[210:213], v[74:77]
	v_mfma_f32_16x16x32_bf16 v[122:125], v[136:139], v[190:193], v[122:125]
	v_mfma_f32_16x16x32_bf16 v[118:121], v[144:147], v[190:193], v[118:121]
	v_mfma_f32_16x16x32_bf16 v[110:113], v[136:139], v[198:201], v[110:113]
	v_mfma_f32_16x16x32_bf16 v[106:109], v[144:147], v[198:201], v[106:109]
	v_mfma_f32_16x16x32_bf16 v[94:97], v[136:139], v[206:209], v[94:97]
	v_mfma_f32_16x16x32_bf16 v[90:93], v[144:147], v[206:209], v[90:93]
	v_mfma_f32_16x16x32_bf16 v[78:81], v[136:139], v[214:217], v[78:81]
	v_mfma_f32_16x16x32_bf16 v[74:77], v[144:147], v[214:217], v[74:77]
	v_mfma_f32_16x16x32_bf16 v[126:129], v[148:151], v[186:189], v[126:129]
	v_mfma_f32_16x16x32_bf16 v[114:117], v[174:177], v[186:189], v[114:117]
	v_mfma_f32_16x16x32_bf16 v[102:105], v[148:151], v[194:197], v[102:105]
	v_mfma_f32_16x16x32_bf16 v[98:101], v[174:177], v[194:197], v[98:101]
	v_mfma_f32_16x16x32_bf16 v[86:89], v[148:151], v[202:205], v[86:89]
	v_mfma_f32_16x16x32_bf16 v[82:85], v[174:177], v[202:205], v[82:85]
	v_mfma_f32_16x16x32_bf16 v[70:73], v[148:151], v[210:213], v[70:73]
	v_mfma_f32_16x16x32_bf16 v[66:69], v[174:177], v[210:213], v[66:69]
	v_mfma_f32_16x16x32_bf16 v[126:129], v[170:173], v[190:193], v[126:129]
	v_mfma_f32_16x16x32_bf16 v[114:117], v[178:181], v[190:193], v[114:117]
	v_mfma_f32_16x16x32_bf16 v[102:105], v[170:173], v[198:201], v[102:105]
	v_mfma_f32_16x16x32_bf16 v[98:101], v[178:181], v[198:201], v[98:101]
	v_mfma_f32_16x16x32_bf16 v[86:89], v[170:173], v[206:209], v[86:89]
	v_mfma_f32_16x16x32_bf16 v[82:85], v[178:181], v[206:209], v[82:85]
	v_mfma_f32_16x16x32_bf16 v[70:73], v[170:173], v[214:217], v[70:73]
	v_mfma_f32_16x16x32_bf16 v[66:69], v[178:181], v[214:217], v[66:69]
	s_barrier
	s_setprio 0
	s_mov_b32 m0, s47
	s_add_u32 s98, s98, 0x80
	s_addc_u32 s99, s99, 0
	s_add_u32 s100, s100, 0x80
	s_addc_u32 s101, s101, 0
	s_add_u32 s38, s38, 0x20080
	ds_read_b128 v[186:189], v184 offset:49152
	ds_read_b128 v[190:193], v184 offset:50176
	ds_read_b128 v[194:197], v184 offset:51200
	ds_read_b128 v[198:201], v184 offset:52224
	ds_read_b128 v[202:205], v184 offset:53248
	ds_read_b128 v[206:209], v184 offset:54272
	ds_read_b128 v[210:213], v184 offset:55296
	ds_read_b128 v[214:217], v184 offset:56320
	global_load_lds_dwordx4 v156, s[98:99]
	s_mov_b32 m0, s68
	s_addc_u32 s39, s39, 0
	global_load_lds_dwordx4 v160, s[98:99]
	s_mov_b32 m0, s56
	s_nop 0
	global_load_lds_dwordx4 v156, s[38:39]
	s_mov_b32 m0, s57
	s_nop 0
	global_load_lds_dwordx4 v160, s[38:39]
	s_waitcnt vmcnt(6)
	s_waitcnt lgkmcnt(0)
	s_setprio 1
	s_barrier
	v_mfma_f32_16x16x32_bf16 v[58:61], v[132:135], v[186:189], v[58:61]
	v_mfma_f32_16x16x32_bf16 v[54:57], v[140:143], v[186:189], v[54:57]
	v_mfma_f32_16x16x32_bf16 v[46:49], v[132:135], v[194:197], v[46:49]
	v_mfma_f32_16x16x32_bf16 v[42:45], v[140:143], v[194:197], v[42:45]
	v_mfma_f32_16x16x32_bf16 v[30:33], v[132:135], v[202:205], v[30:33]
	v_mfma_f32_16x16x32_bf16 v[26:29], v[140:143], v[202:205], v[26:29]
	v_mfma_f32_16x16x32_bf16 v[14:17], v[132:135], v[210:213], v[14:17]
	v_mfma_f32_16x16x32_bf16 v[10:13], v[140:143], v[210:213], v[10:13]
	v_mfma_f32_16x16x32_bf16 v[58:61], v[136:139], v[190:193], v[58:61]
	v_mfma_f32_16x16x32_bf16 v[54:57], v[144:147], v[190:193], v[54:57]
	v_mfma_f32_16x16x32_bf16 v[46:49], v[136:139], v[198:201], v[46:49]
	v_mfma_f32_16x16x32_bf16 v[42:45], v[144:147], v[198:201], v[42:45]
	v_mfma_f32_16x16x32_bf16 v[30:33], v[136:139], v[206:209], v[30:33]
	v_mfma_f32_16x16x32_bf16 v[26:29], v[144:147], v[206:209], v[26:29]
	v_mfma_f32_16x16x32_bf16 v[14:17], v[136:139], v[214:217], v[14:17]
	v_mfma_f32_16x16x32_bf16 v[10:13], v[144:147], v[214:217], v[10:13]
	v_mfma_f32_16x16x32_bf16 v[62:65], v[148:151], v[186:189], v[62:65]
	v_mfma_f32_16x16x32_bf16 v[50:53], v[174:177], v[186:189], v[50:53]
	v_mfma_f32_16x16x32_bf16 v[38:41], v[148:151], v[194:197], v[38:41]
	v_mfma_f32_16x16x32_bf16 v[34:37], v[174:177], v[194:197], v[34:37]
	v_mfma_f32_16x16x32_bf16 v[22:25], v[148:151], v[202:205], v[22:25]
	v_mfma_f32_16x16x32_bf16 v[18:21], v[174:177], v[202:205], v[18:21]
	v_mfma_f32_16x16x32_bf16 v[6:9], v[148:151], v[210:213], v[6:9]
	v_mfma_f32_16x16x32_bf16 v[2:5], v[174:177], v[210:213], v[2:5]
	v_mfma_f32_16x16x32_bf16 v[62:65], v[170:173], v[190:193], v[62:65]
	v_mfma_f32_16x16x32_bf16 v[50:53], v[178:181], v[190:193], v[50:53]
	v_mfma_f32_16x16x32_bf16 v[38:41], v[170:173], v[198:201], v[38:41]
	v_mfma_f32_16x16x32_bf16 v[34:37], v[178:181], v[198:201], v[34:37]
	v_mfma_f32_16x16x32_bf16 v[22:25], v[170:173], v[206:209], v[22:25]
	v_mfma_f32_16x16x32_bf16 v[18:21], v[178:181], v[206:209], v[18:21]
	v_mfma_f32_16x16x32_bf16 v[6:9], v[170:173], v[214:217], v[6:9]
	v_mfma_f32_16x16x32_bf16 v[2:5], v[178:181], v[214:217], v[2:5]
	s_barrier
	s_setprio 0
	s_add_i32 s69, s69, 2
	s_add_u32 s40, s40, 0x100
	s_addc_u32 s41, s41, 0
	s_add_u32 s26, s26, 0x100
	s_addc_u32 s27, s27, 0
	s_cmp_gt_u32 s69, 5
	s_cbranch_scc0 .LBB0_1261
	s_mov_b32 m0, s52
	s_nop 0
	global_load_lds_dwordx4 v154, s[100:101]
	s_mov_b32 m0, s53
	s_nop 0
	global_load_lds_dwordx4 v158, s[100:101]
	s_and_b64 vcc, exec, s[16:17]
	s_cbranch_vccz .LBB0_1264
	s_barrier

;     __host__ __device__ bool next(int i, Unit& u) const { if (!StaticOrder::next(i >> 1, u)) return false; u.seg = i & 1; return true; }
;     ...
;         const bool has_next = S.next(ui + 1, nxt);
;         const char* nA = has_next ? PG8_APTR(nxt) : cA; const char* nB = has_next ? PG8_BPTR(nxt) : cB;
.LBB0_1344:
	s_ashr_i32 s25, s24, 31
	ds_read_b128 v[2:5], v150
	ds_read_b128 v[6:9], v150 offset:1024
	ds_read_b128 v[10:13], v150 offset:2048
	ds_read_b128 v[14:17], v150 offset:3072
	ds_read_b128 v[18:21], v151
	ds_read_b128 v[22:25], v151 offset:1024
	ds_read_b128 v[26:29], v151 offset:2048
	ds_read_b128 v[30:33], v151 offset:3072
	s_lshl_b64 s[26:27], s[24:25], 21
	s_add_u32 s28, s36, s26
	s_addc_u32 s29, s37, s27
	s_and_b64 s[26:27], s[4:5], exec
	s_cselect_b32 s1, s29, s41
	s_cselect_b32 s25, s28, s40
	s_and_b32 s8, s65, 0x7fffffff
	s_lshl_b64 s[26:27], s[8:9], 21
	s_add_u32 s30, s96, s26
	s_addc_u32 s31, s97, s27
	s_and_b64 s[26:27], s[4:5], exec
	s_cselect_b32 s8, s31, s39
	s_cselect_b32 s67, s30, s38
	s_add_u32 s26, s40, 0x100080
	s_addc_u32 s27, s41, 0
	s_mov_b32 m0, s53
	v_lshl_add_u64 v[66:67], s[26:27], 0, v[136:137]
	ds_read_b128 v[34:37], v152
	ds_read_b128 v[38:41], v152 offset:1024
	ds_read_b128 v[42:45], v152 offset:2048
	ds_read_b128 v[46:49], v152 offset:3072
	ds_read_b128 v[50:53], v152 offset:4096
	ds_read_b128 v[54:57], v152 offset:5120
	ds_read_b128 v[58:61], v152 offset:6144
	ds_read_b128 v[62:65], v152 offset:7168
	global_load_lds_dwordx4 v[66:67], off
	v_lshl_add_u64 v[66:67], s[26:27], 0, v[132:133]
	s_mov_b32 m0, s54
	s_nop 0
	global_load_lds_dwordx4 v[66:67], off
	s_waitcnt vmcnt(8)
	s_waitcnt lgkmcnt(0)
	s_setprio 1
	s_barrier
	v_mfma_f32_16x16x32_bf16 v[86:89], v[10:13], v[50:53], 0
	v_mfma_f32_16x16x32_bf16 v[90:93], v[14:17], v[54:57], v[86:89]
	v_mfma_f32_16x16x32_bf16 v[86:89], v[2:5], v[58:61], 0
	v_mfma_f32_16x16x32_bf16 v[66:69], v[2:5], v[34:37], 0
	v_mfma_f32_16x16x32_bf16 v[70:73], v[10:13], v[34:37], 0
	v_mfma_f32_16x16x32_bf16 v[74:77], v[2:5], v[42:45], 0
	v_mfma_f32_16x16x32_bf16 v[78:81], v[10:13], v[42:45], 0
	v_mfma_f32_16x16x32_bf16 v[82:85], v[2:5], v[50:53], 0
	v_mfma_f32_16x16x32_bf16 v[94:97], v[6:9], v[62:65], v[86:89]
	v_mfma_f32_16x16x32_bf16 v[86:89], v[10:13], v[58:61], 0
	v_mfma_f32_16x16x32_bf16 v[66:69], v[6:9], v[38:41], v[66:69]
	v_mfma_f32_16x16x32_bf16 v[70:73], v[14:17], v[38:41], v[70:73]
	v_mfma_f32_16x16x32_bf16 v[74:77], v[6:9], v[46:49], v[74:77]
	v_mfma_f32_16x16x32_bf16 v[78:81], v[14:17], v[46:49], v[78:81]
	v_mfma_f32_16x16x32_bf16 v[82:85], v[6:9], v[54:57], v[82:85]
	v_mfma_f32_16x16x32_bf16 v[106:109], v[14:17], v[62:65], v[86:89]
	v_mfma_f32_16x16x32_bf16 v[86:89], v[18:21], v[34:37], 0
	v_mfma_f32_16x16x32_bf16 v[34:37], v[26:29], v[34:37], 0
	v_mfma_f32_16x16x32_bf16 v[110:113], v[22:25], v[38:41], v[86:89]
	v_mfma_f32_16x16x32_bf16 v[34:37], v[30:33], v[38:41], v[34:37]
	v_mfma_f32_16x16x32_bf16 v[38:41], v[18:21], v[42:45], 0
	v_mfma_f32_16x16x32_bf16 v[42:45], v[26:29], v[42:45], 0
	v_mfma_f32_16x16x32_bf16 v[38:41], v[22:25], v[46:49], v[38:41]
	v_mfma_f32_16x16x32_bf16 v[42:45], v[30:33], v[46:49], v[42:45]
	v_mfma_f32_16x16x32_bf16 v[46:49], v[18:21], v[50:53], 0
	v_mfma_f32_16x16x32_bf16 v[50:53], v[26:29], v[50:53], 0
	v_mfma_f32_16x16x32_bf16 v[46:49], v[22:25], v[54:57], v[46:49]
	v_mfma_f32_16x16x32_bf16 v[50:53], v[30:33], v[54:57], v[50:53]
	v_mfma_f32_16x16x32_bf16 v[54:57], v[18:21], v[58:61], 0
	v_mfma_f32_16x16x32_bf16 v[58:61], v[26:29], v[58:61], 0
	v_mfma_f32_16x16x32_bf16 v[54:57], v[22:25], v[62:65], v[54:57]
	v_mfma_f32_16x16x32_bf16 v[58:61], v[30:33], v[62:65], v[58:61]
	s_barrier
	s_setprio 0
	v_lshl_add_u64 v[252:253], s[38:39], 0, v[134:135]
	s_mov_b32 m0, s59
	v_lshl_add_u64 v[146:147], v[252:253], 0, s[20:21]
	v_lshl_add_u64 v[142:143], s[38:39], 0, v[130:131]
	s_add_u32 s26, s38, 0x100100
	ds_read_b128 v[62:65], v152 offset:16384
	ds_read_b128 v[86:89], v152 offset:17408
	ds_read_b128 v[98:101], v152 offset:18432
	ds_read_b128 v[102:105], v152 offset:19456
	ds_read_b128 v[114:117], v152 offset:20480
	ds_read_b128 v[118:121], v152 offset:21504
	ds_read_b128 v[122:125], v152 offset:22528
	ds_read_b128 v[126:129], v152 offset:23552
	global_load_lds_dwordx4 v[146:147], off
	v_lshl_add_u64 v[146:147], v[142:143], 0, s[20:21]
	s_mov_b32 m0, s60
	s_addc_u32 s27, s39, 0
	global_load_lds_dwordx4 v[146:147], off
	v_lshl_add_u64 v[146:147], s[26:27], 0, v[134:135]
	s_mov_b32 m0, s61
	v_lshl_add_u64 v[144:145], s[40:41], 0, v[136:137]
	global_load_lds_dwordx4 v[146:147], off
	v_lshl_add_u64 v[146:147], s[26:27], 0, v[130:131]
	s_mov_b32 m0, s62
	v_lshl_add_u64 v[138:139], s[40:41], 0, v[132:133]
	global_load_lds_dwordx4 v[146:147], off
	v_lshl_add_u64 v[146:147], v[144:145], 0, s[20:21]
	s_mov_b32 m0, s13
	s_nop 0
	global_load_lds_dwordx4 v[146:147], off
	v_lshl_add_u64 v[146:147], v[138:139], 0, s[20:21]
	s_mov_b32 m0, s33
	s_nop 0
	global_load_lds_dwordx4 v[146:147], off
	s_waitcnt vmcnt(8)
	s_waitcnt lgkmcnt(0)
	s_setprio 1
	s_barrier
	v_mfma_f32_16x16x32_bf16 v[146:149], v[2:5], v[62:65], 0
	v_mfma_f32_16x16x32_bf16 v[156:159], v[6:9], v[86:89], v[146:149]
	v_mfma_f32_16x16x32_bf16 v[146:149], v[10:13], v[62:65], 0
	v_mfma_f32_16x16x32_bf16 v[160:163], v[14:17], v[86:89], v[146:149]
	v_mfma_f32_16x16x32_bf16 v[146:149], v[2:5], v[98:101], 0
	v_mfma_f32_16x16x32_bf16 v[164:167], v[6:9], v[102:105], v[146:149]
	v_mfma_f32_16x16x32_bf16 v[146:149], v[10:13], v[98:101], 0
	v_mfma_f32_16x16x32_bf16 v[168:171], v[14:17], v[102:105], v[146:149]
	v_mfma_f32_16x16x32_bf16 v[146:149], v[2:5], v[114:117], 0
	v_mfma_f32_16x16x32_bf16 v[2:5], v[2:5], v[122:125], 0
	v_mfma_f32_16x16x32_bf16 v[172:175], v[6:9], v[118:121], v[146:149]
	v_mfma_f32_16x16x32_bf16 v[2:5], v[6:9], v[126:129], v[2:5]
	v_mfma_f32_16x16x32_bf16 v[6:9], v[10:13], v[122:125], 0
	v_mfma_f32_16x16x32_bf16 v[146:149], v[10:13], v[114:117], 0
	v_mfma_f32_16x16x32_bf16 v[10:13], v[14:17], v[126:129], v[6:9]
	v_mfma_f32_16x16x32_bf16 v[176:179], v[14:17], v[118:121], v[146:149]
	v_mfma_f32_16x16x32_bf16 v[6:9], v[18:21], v[62:65], 0
	v_mfma_f32_16x16x32_bf16 v[14:17], v[22:25], v[86:89], v[6:9]
	v_mfma_f32_16x16x32_bf16 v[6:9], v[26:29], v[62:65], 0
	v_mfma_f32_16x16x32_bf16 v[180:183], v[30:33], v[86:89], v[6:9]
	v_mfma_f32_16x16x32_bf16 v[6:9], v[18:21], v[98:101], 0
	v_mfma_f32_16x16x32_bf16 v[184:187], v[22:25], v[102:105], v[6:9]
	v_mfma_f32_16x16x32_bf16 v[6:9], v[26:29], v[98:101], 0
	v_mfma_f32_16x16x32_bf16 v[188:191], v[30:33], v[102:105], v[6:9]
	v_mfma_f32_16x16x32_bf16 v[6:9], v[18:21], v[114:117], 0
	v_mfma_f32_16x16x32_bf16 v[192:195], v[22:25], v[118:121], v[6:9]
	v_mfma_f32_16x16x32_bf16 v[6:9], v[26:29], v[114:117], 0
	v_mfma_f32_16x16x32_bf16 v[196:199], v[30:33], v[118:121], v[6:9]
	v_mfma_f32_16x16x32_bf16 v[6:9], v[18:21], v[122:125], 0
	v_mfma_f32_16x16x32_bf16 v[200:203], v[22:25], v[126:129], v[6:9]
	v_mfma_f32_16x16x32_bf16 v[6:9], v[26:29], v[122:125], 0
	v_mfma_f32_16x16x32_bf16 v[204:207], v[30:33], v[126:129], v[6:9]
	s_barrier
	s_setprio 0
	s_add_i32 s56, 0, 0x1c000
	v_add_u32_e32 v146, s56, v155
	s_nop 2
	ds_read_b128 v[6:9], v154
	ds_read_b128 v[26:29], v154 offset:1024
	ds_read_b128 v[30:33], v154 offset:2048
	ds_read_b128 v[208:211], v154 offset:3072
	ds_read_b128 v[212:215], v146
	ds_read_b128 v[216:219], v146 offset:1024
	ds_read_b128 v[220:223], v146 offset:2048
	ds_read_b128 v[224:227], v146 offset:3072
	s_add_u32 s26, s40, 0x100100
	s_addc_u32 s27, s41, 0
	s_mov_b32 m0, s48
	v_lshl_add_u64 v[62:63], s[26:27], 0, v[136:137]
	ds_read_b128 v[18:21], v152 offset:32768
	ds_read_b128 v[22:25], v152 offset:33792
	ds_read_b128 v[228:231], v152 offset:34816
	ds_read_b128 v[232:235], v152 offset:35840
	ds_read_b128 v[236:239], v152 offset:36864
	ds_read_b128 v[240:243], v152 offset:37888
	ds_read_b128 v[244:247], v152 offset:38912
	ds_read_b128 v[248:251], v152 offset:39936
	global_load_lds_dwordx4 v[62:63], off
	v_lshl_add_u64 v[62:63], s[26:27], 0, v[132:133]
	s_mov_b32 m0, s49
	s_nop 0
	global_load_lds_dwordx4 v[62:63], off
	s_waitcnt vmcnt(8)
	s_waitcnt lgkmcnt(0)
	s_setprio 1
	s_barrier
	v_mfma_f32_16x16x32_bf16 v[62:65], v[6:9], v[18:21], v[66:69]
	v_mfma_f32_16x16x32_bf16 v[118:121], v[26:29], v[22:25], v[62:65]
	v_mfma_f32_16x16x32_bf16 v[62:65], v[30:33], v[18:21], v[70:73]
	v_mfma_f32_16x16x32_bf16 v[114:117], v[208:211], v[22:25], v[62:65]
	v_mfma_f32_16x16x32_bf16 v[62:65], v[6:9], v[228:231], v[74:77]
	v_mfma_f32_16x16x32_bf16 v[102:105], v[26:29], v[232:235], v[62:65]
	v_mfma_f32_16x16x32_bf16 v[62:65], v[30:33], v[228:231], v[78:81]
	v_mfma_f32_16x16x32_bf16 v[98:101], v[208:211], v[232:235], v[62:65]
	v_mfma_f32_16x16x32_bf16 v[62:65], v[6:9], v[236:239], v[82:85]
	v_mfma_f32_16x16x32_bf16 v[86:89], v[26:29], v[240:243], v[62:65]
	v_mfma_f32_16x16x32_bf16 v[62:65], v[30:33], v[236:239], v[90:93]
	v_mfma_f32_16x16x32_bf16 v[82:85], v[208:211], v[240:243], v[62:65]
	v_mfma_f32_16x16x32_bf16 v[62:65], v[6:9], v[244:247], v[94:97]
	v_mfma_f32_16x16x32_bf16 v[66:69], v[26:29], v[248:251], v[62:65]
	v_mfma_f32_16x16x32_bf16 v[62:65], v[30:33], v[244:247], v[106:109]
	v_mfma_f32_16x16x32_bf16 v[62:65], v[208:211], v[248:251], v[62:65]
	v_mfma_f32_16x16x32_bf16 v[70:73], v[212:215], v[18:21], v[110:113]
	v_mfma_f32_16x16x32_bf16 v[18:21], v[220:223], v[18:21], v[34:37]
	v_mfma_f32_16x16x32_bf16 v[122:125], v[224:227], v[22:25], v[18:21]
	v_mfma_f32_16x16x32_bf16 v[18:21], v[212:215], v[228:231], v[38:41]
	v_mfma_f32_16x16x32_bf16 v[110:113], v[216:219], v[232:235], v[18:21]
	v_mfma_f32_16x16x32_bf16 v[18:21], v[220:223], v[228:231], v[42:45]
	v_mfma_f32_16x16x32_bf16 v[106:109], v[224:227], v[232:235], v[18:21]
	v_mfma_f32_16x16x32_bf16 v[18:21], v[212:215], v[236:239], v[46:49]
	v_mfma_f32_16x16x32_bf16 v[94:97], v[216:219], v[240:243], v[18:21]
	v_mfma_f32_16x16x32_bf16 v[18:21], v[220:223], v[236:239], v[50:53]
	v_mfma_f32_16x16x32_bf16 v[90:93], v[224:227], v[240:243], v[18:21]
	v_mfma_f32_16x16x32_bf16 v[18:21], v[212:215], v[244:247], v[54:57]
	v_mfma_f32_16x16x32_bf16 v[78:81], v[216:219], v[248:251], v[18:21]
	v_mfma_f32_16x16x32_bf16 v[18:21], v[220:223], v[244:247], v[58:61]
	v_mfma_f32_16x16x32_bf16 v[126:129], v[216:219], v[22:25], v[70:73]
	v_mfma_f32_16x16x32_bf16 v[74:77], v[224:227], v[248:251], v[18:21]
	s_barrier
	s_setprio 0
	s_add_i32 s46, s63, s10
	s_add_i32 s47, s46, 0x2000
	s_nop 1
	v_lshl_add_u64 v[18:19], v[252:253], 0, s[22:23]
	s_mov_b32 m0, s46
	s_add_u32 s26, s38, 0x100180
	ds_read_b128 v[42:45], v152 offset:49152
	ds_read_b128 v[46:49], v152 offset:50176
	ds_read_b128 v[228:231], v152 offset:51200
	ds_read_b128 v[232:235], v152 offset:52224
	ds_read_b128 v[236:239], v152 offset:53248
	ds_read_b128 v[240:243], v152 offset:54272
	ds_read_b128 v[244:247], v152 offset:55296
	ds_read_b128 v[248:251], v152 offset:56320
	global_load_lds_dwordx4 v[18:19], off
	v_lshl_add_u64 v[18:19], v[142:143], 0, s[22:23]
	s_mov_b32 m0, s47
	s_addc_u32 s27, s39, 0
	s_add_i32 s56, s56, s10
	global_load_lds_dwordx4 v[18:19], off
	v_lshl_add_u64 v[18:19], s[26:27], 0, v[134:135]
	s_mov_b32 m0, s56
	s_add_i32 s57, s56, 0x2000
	global_load_lds_dwordx4 v[18:19], off
	v_lshl_add_u64 v[18:19], s[26:27], 0, v[130:131]
	s_mov_b32 m0, s57
	s_nop 0
	global_load_lds_dwordx4 v[18:19], off
	v_lshl_add_u64 v[18:19], v[144:145], 0, s[22:23]
	s_mov_b32 m0, s50
	s_nop 0
	global_load_lds_dwordx4 v[18:19], off
	v_lshl_add_u64 v[18:19], v[138:139], 0, s[22:23]
	s_mov_b32 m0, s51
	s_nop 0
	global_load_lds_dwordx4 v[18:19], off
	s_waitcnt vmcnt(8)
	s_waitcnt lgkmcnt(0)
	s_setprio 1
	s_barrier
	v_mfma_f32_16x16x32_bf16 v[18:21], v[6:9], v[42:45], v[156:159]
	v_mfma_f32_16x16x32_bf16 v[54:57], v[26:29], v[46:49], v[18:21]
	v_mfma_f32_16x16x32_bf16 v[18:21], v[30:33], v[42:45], v[160:163]
	v_mfma_f32_16x16x32_bf16 v[50:53], v[208:211], v[46:49], v[18:21]
	v_mfma_f32_16x16x32_bf16 v[18:21], v[6:9], v[228:231], v[164:167]
	v_mfma_f32_16x16x32_bf16 v[38:41], v[26:29], v[232:235], v[18:21]
	v_mfma_f32_16x16x32_bf16 v[18:21], v[30:33], v[228:231], v[168:171]
	v_mfma_f32_16x16x32_bf16 v[34:37], v[208:211], v[232:235], v[18:21]
	v_mfma_f32_16x16x32_bf16 v[18:21], v[6:9], v[236:239], v[172:175]
	v_mfma_f32_16x16x32_bf16 v[2:5], v[6:9], v[244:247], v[2:5]
	v_mfma_f32_16x16x32_bf16 v[22:25], v[26:29], v[240:243], v[18:21]
	v_mfma_f32_16x16x32_bf16 v[18:21], v[30:33], v[236:239], v[176:179]
	v_mfma_f32_16x16x32_bf16 v[6:9], v[26:29], v[248:251], v[2:5]
	v_mfma_f32_16x16x32_bf16 v[2:5], v[30:33], v[244:247], v[10:13]
	v_mfma_f32_16x16x32_bf16 v[18:21], v[208:211], v[240:243], v[18:21]
	v_mfma_f32_16x16x32_bf16 v[2:5], v[208:211], v[248:251], v[2:5]
	v_mfma_f32_16x16x32_bf16 v[10:13], v[212:215], v[42:45], v[14:17]
	v_mfma_f32_16x16x32_bf16 v[70:73], v[216:219], v[46:49], v[10:13]
	v_mfma_f32_16x16x32_bf16 v[10:13], v[220:223], v[42:45], v[180:183]
	v_mfma_f32_16x16x32_bf16 v[58:61], v[224:227], v[46:49], v[10:13]
	v_mfma_f32_16x16x32_bf16 v[10:13], v[212:215], v[228:231], v[184:187]
	v_mfma_f32_16x16x32_bf16 v[46:49], v[216:219], v[232:235], v[10:13]
	v_mfma_f32_16x16x32_bf16 v[10:13], v[220:223], v[228:231], v[188:191]
	v_mfma_f32_16x16x32_bf16 v[42:45], v[224:227], v[232:235], v[10:13]
	v_mfma_f32_16x16x32_bf16 v[10:13], v[212:215], v[236:239], v[192:195]
	v_mfma_f32_16x16x32_bf16 v[30:33], v[216:219], v[240:243], v[10:13]
	v_mfma_f32_16x16x32_bf16 v[10:13], v[220:223], v[236:239], v[196:199]
	v_mfma_f32_16x16x32_bf16 v[26:29], v[224:227], v[240:243], v[10:13]
	v_mfma_f32_16x16x32_bf16 v[10:13], v[212:215], v[244:247], v[200:203]
	v_mfma_f32_16x16x32_bf16 v[14:17], v[216:219], v[248:251], v[10:13]
	v_mfma_f32_16x16x32_bf16 v[10:13], v[220:223], v[244:247], v[204:207]
	v_mfma_f32_16x16x32_bf16 v[10:13], v[224:227], v[248:251], v[10:13]
	s_barrier
	s_setprio 0
	s_add_u32 s40, s40, 0x100180
	s_addc_u32 s41, s41, 0
	s_add_u32 s26, s38, 0x200
	s_addc_u32 s27, s39, 0
	s_mov_b32 s68, 0

.Lrb2_skip_40588:
	s_mov_b32 m0, s53
	ds_read_b128 v[188:191], v152
	ds_read_b128 v[192:195], v152 offset:1024
	ds_read_b128 v[196:199], v152 offset:2048
	ds_read_b128 v[200:203], v152 offset:3072
	ds_read_b128 v[204:207], v152 offset:4096
	ds_read_b128 v[208:211], v152 offset:5120
	ds_read_b128 v[212:215], v152 offset:6144
	ds_read_b128 v[216:219], v152 offset:7168
	global_load_lds_dwordx4 v0, s[40:41]
	s_mov_b32 m0, s54
	s_nop 0
	global_load_lds_dwordx4 v140, s[40:41]
	s_waitcnt vmcnt(8)
	s_waitcnt lgkmcnt(0)
	s_setprio 1
	s_barrier
	v_mfma_f32_16x16x32_bf16 v[118:121], v[156:159], v[188:191], v[118:121]
	v_mfma_f32_16x16x32_bf16 v[114:117], v[164:167], v[188:191], v[114:117]
	v_mfma_f32_16x16x32_bf16 v[102:105], v[156:159], v[196:199], v[102:105]
	v_mfma_f32_16x16x32_bf16 v[98:101], v[164:167], v[196:199], v[98:101]
	v_mfma_f32_16x16x32_bf16 v[86:89], v[156:159], v[204:207], v[86:89]
	v_mfma_f32_16x16x32_bf16 v[82:85], v[164:167], v[204:207], v[82:85]
	v_mfma_f32_16x16x32_bf16 v[66:69], v[156:159], v[212:215], v[66:69]
	v_mfma_f32_16x16x32_bf16 v[62:65], v[164:167], v[212:215], v[62:65]
	v_mfma_f32_16x16x32_bf16 v[118:121], v[160:163], v[192:195], v[118:121]
	v_mfma_f32_16x16x32_bf16 v[114:117], v[168:171], v[192:195], v[114:117]
	v_mfma_f32_16x16x32_bf16 v[102:105], v[160:163], v[200:203], v[102:105]
	v_mfma_f32_16x16x32_bf16 v[98:101], v[168:171], v[200:203], v[98:101]
	v_mfma_f32_16x16x32_bf16 v[86:89], v[160:163], v[208:211], v[86:89]
	v_mfma_f32_16x16x32_bf16 v[82:85], v[168:171], v[208:211], v[82:85]
	v_mfma_f32_16x16x32_bf16 v[66:69], v[160:163], v[216:219], v[66:69]
	v_mfma_f32_16x16x32_bf16 v[62:65], v[168:171], v[216:219], v[62:65]
	v_mfma_f32_16x16x32_bf16 v[126:129], v[172:175], v[188:191], v[126:129]
	v_mfma_f32_16x16x32_bf16 v[122:125], v[180:183], v[188:191], v[122:125]
	v_mfma_f32_16x16x32_bf16 v[110:113], v[172:175], v[196:199], v[110:113]
	v_mfma_f32_16x16x32_bf16 v[106:109], v[180:183], v[196:199], v[106:109]
	v_mfma_f32_16x16x32_bf16 v[94:97], v[172:175], v[204:207], v[94:97]
	v_mfma_f32_16x16x32_bf16 v[90:93], v[180:183], v[204:207], v[90:93]
	v_mfma_f32_16x16x32_bf16 v[78:81], v[172:175], v[212:215], v[78:81]
	v_mfma_f32_16x16x32_bf16 v[74:77], v[180:183], v[212:215], v[74:77]
	v_mfma_f32_16x16x32_bf16 v[126:129], v[176:179], v[192:195], v[126:129]
	v_mfma_f32_16x16x32_bf16 v[122:125], v[184:187], v[192:195], v[122:125]
	v_mfma_f32_16x16x32_bf16 v[110:113], v[176:179], v[200:203], v[110:113]
	v_mfma_f32_16x16x32_bf16 v[106:109], v[184:187], v[200:203], v[106:109]
	v_mfma_f32_16x16x32_bf16 v[94:97], v[176:179], v[208:211], v[94:97]
	v_mfma_f32_16x16x32_bf16 v[90:93], v[184:187], v[208:211], v[90:93]
	v_mfma_f32_16x16x32_bf16 v[78:81], v[176:179], v[216:219], v[78:81]
	v_mfma_f32_16x16x32_bf16 v[74:77], v[184:187], v[216:219], v[74:77]
	s_barrier
	s_setprio 0
	s_mov_b32 m0, s59
	s_mov_b64 s[98:99], s[38:39]
	s_add_u32 s70, s38, 0x100000
	ds_read_b128 v[188:191], v152 offset:16384
	ds_read_b128 v[192:195], v152 offset:17408
	ds_read_b128 v[196:199], v152 offset:18432
	ds_read_b128 v[200:203], v152 offset:19456
	ds_read_b128 v[204:207], v152 offset:20480
	ds_read_b128 v[208:211], v152 offset:21504
	ds_read_b128 v[212:215], v152 offset:22528
	ds_read_b128 v[216:219], v152 offset:23552
	global_load_lds_dwordx4 v134, s[38:39]
	s_mov_b32 m0, s60
	s_addc_u32 s71, s39, 0
	global_load_lds_dwordx4 v130, s[38:39]
	s_mov_b32 m0, s61
	s_mov_b64 s[100:101], s[42:43]
	global_load_lds_dwordx4 v134, s[70:71]
	s_mov_b32 m0, s62
	s_nop 0
	global_load_lds_dwordx4 v130, s[70:71]
	s_waitcnt vmcnt(6)
	s_waitcnt lgkmcnt(0)
	s_setprio 1
	s_barrier
	v_mfma_f32_16x16x32_bf16 v[54:57], v[156:159], v[188:191], v[54:57]
	v_mfma_f32_16x16x32_bf16 v[50:53], v[164:167], v[188:191], v[50:53]
	v_mfma_f32_16x16x32_bf16 v[38:41], v[156:159], v[196:199], v[38:41]
	v_mfma_f32_16x16x32_bf16 v[34:37], v[164:167], v[196:199], v[34:37]
	v_mfma_f32_16x16x32_bf16 v[22:25], v[156:159], v[204:207], v[22:25]
	v_mfma_f32_16x16x32_bf16 v[18:21], v[164:167], v[204:207], v[18:21]
	v_mfma_f32_16x16x32_bf16 v[6:9], v[156:159], v[212:215], v[6:9]
	v_mfma_f32_16x16x32_bf16 v[2:5], v[164:167], v[212:215], v[2:5]
	v_mfma_f32_16x16x32_bf16 v[54:57], v[160:163], v[192:195], v[54:57]
	v_mfma_f32_16x16x32_bf16 v[50:53], v[168:171], v[192:195], v[50:53]
	v_mfma_f32_16x16x32_bf16 v[38:41], v[160:163], v[200:203], v[38:41]
	v_mfma_f32_16x16x32_bf16 v[34:37], v[168:171], v[200:203], v[34:37]
	v_mfma_f32_16x16x32_bf16 v[22:25], v[160:163], v[208:211], v[22:25]
	v_mfma_f32_16x16x32_bf16 v[18:21], v[168:171], v[208:211], v[18:21]
	v_mfma_f32_16x16x32_bf16 v[6:9], v[160:163], v[216:219], v[6:9]
	v_mfma_f32_16x16x32_bf16 v[2:5], v[168:171], v[216:219], v[2:5]
	v_mfma_f32_16x16x32_bf16 v[70:73], v[172:175], v[188:191], v[70:73]
	v_mfma_f32_16x16x32_bf16 v[58:61], v[180:183], v[188:191], v[58:61]
	v_mfma_f32_16x16x32_bf16 v[46:49], v[172:175], v[196:199], v[46:49]
	v_mfma_f32_16x16x32_bf16 v[42:45], v[180:183], v[196:199], v[42:45]
	v_mfma_f32_16x16x32_bf16 v[30:33], v[172:175], v[204:207], v[30:33]
	v_mfma_f32_16x16x32_bf16 v[26:29], v[180:183], v[204:207], v[26:29]
	v_mfma_f32_16x16x32_bf16 v[14:17], v[172:175], v[212:215], v[14:17]
	v_mfma_f32_16x16x32_bf16 v[10:13], v[180:183], v[212:215], v[10:13]
	v_mfma_f32_16x16x32_bf16 v[70:73], v[176:179], v[192:195], v[70:73]
	v_mfma_f32_16x16x32_bf16 v[58:61], v[184:187], v[192:195], v[58:61]
	v_mfma_f32_16x16x32_bf16 v[46:49], v[176:179], v[200:203], v[46:49]
	v_mfma_f32_16x16x32_bf16 v[42:45], v[184:187], v[200:203], v[42:45]
	v_mfma_f32_16x16x32_bf16 v[30:33], v[176:179], v[208:211], v[30:33]
	v_mfma_f32_16x16x32_bf16 v[26:29], v[184:187], v[208:211], v[26:29]
	v_mfma_f32_16x16x32_bf16 v[14:17], v[176:179], v[216:219], v[14:17]
	v_mfma_f32_16x16x32_bf16 v[10:13], v[184:187], v[216:219], v[10:13]
	s_barrier
; #define PG8_BAR __builtin_amdgcn_s_barrier()
;     ...
;         for (int t = 2; t < nt; t += 2) PG8_KITER(t);
;         if constexpr (ALIGN_EPI) { if (wr == 0) PG8_BAR; }
	s_setprio 0
	ds_read_b128 v[156:159], v154
	ds_read_b128 v[160:163], v154 offset:1024
	ds_read_b128 v[164:167], v154 offset:2048
	ds_read_b128 v[168:171], v154 offset:3072
	ds_read_b128 v[172:175], v146
	ds_read_b128 v[176:179], v146 offset:1024
	ds_read_b128 v[180:183], v146 offset:2048
	ds_read_b128 v[184:187], v146 offset:3072
	s_add_u32 s42, s42, 0x100000
	s_addc_u32 s43, s43, 0
	s_mov_b32 m0, s13
	s_nop 0
	global_load_lds_dwordx4 v136, s[100:101]
	s_mov_b32 m0, s33
	s_nop 0
	global_load_lds_dwordx4 v132, s[100:101]
	s_mov_b32 m0, s48
	ds_read_b128 v[188:191], v152 offset:32768
	ds_read_b128 v[192:195], v152 offset:33792
	ds_read_b128 v[196:199], v152 offset:34816
	ds_read_b128 v[200:203], v152 offset:35840
	ds_read_b128 v[204:207], v152 offset:36864
	ds_read_b128 v[208:211], v152 offset:37888
	ds_read_b128 v[212:215], v152 offset:38912
	ds_read_b128 v[216:219], v152 offset:39936
	global_load_lds_dwordx4 v136, s[42:43]
	s_mov_b32 m0, s49
	s_nop 0
	global_load_lds_dwordx4 v132, s[42:43]
	s_waitcnt vmcnt(8)
	s_waitcnt lgkmcnt(0)
	s_setprio 1
	s_barrier
	v_mfma_f32_16x16x32_bf16 v[118:121], v[156:159], v[188:191], v[118:121]
	v_mfma_f32_16x16x32_bf16 v[114:117], v[164:167], v[188:191], v[114:117]
	v_mfma_f32_16x16x32_bf16 v[102:105], v[156:159], v[196:199], v[102:105]
	v_mfma_f32_16x16x32_bf16 v[98:101], v[164:167], v[196:199], v[98:101]
	v_mfma_f32_16x16x32_bf16 v[86:89], v[156:159], v[204:207], v[86:89]
	v_mfma_f32_16x16x32_bf16 v[82:85], v[164:167], v[204:207], v[82:85]
	v_mfma_f32_16x16x32_bf16 v[66:69], v[156:159], v[212:215], v[66:69]
	v_mfma_f32_16x16x32_bf16 v[62:65], v[164:167], v[212:215], v[62:65]
	v_mfma_f32_16x16x32_bf16 v[118:121], v[160:163], v[192:195], v[118:121]
	v_mfma_f32_16x16x32_bf16 v[114:117], v[168:171], v[192:195], v[114:117]
	v_mfma_f32_16x16x32_bf16 v[102:105], v[160:163], v[200:203], v[102:105]
	v_mfma_f32_16x16x32_bf16 v[98:101], v[168:171], v[200:203], v[98:101]
	v_mfma_f32_16x16x32_bf16 v[86:89], v[160:163], v[208:211], v[86:89]
	v_mfma_f32_16x16x32_bf16 v[82:85], v[168:171], v[208:211], v[82:85]
	v_mfma_f32_16x16x32_bf16 v[66:69], v[160:163], v[216:219], v[66:69]
	v_mfma_f32_16x16x32_bf16 v[62:65], v[168:171], v[216:219], v[62:65]
	v_mfma_f32_16x16x32_bf16 v[126:129], v[172:175], v[188:191], v[126:129]
	v_mfma_f32_16x16x32_bf16 v[122:125], v[180:183], v[188:191], v[122:125]
	v_mfma_f32_16x16x32_bf16 v[110:113], v[172:175], v[196:199], v[110:113]
	v_mfma_f32_16x16x32_bf16 v[106:109], v[180:183], v[196:199], v[106:109]
	v_mfma_f32_16x16x32_bf16 v[94:97], v[172:175], v[204:207], v[94:97]
	v_mfma_f32_16x16x32_bf16 v[90:93], v[180:183], v[204:207], v[90:93]
	v_mfma_f32_16x16x32_bf16 v[78:81], v[172:175], v[212:215], v[78:81]
	v_mfma_f32_16x16x32_bf16 v[74:77], v[180:183], v[212:215], v[74:77]
	v_mfma_f32_16x16x32_bf16 v[126:129], v[176:179], v[192:195], v[126:129]
	v_mfma_f32_16x16x32_bf16 v[122:125], v[184:187], v[192:195], v[122:125]
	v_mfma_f32_16x16x32_bf16 v[110:113], v[176:179], v[200:203], v[110:113]
	v_mfma_f32_16x16x32_bf16 v[106:109], v[184:187], v[200:203], v[106:109]
	v_mfma_f32_16x16x32_bf16 v[94:97], v[176:179], v[208:211], v[94:97]
	v_mfma_f32_16x16x32_bf16 v[90:93], v[184:187], v[208:211], v[90:93]
	v_mfma_f32_16x16x32_bf16 v[78:81], v[176:179], v[216:219], v[78:81]
	v_mfma_f32_16x16x32_bf16 v[74:77], v[184:187], v[216:219], v[74:77]
	s_barrier
	s_setprio 0
	s_mov_b32 m0, s46
	s_add_u32 s98, s98, 0x80
	s_addc_u32 s99, s99, 0
	s_add_u32 s100, s100, 0x80
	s_addc_u32 s101, s101, 0
	s_add_u32 s38, s38, 0x100080
	ds_read_b128 v[188:191], v152 offset:49152
	ds_read_b128 v[192:195], v152 offset:50176
	ds_read_b128 v[196:199], v152 offset:51200
	ds_read_b128 v[200:203], v152 offset:52224
	ds_read_b128 v[204:207], v152 offset:53248
	ds_read_b128 v[208:211], v152 offset:54272
	ds_read_b128 v[212:215], v152 offset:55296
	ds_read_b128 v[216:219], v152 offset:56320
	global_load_lds_dwordx4 v134, s[98:99]
	s_mov_b32 m0, s47
	s_addc_u32 s39, s39, 0
	global_load_lds_dwordx4 v130, s[98:99]
	s_mov_b32 m0, s56
	s_nop 0
	global_load_lds_dwordx4 v134, s[38:39]
	s_mov_b32 m0, s57
	s_nop 0
	global_load_lds_dwordx4 v130, s[38:39]
	s_waitcnt vmcnt(6)
	s_waitcnt lgkmcnt(0)
	s_setprio 1
	s_barrier
	v_mfma_f32_16x16x32_bf16 v[54:57], v[156:159], v[188:191], v[54:57]
	v_mfma_f32_16x16x32_bf16 v[50:53], v[164:167], v[188:191], v[50:53]
	v_mfma_f32_16x16x32_bf16 v[38:41], v[156:159], v[196:199], v[38:41]
	v_mfma_f32_16x16x32_bf16 v[34:37], v[164:167], v[196:199], v[34:37]
	v_mfma_f32_16x16x32_bf16 v[22:25], v[156:159], v[204:207], v[22:25]
	v_mfma_f32_16x16x32_bf16 v[18:21], v[164:167], v[204:207], v[18:21]
	v_mfma_f32_16x16x32_bf16 v[6:9], v[156:159], v[212:215], v[6:9]
	v_mfma_f32_16x16x32_bf16 v[2:5], v[164:167], v[212:215], v[2:5]
	v_mfma_f32_16x16x32_bf16 v[54:57], v[160:163], v[192:195], v[54:57]
	v_mfma_f32_16x16x32_bf16 v[50:53], v[168:171], v[192:195], v[50:53]
	v_mfma_f32_16x16x32_bf16 v[38:41], v[160:163], v[200:203], v[38:41]
	v_mfma_f32_16x16x32_bf16 v[34:37], v[168:171], v[200:203], v[34:37]
	v_mfma_f32_16x16x32_bf16 v[22:25], v[160:163], v[208:211], v[22:25]
	v_mfma_f32_16x16x32_bf16 v[18:21], v[168:171], v[208:211], v[18:21]
	v_mfma_f32_16x16x32_bf16 v[6:9], v[160:163], v[216:219], v[6:9]
	v_mfma_f32_16x16x32_bf16 v[2:5], v[168:171], v[216:219], v[2:5]
	v_mfma_f32_16x16x32_bf16 v[70:73], v[172:175], v[188:191], v[70:73]
	v_mfma_f32_16x16x32_bf16 v[58:61], v[180:183], v[188:191], v[58:61]
	v_mfma_f32_16x16x32_bf16 v[46:49], v[172:175], v[196:199], v[46:49]
	v_mfma_f32_16x16x32_bf16 v[42:45], v[180:183], v[196:199], v[42:45]
	v_mfma_f32_16x16x32_bf16 v[30:33], v[172:175], v[204:207], v[30:33]
	v_mfma_f32_16x16x32_bf16 v[26:29], v[180:183], v[204:207], v[26:29]
	v_mfma_f32_16x16x32_bf16 v[14:17], v[172:175], v[212:215], v[14:17]
	v_mfma_f32_16x16x32_bf16 v[10:13], v[180:183], v[212:215], v[10:13]
	v_mfma_f32_16x16x32_bf16 v[70:73], v[176:179], v[192:195], v[70:73]
	v_mfma_f32_16x16x32_bf16 v[58:61], v[184:187], v[192:195], v[58:61]
	v_mfma_f32_16x16x32_bf16 v[46:49], v[176:179], v[200:203], v[46:49]
	v_mfma_f32_16x16x32_bf16 v[42:45], v[184:187], v[200:203], v[42:45]
	v_mfma_f32_16x16x32_bf16 v[30:33], v[176:179], v[208:211], v[30:33]
	v_mfma_f32_16x16x32_bf16 v[26:29], v[184:187], v[208:211], v[26:29]
	v_mfma_f32_16x16x32_bf16 v[14:17], v[176:179], v[216:219], v[14:17]
	v_mfma_f32_16x16x32_bf16 v[10:13], v[184:187], v[216:219], v[10:13]
	s_barrier
	s_setprio 0
	s_add_i32 s68, s68, 2
	s_add_u32 s40, s40, 0x100
	s_addc_u32 s41, s41, 0
	s_add_u32 s26, s26, 0x100
	s_addc_u32 s27, s27, 0
	s_cmp_gt_u32 s68, 61
	s_cbranch_scc0 .LBB0_1345
	s_mov_b32 m0, s50
	s_nop 0
	global_load_lds_dwordx4 v136, s[100:101]
	s_mov_b32 m0, s51
	s_nop 0
	global_load_lds_dwordx4 v132, s[100:101]
	s_and_b64 vcc, exec, s[18:19]
	s_cbranch_vccz .LBB0_1348
	s_barrier

.LBB0_1424:
	ds_read_b128 v[2:5], v152
	ds_read_b128 v[6:9], v152 offset:1024
	ds_read_b128 v[10:13], v152 offset:2048
	ds_read_b128 v[14:17], v152 offset:3072
	ds_read_b128 v[18:21], v153
	ds_read_b128 v[22:25], v153 offset:1024
	ds_read_b128 v[26:29], v153 offset:2048
	ds_read_b128 v[30:33], v153 offset:3072
	s_add_u32 s22, s18, 0x2b0080
	s_addc_u32 s23, s19, 0
	s_add_i32 s49, s28, 0xc000
	v_lshl_add_u64 v[66:67], s[22:23], 0, v[130:131]
	s_mov_b32 m0, s49
	s_add_i32 s50, s28, 0xe000
	ds_read_b128 v[34:37], v154
	ds_read_b128 v[38:41], v154 offset:1024
	ds_read_b128 v[42:45], v154 offset:2048
	ds_read_b128 v[46:49], v154 offset:3072
	ds_read_b128 v[50:53], v154 offset:4096
	ds_read_b128 v[54:57], v154 offset:5120
	ds_read_b128 v[58:61], v154 offset:6144
	ds_read_b128 v[62:65], v154 offset:7168
	global_load_lds_dwordx4 v[66:67], off
	v_lshl_add_u64 v[66:67], s[22:23], 0, v[134:135]
	s_mov_b32 m0, s50
	s_nop 0
	global_load_lds_dwordx4 v[66:67], off
	s_waitcnt vmcnt(8)
	s_waitcnt lgkmcnt(0)
	s_setprio 1
	s_barrier
	v_mfma_f32_16x16x32_bf16 v[90:93], v[2:5], v[58:61], 0
	v_mfma_f32_16x16x32_bf16 v[66:69], v[2:5], v[34:37], 0
	v_mfma_f32_16x16x32_bf16 v[70:73], v[10:13], v[34:37], 0
	v_mfma_f32_16x16x32_bf16 v[74:77], v[2:5], v[42:45], 0
	v_mfma_f32_16x16x32_bf16 v[78:81], v[10:13], v[42:45], 0
	v_mfma_f32_16x16x32_bf16 v[82:85], v[2:5], v[50:53], 0
	v_mfma_f32_16x16x32_bf16 v[86:89], v[10:13], v[50:53], 0
	v_mfma_f32_16x16x32_bf16 v[98:101], v[6:9], v[62:65], v[90:93]
	v_mfma_f32_16x16x32_bf16 v[90:93], v[10:13], v[58:61], 0
	v_mfma_f32_16x16x32_bf16 v[66:69], v[6:9], v[38:41], v[66:69]
	v_mfma_f32_16x16x32_bf16 v[70:73], v[14:17], v[38:41], v[70:73]
	v_mfma_f32_16x16x32_bf16 v[74:77], v[6:9], v[46:49], v[74:77]
	v_mfma_f32_16x16x32_bf16 v[78:81], v[14:17], v[46:49], v[78:81]
	v_mfma_f32_16x16x32_bf16 v[82:85], v[6:9], v[54:57], v[82:85]
	v_mfma_f32_16x16x32_bf16 v[86:89], v[14:17], v[54:57], v[86:89]
	v_mfma_f32_16x16x32_bf16 v[102:105], v[14:17], v[62:65], v[90:93]
	v_mfma_f32_16x16x32_bf16 v[90:93], v[18:21], v[34:37], 0
	v_mfma_f32_16x16x32_bf16 v[34:37], v[26:29], v[34:37], 0
	v_mfma_f32_16x16x32_bf16 v[114:117], v[22:25], v[38:41], v[90:93]
	v_mfma_f32_16x16x32_bf16 v[34:37], v[30:33], v[38:41], v[34:37]
	v_mfma_f32_16x16x32_bf16 v[38:41], v[18:21], v[42:45], 0
	v_mfma_f32_16x16x32_bf16 v[42:45], v[26:29], v[42:45], 0
	v_mfma_f32_16x16x32_bf16 v[38:41], v[22:25], v[46:49], v[38:41]
	v_mfma_f32_16x16x32_bf16 v[42:45], v[30:33], v[46:49], v[42:45]
	v_mfma_f32_16x16x32_bf16 v[46:49], v[18:21], v[50:53], 0
	v_mfma_f32_16x16x32_bf16 v[50:53], v[26:29], v[50:53], 0
	v_mfma_f32_16x16x32_bf16 v[46:49], v[22:25], v[54:57], v[46:49]
	v_mfma_f32_16x16x32_bf16 v[50:53], v[30:33], v[54:57], v[50:53]
	v_mfma_f32_16x16x32_bf16 v[54:57], v[18:21], v[58:61], 0
	v_mfma_f32_16x16x32_bf16 v[58:61], v[26:29], v[58:61], 0
	v_mfma_f32_16x16x32_bf16 v[54:57], v[22:25], v[62:65], v[54:57]
	v_mfma_f32_16x16x32_bf16 v[58:61], v[30:33], v[62:65], v[58:61]
	s_barrier
	s_setprio 0
	s_add_i32 s51, s39, s25
	v_lshl_add_u64 v[248:249], s[20:21], 0, v[132:133]
	s_add_i32 s52, s51, 0x2000
	v_lshl_add_u64 v[146:147], v[248:249], 0, s[12:13]
	s_mov_b32 m0, s51
	v_lshl_add_u64 v[250:251], s[20:21], 0, v[136:137]
	s_add_u32 s22, s20, 0x2b0100
	ds_read_b128 v[62:65], v154 offset:16384
	ds_read_b128 v[90:93], v154 offset:17408
	ds_read_b128 v[94:97], v154 offset:18432
	ds_read_b128 v[106:109], v154 offset:19456
	ds_read_b128 v[110:113], v154 offset:20480
	ds_read_b128 v[118:121], v154 offset:21504
	ds_read_b128 v[122:125], v154 offset:22528
	ds_read_b128 v[126:129], v154 offset:23552
	global_load_lds_dwordx4 v[146:147], off
	v_lshl_add_u64 v[146:147], v[250:251], 0, s[12:13]
	s_mov_b32 m0, s52
	s_addc_u32 s23, s21, 0
	s_add_i32 s46, s40, s25
	global_load_lds_dwordx4 v[146:147], off
	v_lshl_add_u64 v[146:147], s[22:23], 0, v[132:133]
	s_mov_b32 m0, s46
	s_add_i32 s47, s46, 0x2000
	global_load_lds_dwordx4 v[146:147], off
	v_lshl_add_u64 v[146:147], s[22:23], 0, v[136:137]
	s_mov_b32 m0, s47
	v_lshl_add_u64 v[252:253], s[18:19], 0, v[130:131]
	global_load_lds_dwordx4 v[146:147], off
	v_lshl_add_u64 v[146:147], v[252:253], 0, s[12:13]
	s_mov_b32 m0, s28
	v_lshl_add_u64 v[142:143], s[18:19], 0, v[134:135]
	global_load_lds_dwordx4 v[146:147], off
	v_lshl_add_u64 v[146:147], v[142:143], 0, s[12:13]
	s_mov_b32 m0, s29
	s_nop 0
	global_load_lds_dwordx4 v[146:147], off
	s_waitcnt vmcnt(8)
	s_waitcnt lgkmcnt(0)
	s_setprio 1
	s_barrier
	v_mfma_f32_16x16x32_bf16 v[146:149], v[2:5], v[62:65], 0
	v_mfma_f32_16x16x32_bf16 v[160:163], v[2:5], v[94:97], 0
	v_mfma_f32_16x16x32_bf16 v[168:171], v[2:5], v[110:113], 0
	v_mfma_f32_16x16x32_bf16 v[2:5], v[2:5], v[122:125], 0
	v_mfma_f32_16x16x32_bf16 v[148:151], v[6:9], v[90:93], v[146:149]
	v_mfma_f32_16x16x32_bf16 v[160:163], v[6:9], v[106:109], v[160:163]
	v_mfma_f32_16x16x32_bf16 v[168:171], v[6:9], v[118:121], v[168:171]
	v_mfma_f32_16x16x32_bf16 v[2:5], v[6:9], v[126:129], v[2:5]
	v_mfma_f32_16x16x32_bf16 v[6:9], v[10:13], v[122:125], 0
	v_mfma_f32_16x16x32_bf16 v[156:159], v[10:13], v[62:65], 0
	v_mfma_f32_16x16x32_bf16 v[164:167], v[10:13], v[94:97], 0
	v_mfma_f32_16x16x32_bf16 v[172:175], v[10:13], v[110:113], 0
	v_mfma_f32_16x16x32_bf16 v[6:9], v[14:17], v[126:129], v[6:9]
	v_mfma_f32_16x16x32_bf16 v[156:159], v[14:17], v[90:93], v[156:159]
	v_mfma_f32_16x16x32_bf16 v[164:167], v[14:17], v[106:109], v[164:167]
	v_mfma_f32_16x16x32_bf16 v[172:175], v[14:17], v[118:121], v[172:175]
	v_mfma_f32_16x16x32_bf16 v[10:13], v[18:21], v[62:65], 0
	v_mfma_f32_16x16x32_bf16 v[176:179], v[22:25], v[90:93], v[10:13]
	v_mfma_f32_16x16x32_bf16 v[10:13], v[26:29], v[62:65], 0
	v_mfma_f32_16x16x32_bf16 v[180:183], v[30:33], v[90:93], v[10:13]
	v_mfma_f32_16x16x32_bf16 v[10:13], v[18:21], v[94:97], 0
	v_mfma_f32_16x16x32_bf16 v[184:187], v[22:25], v[106:109], v[10:13]
	v_mfma_f32_16x16x32_bf16 v[10:13], v[26:29], v[94:97], 0
	v_mfma_f32_16x16x32_bf16 v[188:191], v[30:33], v[106:109], v[10:13]
	v_mfma_f32_16x16x32_bf16 v[10:13], v[18:21], v[110:113], 0
	v_mfma_f32_16x16x32_bf16 v[192:195], v[22:25], v[118:121], v[10:13]
	v_mfma_f32_16x16x32_bf16 v[10:13], v[26:29], v[110:113], 0
	v_mfma_f32_16x16x32_bf16 v[196:199], v[30:33], v[118:121], v[10:13]
	v_mfma_f32_16x16x32_bf16 v[10:13], v[18:21], v[122:125], 0
	v_mfma_f32_16x16x32_bf16 v[200:203], v[22:25], v[126:129], v[10:13]
	v_mfma_f32_16x16x32_bf16 v[10:13], v[26:29], v[122:125], 0
	v_mfma_f32_16x16x32_bf16 v[204:207], v[30:33], v[126:129], v[10:13]
	s_barrier
	s_setprio 0
	s_add_i32 s53, 0, 0x18000
	s_add_i32 s55, 0, 0x1c000
	v_add_u32_e32 v146, s53, v1
	v_add_u32_e32 v147, s55, v1
	s_nop 0
	ds_read_b128 v[10:13], v146
	ds_read_b128 v[14:17], v146 offset:1024
	ds_read_b128 v[18:21], v146 offset:2048
	ds_read_b128 v[22:25], v146 offset:3072
	ds_read_b128 v[208:211], v147
	ds_read_b128 v[212:215], v147 offset:1024
	ds_read_b128 v[216:219], v147 offset:2048
	ds_read_b128 v[220:223], v147 offset:3072
	s_add_u32 s22, s18, 0x2b0100
	s_addc_u32 s23, s19, 0
	s_mov_b32 m0, s30
	v_lshl_add_u64 v[90:91], s[22:23], 0, v[130:131]
	ds_read_b128 v[26:29], v154 offset:32768
	ds_read_b128 v[30:33], v154 offset:33792
	ds_read_b128 v[62:65], v154 offset:34816
	ds_read_b128 v[224:227], v154 offset:35840
	ds_read_b128 v[228:231], v154 offset:36864
	ds_read_b128 v[232:235], v154 offset:37888
	ds_read_b128 v[236:239], v154 offset:38912
	ds_read_b128 v[240:243], v154 offset:39936
	global_load_lds_dwordx4 v[90:91], off
	v_lshl_add_u64 v[90:91], s[22:23], 0, v[134:135]
	s_mov_b32 m0, s31
	s_nop 0
	global_load_lds_dwordx4 v[90:91], off
	s_waitcnt vmcnt(8)
	s_waitcnt lgkmcnt(0)
	s_setprio 1
	s_barrier
	v_mfma_f32_16x16x32_bf16 v[66:69], v[10:13], v[26:29], v[66:69]
	v_mfma_f32_16x16x32_bf16 v[126:129], v[14:17], v[30:33], v[66:69]
	v_mfma_f32_16x16x32_bf16 v[66:69], v[18:21], v[26:29], v[70:73]
	v_mfma_f32_16x16x32_bf16 v[122:125], v[22:25], v[30:33], v[66:69]
	v_mfma_f32_16x16x32_bf16 v[66:69], v[10:13], v[62:65], v[74:77]
	v_mfma_f32_16x16x32_bf16 v[110:113], v[14:17], v[224:227], v[66:69]
	v_mfma_f32_16x16x32_bf16 v[66:69], v[18:21], v[62:65], v[78:81]
	v_mfma_f32_16x16x32_bf16 v[106:109], v[22:25], v[224:227], v[66:69]
	v_mfma_f32_16x16x32_bf16 v[66:69], v[10:13], v[228:231], v[82:85]
	v_mfma_f32_16x16x32_bf16 v[94:97], v[14:17], v[232:235], v[66:69]
	v_mfma_f32_16x16x32_bf16 v[66:69], v[18:21], v[228:231], v[86:89]
	v_mfma_f32_16x16x32_bf16 v[90:93], v[22:25], v[232:235], v[66:69]
	v_mfma_f32_16x16x32_bf16 v[66:69], v[10:13], v[236:239], v[98:101]
	v_mfma_f32_16x16x32_bf16 v[78:81], v[14:17], v[240:243], v[66:69]
	v_mfma_f32_16x16x32_bf16 v[66:69], v[18:21], v[236:239], v[102:105]
	v_mfma_f32_16x16x32_bf16 v[74:77], v[22:25], v[240:243], v[66:69]
	v_mfma_f32_16x16x32_bf16 v[66:69], v[208:211], v[26:29], v[114:117]
	v_mfma_f32_16x16x32_bf16 v[26:29], v[216:219], v[26:29], v[34:37]
	v_mfma_f32_16x16x32_bf16 v[114:117], v[220:223], v[30:33], v[26:29]
	v_mfma_f32_16x16x32_bf16 v[26:29], v[208:211], v[62:65], v[38:41]
	v_mfma_f32_16x16x32_bf16 v[102:105], v[212:215], v[224:227], v[26:29]
	v_mfma_f32_16x16x32_bf16 v[26:29], v[216:219], v[62:65], v[42:45]
	v_mfma_f32_16x16x32_bf16 v[98:101], v[220:223], v[224:227], v[26:29]
	v_mfma_f32_16x16x32_bf16 v[26:29], v[208:211], v[228:231], v[46:49]
	v_mfma_f32_16x16x32_bf16 v[86:89], v[212:215], v[232:235], v[26:29]
	v_mfma_f32_16x16x32_bf16 v[26:29], v[216:219], v[228:231], v[50:53]
	v_mfma_f32_16x16x32_bf16 v[82:85], v[220:223], v[232:235], v[26:29]
	v_mfma_f32_16x16x32_bf16 v[26:29], v[208:211], v[236:239], v[54:57]
	v_mfma_f32_16x16x32_bf16 v[70:73], v[212:215], v[240:243], v[26:29]
	v_mfma_f32_16x16x32_bf16 v[26:29], v[216:219], v[236:239], v[58:61]
	v_mfma_f32_16x16x32_bf16 v[118:121], v[212:215], v[30:33], v[66:69]
	v_mfma_f32_16x16x32_bf16 v[66:69], v[220:223], v[240:243], v[26:29]
	s_barrier
	s_setprio 0
	s_add_i32 s53, s53, s25
	s_add_i32 s54, s53, 0x2000
	s_nop 1
	v_lshl_add_u64 v[26:27], v[248:249], 0, s[14:15]
	s_mov_b32 m0, s53
	s_add_u32 s22, s20, 0x2b0180
	ds_read_b128 v[34:37], v154 offset:49152
	ds_read_b128 v[38:41], v154 offset:50176
	ds_read_b128 v[224:227], v154 offset:51200
	ds_read_b128 v[228:231], v154 offset:52224
	ds_read_b128 v[232:235], v154 offset:53248
	ds_read_b128 v[236:239], v154 offset:54272
	ds_read_b128 v[240:243], v154 offset:55296
	ds_read_b128 v[244:247], v154 offset:56320
	global_load_lds_dwordx4 v[26:27], off
	v_lshl_add_u64 v[26:27], v[250:251], 0, s[14:15]
	s_mov_b32 m0, s54
	s_addc_u32 s23, s21, 0
	s_add_i32 s55, s55, s25
	global_load_lds_dwordx4 v[26:27], off
	v_lshl_add_u64 v[26:27], s[22:23], 0, v[132:133]
	s_mov_b32 m0, s55
	s_add_i32 s56, s55, 0x2000
	global_load_lds_dwordx4 v[26:27], off
	v_lshl_add_u64 v[26:27], s[22:23], 0, v[136:137]
	s_mov_b32 m0, s56
	s_nop 0
	global_load_lds_dwordx4 v[26:27], off
	v_lshl_add_u64 v[26:27], v[252:253], 0, s[14:15]
	s_mov_b32 m0, s34
	s_nop 0
	global_load_lds_dwordx4 v[26:27], off
	v_lshl_add_u64 v[26:27], v[142:143], 0, s[14:15]
	s_mov_b32 m0, s35
	s_nop 0
	global_load_lds_dwordx4 v[26:27], off
	s_waitcnt vmcnt(8)
	s_waitcnt lgkmcnt(0)
	s_setprio 1
	s_barrier
	v_mfma_f32_16x16x32_bf16 v[26:29], v[10:13], v[34:37], v[148:151]
	v_mfma_f32_16x16x32_bf16 v[62:65], v[14:17], v[38:41], v[26:29]
	v_mfma_f32_16x16x32_bf16 v[26:29], v[18:21], v[34:37], v[156:159]
	v_mfma_f32_16x16x32_bf16 v[58:61], v[22:25], v[38:41], v[26:29]
	v_mfma_f32_16x16x32_bf16 v[26:29], v[10:13], v[224:227], v[160:163]
	v_mfma_f32_16x16x32_bf16 v[46:49], v[14:17], v[228:231], v[26:29]
	v_mfma_f32_16x16x32_bf16 v[26:29], v[18:21], v[224:227], v[164:167]
	v_mfma_f32_16x16x32_bf16 v[42:45], v[22:25], v[228:231], v[26:29]
	v_mfma_f32_16x16x32_bf16 v[26:29], v[10:13], v[232:235], v[168:171]
	v_mfma_f32_16x16x32_bf16 v[2:5], v[10:13], v[240:243], v[2:5]
	v_mfma_f32_16x16x32_bf16 v[30:33], v[14:17], v[236:239], v[26:29]
	v_mfma_f32_16x16x32_bf16 v[26:29], v[18:21], v[232:235], v[172:175]
	v_mfma_f32_16x16x32_bf16 v[14:17], v[14:17], v[244:247], v[2:5]
	v_mfma_f32_16x16x32_bf16 v[2:5], v[18:21], v[240:243], v[6:9]
	v_mfma_f32_16x16x32_bf16 v[26:29], v[22:25], v[236:239], v[26:29]
	v_mfma_f32_16x16x32_bf16 v[10:13], v[22:25], v[244:247], v[2:5]
	v_mfma_f32_16x16x32_bf16 v[2:5], v[208:211], v[34:37], v[176:179]
	v_mfma_f32_16x16x32_bf16 v[54:57], v[212:215], v[38:41], v[2:5]
	v_mfma_f32_16x16x32_bf16 v[2:5], v[216:219], v[34:37], v[180:183]
	v_mfma_f32_16x16x32_bf16 v[50:53], v[220:223], v[38:41], v[2:5]
	v_mfma_f32_16x16x32_bf16 v[2:5], v[208:211], v[224:227], v[184:187]
	v_mfma_f32_16x16x32_bf16 v[38:41], v[212:215], v[228:231], v[2:5]
	v_mfma_f32_16x16x32_bf16 v[2:5], v[216:219], v[224:227], v[188:191]
	v_mfma_f32_16x16x32_bf16 v[34:37], v[220:223], v[228:231], v[2:5]
	v_mfma_f32_16x16x32_bf16 v[2:5], v[208:211], v[232:235], v[192:195]
	v_mfma_f32_16x16x32_bf16 v[22:25], v[212:215], v[236:239], v[2:5]
	v_mfma_f32_16x16x32_bf16 v[2:5], v[216:219], v[232:235], v[196:199]
	v_mfma_f32_16x16x32_bf16 v[18:21], v[220:223], v[236:239], v[2:5]
	v_mfma_f32_16x16x32_bf16 v[2:5], v[208:211], v[240:243], v[200:203]
	v_mfma_f32_16x16x32_bf16 v[6:9], v[212:215], v[244:247], v[2:5]
	v_mfma_f32_16x16x32_bf16 v[2:5], v[216:219], v[240:243], v[204:207]
	v_mfma_f32_16x16x32_bf16 v[2:5], v[220:223], v[244:247], v[2:5]
	s_barrier
	s_setprio 0
	s_add_u32 s26, s20, 0x200
	s_addc_u32 s27, s21, 0
	s_mov_b32 s57, 0

.Lrb2_skip_42710:
	s_mov_b32 m0, s49
	ds_read_b128 v[184:187], v154
	ds_read_b128 v[188:191], v154 offset:1024
	ds_read_b128 v[192:195], v154 offset:2048
	ds_read_b128 v[196:199], v154 offset:3072
	ds_read_b128 v[200:203], v154 offset:4096
	ds_read_b128 v[204:207], v154 offset:5120
	ds_read_b128 v[208:211], v154 offset:6144
	ds_read_b128 v[212:215], v154 offset:7168
	global_load_lds_dwordx4 v138, s[18:19]
	s_mov_b32 m0, s50
	s_nop 0
	global_load_lds_dwordx4 v140, s[18:19]
	s_waitcnt vmcnt(8)
	s_waitcnt lgkmcnt(0)
	s_setprio 1
	s_barrier
	v_mfma_f32_16x16x32_bf16 v[126:129], v[148:151], v[184:187], v[126:129]
	v_mfma_f32_16x16x32_bf16 v[122:125], v[160:163], v[184:187], v[122:125]
	v_mfma_f32_16x16x32_bf16 v[110:113], v[148:151], v[192:195], v[110:113]
	v_mfma_f32_16x16x32_bf16 v[106:109], v[160:163], v[192:195], v[106:109]
	v_mfma_f32_16x16x32_bf16 v[94:97], v[148:151], v[200:203], v[94:97]
	v_mfma_f32_16x16x32_bf16 v[90:93], v[160:163], v[200:203], v[90:93]
	v_mfma_f32_16x16x32_bf16 v[78:81], v[148:151], v[208:211], v[78:81]
	v_mfma_f32_16x16x32_bf16 v[74:77], v[160:163], v[208:211], v[74:77]
	v_mfma_f32_16x16x32_bf16 v[126:129], v[156:159], v[188:191], v[126:129]
	v_mfma_f32_16x16x32_bf16 v[122:125], v[164:167], v[188:191], v[122:125]
	v_mfma_f32_16x16x32_bf16 v[110:113], v[156:159], v[196:199], v[110:113]
	v_mfma_f32_16x16x32_bf16 v[106:109], v[164:167], v[196:199], v[106:109]
	v_mfma_f32_16x16x32_bf16 v[94:97], v[156:159], v[204:207], v[94:97]
	v_mfma_f32_16x16x32_bf16 v[90:93], v[164:167], v[204:207], v[90:93]
	v_mfma_f32_16x16x32_bf16 v[78:81], v[156:159], v[212:215], v[78:81]
	v_mfma_f32_16x16x32_bf16 v[74:77], v[164:167], v[212:215], v[74:77]
	v_mfma_f32_16x16x32_bf16 v[118:121], v[168:171], v[184:187], v[118:121]
	v_mfma_f32_16x16x32_bf16 v[114:117], v[176:179], v[184:187], v[114:117]
	v_mfma_f32_16x16x32_bf16 v[102:105], v[168:171], v[192:195], v[102:105]
	v_mfma_f32_16x16x32_bf16 v[98:101], v[176:179], v[192:195], v[98:101]
	v_mfma_f32_16x16x32_bf16 v[86:89], v[168:171], v[200:203], v[86:89]
	v_mfma_f32_16x16x32_bf16 v[82:85], v[176:179], v[200:203], v[82:85]
	v_mfma_f32_16x16x32_bf16 v[70:73], v[168:171], v[208:211], v[70:73]
	v_mfma_f32_16x16x32_bf16 v[66:69], v[176:179], v[208:211], v[66:69]
	v_mfma_f32_16x16x32_bf16 v[118:121], v[172:175], v[188:191], v[118:121]
	v_mfma_f32_16x16x32_bf16 v[114:117], v[180:183], v[188:191], v[114:117]
	v_mfma_f32_16x16x32_bf16 v[102:105], v[172:175], v[196:199], v[102:105]
	v_mfma_f32_16x16x32_bf16 v[98:101], v[180:183], v[196:199], v[98:101]
	v_mfma_f32_16x16x32_bf16 v[86:89], v[172:175], v[204:207], v[86:89]
	v_mfma_f32_16x16x32_bf16 v[82:85], v[180:183], v[204:207], v[82:85]
	v_mfma_f32_16x16x32_bf16 v[70:73], v[172:175], v[212:215], v[70:73]
	v_mfma_f32_16x16x32_bf16 v[66:69], v[180:183], v[212:215], v[66:69]
	s_barrier
	s_setprio 0
	s_mov_b32 m0, s51
	s_mov_b64 s[98:99], s[20:21]
	s_add_u32 s58, s20, 0x2b0000
	ds_read_b128 v[184:187], v154 offset:16384
	ds_read_b128 v[188:191], v154 offset:17408
	ds_read_b128 v[192:195], v154 offset:18432
	ds_read_b128 v[196:199], v154 offset:19456
	ds_read_b128 v[200:203], v154 offset:20480
	ds_read_b128 v[204:207], v154 offset:21504
	ds_read_b128 v[208:211], v154 offset:22528
	ds_read_b128 v[212:215], v154 offset:23552
	global_load_lds_dwordx4 v132, s[20:21]
	s_mov_b32 m0, s52
	s_addc_u32 s59, s21, 0
	global_load_lds_dwordx4 v136, s[20:21]
	s_mov_b32 m0, s46
	s_mov_b64 s[100:101], s[22:23]
	global_load_lds_dwordx4 v132, s[58:59]
	s_mov_b32 m0, s47
	s_nop 0
	global_load_lds_dwordx4 v136, s[58:59]
	s_waitcnt vmcnt(6)
	s_waitcnt lgkmcnt(0)
	s_setprio 1
	s_barrier
	v_mfma_f32_16x16x32_bf16 v[62:65], v[148:151], v[184:187], v[62:65]
	v_mfma_f32_16x16x32_bf16 v[58:61], v[160:163], v[184:187], v[58:61]
	v_mfma_f32_16x16x32_bf16 v[46:49], v[148:151], v[192:195], v[46:49]
	v_mfma_f32_16x16x32_bf16 v[42:45], v[160:163], v[192:195], v[42:45]
	v_mfma_f32_16x16x32_bf16 v[30:33], v[148:151], v[200:203], v[30:33]
	v_mfma_f32_16x16x32_bf16 v[26:29], v[160:163], v[200:203], v[26:29]
	v_mfma_f32_16x16x32_bf16 v[14:17], v[148:151], v[208:211], v[14:17]
	v_mfma_f32_16x16x32_bf16 v[10:13], v[160:163], v[208:211], v[10:13]
	v_mfma_f32_16x16x32_bf16 v[62:65], v[156:159], v[188:191], v[62:65]
	v_mfma_f32_16x16x32_bf16 v[58:61], v[164:167], v[188:191], v[58:61]
	v_mfma_f32_16x16x32_bf16 v[46:49], v[156:159], v[196:199], v[46:49]
	v_mfma_f32_16x16x32_bf16 v[42:45], v[164:167], v[196:199], v[42:45]
	v_mfma_f32_16x16x32_bf16 v[30:33], v[156:159], v[204:207], v[30:33]
	v_mfma_f32_16x16x32_bf16 v[26:29], v[164:167], v[204:207], v[26:29]
	v_mfma_f32_16x16x32_bf16 v[14:17], v[156:159], v[212:215], v[14:17]
	v_mfma_f32_16x16x32_bf16 v[10:13], v[164:167], v[212:215], v[10:13]
	v_mfma_f32_16x16x32_bf16 v[54:57], v[168:171], v[184:187], v[54:57]
	v_mfma_f32_16x16x32_bf16 v[50:53], v[176:179], v[184:187], v[50:53]
	v_mfma_f32_16x16x32_bf16 v[38:41], v[168:171], v[192:195], v[38:41]
	v_mfma_f32_16x16x32_bf16 v[34:37], v[176:179], v[192:195], v[34:37]
	v_mfma_f32_16x16x32_bf16 v[22:25], v[168:171], v[200:203], v[22:25]
	v_mfma_f32_16x16x32_bf16 v[18:21], v[176:179], v[200:203], v[18:21]
	v_mfma_f32_16x16x32_bf16 v[6:9], v[168:171], v[208:211], v[6:9]
	v_mfma_f32_16x16x32_bf16 v[2:5], v[176:179], v[208:211], v[2:5]
	v_mfma_f32_16x16x32_bf16 v[54:57], v[172:175], v[188:191], v[54:57]
	v_mfma_f32_16x16x32_bf16 v[50:53], v[180:183], v[188:191], v[50:53]
	v_mfma_f32_16x16x32_bf16 v[38:41], v[172:175], v[196:199], v[38:41]
	v_mfma_f32_16x16x32_bf16 v[34:37], v[180:183], v[196:199], v[34:37]
	v_mfma_f32_16x16x32_bf16 v[22:25], v[172:175], v[204:207], v[22:25]
	v_mfma_f32_16x16x32_bf16 v[18:21], v[180:183], v[204:207], v[18:21]
	v_mfma_f32_16x16x32_bf16 v[6:9], v[172:175], v[212:215], v[6:9]
	v_mfma_f32_16x16x32_bf16 v[2:5], v[180:183], v[212:215], v[2:5]
	s_barrier
;     ...
;         for (int t = 2; t < nt; t += 2) PG8_KITER(t);
	s_setprio 0
	ds_read_b128 v[148:151], v146
	ds_read_b128 v[156:159], v146 offset:1024
	ds_read_b128 v[160:163], v146 offset:2048
	ds_read_b128 v[164:167], v146 offset:3072
	ds_read_b128 v[168:171], v147
	ds_read_b128 v[172:175], v147 offset:1024
	ds_read_b128 v[176:179], v147 offset:2048
	ds_read_b128 v[180:183], v147 offset:3072
	s_add_u32 s22, s22, 0x2b0000
	s_addc_u32 s23, s23, 0
	s_mov_b32 m0, s28
	s_nop 0
	global_load_lds_dwordx4 v130, s[100:101]
	s_mov_b32 m0, s29
	s_nop 0
	global_load_lds_dwordx4 v134, s[100:101]
	s_mov_b32 m0, s30
	ds_read_b128 v[184:187], v154 offset:32768
	ds_read_b128 v[188:191], v154 offset:33792
	ds_read_b128 v[192:195], v154 offset:34816
	ds_read_b128 v[196:199], v154 offset:35840
	ds_read_b128 v[200:203], v154 offset:36864
	ds_read_b128 v[204:207], v154 offset:37888
	ds_read_b128 v[208:211], v154 offset:38912
	ds_read_b128 v[212:215], v154 offset:39936
	global_load_lds_dwordx4 v130, s[22:23]
	s_mov_b32 m0, s31
	s_nop 0
	global_load_lds_dwordx4 v134, s[22:23]
	s_waitcnt vmcnt(8)
	s_waitcnt lgkmcnt(0)
	s_setprio 1
	s_barrier
	v_mfma_f32_16x16x32_bf16 v[126:129], v[148:151], v[184:187], v[126:129]
	v_mfma_f32_16x16x32_bf16 v[122:125], v[160:163], v[184:187], v[122:125]
	v_mfma_f32_16x16x32_bf16 v[110:113], v[148:151], v[192:195], v[110:113]
	v_mfma_f32_16x16x32_bf16 v[106:109], v[160:163], v[192:195], v[106:109]
	v_mfma_f32_16x16x32_bf16 v[94:97], v[148:151], v[200:203], v[94:97]
	v_mfma_f32_16x16x32_bf16 v[90:93], v[160:163], v[200:203], v[90:93]
	v_mfma_f32_16x16x32_bf16 v[78:81], v[148:151], v[208:211], v[78:81]
	v_mfma_f32_16x16x32_bf16 v[74:77], v[160:163], v[208:211], v[74:77]
	v_mfma_f32_16x16x32_bf16 v[126:129], v[156:159], v[188:191], v[126:129]
	v_mfma_f32_16x16x32_bf16 v[122:125], v[164:167], v[188:191], v[122:125]
	v_mfma_f32_16x16x32_bf16 v[110:113], v[156:159], v[196:199], v[110:113]
	v_mfma_f32_16x16x32_bf16 v[106:109], v[164:167], v[196:199], v[106:109]
	v_mfma_f32_16x16x32_bf16 v[94:97], v[156:159], v[204:207], v[94:97]
	v_mfma_f32_16x16x32_bf16 v[90:93], v[164:167], v[204:207], v[90:93]
	v_mfma_f32_16x16x32_bf16 v[78:81], v[156:159], v[212:215], v[78:81]
	v_mfma_f32_16x16x32_bf16 v[74:77], v[164:167], v[212:215], v[74:77]
	v_mfma_f32_16x16x32_bf16 v[118:121], v[168:171], v[184:187], v[118:121]
	v_mfma_f32_16x16x32_bf16 v[114:117], v[176:179], v[184:187], v[114:117]
	v_mfma_f32_16x16x32_bf16 v[102:105], v[168:171], v[192:195], v[102:105]
	v_mfma_f32_16x16x32_bf16 v[98:101], v[176:179], v[192:195], v[98:101]
	v_mfma_f32_16x16x32_bf16 v[86:89], v[168:171], v[200:203], v[86:89]
	v_mfma_f32_16x16x32_bf16 v[82:85], v[176:179], v[200:203], v[82:85]
	v_mfma_f32_16x16x32_bf16 v[70:73], v[168:171], v[208:211], v[70:73]
	v_mfma_f32_16x16x32_bf16 v[66:69], v[176:179], v[208:211], v[66:69]
	v_mfma_f32_16x16x32_bf16 v[118:121], v[172:175], v[188:191], v[118:121]
	v_mfma_f32_16x16x32_bf16 v[114:117], v[180:183], v[188:191], v[114:117]
	v_mfma_f32_16x16x32_bf16 v[102:105], v[172:175], v[196:199], v[102:105]
	v_mfma_f32_16x16x32_bf16 v[98:101], v[180:183], v[196:199], v[98:101]
	v_mfma_f32_16x16x32_bf16 v[86:89], v[172:175], v[204:207], v[86:89]
	v_mfma_f32_16x16x32_bf16 v[82:85], v[180:183], v[204:207], v[82:85]
	v_mfma_f32_16x16x32_bf16 v[70:73], v[172:175], v[212:215], v[70:73]
	v_mfma_f32_16x16x32_bf16 v[66:69], v[180:183], v[212:215], v[66:69]
	s_barrier
	s_setprio 0
	s_mov_b32 m0, s53
	s_add_u32 s98, s98, 0x80
	s_addc_u32 s99, s99, 0
	s_add_u32 s100, s100, 0x80
	s_addc_u32 s101, s101, 0
	s_add_u32 s20, s20, 0x2b0080
	ds_read_b128 v[184:187], v154 offset:49152
	ds_read_b128 v[188:191], v154 offset:50176
	ds_read_b128 v[192:195], v154 offset:51200
	ds_read_b128 v[196:199], v154 offset:52224
	ds_read_b128 v[200:203], v154 offset:53248
	ds_read_b128 v[204:207], v154 offset:54272
	ds_read_b128 v[208:211], v154 offset:55296
	ds_read_b128 v[212:215], v154 offset:56320
	global_load_lds_dwordx4 v132, s[98:99]
	s_mov_b32 m0, s54
	s_addc_u32 s21, s21, 0
	global_load_lds_dwordx4 v136, s[98:99]
	s_mov_b32 m0, s55
	s_nop 0
	global_load_lds_dwordx4 v132, s[20:21]
	s_mov_b32 m0, s56
	s_nop 0
	global_load_lds_dwordx4 v136, s[20:21]
	s_waitcnt vmcnt(6)
	s_waitcnt lgkmcnt(0)
	s_setprio 1
	s_barrier
	v_mfma_f32_16x16x32_bf16 v[62:65], v[148:151], v[184:187], v[62:65]
	v_mfma_f32_16x16x32_bf16 v[58:61], v[160:163], v[184:187], v[58:61]
	v_mfma_f32_16x16x32_bf16 v[46:49], v[148:151], v[192:195], v[46:49]
	v_mfma_f32_16x16x32_bf16 v[42:45], v[160:163], v[192:195], v[42:45]
	v_mfma_f32_16x16x32_bf16 v[30:33], v[148:151], v[200:203], v[30:33]
	v_mfma_f32_16x16x32_bf16 v[26:29], v[160:163], v[200:203], v[26:29]
	v_mfma_f32_16x16x32_bf16 v[14:17], v[148:151], v[208:211], v[14:17]
	v_mfma_f32_16x16x32_bf16 v[10:13], v[160:163], v[208:211], v[10:13]
	v_mfma_f32_16x16x32_bf16 v[62:65], v[156:159], v[188:191], v[62:65]
	v_mfma_f32_16x16x32_bf16 v[58:61], v[164:167], v[188:191], v[58:61]
	v_mfma_f32_16x16x32_bf16 v[46:49], v[156:159], v[196:199], v[46:49]
	v_mfma_f32_16x16x32_bf16 v[42:45], v[164:167], v[196:199], v[42:45]
	v_mfma_f32_16x16x32_bf16 v[30:33], v[156:159], v[204:207], v[30:33]
	v_mfma_f32_16x16x32_bf16 v[26:29], v[164:167], v[204:207], v[26:29]
	v_mfma_f32_16x16x32_bf16 v[14:17], v[156:159], v[212:215], v[14:17]
	v_mfma_f32_16x16x32_bf16 v[10:13], v[164:167], v[212:215], v[10:13]
	v_mfma_f32_16x16x32_bf16 v[54:57], v[168:171], v[184:187], v[54:57]
	v_mfma_f32_16x16x32_bf16 v[50:53], v[176:179], v[184:187], v[50:53]
	v_mfma_f32_16x16x32_bf16 v[38:41], v[168:171], v[192:195], v[38:41]
	v_mfma_f32_16x16x32_bf16 v[34:37], v[176:179], v[192:195], v[34:37]
	v_mfma_f32_16x16x32_bf16 v[22:25], v[168:171], v[200:203], v[22:25]
	v_mfma_f32_16x16x32_bf16 v[18:21], v[176:179], v[200:203], v[18:21]
	v_mfma_f32_16x16x32_bf16 v[6:9], v[168:171], v[208:211], v[6:9]
	v_mfma_f32_16x16x32_bf16 v[2:5], v[176:179], v[208:211], v[2:5]
	v_mfma_f32_16x16x32_bf16 v[54:57], v[172:175], v[188:191], v[54:57]
	v_mfma_f32_16x16x32_bf16 v[50:53], v[180:183], v[188:191], v[50:53]
	v_mfma_f32_16x16x32_bf16 v[38:41], v[172:175], v[196:199], v[38:41]
	v_mfma_f32_16x16x32_bf16 v[34:37], v[180:183], v[196:199], v[34:37]
	v_mfma_f32_16x16x32_bf16 v[22:25], v[172:175], v[204:207], v[22:25]
	v_mfma_f32_16x16x32_bf16 v[18:21], v[180:183], v[204:207], v[18:21]
	v_mfma_f32_16x16x32_bf16 v[6:9], v[172:175], v[212:215], v[6:9]
	v_mfma_f32_16x16x32_bf16 v[2:5], v[180:183], v[212:215], v[2:5]
	s_barrier
	s_setprio 0
	s_add_i32 s57, s57, 2
	s_add_u32 s18, s18, 0x100
	s_addc_u32 s19, s19, 0
	s_add_u32 s26, s26, 0x100
	s_addc_u32 s27, s27, 0
	s_cmpk_gt_u32 s57, 0xa9
	s_cbranch_scc0 .LBB0_1425
	s_mov_b32 m0, s34
	s_nop 0
	global_load_lds_dwordx4 v130, s[100:101]
	s_mov_b32 m0, s35
	s_nop 0
	global_load_lds_dwordx4 v134, s[100:101]
	s_and_b64 vcc, exec, s[10:11]
	s_cbranch_vccz .LBB0_1428
	s_barrier
